# dropdup
# speedup vs baseline: 1.0671x; 1.0671x over previous
; #define STAGE(P, BASE, LD, br, kt) do { const char* _g = (const char*)((BASE) + (size_t)(br) * (LD) + (size_t)(kt) * 64); \
;     for (int _i = 0; _i < 2; ++_i) { int _b = tidx * 16 + _i * 8192; int _r, _c; stage_rc(_b, _r, _c); \
;       __builtin_amdgcn_global_load_lds((const unsigned*)(_g + (unsigned)((_r * (LD) + _c) * 2)), (unsigned*)((char*)(P) + _b), 16, 0, 0); } } while (0)
; #define LDA(dst, b, h) for (int m = 0; m < 4; ++m) for (int k = 0; k < 2; ++k) \
;     dst[m][k] = *reinterpret_cast<const bf16x8*>((char*)SA(b, h) + lds_byte(wr * 64 + m * 16 + fr, k * 32 + fq * 8))
; #define LDB(dst, b, h) for (int n = 0; n < 2; ++n) for (int k = 0; k < 2; ++k) \
;     dst[n][k] = *reinterpret_cast<const bf16x8*>((char*)SB(b, h) + lds_byte(wc * 32 + n * 16 + fr, k * 32 + fq * 8))
; #define MMA(ai, bj, At_, Bt_) do { __builtin_amdgcn_s_setprio(1); \
;     for (int k = 0; k < 2; ++k) for (int m = 0; m < 4; ++m) for (int n = 0; n < 2; ++n) \
;       acc[ai][bj][m][n] = __builtin_amdgcn_mfma_f32_16x16x32_bf16(At_[m][k], Bt_[n][k], acc[ai][bj][m][n], 0, 0, 0); \
;     __builtin_amdgcn_s_setprio(0); } while (0)
; #define WAIT_L(n) asm volatile("s_waitcnt lgkmcnt(" #n ")" ::: "memory")
; #define BAR __builtin_amdgcn_s_barrier()
; #define SCHED __builtin_amdgcn_sched_barrier(0)
; template <int EPI, int lda, int ldb, int N, int K>
; __device__ __forceinline__ void gemm_phase(const u16* __restrict__ A, const u16* __restrict__ Bt, const GemmEpi ep, int wv) {
;     ...
;       LDB(B0, 0, 0); SCHED; LDA(At, 0, 0); STAGE(SA(1, 1), Ab, lda, brow + HALF, t + 1);
;       WAIT_L(8); BAR; WAIT_L(0); MMA(0, 0, At, B0); BAR; SCHED;
;       LDB(B1, 0, 1); STAGE(SB(0, 0), Bt, ldb, bcol, t + 2);
;       BAR; WAIT_L(0); MMA(0, 1, At, B1); BAR;
;       LDA(At, 0, 1); STAGE(SA(0, 0), Ab, lda, brow, t + 2);
;       BAR; WAIT_L(0); MMA(1, 0, At, B0); BAR; SCHED;
.LBB0_53:
	ds_read_b128 v[172:175], v161
	ds_read_b128 v[176:179], v161 offset:1024
	ds_read_b128 v[180:183], v161 offset:2048
	ds_read_b128 v[184:187], v161 offset:3072
	v_add_u32_e32 v169, 0xc000, v148
	v_lshl_add_u64 v[236:237], v[136:137], 0, s[42:43]
	v_readfirstlane_b32 s45, v169
	v_add_u32_e32 v170, 0xe000, v148
	v_lshl_add_u64 v[162:163], v[236:237], 0, s[14:15]
	s_mov_b32 m0, s45
	v_lshl_add_u64 v[238:239], v[134:135], 0, s[42:43]
	v_readfirstlane_b32 s45, v170
	ds_read_b128 v[164:167], v152
	ds_read_b128 v[188:191], v152 offset:1024
	ds_read_b128 v[192:195], v151
	ds_read_b128 v[196:199], v151 offset:1024
	ds_read_b128 v[200:203], v150
	ds_read_b128 v[204:207], v150 offset:1024
	ds_read_b128 v[208:211], v149
	ds_read_b128 v[212:215], v149 offset:1024
	global_load_lds_dwordx4 v[162:163], off
	v_lshl_add_u64 v[162:163], v[238:239], 0, s[14:15]
	s_mov_b32 m0, s45
	s_nop 0
	global_load_lds_dwordx4 v[162:163], off
	s_waitcnt lgkmcnt(8)
	s_barrier
	s_waitcnt lgkmcnt(0)
	v_mfma_f32_16x16x32_bf16 v[124:127], v[172:175], v[164:167], v[124:127]
	v_mfma_f32_16x16x32_bf16 v[120:123], v[180:183], v[164:167], v[120:123]
	v_mfma_f32_16x16x32_bf16 v[116:119], v[172:175], v[192:195], v[116:119]
	v_mfma_f32_16x16x32_bf16 v[112:115], v[180:183], v[192:195], v[112:115]
	v_mfma_f32_16x16x32_bf16 v[108:111], v[172:175], v[200:203], v[108:111]
	v_mfma_f32_16x16x32_bf16 v[104:107], v[180:183], v[200:203], v[104:107]
	v_mfma_f32_16x16x32_bf16 v[100:103], v[172:175], v[208:211], v[100:103]
	v_mfma_f32_16x16x32_bf16 v[96:99], v[180:183], v[208:211], v[96:99]
	v_mfma_f32_16x16x32_bf16 v[124:127], v[176:179], v[188:191], v[124:127]
	v_mfma_f32_16x16x32_bf16 v[120:123], v[184:187], v[188:191], v[120:123]
	v_mfma_f32_16x16x32_bf16 v[116:119], v[176:179], v[196:199], v[116:119]
	v_mfma_f32_16x16x32_bf16 v[112:115], v[184:187], v[196:199], v[112:115]
	v_mfma_f32_16x16x32_bf16 v[108:111], v[176:179], v[204:207], v[108:111]
	v_mfma_f32_16x16x32_bf16 v[104:107], v[184:187], v[204:207], v[104:107]
	v_mfma_f32_16x16x32_bf16 v[100:103], v[176:179], v[212:215], v[100:103]
	v_mfma_f32_16x16x32_bf16 v[96:99], v[184:187], v[212:215], v[96:99]
	s_barrier
	v_add_u32_e32 v162, s54, v153
	v_lshl_add_u64 v[240:241], v[140:141], 0, s[42:43]
	v_readfirstlane_b32 s45, v162
	v_add_u32_e32 v163, 0x2000, v162
	v_lshl_add_u64 v[232:233], v[240:241], 0, s[16:17]
	s_mov_b32 m0, s45
	v_lshl_add_u64 v[242:243], v[138:139], 0, s[42:43]
	v_readfirstlane_b32 s45, v163
	ds_read_b128 v[216:219], v160
	ds_read_b128 v[220:223], v160 offset:1024
	ds_read_b128 v[224:227], v160 offset:2048
	ds_read_b128 v[228:231], v160 offset:3072
	global_load_lds_dwordx4 v[232:233], off
	v_lshl_add_u64 v[232:233], v[242:243], 0, s[16:17]
	s_mov_b32 m0, s45
	s_nop 0
	global_load_lds_dwordx4 v[232:233], off
	s_barrier
	s_waitcnt lgkmcnt(0)
	v_mfma_f32_16x16x32_bf16 v[92:95], v[216:219], v[164:167], v[92:95]
	v_mfma_f32_16x16x32_bf16 v[88:91], v[224:227], v[164:167], v[88:91]
	v_mfma_f32_16x16x32_bf16 v[84:87], v[216:219], v[192:195], v[84:87]
	v_mfma_f32_16x16x32_bf16 v[80:83], v[224:227], v[192:195], v[80:83]
	v_mfma_f32_16x16x32_bf16 v[76:79], v[216:219], v[200:203], v[76:79]
	v_mfma_f32_16x16x32_bf16 v[72:75], v[224:227], v[200:203], v[72:75]
	v_mfma_f32_16x16x32_bf16 v[68:71], v[216:219], v[208:211], v[68:71]
	v_mfma_f32_16x16x32_bf16 v[64:67], v[224:227], v[208:211], v[64:67]
	v_mfma_f32_16x16x32_bf16 v[92:95], v[220:223], v[188:191], v[92:95]
	v_mfma_f32_16x16x32_bf16 v[88:91], v[228:231], v[188:191], v[88:91]
	v_mfma_f32_16x16x32_bf16 v[84:87], v[220:223], v[196:199], v[84:87]
	v_mfma_f32_16x16x32_bf16 v[80:83], v[228:231], v[196:199], v[80:83]
	v_mfma_f32_16x16x32_bf16 v[76:79], v[220:223], v[204:207], v[76:79]
	v_mfma_f32_16x16x32_bf16 v[72:75], v[228:231], v[204:207], v[72:75]
	v_mfma_f32_16x16x32_bf16 v[68:71], v[220:223], v[212:215], v[68:71]
	v_mfma_f32_16x16x32_bf16 v[64:67], v[228:231], v[212:215], v[64:67]
	v_readfirstlane_b32 s45, v148
	v_lshl_add_u64 v[164:165], v[236:237], 0, s[18:19]
	s_mov_b32 m0, s45
	s_barrier
	ds_read_b128 v[188:191], v152 offset:16384
	ds_read_b128 v[192:195], v152 offset:17408
	ds_read_b128 v[196:199], v151 offset:16384
	ds_read_b128 v[200:203], v151 offset:17408
	ds_read_b128 v[204:207], v150 offset:16384
	ds_read_b128 v[208:211], v150 offset:17408
	ds_read_b128 v[212:215], v149 offset:16384
	ds_read_b128 v[232:235], v149 offset:17408
	global_load_lds_dwordx4 v[164:165], off
	v_add_u32_e32 v164, 0x2000, v148
	v_lshl_add_u64 v[166:167], v[238:239], 0, s[18:19]
	v_readfirstlane_b32 s45, v164
	s_mov_b32 m0, s45
	s_nop 0
	global_load_lds_dwordx4 v[166:167], off
	s_barrier
	s_waitcnt lgkmcnt(0)
	v_mfma_f32_16x16x32_bf16 v[60:63], v[172:175], v[188:191], v[60:63]
	v_mfma_f32_16x16x32_bf16 v[56:59], v[180:183], v[188:191], v[56:59]
	v_mfma_f32_16x16x32_bf16 v[52:55], v[172:175], v[196:199], v[52:55]
	v_mfma_f32_16x16x32_bf16 v[48:51], v[180:183], v[196:199], v[48:51]
	v_mfma_f32_16x16x32_bf16 v[44:47], v[172:175], v[204:207], v[44:47]
	v_mfma_f32_16x16x32_bf16 v[40:43], v[180:183], v[204:207], v[40:43]
	v_mfma_f32_16x16x32_bf16 v[36:39], v[172:175], v[212:215], v[36:39]
	v_mfma_f32_16x16x32_bf16 v[32:35], v[180:183], v[212:215], v[32:35]
	v_mfma_f32_16x16x32_bf16 v[60:63], v[176:179], v[192:195], v[60:63]
	v_mfma_f32_16x16x32_bf16 v[56:59], v[184:187], v[192:195], v[56:59]
	v_mfma_f32_16x16x32_bf16 v[52:55], v[176:179], v[200:203], v[52:55]
	v_mfma_f32_16x16x32_bf16 v[48:51], v[184:187], v[200:203], v[48:51]
	v_mfma_f32_16x16x32_bf16 v[44:47], v[176:179], v[208:211], v[44:47]
	v_mfma_f32_16x16x32_bf16 v[40:43], v[184:187], v[208:211], v[40:43]
	v_mfma_f32_16x16x32_bf16 v[36:39], v[176:179], v[232:235], v[36:39]
	v_mfma_f32_16x16x32_bf16 v[32:35], v[184:187], v[232:235], v[32:35]
	s_barrier
; #define STAGE(P, BASE, LD, br, kt) do { const char* _g = (const char*)((BASE) + (size_t)(br) * (LD) + (size_t)(kt) * 64); \
;     for (int _i = 0; _i < 2; ++_i) { int _b = tidx * 16 + _i * 8192; int _r, _c; stage_rc(_b, _r, _c); \
;       __builtin_amdgcn_global_load_lds((const unsigned*)(_g + (unsigned)((_r * (LD) + _c) * 2)), (unsigned*)((char*)(P) + _b), 16, 0, 0); } } while (0)
; #define LDA(dst, b, h) for (int m = 0; m < 4; ++m) for (int k = 0; k < 2; ++k) \
;     dst[m][k] = *reinterpret_cast<const bf16x8*>((char*)SA(b, h) + lds_byte(wr * 64 + m * 16 + fr, k * 32 + fq * 8))
; #define LDB(dst, b, h) for (int n = 0; n < 2; ++n) for (int k = 0; k < 2; ++k) \
;     dst[n][k] = *reinterpret_cast<const bf16x8*>((char*)SB(b, h) + lds_byte(wc * 32 + n * 16 + fr, k * 32 + fq * 8))
; #define MMA(ai, bj, At_, Bt_) do { __builtin_amdgcn_s_setprio(1); \
;     for (int k = 0; k < 2; ++k) for (int m = 0; m < 4; ++m) for (int n = 0; n < 2; ++n) \
;       acc[ai][bj][m][n] = __builtin_amdgcn_mfma_f32_16x16x32_bf16(At_[m][k], Bt_[n][k], acc[ai][bj][m][n], 0, 0, 0); \
;     __builtin_amdgcn_s_setprio(0); } while (0)
; #define WAIT_V(n) asm volatile("s_waitcnt vmcnt(" #n ")" ::: "memory")
; #define WAIT_L(n) asm volatile("s_waitcnt lgkmcnt(" #n ")" ::: "memory")
; #define BAR __builtin_amdgcn_s_barrier()
; #define SCHED __builtin_amdgcn_sched_barrier(0)
; template <int EPI, int lda, int ldb, int N, int K>
; __device__ __forceinline__ void gemm_phase(const u16* __restrict__ A, const u16* __restrict__ Bt, const GemmEpi ep, int wv) {
;     ...
;       STAGE(SB(0, 1), Bt, ldb, bcol + HALF, t + 2);
;       WAIT_V(6); BAR; MMA(1, 1, At, B1); BAR;
;       LDB(B0, 1, 0); SCHED; LDA(At, 1, 0); STAGE(SA(0, 1), Ab, lda, brow + HALF, t + 2);
;       WAIT_L(8); BAR; WAIT_L(0); MMA(0, 0, At, B0); BAR; SCHED;
;       LDB(B1, 1, 1); STAGE(SB(1, 0), Bt, ldb, bcol, t + 3);
;       BAR; WAIT_L(0); MMA(0, 1, At, B1); BAR;
;       LDA(At, 1, 1); STAGE(SA(1, 0), Ab, lda, brow, t + 3);
	v_add_u32_e32 v165, s55, v153
	v_lshl_add_u64 v[166:167], v[240:241], 0, s[20:21]
	v_readfirstlane_b32 s45, v165
	s_mov_b32 m0, s45
	v_lshl_add_u64 v[172:173], v[242:243], 0, s[20:21]
	global_load_lds_dwordx4 v[166:167], off
	v_add_u32_e32 v166, 0x2000, v165
	s_nop 0
	v_readfirstlane_b32 s45, v166
	s_mov_b32 m0, s45
	s_nop 0
	global_load_lds_dwordx4 v[172:173], off
	s_waitcnt vmcnt(6)
	s_barrier
	v_mfma_f32_16x16x32_bf16 v[28:31], v[216:219], v[188:191], v[28:31]
	v_mfma_f32_16x16x32_bf16 v[24:27], v[224:227], v[188:191], v[24:27]
	v_mfma_f32_16x16x32_bf16 v[20:23], v[216:219], v[196:199], v[20:23]
	v_mfma_f32_16x16x32_bf16 v[16:19], v[224:227], v[196:199], v[16:19]
	v_mfma_f32_16x16x32_bf16 v[12:15], v[216:219], v[204:207], v[12:15]
	v_mfma_f32_16x16x32_bf16 v[8:11], v[224:227], v[204:207], v[8:11]
	v_mfma_f32_16x16x32_bf16 v[4:7], v[216:219], v[212:215], v[4:7]
	v_mfma_f32_16x16x32_bf16 v[0:3], v[224:227], v[212:215], v[0:3]
	v_mfma_f32_16x16x32_bf16 v[28:31], v[220:223], v[192:195], v[28:31]
	v_mfma_f32_16x16x32_bf16 v[24:27], v[228:231], v[192:195], v[24:27]
	v_mfma_f32_16x16x32_bf16 v[20:23], v[220:223], v[200:203], v[20:23]
	v_mfma_f32_16x16x32_bf16 v[16:19], v[228:231], v[200:203], v[16:19]
	v_mfma_f32_16x16x32_bf16 v[12:15], v[220:223], v[208:211], v[12:15]
	v_mfma_f32_16x16x32_bf16 v[8:11], v[228:231], v[208:211], v[8:11]
	v_mfma_f32_16x16x32_bf16 v[4:7], v[220:223], v[232:235], v[4:7]
	v_mfma_f32_16x16x32_bf16 v[0:3], v[228:231], v[232:235], v[0:3]
	s_barrier
	ds_read_b128 v[172:175], v156
	ds_read_b128 v[176:179], v156 offset:1024
	ds_read_b128 v[180:183], v156 offset:2048
	ds_read_b128 v[184:187], v156 offset:3072
	v_add_u32_e32 v167, 0x4000, v148
	v_add_u32_e32 v168, 0x6000, v148
	v_readfirstlane_b32 s45, v167
	v_lshl_add_u64 v[220:221], v[236:237], 0, s[22:23]
	s_mov_b32 m0, s45
	v_readfirstlane_b32 s45, v168
	ds_read_b128 v[188:191], v152 offset:32768
	ds_read_b128 v[192:195], v152 offset:33792
	ds_read_b128 v[196:199], v151 offset:32768
	ds_read_b128 v[200:203], v151 offset:33792
	ds_read_b128 v[204:207], v150 offset:32768
	ds_read_b128 v[208:211], v150 offset:33792
	ds_read_b128 v[212:215], v149 offset:32768
	ds_read_b128 v[216:219], v149 offset:33792
	global_load_lds_dwordx4 v[220:221], off
	v_lshl_add_u64 v[220:221], v[238:239], 0, s[22:23]
	s_mov_b32 m0, s45
	s_nop 0
	global_load_lds_dwordx4 v[220:221], off
	s_waitcnt lgkmcnt(8)
	s_barrier
	s_waitcnt lgkmcnt(0)
	v_mfma_f32_16x16x32_bf16 v[124:127], v[172:175], v[188:191], v[124:127]
	v_mfma_f32_16x16x32_bf16 v[120:123], v[180:183], v[188:191], v[120:123]
	v_mfma_f32_16x16x32_bf16 v[116:119], v[172:175], v[196:199], v[116:119]
	v_mfma_f32_16x16x32_bf16 v[112:115], v[180:183], v[196:199], v[112:115]
	v_mfma_f32_16x16x32_bf16 v[108:111], v[172:175], v[204:207], v[108:111]
	v_mfma_f32_16x16x32_bf16 v[104:107], v[180:183], v[204:207], v[104:107]
	v_mfma_f32_16x16x32_bf16 v[100:103], v[172:175], v[212:215], v[100:103]
	v_mfma_f32_16x16x32_bf16 v[96:99], v[180:183], v[212:215], v[96:99]
	v_mfma_f32_16x16x32_bf16 v[124:127], v[176:179], v[192:195], v[124:127]
	v_mfma_f32_16x16x32_bf16 v[120:123], v[184:187], v[192:195], v[120:123]
	v_mfma_f32_16x16x32_bf16 v[116:119], v[176:179], v[200:203], v[116:119]
	v_mfma_f32_16x16x32_bf16 v[112:115], v[184:187], v[200:203], v[112:115]
	v_mfma_f32_16x16x32_bf16 v[108:111], v[176:179], v[208:211], v[108:111]
	v_mfma_f32_16x16x32_bf16 v[104:107], v[184:187], v[208:211], v[104:107]
	v_mfma_f32_16x16x32_bf16 v[100:103], v[176:179], v[216:219], v[100:103]
	v_mfma_f32_16x16x32_bf16 v[96:99], v[184:187], v[216:219], v[96:99]
	s_barrier
	v_readfirstlane_b32 s45, v155
	v_add_u32_e32 v171, 0x2000, v155
	v_lshl_add_u64 v[244:245], v[240:241], 0, s[24:25]
	s_mov_b32 m0, s45
	v_readfirstlane_b32 s45, v171
	ds_read_b128 v[220:223], v154
	ds_read_b128 v[224:227], v154 offset:1024
	ds_read_b128 v[228:231], v154 offset:2048
	ds_read_b128 v[232:235], v154 offset:3072
	global_load_lds_dwordx4 v[244:245], off
	v_lshl_add_u64 v[244:245], v[242:243], 0, s[24:25]
	s_mov_b32 m0, s45
	s_nop 0
	global_load_lds_dwordx4 v[244:245], off
	s_barrier
	s_waitcnt lgkmcnt(0)
	v_mfma_f32_16x16x32_bf16 v[92:95], v[220:223], v[188:191], v[92:95]
	v_mfma_f32_16x16x32_bf16 v[88:91], v[228:231], v[188:191], v[88:91]
	v_mfma_f32_16x16x32_bf16 v[84:87], v[220:223], v[196:199], v[84:87]
	v_mfma_f32_16x16x32_bf16 v[80:83], v[228:231], v[196:199], v[80:83]
	v_mfma_f32_16x16x32_bf16 v[76:79], v[220:223], v[204:207], v[76:79]
	v_mfma_f32_16x16x32_bf16 v[72:75], v[228:231], v[204:207], v[72:75]
	v_mfma_f32_16x16x32_bf16 v[68:71], v[220:223], v[212:215], v[68:71]
	v_mfma_f32_16x16x32_bf16 v[64:67], v[228:231], v[212:215], v[64:67]
	v_mfma_f32_16x16x32_bf16 v[92:95], v[224:227], v[192:195], v[92:95]
	v_mfma_f32_16x16x32_bf16 v[88:91], v[232:235], v[192:195], v[88:91]
	v_mfma_f32_16x16x32_bf16 v[84:87], v[224:227], v[200:203], v[84:87]
	v_mfma_f32_16x16x32_bf16 v[80:83], v[232:235], v[200:203], v[80:83]
	v_mfma_f32_16x16x32_bf16 v[76:79], v[224:227], v[208:211], v[76:79]
	v_mfma_f32_16x16x32_bf16 v[72:75], v[232:235], v[208:211], v[72:75]
	v_mfma_f32_16x16x32_bf16 v[68:71], v[224:227], v[216:219], v[68:71]
	v_mfma_f32_16x16x32_bf16 v[64:67], v[232:235], v[216:219], v[64:67]
	v_readfirstlane_b32 s45, v157
	v_lshl_add_u64 v[236:237], v[236:237], 0, s[26:27]
	s_mov_b32 m0, s45
	v_readfirstlane_b32 s45, v158
	s_barrier
	ds_read_b128 v[188:191], v152 offset:49152
	ds_read_b128 v[192:195], v152 offset:50176
	ds_read_b128 v[196:199], v151 offset:49152
	ds_read_b128 v[200:203], v151 offset:50176
	ds_read_b128 v[204:207], v150 offset:49152
	ds_read_b128 v[208:211], v150 offset:50176
	ds_read_b128 v[212:215], v149 offset:49152
	ds_read_b128 v[216:219], v149 offset:50176
	global_load_lds_dwordx4 v[236:237], off
	v_lshl_add_u64 v[236:237], v[238:239], 0, s[26:27]
	s_mov_b32 m0, s45
	s_nop 0
	global_load_lds_dwordx4 v[236:237], off
	s_barrier
; #define STAGE(P, BASE, LD, br, kt) do { const char* _g = (const char*)((BASE) + (size_t)(br) * (LD) + (size_t)(kt) * 64); \
;     for (int _i = 0; _i < 2; ++_i) { int _b = tidx * 16 + _i * 8192; int _r, _c; stage_rc(_b, _r, _c); \
;       __builtin_amdgcn_global_load_lds((const unsigned*)(_g + (unsigned)((_r * (LD) + _c) * 2)), (unsigned*)((char*)(P) + _b), 16, 0, 0); } } while (0)
; #define LDA(dst, b, h) for (int m = 0; m < 4; ++m) for (int k = 0; k < 2; ++k) \
;     dst[m][k] = *reinterpret_cast<const bf16x8*>((char*)SA(b, h) + lds_byte(wr * 64 + m * 16 + fr, k * 32 + fq * 8))
; #define LDB(dst, b, h) for (int n = 0; n < 2; ++n) for (int k = 0; k < 2; ++k) \
;     dst[n][k] = *reinterpret_cast<const bf16x8*>((char*)SB(b, h) + lds_byte(wc * 32 + n * 16 + fr, k * 32 + fq * 8))
; #define MMA(ai, bj, At_, Bt_) do { __builtin_amdgcn_s_setprio(1); \
;     for (int k = 0; k < 2; ++k) for (int m = 0; m < 4; ++m) for (int n = 0; n < 2; ++n) \
;       acc[ai][bj][m][n] = __builtin_amdgcn_mfma_f32_16x16x32_bf16(At_[m][k], Bt_[n][k], acc[ai][bj][m][n], 0, 0, 0); \
;     __builtin_amdgcn_s_setprio(0); } while (0)
; #define WAIT_V(n) asm volatile("s_waitcnt vmcnt(" #n ")" ::: "memory")
; #define WAIT_L(n) asm volatile("s_waitcnt lgkmcnt(" #n ")" ::: "memory")
; #define BAR __builtin_amdgcn_s_barrier()
; #define SCHED __builtin_amdgcn_sched_barrier(0)
; template <int EPI, int lda, int ldb, int N, int K>
; __device__ __forceinline__ void gemm_phase(const u16* __restrict__ A, const u16* __restrict__ Bt, const GemmEpi ep, int wv) {
;     ...
;       LDA(At, 1, 1); STAGE(SA(1, 0), Ab, lda, brow, t + 3);
;       BAR; WAIT_L(0); MMA(1, 0, At, B0); BAR; SCHED;
;       STAGE(SB(1, 1), Bt, ldb, bcol + HALF, t + 3);
;       WAIT_V(6); BAR; MMA(1, 1, At, B1); BAR;
;     }
;     { LDB(B0, 0, 0); LDA(At, 0, 0); STAGE(SA(1, 1), Ab, lda, brow + HALF, nt - 1);
;       BAR; WAIT_L(0); MMA(0, 0, At, B0); BAR;
;       LDB(B1, 0, 1); BAR; WAIT_L(0); MMA(0, 1, At, B1); BAR;
	s_waitcnt lgkmcnt(0)
	v_mfma_f32_16x16x32_bf16 v[60:63], v[172:175], v[188:191], v[60:63]
	v_mfma_f32_16x16x32_bf16 v[56:59], v[180:183], v[188:191], v[56:59]
	v_mfma_f32_16x16x32_bf16 v[52:55], v[172:175], v[196:199], v[52:55]
	v_mfma_f32_16x16x32_bf16 v[48:51], v[180:183], v[196:199], v[48:51]
	v_mfma_f32_16x16x32_bf16 v[44:47], v[172:175], v[204:207], v[44:47]
	v_mfma_f32_16x16x32_bf16 v[40:43], v[180:183], v[204:207], v[40:43]
	v_mfma_f32_16x16x32_bf16 v[36:39], v[172:175], v[212:215], v[36:39]
	v_mfma_f32_16x16x32_bf16 v[32:35], v[180:183], v[212:215], v[32:35]
	v_mfma_f32_16x16x32_bf16 v[60:63], v[176:179], v[192:195], v[60:63]
	v_mfma_f32_16x16x32_bf16 v[56:59], v[184:187], v[192:195], v[56:59]
	v_mfma_f32_16x16x32_bf16 v[52:55], v[176:179], v[200:203], v[52:55]
	v_mfma_f32_16x16x32_bf16 v[48:51], v[184:187], v[200:203], v[48:51]
	v_mfma_f32_16x16x32_bf16 v[44:47], v[176:179], v[208:211], v[44:47]
	v_mfma_f32_16x16x32_bf16 v[40:43], v[184:187], v[208:211], v[40:43]
	v_mfma_f32_16x16x32_bf16 v[36:39], v[176:179], v[216:219], v[36:39]
	v_mfma_f32_16x16x32_bf16 v[32:35], v[184:187], v[216:219], v[32:35]
	s_barrier
	v_readfirstlane_b32 s45, v159
	v_add_u32_e32 v171, 0x2000, v159
	v_lshl_add_u64 v[172:173], v[240:241], 0, s[34:35]
	s_mov_b32 m0, s45
	v_readfirstlane_b32 s45, v171
	global_load_lds_dwordx4 v[172:173], off
	v_lshl_add_u64 v[172:173], v[242:243], 0, s[34:35]
	s_mov_b32 m0, s45
	s_nop 0
	global_load_lds_dwordx4 v[172:173], off
	s_waitcnt vmcnt(6)
	s_barrier
	v_mfma_f32_16x16x32_bf16 v[28:31], v[220:223], v[188:191], v[28:31]
	v_mfma_f32_16x16x32_bf16 v[24:27], v[228:231], v[188:191], v[24:27]
	v_mfma_f32_16x16x32_bf16 v[20:23], v[220:223], v[196:199], v[20:23]
	v_mfma_f32_16x16x32_bf16 v[16:19], v[228:231], v[196:199], v[16:19]
	v_mfma_f32_16x16x32_bf16 v[12:15], v[220:223], v[204:207], v[12:15]
	v_mfma_f32_16x16x32_bf16 v[8:11], v[228:231], v[204:207], v[8:11]
	v_mfma_f32_16x16x32_bf16 v[4:7], v[220:223], v[212:215], v[4:7]
	v_mfma_f32_16x16x32_bf16 v[0:3], v[228:231], v[212:215], v[0:3]
	v_mfma_f32_16x16x32_bf16 v[28:31], v[224:227], v[192:195], v[28:31]
	v_mfma_f32_16x16x32_bf16 v[24:27], v[232:235], v[192:195], v[24:27]
	v_mfma_f32_16x16x32_bf16 v[20:23], v[224:227], v[200:203], v[20:23]
	v_mfma_f32_16x16x32_bf16 v[16:19], v[232:235], v[200:203], v[16:19]
	v_mfma_f32_16x16x32_bf16 v[12:15], v[224:227], v[208:211], v[12:15]
	v_mfma_f32_16x16x32_bf16 v[8:11], v[232:235], v[208:211], v[8:11]
	v_mfma_f32_16x16x32_bf16 v[4:7], v[224:227], v[216:219], v[4:7]
	v_mfma_f32_16x16x32_bf16 v[0:3], v[232:235], v[216:219], v[0:3]
	s_add_i32 s44, s44, 2
	s_add_u32 s42, s42, 0x100
	s_addc_u32 s43, s43, 0
	s_cmp_gt_u32 s44, 27
	s_barrier
	s_cbranch_scc0 .LBB0_53
	s_add_i32 s42, s38, 0x80
	s_mul_hi_i32 s43, s42, 0x1080
	s_mulk_i32 s42, 0x1080
	s_add_u32 s42, s51, s42
	s_addc_u32 s43, s52, s43
	v_lshl_add_u64 v[158:159], s[42:43], 0, v[128:129]
	v_readfirstlane_b32 s44, v169
	v_lshl_add_u64 v[158:159], v[158:159], 0, s[36:37]
	s_mov_b32 m0, s44
	ds_read_b128 v[134:137], v161
	ds_read_b128 v[138:141], v161 offset:1024
	ds_read_b128 v[172:175], v161 offset:2048
	ds_read_b128 v[176:179], v161 offset:3072
	ds_read_b128 v[180:183], v152
	ds_read_b128 v[184:187], v152 offset:1024
	ds_read_b128 v[188:191], v151
	ds_read_b128 v[192:195], v151 offset:1024
	ds_read_b128 v[196:199], v150
	ds_read_b128 v[200:203], v150 offset:1024
	ds_read_b128 v[204:207], v149
	ds_read_b128 v[208:211], v149 offset:1024
	global_load_lds_dwordx4 v[158:159], off
	v_lshl_add_u64 v[158:159], s[42:43], 0, v[132:133]
	v_readfirstlane_b32 s42, v170
	v_lshl_add_u64 v[158:159], v[158:159], 0, s[36:37]
	s_mov_b32 m0, s42
	s_nop 0
	global_load_lds_dwordx4 v[158:159], off
	s_barrier
	s_waitcnt lgkmcnt(0)
	v_mfma_f32_16x16x32_bf16 v[124:127], v[134:137], v[180:183], v[124:127]
	v_mfma_f32_16x16x32_bf16 v[120:123], v[172:175], v[180:183], v[120:123]
	v_mfma_f32_16x16x32_bf16 v[116:119], v[134:137], v[188:191], v[116:119]
	v_mfma_f32_16x16x32_bf16 v[112:115], v[172:175], v[188:191], v[112:115]
	v_mfma_f32_16x16x32_bf16 v[108:111], v[134:137], v[196:199], v[108:111]
	v_mfma_f32_16x16x32_bf16 v[104:107], v[172:175], v[196:199], v[104:107]
	v_mfma_f32_16x16x32_bf16 v[100:103], v[134:137], v[204:207], v[100:103]
	v_mfma_f32_16x16x32_bf16 v[96:99], v[172:175], v[204:207], v[96:99]
	v_mfma_f32_16x16x32_bf16 v[124:127], v[138:141], v[184:187], v[124:127]
	v_mfma_f32_16x16x32_bf16 v[120:123], v[176:179], v[184:187], v[120:123]
	v_mfma_f32_16x16x32_bf16 v[116:119], v[138:141], v[192:195], v[116:119]
	v_mfma_f32_16x16x32_bf16 v[112:115], v[176:179], v[192:195], v[112:115]
	v_mfma_f32_16x16x32_bf16 v[108:111], v[138:141], v[200:203], v[108:111]
	v_mfma_f32_16x16x32_bf16 v[104:107], v[176:179], v[200:203], v[104:107]
	v_mfma_f32_16x16x32_bf16 v[100:103], v[138:141], v[208:211], v[100:103]
	v_mfma_f32_16x16x32_bf16 v[96:99], v[176:179], v[208:211], v[96:99]
	s_barrier
	ds_read_b128 v[212:215], v160
	ds_read_b128 v[216:219], v160 offset:1024
	ds_read_b128 v[220:223], v160 offset:2048
	ds_read_b128 v[158:161], v160 offset:3072
	s_barrier
; #define LDA(dst, b, h) for (int m = 0; m < 4; ++m) for (int k = 0; k < 2; ++k) \
;     dst[m][k] = *reinterpret_cast<const bf16x8*>((char*)SA(b, h) + lds_byte(wr * 64 + m * 16 + fr, k * 32 + fq * 8))
; #define LDB(dst, b, h) for (int n = 0; n < 2; ++n) for (int k = 0; k < 2; ++k) \
;     dst[n][k] = *reinterpret_cast<const bf16x8*>((char*)SB(b, h) + lds_byte(wc * 32 + n * 16 + fr, k * 32 + fq * 8))
; #define MMA(ai, bj, At_, Bt_) do { __builtin_amdgcn_s_setprio(1); \
;     for (int k = 0; k < 2; ++k) for (int m = 0; m < 4; ++m) for (int n = 0; n < 2; ++n) \
;       acc[ai][bj][m][n] = __builtin_amdgcn_mfma_f32_16x16x32_bf16(At_[m][k], Bt_[n][k], acc[ai][bj][m][n], 0, 0, 0); \
;     __builtin_amdgcn_s_setprio(0); } while (0)
; #define WAIT_V(n) asm volatile("s_waitcnt vmcnt(" #n ")" ::: "memory")
; #define WAIT_L(n) asm volatile("s_waitcnt lgkmcnt(" #n ")" ::: "memory")
; #define BAR __builtin_amdgcn_s_barrier()
; template <int EPI, int lda, int ldb, int N, int K>
; __device__ __forceinline__ void gemm_phase(const u16* __restrict__ A, const u16* __restrict__ Bt, const GemmEpi ep, int wv) {
;     ...
;       LDB(B1, 0, 1); BAR; WAIT_L(0); MMA(0, 1, At, B1); BAR;
;       LDA(At, 0, 1); WAIT_V(4); BAR; WAIT_L(0); MMA(1, 0, At, B0); MMA(1, 1, At, B1); BAR; }
;     { LDB(B0, 1, 0); LDA(At, 1, 0); WAIT_V(2); BAR; WAIT_L(0); MMA(0, 0, At, B0); BAR;
	s_waitcnt lgkmcnt(0)
	v_mfma_f32_16x16x32_bf16 v[92:95], v[212:215], v[180:183], v[92:95]
	v_mfma_f32_16x16x32_bf16 v[88:91], v[220:223], v[180:183], v[88:91]
	v_mfma_f32_16x16x32_bf16 v[76:79], v[212:215], v[196:199], v[76:79]
	v_mfma_f32_16x16x32_bf16 v[72:75], v[220:223], v[196:199], v[72:75]
	v_mfma_f32_16x16x32_bf16 v[84:87], v[212:215], v[188:191], v[84:87]
	v_mfma_f32_16x16x32_bf16 v[80:83], v[220:223], v[188:191], v[80:83]
	v_mfma_f32_16x16x32_bf16 v[68:71], v[212:215], v[204:207], v[68:71]
	v_mfma_f32_16x16x32_bf16 v[64:67], v[220:223], v[204:207], v[64:67]
	v_mfma_f32_16x16x32_bf16 v[92:95], v[216:219], v[184:187], v[92:95]
	v_mfma_f32_16x16x32_bf16 v[88:91], v[158:161], v[184:187], v[88:91]
	v_mfma_f32_16x16x32_bf16 v[76:79], v[216:219], v[200:203], v[76:79]
	v_mfma_f32_16x16x32_bf16 v[72:75], v[158:161], v[200:203], v[72:75]
	v_mfma_f32_16x16x32_bf16 v[180:183], v[216:219], v[192:195], v[84:87]
	v_mfma_f32_16x16x32_bf16 v[184:187], v[158:161], v[192:195], v[80:83]
	v_mfma_f32_16x16x32_bf16 v[188:191], v[216:219], v[208:211], v[68:71]
	v_mfma_f32_16x16x32_bf16 v[192:195], v[158:161], v[208:211], v[64:67]
	s_barrier
	s_nop 0
	ds_read_b128 v[64:67], v152 offset:16384
	ds_read_b128 v[68:71], v152 offset:17408
	ds_read_b128 v[80:83], v151 offset:16384
	ds_read_b128 v[84:87], v151 offset:17408
	ds_read_b128 v[196:199], v150 offset:16384
	ds_read_b128 v[200:203], v150 offset:17408
	ds_read_b128 v[204:207], v149 offset:16384
	ds_read_b128 v[208:211], v149 offset:17408
	s_waitcnt vmcnt(4)
	s_barrier
	s_waitcnt lgkmcnt(0)
	v_mfma_f32_16x16x32_bf16 v[60:63], v[134:137], v[64:67], v[60:63]
	v_mfma_f32_16x16x32_bf16 v[56:59], v[172:175], v[64:67], v[56:59]
	v_mfma_f32_16x16x32_bf16 v[52:55], v[134:137], v[80:83], v[52:55]
	v_mfma_f32_16x16x32_bf16 v[48:51], v[172:175], v[80:83], v[48:51]
	v_mfma_f32_16x16x32_bf16 v[44:47], v[134:137], v[196:199], v[44:47]
	v_mfma_f32_16x16x32_bf16 v[40:43], v[172:175], v[196:199], v[40:43]
	v_mfma_f32_16x16x32_bf16 v[36:39], v[134:137], v[204:207], v[36:39]
	v_mfma_f32_16x16x32_bf16 v[32:35], v[172:175], v[204:207], v[32:35]
	v_mfma_f32_16x16x32_bf16 v[60:63], v[138:141], v[68:71], v[60:63]
	v_mfma_f32_16x16x32_bf16 v[56:59], v[176:179], v[68:71], v[56:59]
	v_mfma_f32_16x16x32_bf16 v[52:55], v[138:141], v[84:87], v[52:55]
	v_mfma_f32_16x16x32_bf16 v[48:51], v[176:179], v[84:87], v[48:51]
	v_mfma_f32_16x16x32_bf16 v[44:47], v[138:141], v[200:203], v[44:47]
	v_mfma_f32_16x16x32_bf16 v[40:43], v[176:179], v[200:203], v[40:43]
	v_mfma_f32_16x16x32_bf16 v[36:39], v[138:141], v[208:211], v[36:39]
	v_mfma_f32_16x16x32_bf16 v[32:35], v[176:179], v[208:211], v[32:35]
	v_mfma_f32_16x16x32_bf16 v[28:31], v[212:215], v[64:67], v[28:31]
	v_mfma_f32_16x16x32_bf16 v[24:27], v[220:223], v[64:67], v[24:27]
	v_mfma_f32_16x16x32_bf16 v[12:15], v[212:215], v[196:199], v[12:15]
	v_mfma_f32_16x16x32_bf16 v[8:11], v[220:223], v[196:199], v[8:11]
	v_mfma_f32_16x16x32_bf16 v[20:23], v[212:215], v[80:83], v[20:23]
	v_mfma_f32_16x16x32_bf16 v[16:19], v[220:223], v[80:83], v[16:19]
	v_mfma_f32_16x16x32_bf16 v[4:7], v[212:215], v[204:207], v[4:7]
	v_mfma_f32_16x16x32_bf16 v[0:3], v[220:223], v[204:207], v[0:3]
	v_mfma_f32_16x16x32_bf16 v[28:31], v[216:219], v[68:71], v[28:31]
	v_mfma_f32_16x16x32_bf16 v[24:27], v[158:161], v[68:71], v[24:27]
	v_mfma_f32_16x16x32_bf16 v[12:15], v[216:219], v[200:203], v[12:15]
	v_mfma_f32_16x16x32_bf16 v[8:11], v[158:161], v[200:203], v[8:11]
	v_mfma_f32_16x16x32_bf16 v[134:137], v[216:219], v[84:87], v[20:23]
	v_mfma_f32_16x16x32_bf16 v[138:141], v[158:161], v[84:87], v[16:19]
	v_mfma_f32_16x16x32_bf16 v[170:173], v[216:219], v[208:211], v[4:7]
	v_mfma_f32_16x16x32_bf16 v[158:161], v[158:161], v[208:211], v[0:3]
	s_barrier
	s_nop 0
	ds_read_b128 v[0:3], v156
	ds_read_b128 v[4:7], v156 offset:1024
	ds_read_b128 v[16:19], v156 offset:2048
	ds_read_b128 v[174:177], v156 offset:3072
	ds_read_b128 v[20:23], v152 offset:32768
	ds_read_b128 v[196:199], v152 offset:33792
	ds_read_b128 v[200:203], v151 offset:32768
	ds_read_b128 v[204:207], v151 offset:33792
	ds_read_b128 v[208:211], v150 offset:32768
	ds_read_b128 v[212:215], v150 offset:33792
	ds_read_b128 v[216:219], v149 offset:32768
	ds_read_b128 v[220:223], v149 offset:33792
	s_waitcnt vmcnt(2)
	s_barrier
; #define LDA(dst, b, h) for (int m = 0; m < 4; ++m) for (int k = 0; k < 2; ++k) \
;     dst[m][k] = *reinterpret_cast<const bf16x8*>((char*)SA(b, h) + lds_byte(wr * 64 + m * 16 + fr, k * 32 + fq * 8))
; #define LDB(dst, b, h) for (int n = 0; n < 2; ++n) for (int k = 0; k < 2; ++k) \
;     dst[n][k] = *reinterpret_cast<const bf16x8*>((char*)SB(b, h) + lds_byte(wc * 32 + n * 16 + fr, k * 32 + fq * 8))
; #define MMA(ai, bj, At_, Bt_) do { __builtin_amdgcn_s_setprio(1); \
;     for (int k = 0; k < 2; ++k) for (int m = 0; m < 4; ++m) for (int n = 0; n < 2; ++n) \
;       acc[ai][bj][m][n] = __builtin_amdgcn_mfma_f32_16x16x32_bf16(At_[m][k], Bt_[n][k], acc[ai][bj][m][n], 0, 0, 0); \
;     __builtin_amdgcn_s_setprio(0); } while (0)
; #define WAIT_V(n) asm volatile("s_waitcnt vmcnt(" #n ")" ::: "memory")
; #define WAIT_L(n) asm volatile("s_waitcnt lgkmcnt(" #n ")" ::: "memory")
; #define BAR __builtin_amdgcn_s_barrier()
; template <int EPI, int lda, int ldb, int N, int K>
; __device__ __forceinline__ void gemm_phase(const u16* __restrict__ A, const u16* __restrict__ Bt, const GemmEpi ep, int wv) {
;     ...
;     { LDB(B0, 1, 0); LDA(At, 1, 0); WAIT_V(2); BAR; WAIT_L(0); MMA(0, 0, At, B0); BAR;
;       LDB(B1, 1, 1); WAIT_V(0); BAR; WAIT_L(0); MMA(0, 1, At, B1); BAR;
;       LDA(At, 1, 1); BAR; WAIT_L(0); MMA(1, 0, At, B0); MMA(1, 1, At, B1); BAR; }
;     if (wr == 0) BAR;
	s_waitcnt lgkmcnt(0)
	v_mfma_f32_16x16x32_bf16 v[64:67], v[0:3], v[20:23], v[124:127]
	v_mfma_f32_16x16x32_bf16 v[68:71], v[16:19], v[20:23], v[120:123]
	v_mfma_f32_16x16x32_bf16 v[80:83], v[0:3], v[200:203], v[116:119]
	v_mfma_f32_16x16x32_bf16 v[84:87], v[16:19], v[200:203], v[112:115]
	v_mfma_f32_16x16x32_bf16 v[108:111], v[0:3], v[208:211], v[108:111]
	v_mfma_f32_16x16x32_bf16 v[104:107], v[16:19], v[208:211], v[104:107]
	v_mfma_f32_16x16x32_bf16 v[120:123], v[0:3], v[216:219], v[100:103]
	v_mfma_f32_16x16x32_bf16 v[124:127], v[16:19], v[216:219], v[96:99]
	v_mfma_f32_16x16x32_bf16 v[116:119], v[4:7], v[196:199], v[64:67]
	v_mfma_f32_16x16x32_bf16 v[112:115], v[174:177], v[196:199], v[68:71]
	v_mfma_f32_16x16x32_bf16 v[100:103], v[4:7], v[204:207], v[80:83]
	v_mfma_f32_16x16x32_bf16 v[96:99], v[174:177], v[204:207], v[84:87]
	v_mfma_f32_16x16x32_bf16 v[84:87], v[4:7], v[212:215], v[108:111]
	v_mfma_f32_16x16x32_bf16 v[80:83], v[174:177], v[212:215], v[104:107]
	v_mfma_f32_16x16x32_bf16 v[68:71], v[4:7], v[220:223], v[120:123]
	v_mfma_f32_16x16x32_bf16 v[64:67], v[174:177], v[220:223], v[124:127]
	s_barrier
	ds_read_b128 v[224:227], v154
	ds_read_b128 v[228:231], v154 offset:1024
	ds_read_b128 v[232:235], v154 offset:2048
	ds_read_b128 v[154:157], v154 offset:3072
	s_waitcnt vmcnt(0)
	s_barrier
	s_waitcnt lgkmcnt(0)
	v_mfma_f32_16x16x32_bf16 v[92:95], v[224:227], v[20:23], v[92:95]
	v_mfma_f32_16x16x32_bf16 v[20:23], v[232:235], v[20:23], v[88:91]
	v_mfma_f32_16x16x32_bf16 v[88:91], v[224:227], v[200:203], v[180:183]
	v_mfma_f32_16x16x32_bf16 v[104:107], v[232:235], v[200:203], v[184:187]
	v_mfma_f32_16x16x32_bf16 v[76:79], v[224:227], v[208:211], v[76:79]
	v_mfma_f32_16x16x32_bf16 v[72:75], v[232:235], v[208:211], v[72:75]
	v_mfma_f32_16x16x32_bf16 v[178:181], v[224:227], v[216:219], v[188:191]
	v_mfma_f32_16x16x32_bf16 v[182:185], v[232:235], v[216:219], v[192:195]
	v_mfma_f32_16x16x32_bf16 v[124:127], v[228:231], v[196:199], v[92:95]
	v_mfma_f32_16x16x32_bf16 v[120:123], v[154:157], v[196:199], v[20:23]
	v_mfma_f32_16x16x32_bf16 v[108:111], v[228:231], v[204:207], v[88:91]
	v_mfma_f32_16x16x32_bf16 v[104:107], v[154:157], v[204:207], v[104:107]
	v_mfma_f32_16x16x32_bf16 v[92:95], v[228:231], v[212:215], v[76:79]
	v_mfma_f32_16x16x32_bf16 v[88:91], v[154:157], v[212:215], v[72:75]
	v_mfma_f32_16x16x32_bf16 v[76:79], v[228:231], v[220:223], v[178:181]
	v_mfma_f32_16x16x32_bf16 v[72:75], v[154:157], v[220:223], v[182:185]
	s_barrier
	ds_read_b128 v[178:181], v152 offset:49152
	ds_read_b128 v[182:185], v152 offset:50176
	ds_read_b128 v[186:189], v151 offset:49152
	ds_read_b128 v[190:193], v151 offset:50176
	ds_read_b128 v[194:197], v150 offset:49152
	ds_read_b128 v[150:153], v150 offset:50176
	ds_read_b128 v[198:201], v149 offset:49152
	ds_read_b128 v[202:205], v149 offset:50176
	s_barrier
	s_waitcnt lgkmcnt(0)
	v_mfma_f32_16x16x32_bf16 v[20:23], v[0:3], v[178:181], v[60:63]
	v_mfma_f32_16x16x32_bf16 v[56:59], v[16:19], v[178:181], v[56:59]
	v_mfma_f32_16x16x32_bf16 v[60:63], v[0:3], v[186:189], v[52:55]
	v_mfma_f32_16x16x32_bf16 v[206:209], v[16:19], v[186:189], v[48:51]
	v_mfma_f32_16x16x32_bf16 v[44:47], v[0:3], v[194:197], v[44:47]
	v_mfma_f32_16x16x32_bf16 v[40:43], v[16:19], v[194:197], v[40:43]
	v_mfma_f32_16x16x32_bf16 v[0:3], v[0:3], v[198:201], v[36:39]
	v_mfma_f32_16x16x32_bf16 v[210:213], v[16:19], v[198:201], v[32:35]
	v_mfma_f32_16x16x32_bf16 v[52:55], v[4:7], v[182:185], v[20:23]
	v_mfma_f32_16x16x32_bf16 v[48:51], v[174:177], v[182:185], v[56:59]
	v_mfma_f32_16x16x32_bf16 v[36:39], v[4:7], v[190:193], v[60:63]
	v_mfma_f32_16x16x32_bf16 v[32:35], v[174:177], v[190:193], v[206:209]
	v_mfma_f32_16x16x32_bf16 v[20:23], v[4:7], v[150:153], v[44:47]
	v_mfma_f32_16x16x32_bf16 v[16:19], v[174:177], v[150:153], v[40:43]
	v_mfma_f32_16x16x32_bf16 v[4:7], v[4:7], v[202:205], v[0:3]
	v_mfma_f32_16x16x32_bf16 v[0:3], v[174:177], v[202:205], v[210:213]
	v_mfma_f32_16x16x32_bf16 v[28:31], v[224:227], v[178:181], v[28:31]
	v_mfma_f32_16x16x32_bf16 v[24:27], v[232:235], v[178:181], v[24:27]
	v_mfma_f32_16x16x32_bf16 v[40:43], v[224:227], v[186:189], v[134:137]
	v_mfma_f32_16x16x32_bf16 v[134:137], v[232:235], v[186:189], v[138:141]
	v_mfma_f32_16x16x32_bf16 v[12:15], v[224:227], v[194:197], v[12:15]
	v_mfma_f32_16x16x32_bf16 v[8:11], v[232:235], v[194:197], v[8:11]
	v_mfma_f32_16x16x32_bf16 v[138:141], v[224:227], v[198:201], v[170:173]
	v_mfma_f32_16x16x32_bf16 v[158:161], v[232:235], v[198:201], v[158:161]
	v_mfma_f32_16x16x32_bf16 v[60:63], v[228:231], v[182:185], v[28:31]
	v_mfma_f32_16x16x32_bf16 v[56:59], v[154:157], v[182:185], v[24:27]
	v_mfma_f32_16x16x32_bf16 v[44:47], v[228:231], v[190:193], v[40:43]
	v_mfma_f32_16x16x32_bf16 v[40:43], v[154:157], v[190:193], v[134:137]
	v_mfma_f32_16x16x32_bf16 v[28:31], v[228:231], v[150:153], v[12:15]
	v_mfma_f32_16x16x32_bf16 v[24:27], v[154:157], v[150:153], v[8:11]
	v_mfma_f32_16x16x32_bf16 v[12:15], v[228:231], v[202:205], v[138:141]
	v_mfma_f32_16x16x32_bf16 v[8:11], v[154:157], v[202:205], v[158:161]
	v_cmp_gt_u32_e32 vcc, s56, v130
	s_barrier
	s_and_saveexec_b64 s[42:43], vcc
	s_cbranch_execz .LBB0_56
	s_barrier

; #define STAGE(P, BASE, LD, br, kt) do { const char* _g = (const char*)((BASE) + (size_t)(br) * (LD) + (size_t)(kt) * 64); \
;     for (int _i = 0; _i < 2; ++_i) { int _b = tidx * 16 + _i * 8192; int _r, _c; stage_rc(_b, _r, _c); \
;       __builtin_amdgcn_global_load_lds((const unsigned*)(_g + (unsigned)((_r * (LD) + _c) * 2)), (unsigned*)((char*)(P) + _b), 16, 0, 0); } } while (0)
; #define LDA(dst, b, h) for (int m = 0; m < 4; ++m) for (int k = 0; k < 2; ++k) \
;     dst[m][k] = *reinterpret_cast<const bf16x8*>((char*)SA(b, h) + lds_byte(wr * 64 + m * 16 + fr, k * 32 + fq * 8))
; #define LDB(dst, b, h) for (int n = 0; n < 2; ++n) for (int k = 0; k < 2; ++k) \
;     dst[n][k] = *reinterpret_cast<const bf16x8*>((char*)SB(b, h) + lds_byte(wc * 32 + n * 16 + fr, k * 32 + fq * 8))
; #define MMA(ai, bj, At_, Bt_) do { __builtin_amdgcn_s_setprio(1); \
;     for (int k = 0; k < 2; ++k) for (int m = 0; m < 4; ++m) for (int n = 0; n < 2; ++n) \
;       acc[ai][bj][m][n] = __builtin_amdgcn_mfma_f32_16x16x32_bf16(At_[m][k], Bt_[n][k], acc[ai][bj][m][n], 0, 0, 0); \
;     __builtin_amdgcn_s_setprio(0); } while (0)
; #define WAIT_L(n) asm volatile("s_waitcnt lgkmcnt(" #n ")" ::: "memory")
; #define BAR __builtin_amdgcn_s_barrier()
; #define SCHED __builtin_amdgcn_sched_barrier(0)
; template <int EPI, int lda, int ldb, int N, int K>
; __device__ __forceinline__ void gemm_phase(const u16* __restrict__ A, const u16* __restrict__ Bt, const GemmEpi ep, int wv) {
;     ...
;       LDB(B0, 0, 0); SCHED; LDA(At, 0, 0); STAGE(SA(1, 1), Ab, lda, brow + HALF, t + 1);
;       WAIT_L(8); BAR; WAIT_L(0); MMA(0, 0, At, B0); BAR; SCHED;
;       LDB(B1, 0, 1); STAGE(SB(0, 0), Bt, ldb, bcol, t + 2);
;       BAR; WAIT_L(0); MMA(0, 1, At, B1); BAR;
;       LDA(At, 0, 1); STAGE(SA(0, 0), Ab, lda, brow, t + 2);
;       BAR; WAIT_L(0); MMA(1, 0, At, B0); BAR; SCHED;
.LBB0_224:
	ds_read_b128 v[168:171], v164
	ds_read_b128 v[174:177], v164 offset:1024
	ds_read_b128 v[178:181], v164 offset:2048
	ds_read_b128 v[182:185], v164 offset:3072
	v_add_u32_e32 v172, 0xc000, v147
	v_lshl_add_u64 v[238:239], v[136:137], 0, s[44:45]
	v_readfirstlane_b32 s66, v172
	v_add_u32_e32 v173, 0xe000, v147
	v_lshl_add_u64 v[166:167], v[238:239], 0, s[18:19]
	s_mov_b32 m0, s66
	v_lshl_add_u64 v[240:241], v[134:135], 0, s[44:45]
	v_readfirstlane_b32 s66, v173
	ds_read_b128 v[186:189], v155
	ds_read_b128 v[190:193], v155 offset:1024
	ds_read_b128 v[194:197], v154
	ds_read_b128 v[198:201], v154 offset:1024
	ds_read_b128 v[202:205], v153
	ds_read_b128 v[206:209], v153 offset:1024
	ds_read_b128 v[210:213], v152
	ds_read_b128 v[214:217], v152 offset:1024
	global_load_lds_dwordx4 v[166:167], off
	v_lshl_add_u64 v[166:167], v[240:241], 0, s[18:19]
	s_mov_b32 m0, s66
	s_nop 0
	global_load_lds_dwordx4 v[166:167], off
	s_waitcnt lgkmcnt(8)
	s_barrier
	s_waitcnt lgkmcnt(0)
	v_mfma_f32_16x16x32_bf16 v[124:127], v[168:171], v[186:189], v[124:127]
	v_mfma_f32_16x16x32_bf16 v[120:123], v[178:181], v[186:189], v[120:123]
	v_mfma_f32_16x16x32_bf16 v[116:119], v[168:171], v[194:197], v[116:119]
	v_mfma_f32_16x16x32_bf16 v[112:115], v[178:181], v[194:197], v[112:115]
	v_mfma_f32_16x16x32_bf16 v[108:111], v[168:171], v[202:205], v[108:111]
	v_mfma_f32_16x16x32_bf16 v[104:107], v[178:181], v[202:205], v[104:107]
	v_mfma_f32_16x16x32_bf16 v[100:103], v[168:171], v[210:213], v[100:103]
	v_mfma_f32_16x16x32_bf16 v[96:99], v[178:181], v[210:213], v[96:99]
	v_mfma_f32_16x16x32_bf16 v[124:127], v[174:177], v[190:193], v[124:127]
	v_mfma_f32_16x16x32_bf16 v[120:123], v[182:185], v[190:193], v[120:123]
	v_mfma_f32_16x16x32_bf16 v[116:119], v[174:177], v[198:201], v[116:119]
	v_mfma_f32_16x16x32_bf16 v[112:115], v[182:185], v[198:201], v[112:115]
	v_mfma_f32_16x16x32_bf16 v[108:111], v[174:177], v[206:209], v[108:111]
	v_mfma_f32_16x16x32_bf16 v[104:107], v[182:185], v[206:209], v[104:107]
	v_mfma_f32_16x16x32_bf16 v[100:103], v[174:177], v[214:217], v[100:103]
	v_mfma_f32_16x16x32_bf16 v[96:99], v[182:185], v[214:217], v[96:99]
	s_barrier
	v_add_u32_e32 v165, s55, v156
	v_lshl_add_u64 v[242:243], v[144:145], 0, s[44:45]
	v_readfirstlane_b32 s66, v165
	v_lshl_add_u64 v[166:167], v[242:243], 0, s[20:21]
	s_mov_b32 m0, s66
	ds_read_b128 v[218:221], v163
	ds_read_b128 v[222:225], v163 offset:1024
	ds_read_b128 v[226:229], v163 offset:2048
	ds_read_b128 v[230:233], v163 offset:3072
	global_load_lds_dwordx4 v[166:167], off
	v_add_u32_e32 v166, 0x2000, v165
	v_lshl_add_u64 v[244:245], v[142:143], 0, s[44:45]
	v_readfirstlane_b32 s66, v166
	v_lshl_add_u64 v[234:235], v[244:245], 0, s[20:21]
	s_mov_b32 m0, s66
	s_nop 0
	global_load_lds_dwordx4 v[234:235], off
	s_barrier
	s_waitcnt lgkmcnt(0)
	v_mfma_f32_16x16x32_bf16 v[92:95], v[218:221], v[186:189], v[92:95]
	v_mfma_f32_16x16x32_bf16 v[88:91], v[226:229], v[186:189], v[88:91]
	v_mfma_f32_16x16x32_bf16 v[84:87], v[218:221], v[194:197], v[84:87]
	v_mfma_f32_16x16x32_bf16 v[80:83], v[226:229], v[194:197], v[80:83]
	v_mfma_f32_16x16x32_bf16 v[76:79], v[218:221], v[202:205], v[76:79]
	v_mfma_f32_16x16x32_bf16 v[72:75], v[226:229], v[202:205], v[72:75]
	v_mfma_f32_16x16x32_bf16 v[68:71], v[218:221], v[210:213], v[68:71]
	v_mfma_f32_16x16x32_bf16 v[64:67], v[226:229], v[210:213], v[64:67]
	v_mfma_f32_16x16x32_bf16 v[92:95], v[222:225], v[190:193], v[92:95]
	v_mfma_f32_16x16x32_bf16 v[88:91], v[230:233], v[190:193], v[88:91]
	v_mfma_f32_16x16x32_bf16 v[84:87], v[222:225], v[198:201], v[84:87]
	v_mfma_f32_16x16x32_bf16 v[80:83], v[230:233], v[198:201], v[80:83]
	v_mfma_f32_16x16x32_bf16 v[76:79], v[222:225], v[206:209], v[76:79]
	v_mfma_f32_16x16x32_bf16 v[72:75], v[230:233], v[206:209], v[72:75]
	v_mfma_f32_16x16x32_bf16 v[68:71], v[222:225], v[214:217], v[68:71]
	v_mfma_f32_16x16x32_bf16 v[64:67], v[230:233], v[214:217], v[64:67]
	v_readfirstlane_b32 s66, v147
	v_add_u32_e32 v167, 0x2000, v147
	v_lshl_add_u64 v[234:235], v[238:239], 0, s[22:23]
	s_mov_b32 m0, s66
	v_readfirstlane_b32 s66, v167
	s_barrier
	ds_read_b128 v[186:189], v155 offset:16384
	ds_read_b128 v[190:193], v155 offset:17408
	ds_read_b128 v[194:197], v154 offset:16384
	ds_read_b128 v[198:201], v154 offset:17408
	ds_read_b128 v[202:205], v153 offset:16384
	ds_read_b128 v[206:209], v153 offset:17408
	ds_read_b128 v[210:213], v152 offset:16384
	ds_read_b128 v[214:217], v152 offset:17408
	global_load_lds_dwordx4 v[234:235], off
	v_lshl_add_u64 v[234:235], v[240:241], 0, s[22:23]
	s_mov_b32 m0, s66
	s_nop 0
	global_load_lds_dwordx4 v[234:235], off
	s_barrier
	s_waitcnt lgkmcnt(0)
	v_mfma_f32_16x16x32_bf16 v[60:63], v[168:171], v[186:189], v[60:63]
	v_mfma_f32_16x16x32_bf16 v[56:59], v[178:181], v[186:189], v[56:59]
	v_mfma_f32_16x16x32_bf16 v[52:55], v[168:171], v[194:197], v[52:55]
	v_mfma_f32_16x16x32_bf16 v[48:51], v[178:181], v[194:197], v[48:51]
	v_mfma_f32_16x16x32_bf16 v[44:47], v[168:171], v[202:205], v[44:47]
	v_mfma_f32_16x16x32_bf16 v[40:43], v[178:181], v[202:205], v[40:43]
	v_mfma_f32_16x16x32_bf16 v[36:39], v[168:171], v[210:213], v[36:39]
	v_mfma_f32_16x16x32_bf16 v[32:35], v[178:181], v[210:213], v[32:35]
	v_mfma_f32_16x16x32_bf16 v[60:63], v[174:177], v[190:193], v[60:63]
	v_mfma_f32_16x16x32_bf16 v[56:59], v[182:185], v[190:193], v[56:59]
	v_mfma_f32_16x16x32_bf16 v[52:55], v[174:177], v[198:201], v[52:55]
	v_mfma_f32_16x16x32_bf16 v[48:51], v[182:185], v[198:201], v[48:51]
	v_mfma_f32_16x16x32_bf16 v[44:47], v[174:177], v[206:209], v[44:47]
	v_mfma_f32_16x16x32_bf16 v[40:43], v[182:185], v[206:209], v[40:43]
	v_mfma_f32_16x16x32_bf16 v[36:39], v[174:177], v[214:217], v[36:39]
	v_mfma_f32_16x16x32_bf16 v[32:35], v[182:185], v[214:217], v[32:35]
	s_barrier
; #define STAGE(P, BASE, LD, br, kt) do { const char* _g = (const char*)((BASE) + (size_t)(br) * (LD) + (size_t)(kt) * 64); \
;     for (int _i = 0; _i < 2; ++_i) { int _b = tidx * 16 + _i * 8192; int _r, _c; stage_rc(_b, _r, _c); \
;       __builtin_amdgcn_global_load_lds((const unsigned*)(_g + (unsigned)((_r * (LD) + _c) * 2)), (unsigned*)((char*)(P) + _b), 16, 0, 0); } } while (0)
; #define LDA(dst, b, h) for (int m = 0; m < 4; ++m) for (int k = 0; k < 2; ++k) \
;     dst[m][k] = *reinterpret_cast<const bf16x8*>((char*)SA(b, h) + lds_byte(wr * 64 + m * 16 + fr, k * 32 + fq * 8))
; #define LDB(dst, b, h) for (int n = 0; n < 2; ++n) for (int k = 0; k < 2; ++k) \
;     dst[n][k] = *reinterpret_cast<const bf16x8*>((char*)SB(b, h) + lds_byte(wc * 32 + n * 16 + fr, k * 32 + fq * 8))
; #define MMA(ai, bj, At_, Bt_) do { __builtin_amdgcn_s_setprio(1); \
;     for (int k = 0; k < 2; ++k) for (int m = 0; m < 4; ++m) for (int n = 0; n < 2; ++n) \
;       acc[ai][bj][m][n] = __builtin_amdgcn_mfma_f32_16x16x32_bf16(At_[m][k], Bt_[n][k], acc[ai][bj][m][n], 0, 0, 0); \
;     __builtin_amdgcn_s_setprio(0); } while (0)
; #define WAIT_V(n) asm volatile("s_waitcnt vmcnt(" #n ")" ::: "memory")
; #define WAIT_L(n) asm volatile("s_waitcnt lgkmcnt(" #n ")" ::: "memory")
; #define BAR __builtin_amdgcn_s_barrier()
; #define SCHED __builtin_amdgcn_sched_barrier(0)
; template <int EPI, int lda, int ldb, int N, int K>
; __device__ __forceinline__ void gemm_phase(const u16* __restrict__ A, const u16* __restrict__ Bt, const GemmEpi ep, int wv) {
;     ...
;       STAGE(SB(0, 1), Bt, ldb, bcol + HALF, t + 2);
;       WAIT_V(6); BAR; MMA(1, 1, At, B1); BAR;
;       LDB(B0, 1, 0); SCHED; LDA(At, 1, 0); STAGE(SA(0, 1), Ab, lda, brow + HALF, t + 2);
;       WAIT_L(8); BAR; WAIT_L(0); MMA(0, 0, At, B0); BAR; SCHED;
;       LDB(B1, 1, 1); STAGE(SB(1, 0), Bt, ldb, bcol, t + 3);
;       BAR; WAIT_L(0); MMA(0, 1, At, B1); BAR;
;       LDA(At, 1, 1); STAGE(SA(1, 0), Ab, lda, brow, t + 3);
	v_add_u32_e32 v168, s56, v156
	v_lshl_add_u64 v[246:247], v[140:141], 0, s[44:45]
	v_readfirstlane_b32 s66, v168
	v_add_u32_e32 v169, 0x2000, v168
	v_lshl_add_u64 v[170:171], v[246:247], 0, s[24:25]
	s_mov_b32 m0, s66
	v_lshl_add_u64 v[248:249], v[138:139], 0, s[44:45]
	v_readfirstlane_b32 s66, v169
	global_load_lds_dwordx4 v[170:171], off
	v_lshl_add_u64 v[170:171], v[248:249], 0, s[24:25]
	s_mov_b32 m0, s66
	s_nop 0
	global_load_lds_dwordx4 v[170:171], off
	s_waitcnt vmcnt(6)
	s_barrier
	v_mfma_f32_16x16x32_bf16 v[28:31], v[218:221], v[186:189], v[28:31]
	v_mfma_f32_16x16x32_bf16 v[24:27], v[226:229], v[186:189], v[24:27]
	v_mfma_f32_16x16x32_bf16 v[20:23], v[218:221], v[194:197], v[20:23]
	v_mfma_f32_16x16x32_bf16 v[16:19], v[226:229], v[194:197], v[16:19]
	v_mfma_f32_16x16x32_bf16 v[12:15], v[218:221], v[202:205], v[12:15]
	v_mfma_f32_16x16x32_bf16 v[8:11], v[226:229], v[202:205], v[8:11]
	v_mfma_f32_16x16x32_bf16 v[4:7], v[218:221], v[210:213], v[4:7]
	v_mfma_f32_16x16x32_bf16 v[0:3], v[226:229], v[210:213], v[0:3]
	v_mfma_f32_16x16x32_bf16 v[28:31], v[222:225], v[190:193], v[28:31]
	v_mfma_f32_16x16x32_bf16 v[24:27], v[230:233], v[190:193], v[24:27]
	v_mfma_f32_16x16x32_bf16 v[20:23], v[222:225], v[198:201], v[20:23]
	v_mfma_f32_16x16x32_bf16 v[16:19], v[230:233], v[198:201], v[16:19]
	v_mfma_f32_16x16x32_bf16 v[12:15], v[222:225], v[206:209], v[12:15]
	v_mfma_f32_16x16x32_bf16 v[8:11], v[230:233], v[206:209], v[8:11]
	v_mfma_f32_16x16x32_bf16 v[4:7], v[222:225], v[214:217], v[4:7]
	v_mfma_f32_16x16x32_bf16 v[0:3], v[230:233], v[214:217], v[0:3]
	s_barrier
	ds_read_b128 v[174:177], v159
	ds_read_b128 v[178:181], v159 offset:1024
	ds_read_b128 v[182:185], v159 offset:2048
	ds_read_b128 v[186:189], v159 offset:3072
	v_add_u32_e32 v170, 0x4000, v147
	v_add_u32_e32 v171, 0x6000, v147
	v_readfirstlane_b32 s66, v170
	v_lshl_add_u64 v[222:223], v[238:239], 0, s[26:27]
	s_mov_b32 m0, s66
	v_readfirstlane_b32 s66, v171
	ds_read_b128 v[190:193], v155 offset:32768
	ds_read_b128 v[194:197], v155 offset:33792
	ds_read_b128 v[198:201], v154 offset:32768
	ds_read_b128 v[202:205], v154 offset:33792
	ds_read_b128 v[206:209], v153 offset:32768
	ds_read_b128 v[210:213], v153 offset:33792
	ds_read_b128 v[214:217], v152 offset:32768
	ds_read_b128 v[218:221], v152 offset:33792
	global_load_lds_dwordx4 v[222:223], off
	v_lshl_add_u64 v[222:223], v[240:241], 0, s[26:27]
	s_mov_b32 m0, s66
	s_nop 0
	global_load_lds_dwordx4 v[222:223], off
	s_waitcnt lgkmcnt(8)
	s_barrier
	s_waitcnt lgkmcnt(0)
	v_mfma_f32_16x16x32_bf16 v[124:127], v[174:177], v[190:193], v[124:127]
	v_mfma_f32_16x16x32_bf16 v[120:123], v[182:185], v[190:193], v[120:123]
	v_mfma_f32_16x16x32_bf16 v[116:119], v[174:177], v[198:201], v[116:119]
	v_mfma_f32_16x16x32_bf16 v[112:115], v[182:185], v[198:201], v[112:115]
	v_mfma_f32_16x16x32_bf16 v[108:111], v[174:177], v[206:209], v[108:111]
	v_mfma_f32_16x16x32_bf16 v[104:107], v[182:185], v[206:209], v[104:107]
	v_mfma_f32_16x16x32_bf16 v[100:103], v[174:177], v[214:217], v[100:103]
	v_mfma_f32_16x16x32_bf16 v[96:99], v[182:185], v[214:217], v[96:99]
	v_mfma_f32_16x16x32_bf16 v[124:127], v[178:181], v[194:197], v[124:127]
	v_mfma_f32_16x16x32_bf16 v[120:123], v[186:189], v[194:197], v[120:123]
	v_mfma_f32_16x16x32_bf16 v[116:119], v[178:181], v[202:205], v[116:119]
	v_mfma_f32_16x16x32_bf16 v[112:115], v[186:189], v[202:205], v[112:115]
	v_mfma_f32_16x16x32_bf16 v[108:111], v[178:181], v[210:213], v[108:111]
	v_mfma_f32_16x16x32_bf16 v[104:107], v[186:189], v[210:213], v[104:107]
	v_mfma_f32_16x16x32_bf16 v[100:103], v[178:181], v[218:221], v[100:103]
	v_mfma_f32_16x16x32_bf16 v[96:99], v[186:189], v[218:221], v[96:99]
	s_barrier
	v_readfirstlane_b32 s66, v158
	v_lshl_add_u64 v[242:243], v[242:243], 0, s[36:37]
	s_mov_b32 m0, s66
	ds_read_b128 v[222:225], v157
	ds_read_b128 v[226:229], v157 offset:1024
	ds_read_b128 v[230:233], v157 offset:2048
	ds_read_b128 v[234:237], v157 offset:3072
	global_load_lds_dwordx4 v[242:243], off
	v_lshl_add_u64 v[242:243], v[244:245], 0, s[36:37]
	v_add_u32_e32 v244, 0x2000, v158
	s_nop 0
	v_readfirstlane_b32 s66, v244
	s_mov_b32 m0, s66
	s_nop 0
	global_load_lds_dwordx4 v[242:243], off
	s_barrier
	s_waitcnt lgkmcnt(0)
	v_mfma_f32_16x16x32_bf16 v[92:95], v[222:225], v[190:193], v[92:95]
	v_mfma_f32_16x16x32_bf16 v[88:91], v[230:233], v[190:193], v[88:91]
	v_mfma_f32_16x16x32_bf16 v[84:87], v[222:225], v[198:201], v[84:87]
	v_mfma_f32_16x16x32_bf16 v[80:83], v[230:233], v[198:201], v[80:83]
	v_mfma_f32_16x16x32_bf16 v[76:79], v[222:225], v[206:209], v[76:79]
	v_mfma_f32_16x16x32_bf16 v[72:75], v[230:233], v[206:209], v[72:75]
	v_mfma_f32_16x16x32_bf16 v[68:71], v[222:225], v[214:217], v[68:71]
	v_mfma_f32_16x16x32_bf16 v[64:67], v[230:233], v[214:217], v[64:67]
	v_mfma_f32_16x16x32_bf16 v[92:95], v[226:229], v[194:197], v[92:95]
	v_mfma_f32_16x16x32_bf16 v[88:91], v[234:237], v[194:197], v[88:91]
	v_mfma_f32_16x16x32_bf16 v[84:87], v[226:229], v[202:205], v[84:87]
	v_mfma_f32_16x16x32_bf16 v[80:83], v[234:237], v[202:205], v[80:83]
	v_mfma_f32_16x16x32_bf16 v[76:79], v[226:229], v[210:213], v[76:79]
	v_mfma_f32_16x16x32_bf16 v[72:75], v[234:237], v[210:213], v[72:75]
	v_mfma_f32_16x16x32_bf16 v[68:71], v[226:229], v[218:221], v[68:71]
	v_mfma_f32_16x16x32_bf16 v[64:67], v[234:237], v[218:221], v[64:67]
	v_readfirstlane_b32 s66, v160
	v_lshl_add_u64 v[238:239], v[238:239], 0, s[38:39]
	s_mov_b32 m0, s66
	v_readfirstlane_b32 s66, v161
	s_barrier
; #define STAGE(P, BASE, LD, br, kt) do { const char* _g = (const char*)((BASE) + (size_t)(br) * (LD) + (size_t)(kt) * 64); \
;     for (int _i = 0; _i < 2; ++_i) { int _b = tidx * 16 + _i * 8192; int _r, _c; stage_rc(_b, _r, _c); \
;       __builtin_amdgcn_global_load_lds((const unsigned*)(_g + (unsigned)((_r * (LD) + _c) * 2)), (unsigned*)((char*)(P) + _b), 16, 0, 0); } } while (0)
; #define LDA(dst, b, h) for (int m = 0; m < 4; ++m) for (int k = 0; k < 2; ++k) \
;     dst[m][k] = *reinterpret_cast<const bf16x8*>((char*)SA(b, h) + lds_byte(wr * 64 + m * 16 + fr, k * 32 + fq * 8))
; #define LDB(dst, b, h) for (int n = 0; n < 2; ++n) for (int k = 0; k < 2; ++k) \
;     dst[n][k] = *reinterpret_cast<const bf16x8*>((char*)SB(b, h) + lds_byte(wc * 32 + n * 16 + fr, k * 32 + fq * 8))
; #define MMA(ai, bj, At_, Bt_) do { __builtin_amdgcn_s_setprio(1); \
;     for (int k = 0; k < 2; ++k) for (int m = 0; m < 4; ++m) for (int n = 0; n < 2; ++n) \
;       acc[ai][bj][m][n] = __builtin_amdgcn_mfma_f32_16x16x32_bf16(At_[m][k], Bt_[n][k], acc[ai][bj][m][n], 0, 0, 0); \
;     __builtin_amdgcn_s_setprio(0); } while (0)
; #define WAIT_V(n) asm volatile("s_waitcnt vmcnt(" #n ")" ::: "memory")
; #define WAIT_L(n) asm volatile("s_waitcnt lgkmcnt(" #n ")" ::: "memory")
; #define BAR __builtin_amdgcn_s_barrier()
; #define SCHED __builtin_amdgcn_sched_barrier(0)
; template <int EPI, int lda, int ldb, int N, int K>
; __device__ __forceinline__ void gemm_phase(const u16* __restrict__ A, const u16* __restrict__ Bt, const GemmEpi ep, int wv) {
;     ...
;       LDA(At, 1, 1); STAGE(SA(1, 0), Ab, lda, brow, t + 3);
;       BAR; WAIT_L(0); MMA(1, 0, At, B0); BAR; SCHED;
;       STAGE(SB(1, 1), Bt, ldb, bcol + HALF, t + 3);
;       WAIT_V(6); BAR; MMA(1, 1, At, B1); BAR;
;     }
;     { LDB(B0, 0, 0); LDA(At, 0, 0); STAGE(SA(1, 1), Ab, lda, brow + HALF, nt - 1);
;       BAR; WAIT_L(0); MMA(0, 0, At, B0); BAR;
;       LDB(B1, 0, 1); BAR; WAIT_L(0); MMA(0, 1, At, B1); BAR;
	ds_read_b128 v[190:193], v155 offset:49152
	ds_read_b128 v[194:197], v155 offset:50176
	ds_read_b128 v[198:201], v154 offset:49152
	ds_read_b128 v[202:205], v154 offset:50176
	ds_read_b128 v[206:209], v153 offset:49152
	ds_read_b128 v[210:213], v153 offset:50176
	ds_read_b128 v[214:217], v152 offset:49152
	ds_read_b128 v[218:221], v152 offset:50176
	global_load_lds_dwordx4 v[238:239], off
	v_lshl_add_u64 v[238:239], v[240:241], 0, s[38:39]
	s_mov_b32 m0, s66
	s_nop 0
	global_load_lds_dwordx4 v[238:239], off
	s_barrier
	s_waitcnt lgkmcnt(0)
	v_mfma_f32_16x16x32_bf16 v[60:63], v[174:177], v[190:193], v[60:63]
	v_mfma_f32_16x16x32_bf16 v[56:59], v[182:185], v[190:193], v[56:59]
	v_mfma_f32_16x16x32_bf16 v[52:55], v[174:177], v[198:201], v[52:55]
	v_mfma_f32_16x16x32_bf16 v[48:51], v[182:185], v[198:201], v[48:51]
	v_mfma_f32_16x16x32_bf16 v[44:47], v[174:177], v[206:209], v[44:47]
	v_mfma_f32_16x16x32_bf16 v[40:43], v[182:185], v[206:209], v[40:43]
	v_mfma_f32_16x16x32_bf16 v[36:39], v[174:177], v[214:217], v[36:39]
	v_mfma_f32_16x16x32_bf16 v[32:35], v[182:185], v[214:217], v[32:35]
	v_mfma_f32_16x16x32_bf16 v[60:63], v[178:181], v[194:197], v[60:63]
	v_mfma_f32_16x16x32_bf16 v[56:59], v[186:189], v[194:197], v[56:59]
	v_mfma_f32_16x16x32_bf16 v[52:55], v[178:181], v[202:205], v[52:55]
	v_mfma_f32_16x16x32_bf16 v[48:51], v[186:189], v[202:205], v[48:51]
	v_mfma_f32_16x16x32_bf16 v[44:47], v[178:181], v[210:213], v[44:47]
	v_mfma_f32_16x16x32_bf16 v[40:43], v[186:189], v[210:213], v[40:43]
	v_mfma_f32_16x16x32_bf16 v[36:39], v[178:181], v[218:221], v[36:39]
	v_mfma_f32_16x16x32_bf16 v[32:35], v[186:189], v[218:221], v[32:35]
	s_barrier
	v_readfirstlane_b32 s66, v162
	v_add_u32_e32 v176, 0x2000, v162
	v_lshl_add_u64 v[174:175], v[246:247], 0, s[42:43]
	s_mov_b32 m0, s66
	v_readfirstlane_b32 s66, v176
	global_load_lds_dwordx4 v[174:175], off
	v_lshl_add_u64 v[174:175], v[248:249], 0, s[42:43]
	s_mov_b32 m0, s66
	s_nop 0
	global_load_lds_dwordx4 v[174:175], off
	s_waitcnt vmcnt(6)
	s_barrier
	v_mfma_f32_16x16x32_bf16 v[28:31], v[222:225], v[190:193], v[28:31]
	v_mfma_f32_16x16x32_bf16 v[24:27], v[230:233], v[190:193], v[24:27]
	v_mfma_f32_16x16x32_bf16 v[20:23], v[222:225], v[198:201], v[20:23]
	v_mfma_f32_16x16x32_bf16 v[16:19], v[230:233], v[198:201], v[16:19]
	v_mfma_f32_16x16x32_bf16 v[12:15], v[222:225], v[206:209], v[12:15]
	v_mfma_f32_16x16x32_bf16 v[8:11], v[230:233], v[206:209], v[8:11]
	v_mfma_f32_16x16x32_bf16 v[4:7], v[222:225], v[214:217], v[4:7]
	v_mfma_f32_16x16x32_bf16 v[0:3], v[230:233], v[214:217], v[0:3]
	v_mfma_f32_16x16x32_bf16 v[28:31], v[226:229], v[194:197], v[28:31]
	v_mfma_f32_16x16x32_bf16 v[24:27], v[234:237], v[194:197], v[24:27]
	v_mfma_f32_16x16x32_bf16 v[20:23], v[226:229], v[202:205], v[20:23]
	v_mfma_f32_16x16x32_bf16 v[16:19], v[234:237], v[202:205], v[16:19]
	v_mfma_f32_16x16x32_bf16 v[12:15], v[226:229], v[210:213], v[12:15]
	v_mfma_f32_16x16x32_bf16 v[8:11], v[234:237], v[210:213], v[8:11]
	v_mfma_f32_16x16x32_bf16 v[4:7], v[226:229], v[218:221], v[4:7]
	v_mfma_f32_16x16x32_bf16 v[0:3], v[234:237], v[218:221], v[0:3]
	s_add_i32 s65, s65, 2
	s_add_u32 s44, s44, 0x100
	s_addc_u32 s45, s45, 0
	s_cmpk_gt_u32 s65, 0x51
	s_barrier
	s_cbranch_scc0 .LBB0_224
	s_add_i32 s44, s14, 0x80
	s_mul_hi_i32 s45, s44, 0x2b00
	s_mulk_i32 s44, 0x2b00
	s_add_u32 s44, s48, s44
	s_addc_u32 s45, s49, s45
	s_add_u32 s44, s44, 0x2a80
	s_addc_u32 s45, s45, 0
	v_readfirstlane_b32 s65, v172
	v_lshl_add_u64 v[160:161], s[44:45], 0, v[128:129]
	s_mov_b32 m0, s65
	ds_read_b128 v[134:137], v164
	ds_read_b128 v[138:141], v164 offset:1024
	ds_read_b128 v[142:145], v164 offset:2048
	ds_read_b128 v[174:177], v164 offset:3072
	ds_read_b128 v[178:181], v155
	ds_read_b128 v[182:185], v155 offset:1024
	ds_read_b128 v[186:189], v154
	ds_read_b128 v[190:193], v154 offset:1024
	ds_read_b128 v[194:197], v153
	ds_read_b128 v[198:201], v153 offset:1024
	ds_read_b128 v[202:205], v152
	ds_read_b128 v[206:209], v152 offset:1024
	global_load_lds_dwordx4 v[160:161], off
	v_lshl_add_u64 v[160:161], s[44:45], 0, v[132:133]
	v_readfirstlane_b32 s44, v173
	s_mov_b32 m0, s44
	s_nop 0
	global_load_lds_dwordx4 v[160:161], off
	s_barrier
	s_waitcnt lgkmcnt(0)
	v_mfma_f32_16x16x32_bf16 v[124:127], v[134:137], v[178:181], v[124:127]
	v_mfma_f32_16x16x32_bf16 v[120:123], v[142:145], v[178:181], v[120:123]
	v_mfma_f32_16x16x32_bf16 v[116:119], v[134:137], v[186:189], v[116:119]
	v_mfma_f32_16x16x32_bf16 v[112:115], v[142:145], v[186:189], v[112:115]
	v_mfma_f32_16x16x32_bf16 v[108:111], v[134:137], v[194:197], v[108:111]
	v_mfma_f32_16x16x32_bf16 v[104:107], v[142:145], v[194:197], v[104:107]
	v_mfma_f32_16x16x32_bf16 v[100:103], v[134:137], v[202:205], v[100:103]
	v_mfma_f32_16x16x32_bf16 v[96:99], v[142:145], v[202:205], v[96:99]
	v_mfma_f32_16x16x32_bf16 v[124:127], v[138:141], v[182:185], v[124:127]
	v_mfma_f32_16x16x32_bf16 v[120:123], v[174:177], v[182:185], v[120:123]
	v_mfma_f32_16x16x32_bf16 v[116:119], v[138:141], v[190:193], v[116:119]
	v_mfma_f32_16x16x32_bf16 v[112:115], v[174:177], v[190:193], v[112:115]
	v_mfma_f32_16x16x32_bf16 v[108:111], v[138:141], v[198:201], v[108:111]
	v_mfma_f32_16x16x32_bf16 v[104:107], v[174:177], v[198:201], v[104:107]
	v_mfma_f32_16x16x32_bf16 v[100:103], v[138:141], v[206:209], v[100:103]
	v_mfma_f32_16x16x32_bf16 v[96:99], v[174:177], v[206:209], v[96:99]
	s_barrier
	ds_read_b128 v[210:213], v163
	ds_read_b128 v[214:217], v163 offset:1024
	ds_read_b128 v[218:221], v163 offset:2048
	ds_read_b128 v[160:163], v163 offset:3072
	s_barrier
; #define LDA(dst, b, h) for (int m = 0; m < 4; ++m) for (int k = 0; k < 2; ++k) \
;     dst[m][k] = *reinterpret_cast<const bf16x8*>((char*)SA(b, h) + lds_byte(wr * 64 + m * 16 + fr, k * 32 + fq * 8))
; #define LDB(dst, b, h) for (int n = 0; n < 2; ++n) for (int k = 0; k < 2; ++k) \
;     dst[n][k] = *reinterpret_cast<const bf16x8*>((char*)SB(b, h) + lds_byte(wc * 32 + n * 16 + fr, k * 32 + fq * 8))
; #define MMA(ai, bj, At_, Bt_) do { __builtin_amdgcn_s_setprio(1); \
;     for (int k = 0; k < 2; ++k) for (int m = 0; m < 4; ++m) for (int n = 0; n < 2; ++n) \
;       acc[ai][bj][m][n] = __builtin_amdgcn_mfma_f32_16x16x32_bf16(At_[m][k], Bt_[n][k], acc[ai][bj][m][n], 0, 0, 0); \
;     __builtin_amdgcn_s_setprio(0); } while (0)
; #define WAIT_V(n) asm volatile("s_waitcnt vmcnt(" #n ")" ::: "memory")
; #define WAIT_L(n) asm volatile("s_waitcnt lgkmcnt(" #n ")" ::: "memory")
; #define BAR __builtin_amdgcn_s_barrier()
; template <int EPI, int lda, int ldb, int N, int K>
; __device__ __forceinline__ void gemm_phase(const u16* __restrict__ A, const u16* __restrict__ Bt, const GemmEpi ep, int wv) {
;     ...
;       LDB(B1, 0, 1); BAR; WAIT_L(0); MMA(0, 1, At, B1); BAR;
;       LDA(At, 0, 1); WAIT_V(4); BAR; WAIT_L(0); MMA(1, 0, At, B0); MMA(1, 1, At, B1); BAR; }
;     { LDB(B0, 1, 0); LDA(At, 1, 0); WAIT_V(2); BAR; WAIT_L(0); MMA(0, 0, At, B0); BAR;
	s_waitcnt lgkmcnt(0)
	v_mfma_f32_16x16x32_bf16 v[92:95], v[210:213], v[178:181], v[92:95]
	v_mfma_f32_16x16x32_bf16 v[88:91], v[218:221], v[178:181], v[88:91]
	v_mfma_f32_16x16x32_bf16 v[76:79], v[210:213], v[194:197], v[76:79]
	v_mfma_f32_16x16x32_bf16 v[72:75], v[218:221], v[194:197], v[72:75]
	v_mfma_f32_16x16x32_bf16 v[84:87], v[210:213], v[186:189], v[84:87]
	v_mfma_f32_16x16x32_bf16 v[80:83], v[218:221], v[186:189], v[80:83]
	v_mfma_f32_16x16x32_bf16 v[68:71], v[210:213], v[202:205], v[68:71]
	v_mfma_f32_16x16x32_bf16 v[64:67], v[218:221], v[202:205], v[64:67]
	v_mfma_f32_16x16x32_bf16 v[92:95], v[214:217], v[182:185], v[92:95]
	v_mfma_f32_16x16x32_bf16 v[88:91], v[160:163], v[182:185], v[88:91]
	v_mfma_f32_16x16x32_bf16 v[76:79], v[214:217], v[198:201], v[76:79]
	v_mfma_f32_16x16x32_bf16 v[72:75], v[160:163], v[198:201], v[72:75]
	v_mfma_f32_16x16x32_bf16 v[178:181], v[214:217], v[190:193], v[84:87]
	v_mfma_f32_16x16x32_bf16 v[182:185], v[160:163], v[190:193], v[80:83]
	v_mfma_f32_16x16x32_bf16 v[186:189], v[214:217], v[206:209], v[68:71]
	v_mfma_f32_16x16x32_bf16 v[190:193], v[160:163], v[206:209], v[64:67]
	s_barrier
	s_nop 0
	ds_read_b128 v[64:67], v155 offset:16384
	ds_read_b128 v[68:71], v155 offset:17408
	ds_read_b128 v[80:83], v154 offset:16384
	ds_read_b128 v[84:87], v154 offset:17408
	ds_read_b128 v[194:197], v153 offset:16384
	ds_read_b128 v[198:201], v153 offset:17408
	ds_read_b128 v[202:205], v152 offset:16384
	ds_read_b128 v[206:209], v152 offset:17408
	s_waitcnt vmcnt(4)
	s_barrier
	s_waitcnt lgkmcnt(0)
	v_mfma_f32_16x16x32_bf16 v[60:63], v[134:137], v[64:67], v[60:63]
	v_mfma_f32_16x16x32_bf16 v[56:59], v[142:145], v[64:67], v[56:59]
	v_mfma_f32_16x16x32_bf16 v[52:55], v[134:137], v[80:83], v[52:55]
	v_mfma_f32_16x16x32_bf16 v[48:51], v[142:145], v[80:83], v[48:51]
	v_mfma_f32_16x16x32_bf16 v[44:47], v[134:137], v[194:197], v[44:47]
	v_mfma_f32_16x16x32_bf16 v[40:43], v[142:145], v[194:197], v[40:43]
	v_mfma_f32_16x16x32_bf16 v[36:39], v[134:137], v[202:205], v[36:39]
	v_mfma_f32_16x16x32_bf16 v[32:35], v[142:145], v[202:205], v[32:35]
	v_mfma_f32_16x16x32_bf16 v[60:63], v[138:141], v[68:71], v[60:63]
	v_mfma_f32_16x16x32_bf16 v[56:59], v[174:177], v[68:71], v[56:59]
	v_mfma_f32_16x16x32_bf16 v[52:55], v[138:141], v[84:87], v[52:55]
	v_mfma_f32_16x16x32_bf16 v[48:51], v[174:177], v[84:87], v[48:51]
	v_mfma_f32_16x16x32_bf16 v[44:47], v[138:141], v[198:201], v[44:47]
	v_mfma_f32_16x16x32_bf16 v[40:43], v[174:177], v[198:201], v[40:43]
	v_mfma_f32_16x16x32_bf16 v[36:39], v[138:141], v[206:209], v[36:39]
	v_mfma_f32_16x16x32_bf16 v[32:35], v[174:177], v[206:209], v[32:35]
	v_mfma_f32_16x16x32_bf16 v[28:31], v[210:213], v[64:67], v[28:31]
	v_mfma_f32_16x16x32_bf16 v[16:19], v[218:221], v[80:83], v[16:19]
	v_mfma_f32_16x16x32_bf16 v[12:15], v[210:213], v[194:197], v[12:15]
	v_mfma_f32_16x16x32_bf16 v[0:3], v[218:221], v[202:205], v[0:3]
	v_mfma_f32_16x16x32_bf16 v[24:27], v[218:221], v[64:67], v[24:27]
	v_mfma_f32_16x16x32_bf16 v[20:23], v[210:213], v[80:83], v[20:23]
	v_mfma_f32_16x16x32_bf16 v[8:11], v[218:221], v[194:197], v[8:11]
	v_mfma_f32_16x16x32_bf16 v[4:7], v[210:213], v[202:205], v[4:7]
	v_mfma_f32_16x16x32_bf16 v[28:31], v[214:217], v[68:71], v[28:31]
	v_mfma_f32_16x16x32_bf16 v[16:19], v[160:163], v[84:87], v[16:19]
	v_mfma_f32_16x16x32_bf16 v[12:15], v[214:217], v[198:201], v[12:15]
	v_mfma_f32_16x16x32_bf16 v[0:3], v[160:163], v[206:209], v[0:3]
	v_mfma_f32_16x16x32_bf16 v[134:137], v[160:163], v[68:71], v[24:27]
	v_mfma_f32_16x16x32_bf16 v[138:141], v[214:217], v[84:87], v[20:23]
	v_mfma_f32_16x16x32_bf16 v[142:145], v[160:163], v[198:201], v[8:11]
	v_mfma_f32_16x16x32_bf16 v[172:175], v[214:217], v[206:209], v[4:7]
	s_barrier
	s_nop 0
	ds_read_b128 v[4:7], v159
	ds_read_b128 v[8:11], v159 offset:1024
	ds_read_b128 v[20:23], v159 offset:2048
	ds_read_b128 v[158:161], v159 offset:3072
	ds_read_b128 v[24:27], v155 offset:32768
	ds_read_b128 v[194:197], v155 offset:33792
	ds_read_b128 v[198:201], v154 offset:32768
	ds_read_b128 v[202:205], v154 offset:33792
	ds_read_b128 v[206:209], v153 offset:32768
	ds_read_b128 v[210:213], v153 offset:33792
	ds_read_b128 v[214:217], v152 offset:32768
	ds_read_b128 v[218:221], v152 offset:33792
	s_waitcnt vmcnt(2)
	s_barrier
; #define LDA(dst, b, h) for (int m = 0; m < 4; ++m) for (int k = 0; k < 2; ++k) \
;     dst[m][k] = *reinterpret_cast<const bf16x8*>((char*)SA(b, h) + lds_byte(wr * 64 + m * 16 + fr, k * 32 + fq * 8))
; #define LDB(dst, b, h) for (int n = 0; n < 2; ++n) for (int k = 0; k < 2; ++k) \
;     dst[n][k] = *reinterpret_cast<const bf16x8*>((char*)SB(b, h) + lds_byte(wc * 32 + n * 16 + fr, k * 32 + fq * 8))
; #define MMA(ai, bj, At_, Bt_) do { __builtin_amdgcn_s_setprio(1); \
;     for (int k = 0; k < 2; ++k) for (int m = 0; m < 4; ++m) for (int n = 0; n < 2; ++n) \
;       acc[ai][bj][m][n] = __builtin_amdgcn_mfma_f32_16x16x32_bf16(At_[m][k], Bt_[n][k], acc[ai][bj][m][n], 0, 0, 0); \
;     __builtin_amdgcn_s_setprio(0); } while (0)
; #define WAIT_V(n) asm volatile("s_waitcnt vmcnt(" #n ")" ::: "memory")
; #define WAIT_L(n) asm volatile("s_waitcnt lgkmcnt(" #n ")" ::: "memory")
; #define BAR __builtin_amdgcn_s_barrier()
; template <int EPI, int lda, int ldb, int N, int K>
; __device__ __forceinline__ void gemm_phase(const u16* __restrict__ A, const u16* __restrict__ Bt, const GemmEpi ep, int wv) {
;     ...
;     { LDB(B0, 1, 0); LDA(At, 1, 0); WAIT_V(2); BAR; WAIT_L(0); MMA(0, 0, At, B0); BAR;
;       LDB(B1, 1, 1); WAIT_V(0); BAR; WAIT_L(0); MMA(0, 1, At, B1); BAR;
;       LDA(At, 1, 1); BAR; WAIT_L(0); MMA(1, 0, At, B0); MMA(1, 1, At, B1); BAR; }
;     if (wr == 0) BAR;
	s_waitcnt lgkmcnt(0)
	v_mfma_f32_16x16x32_bf16 v[64:67], v[4:7], v[24:27], v[124:127]
	v_mfma_f32_16x16x32_bf16 v[68:71], v[20:23], v[24:27], v[120:123]
	v_mfma_f32_16x16x32_bf16 v[80:83], v[4:7], v[198:201], v[116:119]
	v_mfma_f32_16x16x32_bf16 v[84:87], v[20:23], v[198:201], v[112:115]
	v_mfma_f32_16x16x32_bf16 v[108:111], v[4:7], v[206:209], v[108:111]
	v_mfma_f32_16x16x32_bf16 v[104:107], v[20:23], v[206:209], v[104:107]
	v_mfma_f32_16x16x32_bf16 v[120:123], v[4:7], v[214:217], v[100:103]
	v_mfma_f32_16x16x32_bf16 v[124:127], v[20:23], v[214:217], v[96:99]
	v_mfma_f32_16x16x32_bf16 v[116:119], v[8:11], v[194:197], v[64:67]
	v_mfma_f32_16x16x32_bf16 v[112:115], v[158:161], v[194:197], v[68:71]
	v_mfma_f32_16x16x32_bf16 v[100:103], v[8:11], v[202:205], v[80:83]
	v_mfma_f32_16x16x32_bf16 v[96:99], v[158:161], v[202:205], v[84:87]
	v_mfma_f32_16x16x32_bf16 v[84:87], v[8:11], v[210:213], v[108:111]
	v_mfma_f32_16x16x32_bf16 v[80:83], v[158:161], v[210:213], v[104:107]
	v_mfma_f32_16x16x32_bf16 v[68:71], v[8:11], v[218:221], v[120:123]
	v_mfma_f32_16x16x32_bf16 v[64:67], v[158:161], v[218:221], v[124:127]
	s_barrier
	ds_read_b128 v[222:225], v157
	ds_read_b128 v[226:229], v157 offset:1024
	ds_read_b128 v[230:233], v157 offset:2048
	ds_read_b128 v[234:237], v157 offset:3072
	s_waitcnt vmcnt(0)
	s_barrier
	s_waitcnt lgkmcnt(0)
	v_mfma_f32_16x16x32_bf16 v[92:95], v[222:225], v[24:27], v[92:95]
	v_mfma_f32_16x16x32_bf16 v[24:27], v[230:233], v[24:27], v[88:91]
	v_mfma_f32_16x16x32_bf16 v[88:91], v[222:225], v[198:201], v[178:181]
	v_mfma_f32_16x16x32_bf16 v[104:107], v[230:233], v[198:201], v[182:185]
	v_mfma_f32_16x16x32_bf16 v[76:79], v[222:225], v[206:209], v[76:79]
	v_mfma_f32_16x16x32_bf16 v[72:75], v[230:233], v[206:209], v[72:75]
	v_mfma_f32_16x16x32_bf16 v[176:179], v[222:225], v[214:217], v[186:189]
	v_mfma_f32_16x16x32_bf16 v[180:183], v[230:233], v[214:217], v[190:193]
	v_mfma_f32_16x16x32_bf16 v[124:127], v[226:229], v[194:197], v[92:95]
	v_mfma_f32_16x16x32_bf16 v[120:123], v[234:237], v[194:197], v[24:27]
	v_mfma_f32_16x16x32_bf16 v[108:111], v[226:229], v[202:205], v[88:91]
	v_mfma_f32_16x16x32_bf16 v[104:107], v[234:237], v[202:205], v[104:107]
	v_mfma_f32_16x16x32_bf16 v[92:95], v[226:229], v[210:213], v[76:79]
	v_mfma_f32_16x16x32_bf16 v[88:91], v[234:237], v[210:213], v[72:75]
	v_mfma_f32_16x16x32_bf16 v[76:79], v[226:229], v[218:221], v[176:179]
	v_mfma_f32_16x16x32_bf16 v[72:75], v[234:237], v[218:221], v[180:183]
	s_barrier
	ds_read_b128 v[176:179], v155 offset:49152
	ds_read_b128 v[180:183], v155 offset:50176
	ds_read_b128 v[184:187], v154 offset:49152
	ds_read_b128 v[154:157], v154 offset:50176
	ds_read_b128 v[188:191], v153 offset:49152
	ds_read_b128 v[192:195], v153 offset:50176
	ds_read_b128 v[196:199], v152 offset:49152
	ds_read_b128 v[200:203], v152 offset:50176
	s_barrier
	s_waitcnt lgkmcnt(0)
	v_mfma_f32_16x16x32_bf16 v[24:27], v[4:7], v[176:179], v[60:63]
	v_mfma_f32_16x16x32_bf16 v[60:63], v[20:23], v[176:179], v[56:59]
	v_mfma_f32_16x16x32_bf16 v[204:207], v[4:7], v[184:187], v[52:55]
	v_mfma_f32_16x16x32_bf16 v[48:51], v[20:23], v[184:187], v[48:51]
	v_mfma_f32_16x16x32_bf16 v[44:47], v[4:7], v[188:191], v[44:47]
	v_mfma_f32_16x16x32_bf16 v[208:211], v[20:23], v[188:191], v[40:43]
	v_mfma_f32_16x16x32_bf16 v[4:7], v[4:7], v[196:199], v[36:39]
	v_mfma_f32_16x16x32_bf16 v[32:35], v[20:23], v[196:199], v[32:35]
	v_mfma_f32_16x16x32_bf16 v[56:59], v[8:11], v[180:183], v[24:27]
	v_mfma_f32_16x16x32_bf16 v[52:55], v[158:161], v[180:183], v[60:63]
	v_mfma_f32_16x16x32_bf16 v[40:43], v[8:11], v[154:157], v[204:207]
	v_mfma_f32_16x16x32_bf16 v[36:39], v[158:161], v[154:157], v[48:51]
	v_mfma_f32_16x16x32_bf16 v[24:27], v[8:11], v[192:195], v[44:47]
	v_mfma_f32_16x16x32_bf16 v[20:23], v[158:161], v[192:195], v[208:211]
	v_mfma_f32_16x16x32_bf16 v[8:11], v[8:11], v[200:203], v[4:7]
	v_mfma_f32_16x16x32_bf16 v[4:7], v[158:161], v[200:203], v[32:35]
	v_mfma_f32_16x16x32_bf16 v[28:31], v[222:225], v[176:179], v[28:31]
	v_mfma_f32_16x16x32_bf16 v[32:35], v[230:233], v[176:179], v[134:137]
	v_mfma_f32_16x16x32_bf16 v[44:47], v[222:225], v[184:187], v[138:141]
	v_mfma_f32_16x16x32_bf16 v[16:19], v[230:233], v[184:187], v[16:19]
	v_mfma_f32_16x16x32_bf16 v[12:15], v[222:225], v[188:191], v[12:15]
	v_mfma_f32_16x16x32_bf16 v[134:137], v[230:233], v[188:191], v[142:145]
	v_mfma_f32_16x16x32_bf16 v[138:141], v[222:225], v[196:199], v[172:175]
	v_mfma_f32_16x16x32_bf16 v[0:3], v[230:233], v[196:199], v[0:3]
	v_mfma_f32_16x16x32_bf16 v[60:63], v[226:229], v[180:183], v[28:31]
	v_mfma_f32_16x16x32_bf16 v[48:51], v[234:237], v[180:183], v[32:35]
	v_mfma_f32_16x16x32_bf16 v[44:47], v[226:229], v[154:157], v[44:47]
	v_mfma_f32_16x16x32_bf16 v[32:35], v[234:237], v[154:157], v[16:19]
	v_mfma_f32_16x16x32_bf16 v[28:31], v[226:229], v[192:195], v[12:15]
	v_mfma_f32_16x16x32_bf16 v[16:19], v[234:237], v[192:195], v[134:137]
	v_mfma_f32_16x16x32_bf16 v[12:15], v[226:229], v[200:203], v[138:141]
	v_mfma_f32_16x16x32_bf16 v[0:3], v[234:237], v[200:203], v[0:3]
	v_cmp_gt_u32_e32 vcc, s62, v130
	s_barrier
	s_and_saveexec_b64 s[44:45], vcc
	s_cbranch_execz .LBB0_227
	s_barrier

; #define STAGE(P, BASE, LD, br, kt) do { const char* _g = (const char*)((BASE) + (size_t)(br) * (LD) + (size_t)(kt) * 64); \
;     for (int _i = 0; _i < 2; ++_i) { int _b = tidx * 16 + _i * 8192; int _r, _c; stage_rc(_b, _r, _c); \
;       __builtin_amdgcn_global_load_lds((const unsigned*)(_g + (unsigned)((_r * (LD) + _c) * 2)), (unsigned*)((char*)(P) + _b), 16, 0, 0); } } while (0)
; #define LDA(dst, b, h) for (int m = 0; m < 4; ++m) for (int k = 0; k < 2; ++k) \
;     dst[m][k] = *reinterpret_cast<const bf16x8*>((char*)SA(b, h) + lds_byte(wr * 64 + m * 16 + fr, k * 32 + fq * 8))
; #define LDB(dst, b, h) for (int n = 0; n < 2; ++n) for (int k = 0; k < 2; ++k) \
;     dst[n][k] = *reinterpret_cast<const bf16x8*>((char*)SB(b, h) + lds_byte(wc * 32 + n * 16 + fr, k * 32 + fq * 8))
; #define MMA(ai, bj, At_, Bt_) do { __builtin_amdgcn_s_setprio(1); \
;     for (int k = 0; k < 2; ++k) for (int m = 0; m < 4; ++m) for (int n = 0; n < 2; ++n) \
;       acc[ai][bj][m][n] = __builtin_amdgcn_mfma_f32_16x16x32_bf16(At_[m][k], Bt_[n][k], acc[ai][bj][m][n], 0, 0, 0); \
;     __builtin_amdgcn_s_setprio(0); } while (0)
; #define WAIT_L(n) asm volatile("s_waitcnt lgkmcnt(" #n ")" ::: "memory")
; #define BAR __builtin_amdgcn_s_barrier()
; #define SCHED __builtin_amdgcn_sched_barrier(0)
; template <int EPI, int lda, int ldb, int N, int K>
; __device__ __forceinline__ void gemm_phase(const u16* __restrict__ A, const u16* __restrict__ Bt, const GemmEpi ep, int wv) {
;     ...
;       LDB(B0, 0, 0); SCHED; LDA(At, 0, 0); STAGE(SA(1, 1), Ab, lda, brow + HALF, t + 1);
;       WAIT_L(8); BAR; WAIT_L(0); MMA(0, 0, At, B0); BAR; SCHED;
;       LDB(B1, 0, 1); STAGE(SB(0, 0), Bt, ldb, bcol, t + 2);
;       BAR; WAIT_L(0); MMA(0, 1, At, B1); BAR;
;       LDA(At, 0, 1); STAGE(SA(0, 0), Ab, lda, brow, t + 2);
;       BAR; WAIT_L(0); MMA(1, 0, At, B0); BAR; SCHED;
.LBB0_340:
	ds_read_b128 v[166:169], v162
	ds_read_b128 v[172:175], v162 offset:1024
	ds_read_b128 v[176:179], v162 offset:2048
	ds_read_b128 v[180:183], v162 offset:3072
	v_add_u32_e32 v170, 0xc000, v149
	v_lshl_add_u64 v[236:237], v[138:139], 0, s[48:49]
	v_readfirstlane_b32 s51, v170
	v_add_u32_e32 v171, 0xe000, v149
	v_lshl_add_u64 v[164:165], v[236:237], 0, s[18:19]
	s_mov_b32 m0, s51
	v_lshl_add_u64 v[238:239], v[140:141], 0, s[48:49]
	v_readfirstlane_b32 s51, v171
	ds_read_b128 v[184:187], v153
	ds_read_b128 v[188:191], v153 offset:1024
	ds_read_b128 v[192:195], v152
	ds_read_b128 v[196:199], v152 offset:1024
	ds_read_b128 v[200:203], v151
	ds_read_b128 v[204:207], v151 offset:1024
	ds_read_b128 v[208:211], v150
	ds_read_b128 v[212:215], v150 offset:1024
	global_load_lds_dwordx4 v[164:165], off
	v_lshl_add_u64 v[164:165], v[238:239], 0, s[18:19]
	s_mov_b32 m0, s51
	s_nop 0
	global_load_lds_dwordx4 v[164:165], off
	s_waitcnt lgkmcnt(8)
	s_barrier
	s_waitcnt lgkmcnt(0)
	v_mfma_f32_16x16x32_bf16 v[124:127], v[184:187], v[166:169], v[124:127]
	v_mfma_f32_16x16x32_bf16 v[120:123], v[184:187], v[176:179], v[120:123]
	v_mfma_f32_16x16x32_bf16 v[116:119], v[192:195], v[166:169], v[116:119]
	v_mfma_f32_16x16x32_bf16 v[112:115], v[192:195], v[176:179], v[112:115]
	v_mfma_f32_16x16x32_bf16 v[108:111], v[200:203], v[166:169], v[108:111]
	v_mfma_f32_16x16x32_bf16 v[104:107], v[200:203], v[176:179], v[104:107]
	v_mfma_f32_16x16x32_bf16 v[100:103], v[208:211], v[166:169], v[100:103]
	v_mfma_f32_16x16x32_bf16 v[96:99], v[208:211], v[176:179], v[96:99]
	v_mfma_f32_16x16x32_bf16 v[124:127], v[188:191], v[172:175], v[124:127]
	v_mfma_f32_16x16x32_bf16 v[120:123], v[188:191], v[180:183], v[120:123]
	v_mfma_f32_16x16x32_bf16 v[116:119], v[196:199], v[172:175], v[116:119]
	v_mfma_f32_16x16x32_bf16 v[112:115], v[196:199], v[180:183], v[112:115]
	v_mfma_f32_16x16x32_bf16 v[108:111], v[204:207], v[172:175], v[108:111]
	v_mfma_f32_16x16x32_bf16 v[104:107], v[204:207], v[180:183], v[104:107]
	v_mfma_f32_16x16x32_bf16 v[100:103], v[212:215], v[172:175], v[100:103]
	v_mfma_f32_16x16x32_bf16 v[96:99], v[212:215], v[180:183], v[96:99]
	s_barrier
	v_add_u32_e32 v163, s62, v155
	v_lshl_add_u64 v[240:241], v[134:135], 0, s[48:49]
	v_readfirstlane_b32 s51, v163
	v_lshl_add_u64 v[164:165], v[240:241], 0, s[20:21]
	s_mov_b32 m0, s51
	ds_read_b128 v[216:219], v161
	ds_read_b128 v[220:223], v161 offset:1024
	ds_read_b128 v[224:227], v161 offset:2048
	ds_read_b128 v[228:231], v161 offset:3072
	global_load_lds_dwordx4 v[164:165], off
	v_add_u32_e32 v164, 0x2000, v163
	v_lshl_add_u64 v[242:243], v[136:137], 0, s[48:49]
	v_readfirstlane_b32 s51, v164
	v_lshl_add_u64 v[232:233], v[242:243], 0, s[20:21]
	s_mov_b32 m0, s51
	s_nop 0
	global_load_lds_dwordx4 v[232:233], off
	s_barrier
	s_waitcnt lgkmcnt(0)
	v_mfma_f32_16x16x32_bf16 v[92:95], v[184:187], v[216:219], v[92:95]
	v_mfma_f32_16x16x32_bf16 v[88:91], v[184:187], v[224:227], v[88:91]
	v_mfma_f32_16x16x32_bf16 v[84:87], v[192:195], v[216:219], v[84:87]
	v_mfma_f32_16x16x32_bf16 v[80:83], v[192:195], v[224:227], v[80:83]
	v_mfma_f32_16x16x32_bf16 v[76:79], v[200:203], v[216:219], v[76:79]
	v_mfma_f32_16x16x32_bf16 v[72:75], v[200:203], v[224:227], v[72:75]
	v_mfma_f32_16x16x32_bf16 v[68:71], v[208:211], v[216:219], v[68:71]
	v_mfma_f32_16x16x32_bf16 v[64:67], v[208:211], v[224:227], v[64:67]
	v_mfma_f32_16x16x32_bf16 v[92:95], v[188:191], v[220:223], v[92:95]
	v_mfma_f32_16x16x32_bf16 v[88:91], v[188:191], v[228:231], v[88:91]
	v_mfma_f32_16x16x32_bf16 v[84:87], v[196:199], v[220:223], v[84:87]
	v_mfma_f32_16x16x32_bf16 v[80:83], v[196:199], v[228:231], v[80:83]
	v_mfma_f32_16x16x32_bf16 v[76:79], v[204:207], v[220:223], v[76:79]
	v_mfma_f32_16x16x32_bf16 v[72:75], v[204:207], v[228:231], v[72:75]
	v_mfma_f32_16x16x32_bf16 v[68:71], v[212:215], v[220:223], v[68:71]
	v_mfma_f32_16x16x32_bf16 v[64:67], v[212:215], v[228:231], v[64:67]
	v_readfirstlane_b32 s51, v149
	v_add_u32_e32 v165, 0x2000, v149
	v_lshl_add_u64 v[232:233], v[236:237], 0, s[22:23]
	s_mov_b32 m0, s51
	v_readfirstlane_b32 s51, v165
	s_barrier
	ds_read_b128 v[184:187], v153 offset:16384
	ds_read_b128 v[188:191], v153 offset:17408
	ds_read_b128 v[192:195], v152 offset:16384
	ds_read_b128 v[196:199], v152 offset:17408
	ds_read_b128 v[200:203], v151 offset:16384
	ds_read_b128 v[204:207], v151 offset:17408
	ds_read_b128 v[208:211], v150 offset:16384
	ds_read_b128 v[212:215], v150 offset:17408
	global_load_lds_dwordx4 v[232:233], off
	v_lshl_add_u64 v[232:233], v[238:239], 0, s[22:23]
	s_mov_b32 m0, s51
	s_nop 0
	global_load_lds_dwordx4 v[232:233], off
	s_barrier
	s_waitcnt lgkmcnt(0)
	v_mfma_f32_16x16x32_bf16 v[60:63], v[184:187], v[166:169], v[60:63]
	v_mfma_f32_16x16x32_bf16 v[56:59], v[184:187], v[176:179], v[56:59]
	v_mfma_f32_16x16x32_bf16 v[52:55], v[192:195], v[166:169], v[52:55]
	v_mfma_f32_16x16x32_bf16 v[48:51], v[192:195], v[176:179], v[48:51]
	v_mfma_f32_16x16x32_bf16 v[44:47], v[200:203], v[166:169], v[44:47]
	v_mfma_f32_16x16x32_bf16 v[40:43], v[200:203], v[176:179], v[40:43]
	v_mfma_f32_16x16x32_bf16 v[36:39], v[208:211], v[166:169], v[36:39]
	v_mfma_f32_16x16x32_bf16 v[32:35], v[208:211], v[176:179], v[32:35]
	v_mfma_f32_16x16x32_bf16 v[60:63], v[188:191], v[172:175], v[60:63]
	v_mfma_f32_16x16x32_bf16 v[56:59], v[188:191], v[180:183], v[56:59]
	v_mfma_f32_16x16x32_bf16 v[52:55], v[196:199], v[172:175], v[52:55]
	v_mfma_f32_16x16x32_bf16 v[48:51], v[196:199], v[180:183], v[48:51]
	v_mfma_f32_16x16x32_bf16 v[44:47], v[204:207], v[172:175], v[44:47]
	v_mfma_f32_16x16x32_bf16 v[40:43], v[204:207], v[180:183], v[40:43]
	v_mfma_f32_16x16x32_bf16 v[36:39], v[212:215], v[172:175], v[36:39]
	v_mfma_f32_16x16x32_bf16 v[32:35], v[212:215], v[180:183], v[32:35]
	s_barrier
; #define STAGE(P, BASE, LD, br, kt) do { const char* _g = (const char*)((BASE) + (size_t)(br) * (LD) + (size_t)(kt) * 64); \
;     for (int _i = 0; _i < 2; ++_i) { int _b = tidx * 16 + _i * 8192; int _r, _c; stage_rc(_b, _r, _c); \
;       __builtin_amdgcn_global_load_lds((const unsigned*)(_g + (unsigned)((_r * (LD) + _c) * 2)), (unsigned*)((char*)(P) + _b), 16, 0, 0); } } while (0)
; #define LDA(dst, b, h) for (int m = 0; m < 4; ++m) for (int k = 0; k < 2; ++k) \
;     dst[m][k] = *reinterpret_cast<const bf16x8*>((char*)SA(b, h) + lds_byte(wr * 64 + m * 16 + fr, k * 32 + fq * 8))
; #define LDB(dst, b, h) for (int n = 0; n < 2; ++n) for (int k = 0; k < 2; ++k) \
;     dst[n][k] = *reinterpret_cast<const bf16x8*>((char*)SB(b, h) + lds_byte(wc * 32 + n * 16 + fr, k * 32 + fq * 8))
; #define MMA(ai, bj, At_, Bt_) do { __builtin_amdgcn_s_setprio(1); \
;     for (int k = 0; k < 2; ++k) for (int m = 0; m < 4; ++m) for (int n = 0; n < 2; ++n) \
;       acc[ai][bj][m][n] = __builtin_amdgcn_mfma_f32_16x16x32_bf16(At_[m][k], Bt_[n][k], acc[ai][bj][m][n], 0, 0, 0); \
;     __builtin_amdgcn_s_setprio(0); } while (0)
; #define WAIT_V(n) asm volatile("s_waitcnt vmcnt(" #n ")" ::: "memory")
; #define WAIT_L(n) asm volatile("s_waitcnt lgkmcnt(" #n ")" ::: "memory")
; #define BAR __builtin_amdgcn_s_barrier()
; #define SCHED __builtin_amdgcn_sched_barrier(0)
; template <int EPI, int lda, int ldb, int N, int K>
; __device__ __forceinline__ void gemm_phase(const u16* __restrict__ A, const u16* __restrict__ Bt, const GemmEpi ep, int wv) {
;     ...
;       STAGE(SB(0, 1), Bt, ldb, bcol + HALF, t + 2);
;       WAIT_V(6); BAR; MMA(1, 1, At, B1); BAR;
;       LDB(B0, 1, 0); SCHED; LDA(At, 1, 0); STAGE(SA(0, 1), Ab, lda, brow + HALF, t + 2);
;       WAIT_L(8); BAR; WAIT_L(0); MMA(0, 0, At, B0); BAR; SCHED;
;       LDB(B1, 1, 1); STAGE(SB(1, 0), Bt, ldb, bcol, t + 3);
;       BAR; WAIT_L(0); MMA(0, 1, At, B1); BAR;
;       LDA(At, 1, 1); STAGE(SA(1, 0), Ab, lda, brow, t + 3);
	v_add_u32_e32 v166, s63, v155
	v_add_u32_e32 v167, 0x2000, v166
	v_readfirstlane_b32 s51, v166
	v_lshl_add_u64 v[168:169], v[240:241], 0, s[24:25]
	s_mov_b32 m0, s51
	v_readfirstlane_b32 s51, v167
	global_load_lds_dwordx4 v[168:169], off
	v_lshl_add_u64 v[168:169], v[242:243], 0, s[24:25]
	s_mov_b32 m0, s51
	s_nop 0
	global_load_lds_dwordx4 v[168:169], off
	s_waitcnt vmcnt(6)
	s_barrier
	v_mfma_f32_16x16x32_bf16 v[28:31], v[184:187], v[216:219], v[28:31]
	v_mfma_f32_16x16x32_bf16 v[24:27], v[184:187], v[224:227], v[24:27]
	v_mfma_f32_16x16x32_bf16 v[20:23], v[192:195], v[216:219], v[20:23]
	v_mfma_f32_16x16x32_bf16 v[16:19], v[192:195], v[224:227], v[16:19]
	v_mfma_f32_16x16x32_bf16 v[12:15], v[200:203], v[216:219], v[12:15]
	v_mfma_f32_16x16x32_bf16 v[8:11], v[200:203], v[224:227], v[8:11]
	v_mfma_f32_16x16x32_bf16 v[4:7], v[208:211], v[216:219], v[4:7]
	v_mfma_f32_16x16x32_bf16 v[0:3], v[208:211], v[224:227], v[0:3]
	v_mfma_f32_16x16x32_bf16 v[28:31], v[188:191], v[220:223], v[28:31]
	v_mfma_f32_16x16x32_bf16 v[24:27], v[188:191], v[228:231], v[24:27]
	v_mfma_f32_16x16x32_bf16 v[20:23], v[196:199], v[220:223], v[20:23]
	v_mfma_f32_16x16x32_bf16 v[16:19], v[196:199], v[228:231], v[16:19]
	v_mfma_f32_16x16x32_bf16 v[12:15], v[204:207], v[220:223], v[12:15]
	v_mfma_f32_16x16x32_bf16 v[8:11], v[204:207], v[228:231], v[8:11]
	v_mfma_f32_16x16x32_bf16 v[4:7], v[212:215], v[220:223], v[4:7]
	v_mfma_f32_16x16x32_bf16 v[0:3], v[212:215], v[228:231], v[0:3]
	s_barrier
	ds_read_b128 v[172:175], v156
	ds_read_b128 v[176:179], v156 offset:1024
	ds_read_b128 v[180:183], v156 offset:2048
	ds_read_b128 v[184:187], v156 offset:3072
	v_add_u32_e32 v168, 0x4000, v149
	v_add_u32_e32 v169, 0x6000, v149
	v_readfirstlane_b32 s51, v168
	v_lshl_add_u64 v[220:221], v[236:237], 0, s[26:27]
	s_mov_b32 m0, s51
	v_readfirstlane_b32 s51, v169
	ds_read_b128 v[188:191], v153 offset:32768
	ds_read_b128 v[192:195], v153 offset:33792
	ds_read_b128 v[196:199], v152 offset:32768
	ds_read_b128 v[200:203], v152 offset:33792
	ds_read_b128 v[204:207], v151 offset:32768
	ds_read_b128 v[208:211], v151 offset:33792
	ds_read_b128 v[212:215], v150 offset:32768
	ds_read_b128 v[216:219], v150 offset:33792
	global_load_lds_dwordx4 v[220:221], off
	v_lshl_add_u64 v[220:221], v[238:239], 0, s[26:27]
	s_mov_b32 m0, s51
	s_nop 0
	global_load_lds_dwordx4 v[220:221], off
	s_waitcnt lgkmcnt(8)
	s_barrier
	s_waitcnt lgkmcnt(0)
	v_mfma_f32_16x16x32_bf16 v[124:127], v[188:191], v[172:175], v[124:127]
	v_mfma_f32_16x16x32_bf16 v[120:123], v[188:191], v[180:183], v[120:123]
	v_mfma_f32_16x16x32_bf16 v[116:119], v[196:199], v[172:175], v[116:119]
	v_mfma_f32_16x16x32_bf16 v[112:115], v[196:199], v[180:183], v[112:115]
	v_mfma_f32_16x16x32_bf16 v[108:111], v[204:207], v[172:175], v[108:111]
	v_mfma_f32_16x16x32_bf16 v[104:107], v[204:207], v[180:183], v[104:107]
	v_mfma_f32_16x16x32_bf16 v[100:103], v[212:215], v[172:175], v[100:103]
	v_mfma_f32_16x16x32_bf16 v[96:99], v[212:215], v[180:183], v[96:99]
	v_mfma_f32_16x16x32_bf16 v[124:127], v[192:195], v[176:179], v[124:127]
	v_mfma_f32_16x16x32_bf16 v[120:123], v[192:195], v[184:187], v[120:123]
	v_mfma_f32_16x16x32_bf16 v[116:119], v[200:203], v[176:179], v[116:119]
	v_mfma_f32_16x16x32_bf16 v[112:115], v[200:203], v[184:187], v[112:115]
	v_mfma_f32_16x16x32_bf16 v[108:111], v[208:211], v[176:179], v[108:111]
	v_mfma_f32_16x16x32_bf16 v[104:107], v[208:211], v[184:187], v[104:107]
	v_mfma_f32_16x16x32_bf16 v[100:103], v[216:219], v[176:179], v[100:103]
	v_mfma_f32_16x16x32_bf16 v[96:99], v[216:219], v[184:187], v[96:99]
	s_barrier
	v_readfirstlane_b32 s51, v157
	v_add_u32_e32 v246, 0x2000, v157
	v_lshl_add_u64 v[244:245], v[240:241], 0, s[36:37]
	s_mov_b32 m0, s51
	v_readfirstlane_b32 s51, v246
	ds_read_b128 v[220:223], v154
	ds_read_b128 v[224:227], v154 offset:1024
	ds_read_b128 v[228:231], v154 offset:2048
	ds_read_b128 v[232:235], v154 offset:3072
	global_load_lds_dwordx4 v[244:245], off
	v_lshl_add_u64 v[244:245], v[242:243], 0, s[36:37]
	s_mov_b32 m0, s51
	s_nop 0
	global_load_lds_dwordx4 v[244:245], off
	s_barrier
	s_waitcnt lgkmcnt(0)
	v_mfma_f32_16x16x32_bf16 v[92:95], v[188:191], v[220:223], v[92:95]
	v_mfma_f32_16x16x32_bf16 v[88:91], v[188:191], v[228:231], v[88:91]
	v_mfma_f32_16x16x32_bf16 v[84:87], v[196:199], v[220:223], v[84:87]
	v_mfma_f32_16x16x32_bf16 v[80:83], v[196:199], v[228:231], v[80:83]
	v_mfma_f32_16x16x32_bf16 v[76:79], v[204:207], v[220:223], v[76:79]
	v_mfma_f32_16x16x32_bf16 v[72:75], v[204:207], v[228:231], v[72:75]
	v_mfma_f32_16x16x32_bf16 v[68:71], v[212:215], v[220:223], v[68:71]
	v_mfma_f32_16x16x32_bf16 v[64:67], v[212:215], v[228:231], v[64:67]
	v_mfma_f32_16x16x32_bf16 v[92:95], v[192:195], v[224:227], v[92:95]
	v_mfma_f32_16x16x32_bf16 v[88:91], v[192:195], v[232:235], v[88:91]
	v_mfma_f32_16x16x32_bf16 v[84:87], v[200:203], v[224:227], v[84:87]
	v_mfma_f32_16x16x32_bf16 v[80:83], v[200:203], v[232:235], v[80:83]
	v_mfma_f32_16x16x32_bf16 v[76:79], v[208:211], v[224:227], v[76:79]
	v_mfma_f32_16x16x32_bf16 v[72:75], v[208:211], v[232:235], v[72:75]
	v_mfma_f32_16x16x32_bf16 v[68:71], v[216:219], v[224:227], v[68:71]
	v_mfma_f32_16x16x32_bf16 v[64:67], v[216:219], v[232:235], v[64:67]
	v_readfirstlane_b32 s51, v158
	v_lshl_add_u64 v[236:237], v[236:237], 0, s[38:39]
	s_mov_b32 m0, s51
	v_readfirstlane_b32 s51, v159
	s_barrier
	ds_read_b128 v[188:191], v153 offset:49152
	ds_read_b128 v[192:195], v153 offset:50176
	ds_read_b128 v[196:199], v152 offset:49152
	ds_read_b128 v[200:203], v152 offset:50176
	ds_read_b128 v[204:207], v151 offset:49152
	ds_read_b128 v[208:211], v151 offset:50176
	ds_read_b128 v[212:215], v150 offset:49152
	ds_read_b128 v[216:219], v150 offset:50176
	global_load_lds_dwordx4 v[236:237], off
	v_lshl_add_u64 v[236:237], v[238:239], 0, s[38:39]
	s_mov_b32 m0, s51
	s_nop 0
	global_load_lds_dwordx4 v[236:237], off
	s_barrier
; #define STAGE(P, BASE, LD, br, kt) do { const char* _g = (const char*)((BASE) + (size_t)(br) * (LD) + (size_t)(kt) * 64); \
;     for (int _i = 0; _i < 2; ++_i) { int _b = tidx * 16 + _i * 8192; int _r, _c; stage_rc(_b, _r, _c); \
;       __builtin_amdgcn_global_load_lds((const unsigned*)(_g + (unsigned)((_r * (LD) + _c) * 2)), (unsigned*)((char*)(P) + _b), 16, 0, 0); } } while (0)
; #define LDA(dst, b, h) for (int m = 0; m < 4; ++m) for (int k = 0; k < 2; ++k) \
;     dst[m][k] = *reinterpret_cast<const bf16x8*>((char*)SA(b, h) + lds_byte(wr * 64 + m * 16 + fr, k * 32 + fq * 8))
; #define LDB(dst, b, h) for (int n = 0; n < 2; ++n) for (int k = 0; k < 2; ++k) \
;     dst[n][k] = *reinterpret_cast<const bf16x8*>((char*)SB(b, h) + lds_byte(wc * 32 + n * 16 + fr, k * 32 + fq * 8))
; #define MMA(ai, bj, At_, Bt_) do { __builtin_amdgcn_s_setprio(1); \
;     for (int k = 0; k < 2; ++k) for (int m = 0; m < 4; ++m) for (int n = 0; n < 2; ++n) \
;       acc[ai][bj][m][n] = __builtin_amdgcn_mfma_f32_16x16x32_bf16(At_[m][k], Bt_[n][k], acc[ai][bj][m][n], 0, 0, 0); \
;     __builtin_amdgcn_s_setprio(0); } while (0)
; #define WAIT_V(n) asm volatile("s_waitcnt vmcnt(" #n ")" ::: "memory")
; #define WAIT_L(n) asm volatile("s_waitcnt lgkmcnt(" #n ")" ::: "memory")
; #define BAR __builtin_amdgcn_s_barrier()
; #define SCHED __builtin_amdgcn_sched_barrier(0)
; template <int EPI, int lda, int ldb, int N, int K>
; __device__ __forceinline__ void gemm_phase(const u16* __restrict__ A, const u16* __restrict__ Bt, const GemmEpi ep, int wv) {
;     ...
;       LDA(At, 1, 1); STAGE(SA(1, 0), Ab, lda, brow, t + 3);
;       BAR; WAIT_L(0); MMA(1, 0, At, B0); BAR; SCHED;
;       STAGE(SB(1, 1), Bt, ldb, bcol + HALF, t + 3);
;       WAIT_V(6); BAR; MMA(1, 1, At, B1); BAR;
;     }
;     { LDB(B0, 0, 0); LDA(At, 0, 0); STAGE(SA(1, 1), Ab, lda, brow + HALF, nt - 1);
;       BAR; WAIT_L(0); MMA(0, 0, At, B0); BAR;
;       LDB(B1, 0, 1); BAR; WAIT_L(0); MMA(0, 1, At, B1); BAR;
	s_waitcnt lgkmcnt(0)
	v_mfma_f32_16x16x32_bf16 v[60:63], v[188:191], v[172:175], v[60:63]
	v_mfma_f32_16x16x32_bf16 v[56:59], v[188:191], v[180:183], v[56:59]
	v_mfma_f32_16x16x32_bf16 v[52:55], v[196:199], v[172:175], v[52:55]
	v_mfma_f32_16x16x32_bf16 v[48:51], v[196:199], v[180:183], v[48:51]
	v_mfma_f32_16x16x32_bf16 v[44:47], v[204:207], v[172:175], v[44:47]
	v_mfma_f32_16x16x32_bf16 v[40:43], v[204:207], v[180:183], v[40:43]
	v_mfma_f32_16x16x32_bf16 v[36:39], v[212:215], v[172:175], v[36:39]
	v_mfma_f32_16x16x32_bf16 v[32:35], v[212:215], v[180:183], v[32:35]
	v_mfma_f32_16x16x32_bf16 v[60:63], v[192:195], v[176:179], v[60:63]
	v_mfma_f32_16x16x32_bf16 v[56:59], v[192:195], v[184:187], v[56:59]
	v_mfma_f32_16x16x32_bf16 v[52:55], v[200:203], v[176:179], v[52:55]
	v_mfma_f32_16x16x32_bf16 v[48:51], v[200:203], v[184:187], v[48:51]
	v_mfma_f32_16x16x32_bf16 v[44:47], v[208:211], v[176:179], v[44:47]
	v_mfma_f32_16x16x32_bf16 v[40:43], v[208:211], v[184:187], v[40:43]
	v_mfma_f32_16x16x32_bf16 v[36:39], v[216:219], v[176:179], v[36:39]
	v_mfma_f32_16x16x32_bf16 v[32:35], v[216:219], v[184:187], v[32:35]
	s_barrier
	v_readfirstlane_b32 s51, v160
	v_add_u32_e32 v174, 0x2000, v160
	v_lshl_add_u64 v[172:173], v[240:241], 0, s[42:43]
	s_mov_b32 m0, s51
	v_readfirstlane_b32 s51, v174
	global_load_lds_dwordx4 v[172:173], off
	v_lshl_add_u64 v[172:173], v[242:243], 0, s[42:43]
	s_mov_b32 m0, s51
	s_nop 0
	global_load_lds_dwordx4 v[172:173], off
	s_waitcnt vmcnt(6)
	s_barrier
	v_mfma_f32_16x16x32_bf16 v[28:31], v[188:191], v[220:223], v[28:31]
	v_mfma_f32_16x16x32_bf16 v[24:27], v[188:191], v[228:231], v[24:27]
	v_mfma_f32_16x16x32_bf16 v[20:23], v[196:199], v[220:223], v[20:23]
	v_mfma_f32_16x16x32_bf16 v[16:19], v[196:199], v[228:231], v[16:19]
	v_mfma_f32_16x16x32_bf16 v[12:15], v[204:207], v[220:223], v[12:15]
	v_mfma_f32_16x16x32_bf16 v[8:11], v[204:207], v[228:231], v[8:11]
	v_mfma_f32_16x16x32_bf16 v[4:7], v[212:215], v[220:223], v[4:7]
	v_mfma_f32_16x16x32_bf16 v[0:3], v[212:215], v[228:231], v[0:3]
	v_mfma_f32_16x16x32_bf16 v[28:31], v[192:195], v[224:227], v[28:31]
	v_mfma_f32_16x16x32_bf16 v[24:27], v[192:195], v[232:235], v[24:27]
	v_mfma_f32_16x16x32_bf16 v[20:23], v[200:203], v[224:227], v[20:23]
	v_mfma_f32_16x16x32_bf16 v[16:19], v[200:203], v[232:235], v[16:19]
	v_mfma_f32_16x16x32_bf16 v[12:15], v[208:211], v[224:227], v[12:15]
	v_mfma_f32_16x16x32_bf16 v[8:11], v[208:211], v[232:235], v[8:11]
	v_mfma_f32_16x16x32_bf16 v[4:7], v[216:219], v[224:227], v[4:7]
	v_mfma_f32_16x16x32_bf16 v[0:3], v[216:219], v[232:235], v[0:3]
	s_add_i32 s50, s50, 2
	s_add_u32 s48, s48, 0x100
	s_addc_u32 s49, s49, 0
	s_cmp_gt_u32 s50, 27
	s_barrier
	s_cbranch_scc0 .LBB0_340
	s_add_i32 s48, s46, 0x80
	s_mul_hi_i32 s49, s48, 0x1080
	s_mulk_i32 s48, 0x1080
	s_add_u32 s48, s31, s48
	s_addc_u32 s49, s56, s49
	v_lshl_add_u64 v[158:159], s[48:49], 0, v[128:129]
	v_readfirstlane_b32 s50, v170
	v_lshl_add_u64 v[158:159], v[158:159], 0, s[44:45]
	s_mov_b32 m0, s50
	ds_read_b128 v[134:137], v162
	ds_read_b128 v[138:141], v162 offset:1024
	ds_read_b128 v[172:175], v162 offset:2048
	ds_read_b128 v[176:179], v162 offset:3072
	ds_read_b128 v[180:183], v153
	ds_read_b128 v[184:187], v153 offset:1024
	ds_read_b128 v[188:191], v152
	ds_read_b128 v[192:195], v152 offset:1024
	ds_read_b128 v[196:199], v151
	ds_read_b128 v[200:203], v151 offset:1024
	ds_read_b128 v[204:207], v150
	ds_read_b128 v[208:211], v150 offset:1024
	global_load_lds_dwordx4 v[158:159], off
	v_lshl_add_u64 v[158:159], s[48:49], 0, v[132:133]
	v_readfirstlane_b32 s48, v171
	v_lshl_add_u64 v[158:159], v[158:159], 0, s[44:45]
	s_mov_b32 m0, s48
	s_nop 0
	global_load_lds_dwordx4 v[158:159], off
	s_barrier
	s_waitcnt lgkmcnt(0)
	v_mfma_f32_16x16x32_bf16 v[124:127], v[180:183], v[134:137], v[124:127]
	v_mfma_f32_16x16x32_bf16 v[120:123], v[180:183], v[172:175], v[120:123]
	v_mfma_f32_16x16x32_bf16 v[116:119], v[188:191], v[134:137], v[116:119]
	v_mfma_f32_16x16x32_bf16 v[112:115], v[188:191], v[172:175], v[112:115]
	v_mfma_f32_16x16x32_bf16 v[108:111], v[196:199], v[134:137], v[108:111]
	v_mfma_f32_16x16x32_bf16 v[104:107], v[196:199], v[172:175], v[104:107]
	v_mfma_f32_16x16x32_bf16 v[100:103], v[204:207], v[134:137], v[100:103]
	v_mfma_f32_16x16x32_bf16 v[96:99], v[204:207], v[172:175], v[96:99]
	v_mfma_f32_16x16x32_bf16 v[124:127], v[184:187], v[138:141], v[124:127]
	v_mfma_f32_16x16x32_bf16 v[120:123], v[184:187], v[176:179], v[120:123]
	v_mfma_f32_16x16x32_bf16 v[116:119], v[192:195], v[138:141], v[116:119]
	v_mfma_f32_16x16x32_bf16 v[112:115], v[192:195], v[176:179], v[112:115]
	v_mfma_f32_16x16x32_bf16 v[108:111], v[200:203], v[138:141], v[108:111]
	v_mfma_f32_16x16x32_bf16 v[104:107], v[200:203], v[176:179], v[104:107]
	v_mfma_f32_16x16x32_bf16 v[100:103], v[208:211], v[138:141], v[100:103]
	v_mfma_f32_16x16x32_bf16 v[96:99], v[208:211], v[176:179], v[96:99]
	s_barrier
	ds_read_b128 v[212:215], v161
	ds_read_b128 v[216:219], v161 offset:1024
	ds_read_b128 v[220:223], v161 offset:2048
	ds_read_b128 v[158:161], v161 offset:3072
	s_barrier
; #define LDA(dst, b, h) for (int m = 0; m < 4; ++m) for (int k = 0; k < 2; ++k) \
;     dst[m][k] = *reinterpret_cast<const bf16x8*>((char*)SA(b, h) + lds_byte(wr * 64 + m * 16 + fr, k * 32 + fq * 8))
; #define LDB(dst, b, h) for (int n = 0; n < 2; ++n) for (int k = 0; k < 2; ++k) \
;     dst[n][k] = *reinterpret_cast<const bf16x8*>((char*)SB(b, h) + lds_byte(wc * 32 + n * 16 + fr, k * 32 + fq * 8))
; #define MMA(ai, bj, At_, Bt_) do { __builtin_amdgcn_s_setprio(1); \
;     for (int k = 0; k < 2; ++k) for (int m = 0; m < 4; ++m) for (int n = 0; n < 2; ++n) \
;       acc[ai][bj][m][n] = __builtin_amdgcn_mfma_f32_16x16x32_bf16(At_[m][k], Bt_[n][k], acc[ai][bj][m][n], 0, 0, 0); \
;     __builtin_amdgcn_s_setprio(0); } while (0)
; #define WAIT_V(n) asm volatile("s_waitcnt vmcnt(" #n ")" ::: "memory")
; #define WAIT_L(n) asm volatile("s_waitcnt lgkmcnt(" #n ")" ::: "memory")
; #define BAR __builtin_amdgcn_s_barrier()
; template <int EPI, int lda, int ldb, int N, int K>
; __device__ __forceinline__ void gemm_phase(const u16* __restrict__ A, const u16* __restrict__ Bt, const GemmEpi ep, int wv) {
;     ...
;       LDB(B1, 0, 1); BAR; WAIT_L(0); MMA(0, 1, At, B1); BAR;
;       LDA(At, 0, 1); WAIT_V(4); BAR; WAIT_L(0); MMA(1, 0, At, B0); MMA(1, 1, At, B1); BAR; }
;     { LDB(B0, 1, 0); LDA(At, 1, 0); WAIT_V(2); BAR; WAIT_L(0); MMA(0, 0, At, B0); BAR;
	s_waitcnt lgkmcnt(0)
	v_mfma_f32_16x16x32_bf16 v[92:95], v[180:183], v[212:215], v[92:95]
	v_mfma_f32_16x16x32_bf16 v[88:91], v[180:183], v[220:223], v[88:91]
	v_mfma_f32_16x16x32_bf16 v[76:79], v[196:199], v[212:215], v[76:79]
	v_mfma_f32_16x16x32_bf16 v[72:75], v[196:199], v[220:223], v[72:75]
	v_mfma_f32_16x16x32_bf16 v[68:71], v[204:207], v[212:215], v[68:71]
	v_mfma_f32_16x16x32_bf16 v[64:67], v[204:207], v[220:223], v[64:67]
	v_mfma_f32_16x16x32_bf16 v[84:87], v[188:191], v[212:215], v[84:87]
	v_mfma_f32_16x16x32_bf16 v[80:83], v[188:191], v[220:223], v[80:83]
	v_mfma_f32_16x16x32_bf16 v[92:95], v[184:187], v[216:219], v[92:95]
	v_mfma_f32_16x16x32_bf16 v[88:91], v[184:187], v[158:161], v[88:91]
	v_mfma_f32_16x16x32_bf16 v[76:79], v[200:203], v[216:219], v[76:79]
	v_mfma_f32_16x16x32_bf16 v[72:75], v[200:203], v[158:161], v[72:75]
	v_mfma_f32_16x16x32_bf16 v[68:71], v[208:211], v[216:219], v[68:71]
	v_mfma_f32_16x16x32_bf16 v[64:67], v[208:211], v[158:161], v[64:67]
	v_mfma_f32_16x16x32_bf16 v[180:183], v[192:195], v[216:219], v[84:87]
	v_mfma_f32_16x16x32_bf16 v[184:187], v[192:195], v[158:161], v[80:83]
	s_barrier
	s_nop 0
	ds_read_b128 v[80:83], v153 offset:16384
	ds_read_b128 v[84:87], v153 offset:17408
	ds_read_b128 v[188:191], v152 offset:16384
	ds_read_b128 v[192:195], v152 offset:17408
	ds_read_b128 v[196:199], v151 offset:16384
	ds_read_b128 v[200:203], v151 offset:17408
	ds_read_b128 v[204:207], v150 offset:16384
	ds_read_b128 v[208:211], v150 offset:17408
	s_waitcnt vmcnt(4)
	s_barrier
	s_waitcnt lgkmcnt(0)
	v_mfma_f32_16x16x32_bf16 v[60:63], v[80:83], v[134:137], v[60:63]
	v_mfma_f32_16x16x32_bf16 v[44:47], v[196:199], v[134:137], v[44:47]
	v_mfma_f32_16x16x32_bf16 v[40:43], v[196:199], v[172:175], v[40:43]
	v_mfma_f32_16x16x32_bf16 v[36:39], v[204:207], v[134:137], v[36:39]
	v_mfma_f32_16x16x32_bf16 v[32:35], v[204:207], v[172:175], v[32:35]
	v_mfma_f32_16x16x32_bf16 v[56:59], v[80:83], v[172:175], v[56:59]
	v_mfma_f32_16x16x32_bf16 v[52:55], v[188:191], v[134:137], v[52:55]
	v_mfma_f32_16x16x32_bf16 v[48:51], v[188:191], v[172:175], v[48:51]
	v_mfma_f32_16x16x32_bf16 v[60:63], v[84:87], v[138:141], v[60:63]
	v_mfma_f32_16x16x32_bf16 v[44:47], v[200:203], v[138:141], v[44:47]
	v_mfma_f32_16x16x32_bf16 v[40:43], v[200:203], v[176:179], v[40:43]
	v_mfma_f32_16x16x32_bf16 v[36:39], v[208:211], v[138:141], v[36:39]
	v_mfma_f32_16x16x32_bf16 v[32:35], v[208:211], v[176:179], v[32:35]
	v_mfma_f32_16x16x32_bf16 v[134:137], v[84:87], v[176:179], v[56:59]
	v_mfma_f32_16x16x32_bf16 v[170:173], v[192:195], v[138:141], v[52:55]
	v_mfma_f32_16x16x32_bf16 v[224:227], v[192:195], v[176:179], v[48:51]
	v_mfma_f32_16x16x32_bf16 v[28:31], v[80:83], v[212:215], v[28:31]
	v_mfma_f32_16x16x32_bf16 v[20:23], v[188:191], v[212:215], v[20:23]
	v_mfma_f32_16x16x32_bf16 v[12:15], v[196:199], v[212:215], v[12:15]
	v_mfma_f32_16x16x32_bf16 v[4:7], v[204:207], v[212:215], v[4:7]
	v_mfma_f32_16x16x32_bf16 v[24:27], v[80:83], v[220:223], v[24:27]
	v_mfma_f32_16x16x32_bf16 v[16:19], v[188:191], v[220:223], v[16:19]
	v_mfma_f32_16x16x32_bf16 v[8:11], v[196:199], v[220:223], v[8:11]
	v_mfma_f32_16x16x32_bf16 v[0:3], v[204:207], v[220:223], v[0:3]
	v_mfma_f32_16x16x32_bf16 v[28:31], v[84:87], v[216:219], v[28:31]
	v_mfma_f32_16x16x32_bf16 v[20:23], v[192:195], v[216:219], v[20:23]
	v_mfma_f32_16x16x32_bf16 v[12:15], v[200:203], v[216:219], v[12:15]
	v_mfma_f32_16x16x32_bf16 v[4:7], v[208:211], v[216:219], v[4:7]
	v_mfma_f32_16x16x32_bf16 v[138:141], v[84:87], v[158:161], v[24:27]
	v_mfma_f32_16x16x32_bf16 v[174:177], v[192:195], v[158:161], v[16:19]
	v_mfma_f32_16x16x32_bf16 v[188:191], v[200:203], v[158:161], v[8:11]
	v_mfma_f32_16x16x32_bf16 v[158:161], v[208:211], v[158:161], v[0:3]
	s_barrier
	s_nop 0
	ds_read_b128 v[0:3], v156
	ds_read_b128 v[8:11], v156 offset:1024
	ds_read_b128 v[16:19], v156 offset:2048
	ds_read_b128 v[192:195], v156 offset:3072
	ds_read_b128 v[24:27], v153 offset:32768
	ds_read_b128 v[56:59], v153 offset:33792
	ds_read_b128 v[196:199], v152 offset:32768
	ds_read_b128 v[200:203], v152 offset:33792
	ds_read_b128 v[204:207], v151 offset:32768
	ds_read_b128 v[208:211], v151 offset:33792
	ds_read_b128 v[212:215], v150 offset:32768
	ds_read_b128 v[216:219], v150 offset:33792
	s_waitcnt vmcnt(2)
	s_barrier
; #define LDA(dst, b, h) for (int m = 0; m < 4; ++m) for (int k = 0; k < 2; ++k) \
;     dst[m][k] = *reinterpret_cast<const bf16x8*>((char*)SA(b, h) + lds_byte(wr * 64 + m * 16 + fr, k * 32 + fq * 8))
; #define LDB(dst, b, h) for (int n = 0; n < 2; ++n) for (int k = 0; k < 2; ++k) \
;     dst[n][k] = *reinterpret_cast<const bf16x8*>((char*)SB(b, h) + lds_byte(wc * 32 + n * 16 + fr, k * 32 + fq * 8))
; #define MMA(ai, bj, At_, Bt_) do { __builtin_amdgcn_s_setprio(1); \
;     for (int k = 0; k < 2; ++k) for (int m = 0; m < 4; ++m) for (int n = 0; n < 2; ++n) \
;       acc[ai][bj][m][n] = __builtin_amdgcn_mfma_f32_16x16x32_bf16(At_[m][k], Bt_[n][k], acc[ai][bj][m][n], 0, 0, 0); \
;     __builtin_amdgcn_s_setprio(0); } while (0)
; #define WAIT_V(n) asm volatile("s_waitcnt vmcnt(" #n ")" ::: "memory")
; #define WAIT_L(n) asm volatile("s_waitcnt lgkmcnt(" #n ")" ::: "memory")
; #define BAR __builtin_amdgcn_s_barrier()
; template <int EPI, int lda, int ldb, int N, int K>
; __device__ __forceinline__ void gemm_phase(const u16* __restrict__ A, const u16* __restrict__ Bt, const GemmEpi ep, int wv) {
;     ...
;     { LDB(B0, 1, 0); LDA(At, 1, 0); WAIT_V(2); BAR; WAIT_L(0); MMA(0, 0, At, B0); BAR;
;       LDB(B1, 1, 1); WAIT_V(0); BAR; WAIT_L(0); MMA(0, 1, At, B1); BAR;
;       LDA(At, 1, 1); BAR; WAIT_L(0); MMA(1, 0, At, B0); MMA(1, 1, At, B1); BAR; }
;     if (wr == 0) BAR;
	s_waitcnt lgkmcnt(0)
	v_mfma_f32_16x16x32_bf16 v[48:51], v[24:27], v[0:3], v[124:127]
	v_mfma_f32_16x16x32_bf16 v[52:55], v[24:27], v[16:19], v[120:123]
	v_mfma_f32_16x16x32_bf16 v[80:83], v[196:199], v[0:3], v[116:119]
	v_mfma_f32_16x16x32_bf16 v[84:87], v[196:199], v[16:19], v[112:115]
	v_mfma_f32_16x16x32_bf16 v[108:111], v[204:207], v[0:3], v[108:111]
	v_mfma_f32_16x16x32_bf16 v[104:107], v[204:207], v[16:19], v[104:107]
	v_mfma_f32_16x16x32_bf16 v[112:115], v[212:215], v[0:3], v[100:103]
	v_mfma_f32_16x16x32_bf16 v[120:123], v[212:215], v[16:19], v[96:99]
	v_mfma_f32_16x16x32_bf16 v[124:127], v[56:59], v[8:11], v[48:51]
	v_mfma_f32_16x16x32_bf16 v[116:119], v[56:59], v[192:195], v[52:55]
	v_mfma_f32_16x16x32_bf16 v[100:103], v[200:203], v[8:11], v[80:83]
	v_mfma_f32_16x16x32_bf16 v[96:99], v[200:203], v[192:195], v[84:87]
	v_mfma_f32_16x16x32_bf16 v[84:87], v[208:211], v[8:11], v[108:111]
	v_mfma_f32_16x16x32_bf16 v[80:83], v[208:211], v[192:195], v[104:107]
	v_mfma_f32_16x16x32_bf16 v[52:55], v[216:219], v[8:11], v[112:115]
	v_mfma_f32_16x16x32_bf16 v[48:51], v[216:219], v[192:195], v[120:123]
	s_barrier
	ds_read_b128 v[220:223], v154
	ds_read_b128 v[228:231], v154 offset:1024
	ds_read_b128 v[232:235], v154 offset:2048
	ds_read_b128 v[154:157], v154 offset:3072
	s_waitcnt vmcnt(0)
	s_barrier
	s_waitcnt lgkmcnt(0)
	v_mfma_f32_16x16x32_bf16 v[92:95], v[24:27], v[220:223], v[92:95]
	v_mfma_f32_16x16x32_bf16 v[24:27], v[24:27], v[232:235], v[88:91]
	v_mfma_f32_16x16x32_bf16 v[88:91], v[196:199], v[220:223], v[180:183]
	v_mfma_f32_16x16x32_bf16 v[104:107], v[196:199], v[232:235], v[184:187]
	v_mfma_f32_16x16x32_bf16 v[76:79], v[204:207], v[220:223], v[76:79]
	v_mfma_f32_16x16x32_bf16 v[72:75], v[204:207], v[232:235], v[72:75]
	v_mfma_f32_16x16x32_bf16 v[68:71], v[212:215], v[220:223], v[68:71]
	v_mfma_f32_16x16x32_bf16 v[64:67], v[212:215], v[232:235], v[64:67]
	v_mfma_f32_16x16x32_bf16 v[120:123], v[56:59], v[228:231], v[92:95]
	v_mfma_f32_16x16x32_bf16 v[112:115], v[56:59], v[154:157], v[24:27]
	v_mfma_f32_16x16x32_bf16 v[108:111], v[200:203], v[228:231], v[88:91]
	v_mfma_f32_16x16x32_bf16 v[104:107], v[200:203], v[154:157], v[104:107]
	v_mfma_f32_16x16x32_bf16 v[92:95], v[208:211], v[228:231], v[76:79]
	v_mfma_f32_16x16x32_bf16 v[88:91], v[208:211], v[154:157], v[72:75]
	v_mfma_f32_16x16x32_bf16 v[68:71], v[216:219], v[228:231], v[68:71]
	v_mfma_f32_16x16x32_bf16 v[56:59], v[216:219], v[154:157], v[64:67]
	s_barrier
	s_nop 0
	ds_read_b128 v[64:67], v153 offset:49152
	ds_read_b128 v[178:181], v153 offset:50176
	ds_read_b128 v[76:79], v152 offset:49152
	ds_read_b128 v[182:185], v152 offset:50176
	ds_read_b128 v[196:199], v151 offset:49152
	ds_read_b128 v[200:203], v151 offset:50176
	ds_read_b128 v[204:207], v150 offset:49152
	ds_read_b128 v[150:153], v150 offset:50176
	s_barrier
	s_waitcnt lgkmcnt(0)
	v_mfma_f32_16x16x32_bf16 v[24:27], v[64:67], v[0:3], v[60:63]
	v_mfma_f32_16x16x32_bf16 v[60:63], v[64:67], v[16:19], v[134:137]
	v_mfma_f32_16x16x32_bf16 v[134:137], v[76:79], v[0:3], v[170:173]
	v_mfma_f32_16x16x32_bf16 v[170:173], v[76:79], v[16:19], v[224:227]
	v_mfma_f32_16x16x32_bf16 v[44:47], v[196:199], v[0:3], v[44:47]
	v_mfma_f32_16x16x32_bf16 v[208:211], v[196:199], v[16:19], v[40:43]
	v_mfma_f32_16x16x32_bf16 v[0:3], v[204:207], v[0:3], v[36:39]
	v_mfma_f32_16x16x32_bf16 v[36:39], v[204:207], v[16:19], v[32:35]
	v_mfma_f32_16x16x32_bf16 v[72:75], v[178:181], v[8:11], v[24:27]
	v_mfma_f32_16x16x32_bf16 v[60:63], v[178:181], v[192:195], v[60:63]
	v_mfma_f32_16x16x32_bf16 v[40:43], v[182:185], v[8:11], v[134:137]
	v_mfma_f32_16x16x32_bf16 v[32:35], v[182:185], v[192:195], v[170:173]
	v_mfma_f32_16x16x32_bf16 v[24:27], v[200:203], v[8:11], v[44:47]
	v_mfma_f32_16x16x32_bf16 v[16:19], v[200:203], v[192:195], v[208:211]
	v_mfma_f32_16x16x32_bf16 v[8:11], v[150:153], v[8:11], v[0:3]
	v_mfma_f32_16x16x32_bf16 v[0:3], v[150:153], v[192:195], v[36:39]
	v_mfma_f32_16x16x32_bf16 v[28:31], v[64:67], v[220:223], v[28:31]
	v_mfma_f32_16x16x32_bf16 v[36:39], v[64:67], v[232:235], v[138:141]
	v_mfma_f32_16x16x32_bf16 v[20:23], v[76:79], v[220:223], v[20:23]
	v_mfma_f32_16x16x32_bf16 v[134:137], v[76:79], v[232:235], v[174:177]
	v_mfma_f32_16x16x32_bf16 v[12:15], v[196:199], v[220:223], v[12:15]
	v_mfma_f32_16x16x32_bf16 v[138:141], v[196:199], v[232:235], v[188:191]
	v_mfma_f32_16x16x32_bf16 v[4:7], v[204:207], v[220:223], v[4:7]
	v_mfma_f32_16x16x32_bf16 v[158:161], v[204:207], v[232:235], v[158:161]
	v_mfma_f32_16x16x32_bf16 v[76:79], v[178:181], v[228:231], v[28:31]
	v_mfma_f32_16x16x32_bf16 v[64:67], v[178:181], v[154:157], v[36:39]
	v_mfma_f32_16x16x32_bf16 v[44:47], v[182:185], v[228:231], v[20:23]
	v_mfma_f32_16x16x32_bf16 v[36:39], v[182:185], v[154:157], v[134:137]
	v_mfma_f32_16x16x32_bf16 v[28:31], v[200:203], v[228:231], v[12:15]
	v_mfma_f32_16x16x32_bf16 v[20:23], v[200:203], v[154:157], v[138:141]
	v_mfma_f32_16x16x32_bf16 v[12:15], v[150:153], v[228:231], v[4:7]
	v_mfma_f32_16x16x32_bf16 v[4:7], v[150:153], v[154:157], v[158:161]
	v_cmp_gt_u32_e32 vcc, s64, v130
	s_barrier
	s_and_saveexec_b64 s[48:49], vcc
	s_cbranch_execz .LBB0_343
	s_barrier

; #define STAGE(P, BASE, LD, br, kt) do { const char* _g = (const char*)((BASE) + (size_t)(br) * (LD) + (size_t)(kt) * 64); \
;     for (int _i = 0; _i < 2; ++_i) { int _b = tidx * 16 + _i * 8192; int _r, _c; stage_rc(_b, _r, _c); \
;       __builtin_amdgcn_global_load_lds((const unsigned*)(_g + (unsigned)((_r * (LD) + _c) * 2)), (unsigned*)((char*)(P) + _b), 16, 0, 0); } } while (0)
; #define LDA(dst, b, h) for (int m = 0; m < 4; ++m) for (int k = 0; k < 2; ++k) \
;     dst[m][k] = *reinterpret_cast<const bf16x8*>((char*)SA(b, h) + lds_byte(wr * 64 + m * 16 + fr, k * 32 + fq * 8))
; #define LDB(dst, b, h) for (int n = 0; n < 2; ++n) for (int k = 0; k < 2; ++k) \
;     dst[n][k] = *reinterpret_cast<const bf16x8*>((char*)SB(b, h) + lds_byte(wc * 32 + n * 16 + fr, k * 32 + fq * 8))
; #define MMA(ai, bj, At_, Bt_) do { __builtin_amdgcn_s_setprio(1); \
;     for (int k = 0; k < 2; ++k) for (int m = 0; m < 4; ++m) for (int n = 0; n < 2; ++n) \
;       acc[ai][bj][m][n] = __builtin_amdgcn_mfma_f32_16x16x32_bf16(At_[m][k], Bt_[n][k], acc[ai][bj][m][n], 0, 0, 0); \
;     __builtin_amdgcn_s_setprio(0); } while (0)
; #define WAIT_L(n) asm volatile("s_waitcnt lgkmcnt(" #n ")" ::: "memory")
; #define BAR __builtin_amdgcn_s_barrier()
; #define SCHED __builtin_amdgcn_sched_barrier(0)
; template <int EPI, int lda, int ldb, int N, int K>
; __device__ __forceinline__ void gemm_phase(const u16* __restrict__ A, const u16* __restrict__ Bt, const GemmEpi ep, int wv) {
;     ...
;     for (int t = 0; t < nt - 2; t += 2) {
;       LDB(B0, 0, 0); SCHED; LDA(At, 0, 0); STAGE(SA(1, 1), Ab, lda, brow + HALF, t + 1);
;       WAIT_L(8); BAR; WAIT_L(0); MMA(0, 0, At, B0); BAR; SCHED;
;       LDB(B1, 0, 1); STAGE(SB(0, 0), Bt, ldb, bcol, t + 2);
;       BAR; WAIT_L(0); MMA(0, 1, At, B1); BAR;
;       LDA(At, 0, 1); STAGE(SA(0, 0), Ab, lda, brow, t + 2);
;       BAR; WAIT_L(0); MMA(1, 0, At, B0); BAR; SCHED;
.LBB0_654:
	ds_read_b128 v[164:167], v160
	ds_read_b128 v[170:173], v160 offset:1024
	ds_read_b128 v[174:177], v160 offset:2048
	ds_read_b128 v[178:181], v160 offset:3072
	v_add_u32_e32 v168, 0xc000, v143
	v_lshl_add_u64 v[234:235], v[138:139], 0, s[52:53]
	v_readfirstlane_b32 s55, v168
	v_add_u32_e32 v169, 0xe000, v143
	v_lshl_add_u64 v[162:163], v[234:235], 0, s[20:21]
	s_mov_b32 m0, s55
	v_lshl_add_u64 v[236:237], v[140:141], 0, s[52:53]
	v_readfirstlane_b32 s55, v169
	ds_read_b128 v[182:185], v151
	ds_read_b128 v[186:189], v151 offset:1024
	ds_read_b128 v[190:193], v150
	ds_read_b128 v[194:197], v150 offset:1024
	ds_read_b128 v[198:201], v149
	ds_read_b128 v[202:205], v149 offset:1024
	ds_read_b128 v[206:209], v148
	ds_read_b128 v[210:213], v148 offset:1024
	global_load_lds_dwordx4 v[162:163], off
	v_lshl_add_u64 v[162:163], v[236:237], 0, s[20:21]
	s_mov_b32 m0, s55
	s_nop 0
	global_load_lds_dwordx4 v[162:163], off
	s_waitcnt lgkmcnt(8)
	s_barrier
	s_waitcnt lgkmcnt(0)
	v_mfma_f32_16x16x32_bf16 v[124:127], v[164:167], v[182:185], v[124:127]
	v_mfma_f32_16x16x32_bf16 v[120:123], v[174:177], v[182:185], v[120:123]
	v_mfma_f32_16x16x32_bf16 v[116:119], v[164:167], v[190:193], v[116:119]
	v_mfma_f32_16x16x32_bf16 v[112:115], v[174:177], v[190:193], v[112:115]
	v_mfma_f32_16x16x32_bf16 v[108:111], v[164:167], v[198:201], v[108:111]
	v_mfma_f32_16x16x32_bf16 v[104:107], v[174:177], v[198:201], v[104:107]
	v_mfma_f32_16x16x32_bf16 v[100:103], v[164:167], v[206:209], v[100:103]
	v_mfma_f32_16x16x32_bf16 v[96:99], v[174:177], v[206:209], v[96:99]
	v_mfma_f32_16x16x32_bf16 v[124:127], v[170:173], v[186:189], v[124:127]
	v_mfma_f32_16x16x32_bf16 v[120:123], v[178:181], v[186:189], v[120:123]
	v_mfma_f32_16x16x32_bf16 v[116:119], v[170:173], v[194:197], v[116:119]
	v_mfma_f32_16x16x32_bf16 v[112:115], v[178:181], v[194:197], v[112:115]
	v_mfma_f32_16x16x32_bf16 v[108:111], v[170:173], v[202:205], v[108:111]
	v_mfma_f32_16x16x32_bf16 v[104:107], v[178:181], v[202:205], v[104:107]
	v_mfma_f32_16x16x32_bf16 v[100:103], v[170:173], v[210:213], v[100:103]
	v_mfma_f32_16x16x32_bf16 v[96:99], v[178:181], v[210:213], v[96:99]
	s_barrier
	v_add_u32_e32 v161, s65, v153
	v_lshl_add_u64 v[238:239], v[134:135], 0, s[52:53]
	v_readfirstlane_b32 s55, v161
	v_lshl_add_u64 v[162:163], v[238:239], 0, s[22:23]
	s_mov_b32 m0, s55
	ds_read_b128 v[214:217], v159
	ds_read_b128 v[218:221], v159 offset:1024
	ds_read_b128 v[222:225], v159 offset:2048
	ds_read_b128 v[226:229], v159 offset:3072
	global_load_lds_dwordx4 v[162:163], off
	v_add_u32_e32 v162, 0x2000, v161
	v_lshl_add_u64 v[240:241], v[136:137], 0, s[52:53]
	v_readfirstlane_b32 s55, v162
	v_lshl_add_u64 v[230:231], v[240:241], 0, s[22:23]
	s_mov_b32 m0, s55
	s_nop 0
	global_load_lds_dwordx4 v[230:231], off
	s_barrier
	s_waitcnt lgkmcnt(0)
	v_mfma_f32_16x16x32_bf16 v[92:95], v[214:217], v[182:185], v[92:95]
	v_mfma_f32_16x16x32_bf16 v[88:91], v[222:225], v[182:185], v[88:91]
	v_mfma_f32_16x16x32_bf16 v[84:87], v[214:217], v[190:193], v[84:87]
	v_mfma_f32_16x16x32_bf16 v[80:83], v[222:225], v[190:193], v[80:83]
	v_mfma_f32_16x16x32_bf16 v[76:79], v[214:217], v[198:201], v[76:79]
	v_mfma_f32_16x16x32_bf16 v[72:75], v[222:225], v[198:201], v[72:75]
	v_mfma_f32_16x16x32_bf16 v[68:71], v[214:217], v[206:209], v[68:71]
	v_mfma_f32_16x16x32_bf16 v[64:67], v[222:225], v[206:209], v[64:67]
	v_mfma_f32_16x16x32_bf16 v[92:95], v[218:221], v[186:189], v[92:95]
	v_mfma_f32_16x16x32_bf16 v[88:91], v[226:229], v[186:189], v[88:91]
	v_mfma_f32_16x16x32_bf16 v[84:87], v[218:221], v[194:197], v[84:87]
	v_mfma_f32_16x16x32_bf16 v[80:83], v[226:229], v[194:197], v[80:83]
	v_mfma_f32_16x16x32_bf16 v[76:79], v[218:221], v[202:205], v[76:79]
	v_mfma_f32_16x16x32_bf16 v[72:75], v[226:229], v[202:205], v[72:75]
	v_mfma_f32_16x16x32_bf16 v[68:71], v[218:221], v[210:213], v[68:71]
	v_mfma_f32_16x16x32_bf16 v[64:67], v[226:229], v[210:213], v[64:67]
	v_readfirstlane_b32 s55, v143
	v_add_u32_e32 v163, 0x2000, v143
	v_lshl_add_u64 v[230:231], v[234:235], 0, s[24:25]
	s_mov_b32 m0, s55
	v_readfirstlane_b32 s55, v163
	s_barrier
	ds_read_b128 v[182:185], v151 offset:16384
	ds_read_b128 v[186:189], v151 offset:17408
	ds_read_b128 v[190:193], v150 offset:16384
	ds_read_b128 v[194:197], v150 offset:17408
	ds_read_b128 v[198:201], v149 offset:16384
	ds_read_b128 v[202:205], v149 offset:17408
	ds_read_b128 v[206:209], v148 offset:16384
	ds_read_b128 v[210:213], v148 offset:17408
	global_load_lds_dwordx4 v[230:231], off
	v_lshl_add_u64 v[230:231], v[236:237], 0, s[24:25]
	s_mov_b32 m0, s55
	s_nop 0
	global_load_lds_dwordx4 v[230:231], off
	s_barrier
	s_waitcnt lgkmcnt(0)
	v_mfma_f32_16x16x32_bf16 v[60:63], v[164:167], v[182:185], v[60:63]
	v_mfma_f32_16x16x32_bf16 v[56:59], v[174:177], v[182:185], v[56:59]
	v_mfma_f32_16x16x32_bf16 v[52:55], v[164:167], v[190:193], v[52:55]
	v_mfma_f32_16x16x32_bf16 v[48:51], v[174:177], v[190:193], v[48:51]
	v_mfma_f32_16x16x32_bf16 v[44:47], v[164:167], v[198:201], v[44:47]
	v_mfma_f32_16x16x32_bf16 v[40:43], v[174:177], v[198:201], v[40:43]
	v_mfma_f32_16x16x32_bf16 v[36:39], v[164:167], v[206:209], v[36:39]
	v_mfma_f32_16x16x32_bf16 v[32:35], v[174:177], v[206:209], v[32:35]
	v_mfma_f32_16x16x32_bf16 v[60:63], v[170:173], v[186:189], v[60:63]
	v_mfma_f32_16x16x32_bf16 v[56:59], v[178:181], v[186:189], v[56:59]
	v_mfma_f32_16x16x32_bf16 v[52:55], v[170:173], v[194:197], v[52:55]
	v_mfma_f32_16x16x32_bf16 v[48:51], v[178:181], v[194:197], v[48:51]
	v_mfma_f32_16x16x32_bf16 v[44:47], v[170:173], v[202:205], v[44:47]
	v_mfma_f32_16x16x32_bf16 v[40:43], v[178:181], v[202:205], v[40:43]
	v_mfma_f32_16x16x32_bf16 v[36:39], v[170:173], v[210:213], v[36:39]
	v_mfma_f32_16x16x32_bf16 v[32:35], v[178:181], v[210:213], v[32:35]
	s_barrier
; #define STAGE(P, BASE, LD, br, kt) do { const char* _g = (const char*)((BASE) + (size_t)(br) * (LD) + (size_t)(kt) * 64); \
;     for (int _i = 0; _i < 2; ++_i) { int _b = tidx * 16 + _i * 8192; int _r, _c; stage_rc(_b, _r, _c); \
;       __builtin_amdgcn_global_load_lds((const unsigned*)(_g + (unsigned)((_r * (LD) + _c) * 2)), (unsigned*)((char*)(P) + _b), 16, 0, 0); } } while (0)
; #define LDA(dst, b, h) for (int m = 0; m < 4; ++m) for (int k = 0; k < 2; ++k) \
;     dst[m][k] = *reinterpret_cast<const bf16x8*>((char*)SA(b, h) + lds_byte(wr * 64 + m * 16 + fr, k * 32 + fq * 8))
; #define LDB(dst, b, h) for (int n = 0; n < 2; ++n) for (int k = 0; k < 2; ++k) \
;     dst[n][k] = *reinterpret_cast<const bf16x8*>((char*)SB(b, h) + lds_byte(wc * 32 + n * 16 + fr, k * 32 + fq * 8))
; #define MMA(ai, bj, At_, Bt_) do { __builtin_amdgcn_s_setprio(1); \
;     for (int k = 0; k < 2; ++k) for (int m = 0; m < 4; ++m) for (int n = 0; n < 2; ++n) \
;       acc[ai][bj][m][n] = __builtin_amdgcn_mfma_f32_16x16x32_bf16(At_[m][k], Bt_[n][k], acc[ai][bj][m][n], 0, 0, 0); \
;     __builtin_amdgcn_s_setprio(0); } while (0)
; #define WAIT_V(n) asm volatile("s_waitcnt vmcnt(" #n ")" ::: "memory")
; #define WAIT_L(n) asm volatile("s_waitcnt lgkmcnt(" #n ")" ::: "memory")
; #define BAR __builtin_amdgcn_s_barrier()
; #define SCHED __builtin_amdgcn_sched_barrier(0)
; template <int EPI, int lda, int ldb, int N, int K>
; __device__ __forceinline__ void gemm_phase(const u16* __restrict__ A, const u16* __restrict__ Bt, const GemmEpi ep, int wv) {
;     ...
;       STAGE(SB(0, 1), Bt, ldb, bcol + HALF, t + 2);
;       WAIT_V(6); BAR; MMA(1, 1, At, B1); BAR;
;       LDB(B0, 1, 0); SCHED; LDA(At, 1, 0); STAGE(SA(0, 1), Ab, lda, brow + HALF, t + 2);
;       WAIT_L(8); BAR; WAIT_L(0); MMA(0, 0, At, B0); BAR; SCHED;
;       LDB(B1, 1, 1); STAGE(SB(1, 0), Bt, ldb, bcol, t + 3);
;       BAR; WAIT_L(0); MMA(0, 1, At, B1); BAR;
;       LDA(At, 1, 1); STAGE(SA(1, 0), Ab, lda, brow, t + 3);
	v_add_u32_e32 v164, s66, v153
	v_add_u32_e32 v165, 0x2000, v164
	v_readfirstlane_b32 s55, v164
	v_lshl_add_u64 v[166:167], v[238:239], 0, s[26:27]
	s_mov_b32 m0, s55
	v_readfirstlane_b32 s55, v165
	global_load_lds_dwordx4 v[166:167], off
	v_lshl_add_u64 v[166:167], v[240:241], 0, s[26:27]
	s_mov_b32 m0, s55
	s_nop 0
	global_load_lds_dwordx4 v[166:167], off
	s_waitcnt vmcnt(6)
	s_barrier
	v_mfma_f32_16x16x32_bf16 v[28:31], v[214:217], v[182:185], v[28:31]
	v_mfma_f32_16x16x32_bf16 v[24:27], v[222:225], v[182:185], v[24:27]
	v_mfma_f32_16x16x32_bf16 v[20:23], v[214:217], v[190:193], v[20:23]
	v_mfma_f32_16x16x32_bf16 v[16:19], v[222:225], v[190:193], v[16:19]
	v_mfma_f32_16x16x32_bf16 v[12:15], v[214:217], v[198:201], v[12:15]
	v_mfma_f32_16x16x32_bf16 v[8:11], v[222:225], v[198:201], v[8:11]
	v_mfma_f32_16x16x32_bf16 v[4:7], v[214:217], v[206:209], v[4:7]
	v_mfma_f32_16x16x32_bf16 v[0:3], v[222:225], v[206:209], v[0:3]
	v_mfma_f32_16x16x32_bf16 v[28:31], v[218:221], v[186:189], v[28:31]
	v_mfma_f32_16x16x32_bf16 v[24:27], v[226:229], v[186:189], v[24:27]
	v_mfma_f32_16x16x32_bf16 v[20:23], v[218:221], v[194:197], v[20:23]
	v_mfma_f32_16x16x32_bf16 v[16:19], v[226:229], v[194:197], v[16:19]
	v_mfma_f32_16x16x32_bf16 v[12:15], v[218:221], v[202:205], v[12:15]
	v_mfma_f32_16x16x32_bf16 v[8:11], v[226:229], v[202:205], v[8:11]
	v_mfma_f32_16x16x32_bf16 v[4:7], v[218:221], v[210:213], v[4:7]
	v_mfma_f32_16x16x32_bf16 v[0:3], v[226:229], v[210:213], v[0:3]
	s_barrier
	ds_read_b128 v[170:173], v154
	ds_read_b128 v[174:177], v154 offset:1024
	ds_read_b128 v[178:181], v154 offset:2048
	ds_read_b128 v[182:185], v154 offset:3072
	v_add_u32_e32 v166, 0x4000, v143
	v_add_u32_e32 v167, 0x6000, v143
	v_readfirstlane_b32 s55, v166
	v_lshl_add_u64 v[218:219], v[234:235], 0, s[42:43]
	s_mov_b32 m0, s55
	v_readfirstlane_b32 s55, v167
	ds_read_b128 v[186:189], v151 offset:32768
	ds_read_b128 v[190:193], v151 offset:33792
	ds_read_b128 v[194:197], v150 offset:32768
	ds_read_b128 v[198:201], v150 offset:33792
	ds_read_b128 v[202:205], v149 offset:32768
	ds_read_b128 v[206:209], v149 offset:33792
	ds_read_b128 v[210:213], v148 offset:32768
	ds_read_b128 v[214:217], v148 offset:33792
	global_load_lds_dwordx4 v[218:219], off
	v_lshl_add_u64 v[218:219], v[236:237], 0, s[42:43]
	s_mov_b32 m0, s55
	s_nop 0
	global_load_lds_dwordx4 v[218:219], off
	s_waitcnt lgkmcnt(8)
	s_barrier
	s_waitcnt lgkmcnt(0)
	v_mfma_f32_16x16x32_bf16 v[124:127], v[170:173], v[186:189], v[124:127]
	v_mfma_f32_16x16x32_bf16 v[120:123], v[178:181], v[186:189], v[120:123]
	v_mfma_f32_16x16x32_bf16 v[116:119], v[170:173], v[194:197], v[116:119]
	v_mfma_f32_16x16x32_bf16 v[112:115], v[178:181], v[194:197], v[112:115]
	v_mfma_f32_16x16x32_bf16 v[108:111], v[170:173], v[202:205], v[108:111]
	v_mfma_f32_16x16x32_bf16 v[104:107], v[178:181], v[202:205], v[104:107]
	v_mfma_f32_16x16x32_bf16 v[100:103], v[170:173], v[210:213], v[100:103]
	v_mfma_f32_16x16x32_bf16 v[96:99], v[178:181], v[210:213], v[96:99]
	v_mfma_f32_16x16x32_bf16 v[124:127], v[174:177], v[190:193], v[124:127]
	v_mfma_f32_16x16x32_bf16 v[120:123], v[182:185], v[190:193], v[120:123]
	v_mfma_f32_16x16x32_bf16 v[116:119], v[174:177], v[198:201], v[116:119]
	v_mfma_f32_16x16x32_bf16 v[112:115], v[182:185], v[198:201], v[112:115]
	v_mfma_f32_16x16x32_bf16 v[108:111], v[174:177], v[206:209], v[108:111]
	v_mfma_f32_16x16x32_bf16 v[104:107], v[182:185], v[206:209], v[104:107]
	v_mfma_f32_16x16x32_bf16 v[100:103], v[174:177], v[214:217], v[100:103]
	v_mfma_f32_16x16x32_bf16 v[96:99], v[182:185], v[214:217], v[96:99]
	s_barrier
	v_readfirstlane_b32 s55, v155
	v_add_u32_e32 v244, 0x2000, v155
	v_lshl_add_u64 v[242:243], v[238:239], 0, s[44:45]
	s_mov_b32 m0, s55
	v_readfirstlane_b32 s55, v244
	ds_read_b128 v[218:221], v152
	ds_read_b128 v[222:225], v152 offset:1024
	ds_read_b128 v[226:229], v152 offset:2048
	ds_read_b128 v[230:233], v152 offset:3072
	global_load_lds_dwordx4 v[242:243], off
	v_lshl_add_u64 v[242:243], v[240:241], 0, s[44:45]
	s_mov_b32 m0, s55
	s_nop 0
	global_load_lds_dwordx4 v[242:243], off
	s_barrier
	s_waitcnt lgkmcnt(0)
	v_mfma_f32_16x16x32_bf16 v[92:95], v[218:221], v[186:189], v[92:95]
	v_mfma_f32_16x16x32_bf16 v[88:91], v[226:229], v[186:189], v[88:91]
	v_mfma_f32_16x16x32_bf16 v[84:87], v[218:221], v[194:197], v[84:87]
	v_mfma_f32_16x16x32_bf16 v[80:83], v[226:229], v[194:197], v[80:83]
	v_mfma_f32_16x16x32_bf16 v[76:79], v[218:221], v[202:205], v[76:79]
	v_mfma_f32_16x16x32_bf16 v[72:75], v[226:229], v[202:205], v[72:75]
	v_mfma_f32_16x16x32_bf16 v[68:71], v[218:221], v[210:213], v[68:71]
	v_mfma_f32_16x16x32_bf16 v[64:67], v[226:229], v[210:213], v[64:67]
	v_mfma_f32_16x16x32_bf16 v[92:95], v[222:225], v[190:193], v[92:95]
	v_mfma_f32_16x16x32_bf16 v[88:91], v[230:233], v[190:193], v[88:91]
	v_mfma_f32_16x16x32_bf16 v[84:87], v[222:225], v[198:201], v[84:87]
	v_mfma_f32_16x16x32_bf16 v[80:83], v[230:233], v[198:201], v[80:83]
	v_mfma_f32_16x16x32_bf16 v[76:79], v[222:225], v[206:209], v[76:79]
	v_mfma_f32_16x16x32_bf16 v[72:75], v[230:233], v[206:209], v[72:75]
	v_mfma_f32_16x16x32_bf16 v[68:71], v[222:225], v[214:217], v[68:71]
	v_mfma_f32_16x16x32_bf16 v[64:67], v[230:233], v[214:217], v[64:67]
	v_readfirstlane_b32 s55, v156
	v_lshl_add_u64 v[234:235], v[234:235], 0, s[46:47]
	s_mov_b32 m0, s55
	v_readfirstlane_b32 s55, v157
	s_barrier
	ds_read_b128 v[186:189], v151 offset:49152
	ds_read_b128 v[190:193], v151 offset:50176
	ds_read_b128 v[194:197], v150 offset:49152
	ds_read_b128 v[198:201], v150 offset:50176
	ds_read_b128 v[202:205], v149 offset:49152
	ds_read_b128 v[206:209], v149 offset:50176
	ds_read_b128 v[210:213], v148 offset:49152
	ds_read_b128 v[214:217], v148 offset:50176
	global_load_lds_dwordx4 v[234:235], off
	v_lshl_add_u64 v[234:235], v[236:237], 0, s[46:47]
	s_mov_b32 m0, s55
	s_nop 0
	global_load_lds_dwordx4 v[234:235], off
	s_barrier
; #define STAGE(P, BASE, LD, br, kt) do { const char* _g = (const char*)((BASE) + (size_t)(br) * (LD) + (size_t)(kt) * 64); \
;     for (int _i = 0; _i < 2; ++_i) { int _b = tidx * 16 + _i * 8192; int _r, _c; stage_rc(_b, _r, _c); \
;       __builtin_amdgcn_global_load_lds((const unsigned*)(_g + (unsigned)((_r * (LD) + _c) * 2)), (unsigned*)((char*)(P) + _b), 16, 0, 0); } } while (0)
; #define LDA(dst, b, h) for (int m = 0; m < 4; ++m) for (int k = 0; k < 2; ++k) \
;     dst[m][k] = *reinterpret_cast<const bf16x8*>((char*)SA(b, h) + lds_byte(wr * 64 + m * 16 + fr, k * 32 + fq * 8))
; #define LDB(dst, b, h) for (int n = 0; n < 2; ++n) for (int k = 0; k < 2; ++k) \
;     dst[n][k] = *reinterpret_cast<const bf16x8*>((char*)SB(b, h) + lds_byte(wc * 32 + n * 16 + fr, k * 32 + fq * 8))
; #define MMA(ai, bj, At_, Bt_) do { __builtin_amdgcn_s_setprio(1); \
;     for (int k = 0; k < 2; ++k) for (int m = 0; m < 4; ++m) for (int n = 0; n < 2; ++n) \
;       acc[ai][bj][m][n] = __builtin_amdgcn_mfma_f32_16x16x32_bf16(At_[m][k], Bt_[n][k], acc[ai][bj][m][n], 0, 0, 0); \
;     __builtin_amdgcn_s_setprio(0); } while (0)
; #define WAIT_V(n) asm volatile("s_waitcnt vmcnt(" #n ")" ::: "memory")
; #define WAIT_L(n) asm volatile("s_waitcnt lgkmcnt(" #n ")" ::: "memory")
; #define BAR __builtin_amdgcn_s_barrier()
; #define SCHED __builtin_amdgcn_sched_barrier(0)
; template <int EPI, int lda, int ldb, int N, int K>
; __device__ __forceinline__ void gemm_phase(const u16* __restrict__ A, const u16* __restrict__ Bt, const GemmEpi ep, int wv) {
;     ...
;       BAR; WAIT_L(0); MMA(1, 0, At, B0); BAR; SCHED;
;       STAGE(SB(1, 1), Bt, ldb, bcol + HALF, t + 3);
;       WAIT_V(6); BAR; MMA(1, 1, At, B1); BAR;
;     }
;     { LDB(B0, 0, 0); LDA(At, 0, 0); STAGE(SA(1, 1), Ab, lda, brow + HALF, nt - 1);
;       BAR; WAIT_L(0); MMA(0, 0, At, B0); BAR;
;       LDB(B1, 0, 1); BAR; WAIT_L(0); MMA(0, 1, At, B1); BAR;
	s_waitcnt lgkmcnt(0)
	v_mfma_f32_16x16x32_bf16 v[60:63], v[170:173], v[186:189], v[60:63]
	v_mfma_f32_16x16x32_bf16 v[56:59], v[178:181], v[186:189], v[56:59]
	v_mfma_f32_16x16x32_bf16 v[52:55], v[170:173], v[194:197], v[52:55]
	v_mfma_f32_16x16x32_bf16 v[48:51], v[178:181], v[194:197], v[48:51]
	v_mfma_f32_16x16x32_bf16 v[44:47], v[170:173], v[202:205], v[44:47]
	v_mfma_f32_16x16x32_bf16 v[40:43], v[178:181], v[202:205], v[40:43]
	v_mfma_f32_16x16x32_bf16 v[36:39], v[170:173], v[210:213], v[36:39]
	v_mfma_f32_16x16x32_bf16 v[32:35], v[178:181], v[210:213], v[32:35]
	v_mfma_f32_16x16x32_bf16 v[60:63], v[174:177], v[190:193], v[60:63]
	v_mfma_f32_16x16x32_bf16 v[56:59], v[182:185], v[190:193], v[56:59]
	v_mfma_f32_16x16x32_bf16 v[52:55], v[174:177], v[198:201], v[52:55]
	v_mfma_f32_16x16x32_bf16 v[48:51], v[182:185], v[198:201], v[48:51]
	v_mfma_f32_16x16x32_bf16 v[44:47], v[174:177], v[206:209], v[44:47]
	v_mfma_f32_16x16x32_bf16 v[40:43], v[182:185], v[206:209], v[40:43]
	v_mfma_f32_16x16x32_bf16 v[36:39], v[174:177], v[214:217], v[36:39]
	v_mfma_f32_16x16x32_bf16 v[32:35], v[182:185], v[214:217], v[32:35]
	s_barrier
	v_readfirstlane_b32 s55, v158
	v_add_u32_e32 v172, 0x2000, v158
	v_lshl_add_u64 v[170:171], v[238:239], 0, s[48:49]
	s_mov_b32 m0, s55
	v_readfirstlane_b32 s55, v172
	global_load_lds_dwordx4 v[170:171], off
	v_lshl_add_u64 v[170:171], v[240:241], 0, s[48:49]
	s_mov_b32 m0, s55
	s_nop 0
	global_load_lds_dwordx4 v[170:171], off
	s_waitcnt vmcnt(6)
	s_barrier
	v_mfma_f32_16x16x32_bf16 v[28:31], v[218:221], v[186:189], v[28:31]
	v_mfma_f32_16x16x32_bf16 v[24:27], v[226:229], v[186:189], v[24:27]
	v_mfma_f32_16x16x32_bf16 v[20:23], v[218:221], v[194:197], v[20:23]
	v_mfma_f32_16x16x32_bf16 v[16:19], v[226:229], v[194:197], v[16:19]
	v_mfma_f32_16x16x32_bf16 v[12:15], v[218:221], v[202:205], v[12:15]
	v_mfma_f32_16x16x32_bf16 v[8:11], v[226:229], v[202:205], v[8:11]
	v_mfma_f32_16x16x32_bf16 v[4:7], v[218:221], v[210:213], v[4:7]
	v_mfma_f32_16x16x32_bf16 v[0:3], v[226:229], v[210:213], v[0:3]
	v_mfma_f32_16x16x32_bf16 v[28:31], v[222:225], v[190:193], v[28:31]
	v_mfma_f32_16x16x32_bf16 v[24:27], v[230:233], v[190:193], v[24:27]
	v_mfma_f32_16x16x32_bf16 v[20:23], v[222:225], v[198:201], v[20:23]
	v_mfma_f32_16x16x32_bf16 v[16:19], v[230:233], v[198:201], v[16:19]
	v_mfma_f32_16x16x32_bf16 v[12:15], v[222:225], v[206:209], v[12:15]
	v_mfma_f32_16x16x32_bf16 v[8:11], v[230:233], v[206:209], v[8:11]
	v_mfma_f32_16x16x32_bf16 v[4:7], v[222:225], v[214:217], v[4:7]
	v_mfma_f32_16x16x32_bf16 v[0:3], v[230:233], v[214:217], v[0:3]
	s_add_i32 s54, s54, 2
	s_add_u32 s52, s52, 0x100
	s_addc_u32 s53, s53, 0
	s_cmp_gt_u32 s54, 27
	s_barrier
	s_cbranch_scc0 .LBB0_654
	s_lshl_b64 s[52:53], s[16:17], 12
	s_add_u32 s52, s14, s52
	s_addc_u32 s53, s15, s53
	s_add_u32 s52, s52, 0x80000
	s_addc_u32 s53, s53, 0
	v_lshl_add_u64 v[156:157], s[52:53], 0, v[128:129]
	v_readfirstlane_b32 s54, v168
	v_lshl_add_u64 v[156:157], v[156:157], 0, s[50:51]
	s_mov_b32 m0, s54
	ds_read_b128 v[134:137], v160
	ds_read_b128 v[138:141], v160 offset:1024
	ds_read_b128 v[170:173], v160 offset:2048
	ds_read_b128 v[174:177], v160 offset:3072
	ds_read_b128 v[178:181], v151
	ds_read_b128 v[182:185], v151 offset:1024
	ds_read_b128 v[186:189], v150
	ds_read_b128 v[190:193], v150 offset:1024
	ds_read_b128 v[194:197], v149
	ds_read_b128 v[198:201], v149 offset:1024
	ds_read_b128 v[202:205], v148
	ds_read_b128 v[206:209], v148 offset:1024
	global_load_lds_dwordx4 v[156:157], off
	v_lshl_add_u64 v[156:157], s[52:53], 0, v[132:133]
	v_readfirstlane_b32 s52, v169
	v_lshl_add_u64 v[156:157], v[156:157], 0, s[50:51]
	s_mov_b32 m0, s52
	s_nop 0
	global_load_lds_dwordx4 v[156:157], off
	s_barrier
	s_waitcnt lgkmcnt(0)
	v_mfma_f32_16x16x32_bf16 v[124:127], v[134:137], v[178:181], v[124:127]
	v_mfma_f32_16x16x32_bf16 v[120:123], v[170:173], v[178:181], v[120:123]
	v_mfma_f32_16x16x32_bf16 v[116:119], v[134:137], v[186:189], v[116:119]
	v_mfma_f32_16x16x32_bf16 v[112:115], v[170:173], v[186:189], v[112:115]
	v_mfma_f32_16x16x32_bf16 v[108:111], v[134:137], v[194:197], v[108:111]
	v_mfma_f32_16x16x32_bf16 v[104:107], v[170:173], v[194:197], v[104:107]
	v_mfma_f32_16x16x32_bf16 v[100:103], v[134:137], v[202:205], v[100:103]
	v_mfma_f32_16x16x32_bf16 v[96:99], v[170:173], v[202:205], v[96:99]
	v_mfma_f32_16x16x32_bf16 v[124:127], v[138:141], v[182:185], v[124:127]
	v_mfma_f32_16x16x32_bf16 v[120:123], v[174:177], v[182:185], v[120:123]
	v_mfma_f32_16x16x32_bf16 v[116:119], v[138:141], v[190:193], v[116:119]
	v_mfma_f32_16x16x32_bf16 v[112:115], v[174:177], v[190:193], v[112:115]
	v_mfma_f32_16x16x32_bf16 v[108:111], v[138:141], v[198:201], v[108:111]
	v_mfma_f32_16x16x32_bf16 v[104:107], v[174:177], v[198:201], v[104:107]
	v_mfma_f32_16x16x32_bf16 v[100:103], v[138:141], v[206:209], v[100:103]
	v_mfma_f32_16x16x32_bf16 v[96:99], v[174:177], v[206:209], v[96:99]
	s_barrier
	ds_read_b128 v[210:213], v159
	ds_read_b128 v[214:217], v159 offset:1024
	ds_read_b128 v[218:221], v159 offset:2048
	ds_read_b128 v[156:159], v159 offset:3072
	s_barrier
; #define LDA(dst, b, h) for (int m = 0; m < 4; ++m) for (int k = 0; k < 2; ++k) \
;     dst[m][k] = *reinterpret_cast<const bf16x8*>((char*)SA(b, h) + lds_byte(wr * 64 + m * 16 + fr, k * 32 + fq * 8))
; #define LDB(dst, b, h) for (int n = 0; n < 2; ++n) for (int k = 0; k < 2; ++k) \
;     dst[n][k] = *reinterpret_cast<const bf16x8*>((char*)SB(b, h) + lds_byte(wc * 32 + n * 16 + fr, k * 32 + fq * 8))
; #define MMA(ai, bj, At_, Bt_) do { __builtin_amdgcn_s_setprio(1); \
;     for (int k = 0; k < 2; ++k) for (int m = 0; m < 4; ++m) for (int n = 0; n < 2; ++n) \
;       acc[ai][bj][m][n] = __builtin_amdgcn_mfma_f32_16x16x32_bf16(At_[m][k], Bt_[n][k], acc[ai][bj][m][n], 0, 0, 0); \
;     __builtin_amdgcn_s_setprio(0); } while (0)
; #define WAIT_V(n) asm volatile("s_waitcnt vmcnt(" #n ")" ::: "memory")
; #define WAIT_L(n) asm volatile("s_waitcnt lgkmcnt(" #n ")" ::: "memory")
; #define BAR __builtin_amdgcn_s_barrier()
; template <int EPI, int lda, int ldb, int N, int K>
; __device__ __forceinline__ void gemm_phase(const u16* __restrict__ A, const u16* __restrict__ Bt, const GemmEpi ep, int wv) {
;     ...
;       LDB(B1, 0, 1); BAR; WAIT_L(0); MMA(0, 1, At, B1); BAR;
;       LDA(At, 0, 1); WAIT_V(4); BAR; WAIT_L(0); MMA(1, 0, At, B0); MMA(1, 1, At, B1); BAR; }
;     { LDB(B0, 1, 0); LDA(At, 1, 0); WAIT_V(2); BAR; WAIT_L(0); MMA(0, 0, At, B0); BAR;
	s_waitcnt lgkmcnt(0)
	v_mfma_f32_16x16x32_bf16 v[92:95], v[210:213], v[178:181], v[92:95]
	v_mfma_f32_16x16x32_bf16 v[88:91], v[218:221], v[178:181], v[88:91]
	v_mfma_f32_16x16x32_bf16 v[76:79], v[210:213], v[194:197], v[76:79]
	v_mfma_f32_16x16x32_bf16 v[72:75], v[218:221], v[194:197], v[72:75]
	v_mfma_f32_16x16x32_bf16 v[84:87], v[210:213], v[186:189], v[84:87]
	v_mfma_f32_16x16x32_bf16 v[80:83], v[218:221], v[186:189], v[80:83]
	v_mfma_f32_16x16x32_bf16 v[68:71], v[210:213], v[202:205], v[68:71]
	v_mfma_f32_16x16x32_bf16 v[64:67], v[218:221], v[202:205], v[64:67]
	v_mfma_f32_16x16x32_bf16 v[92:95], v[214:217], v[182:185], v[92:95]
	v_mfma_f32_16x16x32_bf16 v[88:91], v[156:159], v[182:185], v[88:91]
	v_mfma_f32_16x16x32_bf16 v[76:79], v[214:217], v[198:201], v[76:79]
	v_mfma_f32_16x16x32_bf16 v[72:75], v[156:159], v[198:201], v[72:75]
	v_mfma_f32_16x16x32_bf16 v[178:181], v[214:217], v[190:193], v[84:87]
	v_mfma_f32_16x16x32_bf16 v[182:185], v[156:159], v[190:193], v[80:83]
	v_mfma_f32_16x16x32_bf16 v[186:189], v[214:217], v[206:209], v[68:71]
	v_mfma_f32_16x16x32_bf16 v[190:193], v[156:159], v[206:209], v[64:67]
	s_barrier
	s_nop 0
	ds_read_b128 v[64:67], v151 offset:16384
	ds_read_b128 v[68:71], v151 offset:17408
	ds_read_b128 v[80:83], v150 offset:16384
	ds_read_b128 v[84:87], v150 offset:17408
	ds_read_b128 v[194:197], v149 offset:16384
	ds_read_b128 v[198:201], v149 offset:17408
	ds_read_b128 v[202:205], v148 offset:16384
	ds_read_b128 v[206:209], v148 offset:17408
	s_waitcnt vmcnt(4)
	s_barrier
	s_waitcnt lgkmcnt(0)
	v_mfma_f32_16x16x32_bf16 v[60:63], v[134:137], v[64:67], v[60:63]
	v_mfma_f32_16x16x32_bf16 v[56:59], v[170:173], v[64:67], v[56:59]
	v_mfma_f32_16x16x32_bf16 v[52:55], v[134:137], v[80:83], v[52:55]
	v_mfma_f32_16x16x32_bf16 v[48:51], v[170:173], v[80:83], v[48:51]
	v_mfma_f32_16x16x32_bf16 v[44:47], v[134:137], v[194:197], v[44:47]
	v_mfma_f32_16x16x32_bf16 v[40:43], v[170:173], v[194:197], v[40:43]
	v_mfma_f32_16x16x32_bf16 v[36:39], v[134:137], v[202:205], v[36:39]
	v_mfma_f32_16x16x32_bf16 v[32:35], v[170:173], v[202:205], v[32:35]
	v_mfma_f32_16x16x32_bf16 v[60:63], v[138:141], v[68:71], v[60:63]
	v_mfma_f32_16x16x32_bf16 v[56:59], v[174:177], v[68:71], v[56:59]
	v_mfma_f32_16x16x32_bf16 v[52:55], v[138:141], v[84:87], v[52:55]
	v_mfma_f32_16x16x32_bf16 v[48:51], v[174:177], v[84:87], v[48:51]
	v_mfma_f32_16x16x32_bf16 v[44:47], v[138:141], v[198:201], v[44:47]
	v_mfma_f32_16x16x32_bf16 v[40:43], v[174:177], v[198:201], v[40:43]
	v_mfma_f32_16x16x32_bf16 v[36:39], v[138:141], v[206:209], v[36:39]
	v_mfma_f32_16x16x32_bf16 v[32:35], v[174:177], v[206:209], v[32:35]
	v_mfma_f32_16x16x32_bf16 v[28:31], v[210:213], v[64:67], v[28:31]
	v_mfma_f32_16x16x32_bf16 v[20:23], v[210:213], v[80:83], v[20:23]
	v_mfma_f32_16x16x32_bf16 v[12:15], v[210:213], v[194:197], v[12:15]
	v_mfma_f32_16x16x32_bf16 v[4:7], v[210:213], v[202:205], v[4:7]
	v_mfma_f32_16x16x32_bf16 v[24:27], v[218:221], v[64:67], v[24:27]
	v_mfma_f32_16x16x32_bf16 v[16:19], v[218:221], v[80:83], v[16:19]
	v_mfma_f32_16x16x32_bf16 v[8:11], v[218:221], v[194:197], v[8:11]
	v_mfma_f32_16x16x32_bf16 v[0:3], v[218:221], v[202:205], v[0:3]
	v_mfma_f32_16x16x32_bf16 v[28:31], v[214:217], v[68:71], v[28:31]
	v_mfma_f32_16x16x32_bf16 v[20:23], v[214:217], v[84:87], v[20:23]
	v_mfma_f32_16x16x32_bf16 v[12:15], v[214:217], v[198:201], v[12:15]
	v_mfma_f32_16x16x32_bf16 v[4:7], v[214:217], v[206:209], v[4:7]
	v_mfma_f32_16x16x32_bf16 v[134:137], v[156:159], v[68:71], v[24:27]
	v_mfma_f32_16x16x32_bf16 v[138:141], v[156:159], v[84:87], v[16:19]
	v_mfma_f32_16x16x32_bf16 v[168:171], v[156:159], v[198:201], v[8:11]
	v_mfma_f32_16x16x32_bf16 v[156:159], v[156:159], v[206:209], v[0:3]
	s_barrier
	s_nop 0
	ds_read_b128 v[0:3], v154
	ds_read_b128 v[8:11], v154 offset:1024
	ds_read_b128 v[16:19], v154 offset:2048
	ds_read_b128 v[172:175], v154 offset:3072
	ds_read_b128 v[24:27], v151 offset:32768
	ds_read_b128 v[194:197], v151 offset:33792
	ds_read_b128 v[198:201], v150 offset:32768
	ds_read_b128 v[202:205], v150 offset:33792
	ds_read_b128 v[206:209], v149 offset:32768
	ds_read_b128 v[210:213], v149 offset:33792
	ds_read_b128 v[214:217], v148 offset:32768
	ds_read_b128 v[218:221], v148 offset:33792
	s_waitcnt vmcnt(2)
	s_barrier
; #define LDA(dst, b, h) for (int m = 0; m < 4; ++m) for (int k = 0; k < 2; ++k) \
;     dst[m][k] = *reinterpret_cast<const bf16x8*>((char*)SA(b, h) + lds_byte(wr * 64 + m * 16 + fr, k * 32 + fq * 8))
; #define LDB(dst, b, h) for (int n = 0; n < 2; ++n) for (int k = 0; k < 2; ++k) \
;     dst[n][k] = *reinterpret_cast<const bf16x8*>((char*)SB(b, h) + lds_byte(wc * 32 + n * 16 + fr, k * 32 + fq * 8))
; #define MMA(ai, bj, At_, Bt_) do { __builtin_amdgcn_s_setprio(1); \
;     for (int k = 0; k < 2; ++k) for (int m = 0; m < 4; ++m) for (int n = 0; n < 2; ++n) \
;       acc[ai][bj][m][n] = __builtin_amdgcn_mfma_f32_16x16x32_bf16(At_[m][k], Bt_[n][k], acc[ai][bj][m][n], 0, 0, 0); \
;     __builtin_amdgcn_s_setprio(0); } while (0)
; #define WAIT_V(n) asm volatile("s_waitcnt vmcnt(" #n ")" ::: "memory")
; #define WAIT_L(n) asm volatile("s_waitcnt lgkmcnt(" #n ")" ::: "memory")
; #define BAR __builtin_amdgcn_s_barrier()
; template <int EPI, int lda, int ldb, int N, int K>
; __device__ __forceinline__ void gemm_phase(const u16* __restrict__ A, const u16* __restrict__ Bt, const GemmEpi ep, int wv) {
;     ...
;     { LDB(B0, 1, 0); LDA(At, 1, 0); WAIT_V(2); BAR; WAIT_L(0); MMA(0, 0, At, B0); BAR;
;       LDB(B1, 1, 1); WAIT_V(0); BAR; WAIT_L(0); MMA(0, 1, At, B1); BAR;
;       LDA(At, 1, 1); BAR; WAIT_L(0); MMA(1, 0, At, B0); MMA(1, 1, At, B1); BAR; }
;     if (wr == 0) BAR;
	s_waitcnt lgkmcnt(0)
	v_mfma_f32_16x16x32_bf16 v[64:67], v[0:3], v[24:27], v[124:127]
	v_mfma_f32_16x16x32_bf16 v[68:71], v[16:19], v[24:27], v[120:123]
	v_mfma_f32_16x16x32_bf16 v[80:83], v[0:3], v[198:201], v[116:119]
	v_mfma_f32_16x16x32_bf16 v[84:87], v[16:19], v[198:201], v[112:115]
	v_mfma_f32_16x16x32_bf16 v[108:111], v[0:3], v[206:209], v[108:111]
	v_mfma_f32_16x16x32_bf16 v[104:107], v[16:19], v[206:209], v[104:107]
	v_mfma_f32_16x16x32_bf16 v[120:123], v[0:3], v[214:217], v[100:103]
	v_mfma_f32_16x16x32_bf16 v[124:127], v[16:19], v[214:217], v[96:99]
	v_mfma_f32_16x16x32_bf16 v[116:119], v[8:11], v[194:197], v[64:67]
	v_mfma_f32_16x16x32_bf16 v[112:115], v[172:175], v[194:197], v[68:71]
	v_mfma_f32_16x16x32_bf16 v[100:103], v[8:11], v[202:205], v[80:83]
	v_mfma_f32_16x16x32_bf16 v[96:99], v[172:175], v[202:205], v[84:87]
	v_mfma_f32_16x16x32_bf16 v[84:87], v[8:11], v[210:213], v[108:111]
	v_mfma_f32_16x16x32_bf16 v[80:83], v[172:175], v[210:213], v[104:107]
	v_mfma_f32_16x16x32_bf16 v[68:71], v[8:11], v[218:221], v[120:123]
	v_mfma_f32_16x16x32_bf16 v[64:67], v[172:175], v[218:221], v[124:127]
	s_barrier
	ds_read_b128 v[222:225], v152
	ds_read_b128 v[226:229], v152 offset:1024
	ds_read_b128 v[230:233], v152 offset:2048
	ds_read_b128 v[152:155], v152 offset:3072
	s_waitcnt vmcnt(0)
	s_barrier
	s_waitcnt lgkmcnt(0)
	v_mfma_f32_16x16x32_bf16 v[92:95], v[222:225], v[24:27], v[92:95]
	v_mfma_f32_16x16x32_bf16 v[24:27], v[230:233], v[24:27], v[88:91]
	v_mfma_f32_16x16x32_bf16 v[88:91], v[222:225], v[198:201], v[178:181]
	v_mfma_f32_16x16x32_bf16 v[104:107], v[230:233], v[198:201], v[182:185]
	v_mfma_f32_16x16x32_bf16 v[76:79], v[222:225], v[206:209], v[76:79]
	v_mfma_f32_16x16x32_bf16 v[72:75], v[230:233], v[206:209], v[72:75]
	v_mfma_f32_16x16x32_bf16 v[176:179], v[222:225], v[214:217], v[186:189]
	v_mfma_f32_16x16x32_bf16 v[180:183], v[230:233], v[214:217], v[190:193]
	v_mfma_f32_16x16x32_bf16 v[124:127], v[226:229], v[194:197], v[92:95]
	v_mfma_f32_16x16x32_bf16 v[120:123], v[152:155], v[194:197], v[24:27]
	v_mfma_f32_16x16x32_bf16 v[108:111], v[226:229], v[202:205], v[88:91]
	v_mfma_f32_16x16x32_bf16 v[104:107], v[152:155], v[202:205], v[104:107]
	v_mfma_f32_16x16x32_bf16 v[92:95], v[226:229], v[210:213], v[76:79]
	v_mfma_f32_16x16x32_bf16 v[88:91], v[152:155], v[210:213], v[72:75]
	v_mfma_f32_16x16x32_bf16 v[76:79], v[226:229], v[218:221], v[176:179]
	v_mfma_f32_16x16x32_bf16 v[72:75], v[152:155], v[218:221], v[180:183]
	s_barrier
	ds_read_b128 v[176:179], v151 offset:49152
	ds_read_b128 v[180:183], v151 offset:50176
	ds_read_b128 v[184:187], v150 offset:49152
	ds_read_b128 v[188:191], v150 offset:50176
	ds_read_b128 v[192:195], v149 offset:49152
	ds_read_b128 v[196:199], v149 offset:50176
	ds_read_b128 v[200:203], v148 offset:49152
	ds_read_b128 v[148:151], v148 offset:50176
	s_barrier
	s_waitcnt lgkmcnt(0)
	v_mfma_f32_16x16x32_bf16 v[24:27], v[0:3], v[176:179], v[60:63]
	v_mfma_f32_16x16x32_bf16 v[60:63], v[16:19], v[176:179], v[56:59]
	v_mfma_f32_16x16x32_bf16 v[52:55], v[0:3], v[184:187], v[52:55]
	v_mfma_f32_16x16x32_bf16 v[204:207], v[16:19], v[184:187], v[48:51]
	v_mfma_f32_16x16x32_bf16 v[44:47], v[0:3], v[192:195], v[44:47]
	v_mfma_f32_16x16x32_bf16 v[208:211], v[16:19], v[192:195], v[40:43]
	v_mfma_f32_16x16x32_bf16 v[0:3], v[0:3], v[200:203], v[36:39]
	v_mfma_f32_16x16x32_bf16 v[36:39], v[16:19], v[200:203], v[32:35]
	v_mfma_f32_16x16x32_bf16 v[56:59], v[8:11], v[180:183], v[24:27]
	v_mfma_f32_16x16x32_bf16 v[48:51], v[172:175], v[180:183], v[60:63]
	v_mfma_f32_16x16x32_bf16 v[40:43], v[8:11], v[188:191], v[52:55]
	v_mfma_f32_16x16x32_bf16 v[32:35], v[172:175], v[188:191], v[204:207]
	v_mfma_f32_16x16x32_bf16 v[24:27], v[8:11], v[196:199], v[44:47]
	v_mfma_f32_16x16x32_bf16 v[16:19], v[172:175], v[196:199], v[208:211]
	v_mfma_f32_16x16x32_bf16 v[8:11], v[8:11], v[148:151], v[0:3]
	v_mfma_f32_16x16x32_bf16 v[0:3], v[172:175], v[148:151], v[36:39]
	v_mfma_f32_16x16x32_bf16 v[28:31], v[222:225], v[176:179], v[28:31]
	v_mfma_f32_16x16x32_bf16 v[36:39], v[230:233], v[176:179], v[134:137]
	v_mfma_f32_16x16x32_bf16 v[20:23], v[222:225], v[184:187], v[20:23]
	v_mfma_f32_16x16x32_bf16 v[134:137], v[230:233], v[184:187], v[138:141]
	v_mfma_f32_16x16x32_bf16 v[12:15], v[222:225], v[192:195], v[12:15]
	v_mfma_f32_16x16x32_bf16 v[138:141], v[230:233], v[192:195], v[168:171]
	v_mfma_f32_16x16x32_bf16 v[4:7], v[222:225], v[200:203], v[4:7]
	v_mfma_f32_16x16x32_bf16 v[156:159], v[230:233], v[200:203], v[156:159]
	v_mfma_f32_16x16x32_bf16 v[60:63], v[226:229], v[180:183], v[28:31]
	v_mfma_f32_16x16x32_bf16 v[52:55], v[152:155], v[180:183], v[36:39]
	v_mfma_f32_16x16x32_bf16 v[44:47], v[226:229], v[188:191], v[20:23]
	v_mfma_f32_16x16x32_bf16 v[36:39], v[152:155], v[188:191], v[134:137]
	v_mfma_f32_16x16x32_bf16 v[28:31], v[226:229], v[196:199], v[12:15]
	v_mfma_f32_16x16x32_bf16 v[20:23], v[152:155], v[196:199], v[138:141]
	v_mfma_f32_16x16x32_bf16 v[12:15], v[226:229], v[148:151], v[4:7]
	v_mfma_f32_16x16x32_bf16 v[4:7], v[152:155], v[148:151], v[156:159]
	v_cmp_gt_u32_e32 vcc, s70, v130
	s_barrier
	s_and_saveexec_b64 s[52:53], vcc
	s_cbranch_execz .LBB0_657
	s_barrier

; #define STAGE(P, BASE, LD, br, kt) do { const char* _g = (const char*)((BASE) + (size_t)(br) * (LD) + (size_t)(kt) * 64); \
;     for (int _i = 0; _i < 2; ++_i) { int _b = tidx * 16 + _i * 8192; int _r, _c; stage_rc(_b, _r, _c); \
;       __builtin_amdgcn_global_load_lds((const unsigned*)(_g + (unsigned)((_r * (LD) + _c) * 2)), (unsigned*)((char*)(P) + _b), 16, 0, 0); } } while (0)
; #define LDA(dst, b, h) for (int m = 0; m < 4; ++m) for (int k = 0; k < 2; ++k) \
;     dst[m][k] = *reinterpret_cast<const bf16x8*>((char*)SA(b, h) + lds_byte(wr * 64 + m * 16 + fr, k * 32 + fq * 8))
; #define LDB(dst, b, h) for (int n = 0; n < 2; ++n) for (int k = 0; k < 2; ++k) \
;     dst[n][k] = *reinterpret_cast<const bf16x8*>((char*)SB(b, h) + lds_byte(wc * 32 + n * 16 + fr, k * 32 + fq * 8))
; #define MMA(ai, bj, At_, Bt_) do { __builtin_amdgcn_s_setprio(1); \
;     for (int k = 0; k < 2; ++k) for (int m = 0; m < 4; ++m) for (int n = 0; n < 2; ++n) \
;       acc[ai][bj][m][n] = __builtin_amdgcn_mfma_f32_16x16x32_bf16(At_[m][k], Bt_[n][k], acc[ai][bj][m][n], 0, 0, 0); \
;     __builtin_amdgcn_s_setprio(0); } while (0)
; #define WAIT_L(n) asm volatile("s_waitcnt lgkmcnt(" #n ")" ::: "memory")
; #define BAR __builtin_amdgcn_s_barrier()
; #define SCHED __builtin_amdgcn_sched_barrier(0)
; template <int EPI, int lda, int ldb, int N, int K>
; __device__ __forceinline__ void gemm_phase(const u16* __restrict__ A, const u16* __restrict__ Bt, const GemmEpi ep, int wv) {
;     ...
;     for (int t = 0; t < nt - 2; t += 2) {
;       LDB(B0, 0, 0); SCHED; LDA(At, 0, 0); STAGE(SA(1, 1), Ab, lda, brow + HALF, t + 1);
;       WAIT_L(8); BAR; WAIT_L(0); MMA(0, 0, At, B0); BAR; SCHED;
;       LDB(B1, 0, 1); STAGE(SB(0, 0), Bt, ldb, bcol, t + 2);
;       BAR; WAIT_L(0); MMA(0, 1, At, B1); BAR;
;       LDA(At, 0, 1); STAGE(SA(0, 0), Ab, lda, brow, t + 2);
;       BAR; WAIT_L(0); MMA(1, 0, At, B0); BAR; SCHED;
.LBB0_770:
	ds_read_b128 v[172:175], v161
	ds_read_b128 v[176:179], v161 offset:1024
	ds_read_b128 v[180:183], v161 offset:2048
	ds_read_b128 v[184:187], v161 offset:3072
	v_add_u32_e32 v169, 0xc000, v148
	v_lshl_add_u64 v[236:237], v[136:137], 0, s[50:51]
	v_readfirstlane_b32 s53, v169
	v_add_u32_e32 v170, 0xe000, v148
	v_lshl_add_u64 v[162:163], v[236:237], 0, s[18:19]
	s_mov_b32 m0, s53
	v_lshl_add_u64 v[238:239], v[134:135], 0, s[50:51]
	v_readfirstlane_b32 s53, v170
	ds_read_b128 v[164:167], v152
	ds_read_b128 v[188:191], v152 offset:1024
	ds_read_b128 v[192:195], v151
	ds_read_b128 v[196:199], v151 offset:1024
	ds_read_b128 v[200:203], v150
	ds_read_b128 v[204:207], v150 offset:1024
	ds_read_b128 v[208:211], v149
	ds_read_b128 v[212:215], v149 offset:1024
	global_load_lds_dwordx4 v[162:163], off
	v_lshl_add_u64 v[162:163], v[238:239], 0, s[18:19]
	s_mov_b32 m0, s53
	s_nop 0
	global_load_lds_dwordx4 v[162:163], off
	s_waitcnt lgkmcnt(8)
	s_barrier
	s_waitcnt lgkmcnt(0)
	v_mfma_f32_16x16x32_bf16 v[124:127], v[172:175], v[164:167], v[124:127]
	v_mfma_f32_16x16x32_bf16 v[120:123], v[180:183], v[164:167], v[120:123]
	v_mfma_f32_16x16x32_bf16 v[116:119], v[172:175], v[192:195], v[116:119]
	v_mfma_f32_16x16x32_bf16 v[112:115], v[180:183], v[192:195], v[112:115]
	v_mfma_f32_16x16x32_bf16 v[108:111], v[172:175], v[200:203], v[108:111]
	v_mfma_f32_16x16x32_bf16 v[104:107], v[180:183], v[200:203], v[104:107]
	v_mfma_f32_16x16x32_bf16 v[100:103], v[172:175], v[208:211], v[100:103]
	v_mfma_f32_16x16x32_bf16 v[96:99], v[180:183], v[208:211], v[96:99]
	v_mfma_f32_16x16x32_bf16 v[124:127], v[176:179], v[188:191], v[124:127]
	v_mfma_f32_16x16x32_bf16 v[120:123], v[184:187], v[188:191], v[120:123]
	v_mfma_f32_16x16x32_bf16 v[116:119], v[176:179], v[196:199], v[116:119]
	v_mfma_f32_16x16x32_bf16 v[112:115], v[184:187], v[196:199], v[112:115]
	v_mfma_f32_16x16x32_bf16 v[108:111], v[176:179], v[204:207], v[108:111]
	v_mfma_f32_16x16x32_bf16 v[104:107], v[184:187], v[204:207], v[104:107]
	v_mfma_f32_16x16x32_bf16 v[100:103], v[176:179], v[212:215], v[100:103]
	v_mfma_f32_16x16x32_bf16 v[96:99], v[184:187], v[212:215], v[96:99]
	s_barrier
	v_add_u32_e32 v162, s64, v153
	v_lshl_add_u64 v[240:241], v[140:141], 0, s[50:51]
	v_readfirstlane_b32 s53, v162
	v_add_u32_e32 v163, 0x2000, v162
	v_lshl_add_u64 v[232:233], v[240:241], 0, s[20:21]
	s_mov_b32 m0, s53
	v_lshl_add_u64 v[242:243], v[138:139], 0, s[50:51]
	v_readfirstlane_b32 s53, v163
	ds_read_b128 v[216:219], v160
	ds_read_b128 v[220:223], v160 offset:1024
	ds_read_b128 v[224:227], v160 offset:2048
	ds_read_b128 v[228:231], v160 offset:3072
	global_load_lds_dwordx4 v[232:233], off
	v_lshl_add_u64 v[232:233], v[242:243], 0, s[20:21]
	s_mov_b32 m0, s53
	s_nop 0
	global_load_lds_dwordx4 v[232:233], off
	s_barrier
	s_waitcnt lgkmcnt(0)
	v_mfma_f32_16x16x32_bf16 v[92:95], v[216:219], v[164:167], v[92:95]
	v_mfma_f32_16x16x32_bf16 v[88:91], v[224:227], v[164:167], v[88:91]
	v_mfma_f32_16x16x32_bf16 v[84:87], v[216:219], v[192:195], v[84:87]
	v_mfma_f32_16x16x32_bf16 v[80:83], v[224:227], v[192:195], v[80:83]
	v_mfma_f32_16x16x32_bf16 v[76:79], v[216:219], v[200:203], v[76:79]
	v_mfma_f32_16x16x32_bf16 v[72:75], v[224:227], v[200:203], v[72:75]
	v_mfma_f32_16x16x32_bf16 v[68:71], v[216:219], v[208:211], v[68:71]
	v_mfma_f32_16x16x32_bf16 v[64:67], v[224:227], v[208:211], v[64:67]
	v_mfma_f32_16x16x32_bf16 v[92:95], v[220:223], v[188:191], v[92:95]
	v_mfma_f32_16x16x32_bf16 v[88:91], v[228:231], v[188:191], v[88:91]
	v_mfma_f32_16x16x32_bf16 v[84:87], v[220:223], v[196:199], v[84:87]
	v_mfma_f32_16x16x32_bf16 v[80:83], v[228:231], v[196:199], v[80:83]
	v_mfma_f32_16x16x32_bf16 v[76:79], v[220:223], v[204:207], v[76:79]
	v_mfma_f32_16x16x32_bf16 v[72:75], v[228:231], v[204:207], v[72:75]
	v_mfma_f32_16x16x32_bf16 v[68:71], v[220:223], v[212:215], v[68:71]
	v_mfma_f32_16x16x32_bf16 v[64:67], v[228:231], v[212:215], v[64:67]
	v_readfirstlane_b32 s53, v148
	v_lshl_add_u64 v[164:165], v[236:237], 0, s[22:23]
	s_mov_b32 m0, s53
	s_barrier
	ds_read_b128 v[188:191], v152 offset:16384
	ds_read_b128 v[192:195], v152 offset:17408
	ds_read_b128 v[196:199], v151 offset:16384
	ds_read_b128 v[200:203], v151 offset:17408
	ds_read_b128 v[204:207], v150 offset:16384
	ds_read_b128 v[208:211], v150 offset:17408
	ds_read_b128 v[212:215], v149 offset:16384
	ds_read_b128 v[232:235], v149 offset:17408
	global_load_lds_dwordx4 v[164:165], off
	v_add_u32_e32 v164, 0x2000, v148
	v_lshl_add_u64 v[166:167], v[238:239], 0, s[22:23]
	v_readfirstlane_b32 s53, v164
	s_mov_b32 m0, s53
	s_nop 0
	global_load_lds_dwordx4 v[166:167], off
	s_barrier
	s_waitcnt lgkmcnt(0)
	v_mfma_f32_16x16x32_bf16 v[60:63], v[172:175], v[188:191], v[60:63]
	v_mfma_f32_16x16x32_bf16 v[56:59], v[180:183], v[188:191], v[56:59]
	v_mfma_f32_16x16x32_bf16 v[52:55], v[172:175], v[196:199], v[52:55]
	v_mfma_f32_16x16x32_bf16 v[48:51], v[180:183], v[196:199], v[48:51]
	v_mfma_f32_16x16x32_bf16 v[44:47], v[172:175], v[204:207], v[44:47]
	v_mfma_f32_16x16x32_bf16 v[40:43], v[180:183], v[204:207], v[40:43]
	v_mfma_f32_16x16x32_bf16 v[36:39], v[172:175], v[212:215], v[36:39]
	v_mfma_f32_16x16x32_bf16 v[32:35], v[180:183], v[212:215], v[32:35]
	v_mfma_f32_16x16x32_bf16 v[60:63], v[176:179], v[192:195], v[60:63]
	v_mfma_f32_16x16x32_bf16 v[56:59], v[184:187], v[192:195], v[56:59]
	v_mfma_f32_16x16x32_bf16 v[52:55], v[176:179], v[200:203], v[52:55]
	v_mfma_f32_16x16x32_bf16 v[48:51], v[184:187], v[200:203], v[48:51]
	v_mfma_f32_16x16x32_bf16 v[44:47], v[176:179], v[208:211], v[44:47]
	v_mfma_f32_16x16x32_bf16 v[40:43], v[184:187], v[208:211], v[40:43]
	v_mfma_f32_16x16x32_bf16 v[36:39], v[176:179], v[232:235], v[36:39]
	v_mfma_f32_16x16x32_bf16 v[32:35], v[184:187], v[232:235], v[32:35]
	s_barrier
; #define STAGE(P, BASE, LD, br, kt) do { const char* _g = (const char*)((BASE) + (size_t)(br) * (LD) + (size_t)(kt) * 64); \
;     for (int _i = 0; _i < 2; ++_i) { int _b = tidx * 16 + _i * 8192; int _r, _c; stage_rc(_b, _r, _c); \
;       __builtin_amdgcn_global_load_lds((const unsigned*)(_g + (unsigned)((_r * (LD) + _c) * 2)), (unsigned*)((char*)(P) + _b), 16, 0, 0); } } while (0)
; #define LDA(dst, b, h) for (int m = 0; m < 4; ++m) for (int k = 0; k < 2; ++k) \
;     dst[m][k] = *reinterpret_cast<const bf16x8*>((char*)SA(b, h) + lds_byte(wr * 64 + m * 16 + fr, k * 32 + fq * 8))
; #define LDB(dst, b, h) for (int n = 0; n < 2; ++n) for (int k = 0; k < 2; ++k) \
;     dst[n][k] = *reinterpret_cast<const bf16x8*>((char*)SB(b, h) + lds_byte(wc * 32 + n * 16 + fr, k * 32 + fq * 8))
; #define MMA(ai, bj, At_, Bt_) do { __builtin_amdgcn_s_setprio(1); \
;     for (int k = 0; k < 2; ++k) for (int m = 0; m < 4; ++m) for (int n = 0; n < 2; ++n) \
;       acc[ai][bj][m][n] = __builtin_amdgcn_mfma_f32_16x16x32_bf16(At_[m][k], Bt_[n][k], acc[ai][bj][m][n], 0, 0, 0); \
;     __builtin_amdgcn_s_setprio(0); } while (0)
; #define WAIT_V(n) asm volatile("s_waitcnt vmcnt(" #n ")" ::: "memory")
; #define WAIT_L(n) asm volatile("s_waitcnt lgkmcnt(" #n ")" ::: "memory")
; #define BAR __builtin_amdgcn_s_barrier()
; #define SCHED __builtin_amdgcn_sched_barrier(0)
; template <int EPI, int lda, int ldb, int N, int K>
; __device__ __forceinline__ void gemm_phase(const u16* __restrict__ A, const u16* __restrict__ Bt, const GemmEpi ep, int wv) {
;     ...
;       STAGE(SB(0, 1), Bt, ldb, bcol + HALF, t + 2);
;       WAIT_V(6); BAR; MMA(1, 1, At, B1); BAR;
;       LDB(B0, 1, 0); SCHED; LDA(At, 1, 0); STAGE(SA(0, 1), Ab, lda, brow + HALF, t + 2);
;       WAIT_L(8); BAR; WAIT_L(0); MMA(0, 0, At, B0); BAR; SCHED;
;       LDB(B1, 1, 1); STAGE(SB(1, 0), Bt, ldb, bcol, t + 3);
;       BAR; WAIT_L(0); MMA(0, 1, At, B1); BAR;
;       LDA(At, 1, 1); STAGE(SA(1, 0), Ab, lda, brow, t + 3);
	v_add_u32_e32 v165, s65, v153
	v_lshl_add_u64 v[166:167], v[240:241], 0, s[24:25]
	v_readfirstlane_b32 s53, v165
	s_mov_b32 m0, s53
	v_lshl_add_u64 v[172:173], v[242:243], 0, s[24:25]
	global_load_lds_dwordx4 v[166:167], off
	v_add_u32_e32 v166, 0x2000, v165
	s_nop 0
	v_readfirstlane_b32 s53, v166
	s_mov_b32 m0, s53
	s_nop 0
	global_load_lds_dwordx4 v[172:173], off
	s_waitcnt vmcnt(6)
	s_barrier
	v_mfma_f32_16x16x32_bf16 v[28:31], v[216:219], v[188:191], v[28:31]
	v_mfma_f32_16x16x32_bf16 v[24:27], v[224:227], v[188:191], v[24:27]
	v_mfma_f32_16x16x32_bf16 v[20:23], v[216:219], v[196:199], v[20:23]
	v_mfma_f32_16x16x32_bf16 v[16:19], v[224:227], v[196:199], v[16:19]
	v_mfma_f32_16x16x32_bf16 v[12:15], v[216:219], v[204:207], v[12:15]
	v_mfma_f32_16x16x32_bf16 v[8:11], v[224:227], v[204:207], v[8:11]
	v_mfma_f32_16x16x32_bf16 v[4:7], v[216:219], v[212:215], v[4:7]
	v_mfma_f32_16x16x32_bf16 v[0:3], v[224:227], v[212:215], v[0:3]
	v_mfma_f32_16x16x32_bf16 v[28:31], v[220:223], v[192:195], v[28:31]
	v_mfma_f32_16x16x32_bf16 v[24:27], v[228:231], v[192:195], v[24:27]
	v_mfma_f32_16x16x32_bf16 v[20:23], v[220:223], v[200:203], v[20:23]
	v_mfma_f32_16x16x32_bf16 v[16:19], v[228:231], v[200:203], v[16:19]
	v_mfma_f32_16x16x32_bf16 v[12:15], v[220:223], v[208:211], v[12:15]
	v_mfma_f32_16x16x32_bf16 v[8:11], v[228:231], v[208:211], v[8:11]
	v_mfma_f32_16x16x32_bf16 v[4:7], v[220:223], v[232:235], v[4:7]
	v_mfma_f32_16x16x32_bf16 v[0:3], v[228:231], v[232:235], v[0:3]
	s_barrier
	ds_read_b128 v[172:175], v156
	ds_read_b128 v[176:179], v156 offset:1024
	ds_read_b128 v[180:183], v156 offset:2048
	ds_read_b128 v[184:187], v156 offset:3072
	v_add_u32_e32 v167, 0x4000, v148
	v_add_u32_e32 v168, 0x6000, v148
	v_readfirstlane_b32 s53, v167
	v_lshl_add_u64 v[220:221], v[236:237], 0, s[26:27]
	s_mov_b32 m0, s53
	v_readfirstlane_b32 s53, v168
	ds_read_b128 v[188:191], v152 offset:32768
	ds_read_b128 v[192:195], v152 offset:33792
	ds_read_b128 v[196:199], v151 offset:32768
	ds_read_b128 v[200:203], v151 offset:33792
	ds_read_b128 v[204:207], v150 offset:32768
	ds_read_b128 v[208:211], v150 offset:33792
	ds_read_b128 v[212:215], v149 offset:32768
	ds_read_b128 v[216:219], v149 offset:33792
	global_load_lds_dwordx4 v[220:221], off
	v_lshl_add_u64 v[220:221], v[238:239], 0, s[26:27]
	s_mov_b32 m0, s53
	s_nop 0
	global_load_lds_dwordx4 v[220:221], off
	s_waitcnt lgkmcnt(8)
	s_barrier
	s_waitcnt lgkmcnt(0)
	v_mfma_f32_16x16x32_bf16 v[124:127], v[172:175], v[188:191], v[124:127]
	v_mfma_f32_16x16x32_bf16 v[120:123], v[180:183], v[188:191], v[120:123]
	v_mfma_f32_16x16x32_bf16 v[116:119], v[172:175], v[196:199], v[116:119]
	v_mfma_f32_16x16x32_bf16 v[112:115], v[180:183], v[196:199], v[112:115]
	v_mfma_f32_16x16x32_bf16 v[108:111], v[172:175], v[204:207], v[108:111]
	v_mfma_f32_16x16x32_bf16 v[104:107], v[180:183], v[204:207], v[104:107]
	v_mfma_f32_16x16x32_bf16 v[100:103], v[172:175], v[212:215], v[100:103]
	v_mfma_f32_16x16x32_bf16 v[96:99], v[180:183], v[212:215], v[96:99]
	v_mfma_f32_16x16x32_bf16 v[124:127], v[176:179], v[192:195], v[124:127]
	v_mfma_f32_16x16x32_bf16 v[120:123], v[184:187], v[192:195], v[120:123]
	v_mfma_f32_16x16x32_bf16 v[116:119], v[176:179], v[200:203], v[116:119]
	v_mfma_f32_16x16x32_bf16 v[112:115], v[184:187], v[200:203], v[112:115]
	v_mfma_f32_16x16x32_bf16 v[108:111], v[176:179], v[208:211], v[108:111]
	v_mfma_f32_16x16x32_bf16 v[104:107], v[184:187], v[208:211], v[104:107]
	v_mfma_f32_16x16x32_bf16 v[100:103], v[176:179], v[216:219], v[100:103]
	v_mfma_f32_16x16x32_bf16 v[96:99], v[184:187], v[216:219], v[96:99]
	s_barrier
	v_readfirstlane_b32 s53, v155
	v_add_u32_e32 v171, 0x2000, v155
	v_lshl_add_u64 v[244:245], v[240:241], 0, s[40:41]
	s_mov_b32 m0, s53
	v_readfirstlane_b32 s53, v171
	ds_read_b128 v[220:223], v154
	ds_read_b128 v[224:227], v154 offset:1024
	ds_read_b128 v[228:231], v154 offset:2048
	ds_read_b128 v[232:235], v154 offset:3072
	global_load_lds_dwordx4 v[244:245], off
	v_lshl_add_u64 v[244:245], v[242:243], 0, s[40:41]
	s_mov_b32 m0, s53
	s_nop 0
	global_load_lds_dwordx4 v[244:245], off
	s_barrier
	s_waitcnt lgkmcnt(0)
	v_mfma_f32_16x16x32_bf16 v[92:95], v[220:223], v[188:191], v[92:95]
	v_mfma_f32_16x16x32_bf16 v[88:91], v[228:231], v[188:191], v[88:91]
	v_mfma_f32_16x16x32_bf16 v[84:87], v[220:223], v[196:199], v[84:87]
	v_mfma_f32_16x16x32_bf16 v[80:83], v[228:231], v[196:199], v[80:83]
	v_mfma_f32_16x16x32_bf16 v[76:79], v[220:223], v[204:207], v[76:79]
	v_mfma_f32_16x16x32_bf16 v[72:75], v[228:231], v[204:207], v[72:75]
	v_mfma_f32_16x16x32_bf16 v[68:71], v[220:223], v[212:215], v[68:71]
	v_mfma_f32_16x16x32_bf16 v[64:67], v[228:231], v[212:215], v[64:67]
	v_mfma_f32_16x16x32_bf16 v[92:95], v[224:227], v[192:195], v[92:95]
	v_mfma_f32_16x16x32_bf16 v[88:91], v[232:235], v[192:195], v[88:91]
	v_mfma_f32_16x16x32_bf16 v[84:87], v[224:227], v[200:203], v[84:87]
	v_mfma_f32_16x16x32_bf16 v[80:83], v[232:235], v[200:203], v[80:83]
	v_mfma_f32_16x16x32_bf16 v[76:79], v[224:227], v[208:211], v[76:79]
	v_mfma_f32_16x16x32_bf16 v[72:75], v[232:235], v[208:211], v[72:75]
	v_mfma_f32_16x16x32_bf16 v[68:71], v[224:227], v[216:219], v[68:71]
	v_mfma_f32_16x16x32_bf16 v[64:67], v[232:235], v[216:219], v[64:67]
	v_readfirstlane_b32 s53, v157
	v_lshl_add_u64 v[236:237], v[236:237], 0, s[42:43]
	s_mov_b32 m0, s53
	v_readfirstlane_b32 s53, v158
	s_barrier
	ds_read_b128 v[188:191], v152 offset:49152
	ds_read_b128 v[192:195], v152 offset:50176
	ds_read_b128 v[196:199], v151 offset:49152
	ds_read_b128 v[200:203], v151 offset:50176
	ds_read_b128 v[204:207], v150 offset:49152
	ds_read_b128 v[208:211], v150 offset:50176
	ds_read_b128 v[212:215], v149 offset:49152
	ds_read_b128 v[216:219], v149 offset:50176
	global_load_lds_dwordx4 v[236:237], off
	v_lshl_add_u64 v[236:237], v[238:239], 0, s[42:43]
	s_mov_b32 m0, s53
	s_nop 0
	global_load_lds_dwordx4 v[236:237], off
	s_barrier
; #define STAGE(P, BASE, LD, br, kt) do { const char* _g = (const char*)((BASE) + (size_t)(br) * (LD) + (size_t)(kt) * 64); \
;     for (int _i = 0; _i < 2; ++_i) { int _b = tidx * 16 + _i * 8192; int _r, _c; stage_rc(_b, _r, _c); \
;       __builtin_amdgcn_global_load_lds((const unsigned*)(_g + (unsigned)((_r * (LD) + _c) * 2)), (unsigned*)((char*)(P) + _b), 16, 0, 0); } } while (0)
; #define LDA(dst, b, h) for (int m = 0; m < 4; ++m) for (int k = 0; k < 2; ++k) \
;     dst[m][k] = *reinterpret_cast<const bf16x8*>((char*)SA(b, h) + lds_byte(wr * 64 + m * 16 + fr, k * 32 + fq * 8))
; #define LDB(dst, b, h) for (int n = 0; n < 2; ++n) for (int k = 0; k < 2; ++k) \
;     dst[n][k] = *reinterpret_cast<const bf16x8*>((char*)SB(b, h) + lds_byte(wc * 32 + n * 16 + fr, k * 32 + fq * 8))
; #define MMA(ai, bj, At_, Bt_) do { __builtin_amdgcn_s_setprio(1); \
;     for (int k = 0; k < 2; ++k) for (int m = 0; m < 4; ++m) for (int n = 0; n < 2; ++n) \
;       acc[ai][bj][m][n] = __builtin_amdgcn_mfma_f32_16x16x32_bf16(At_[m][k], Bt_[n][k], acc[ai][bj][m][n], 0, 0, 0); \
;     __builtin_amdgcn_s_setprio(0); } while (0)
; #define WAIT_V(n) asm volatile("s_waitcnt vmcnt(" #n ")" ::: "memory")
; #define WAIT_L(n) asm volatile("s_waitcnt lgkmcnt(" #n ")" ::: "memory")
; #define BAR __builtin_amdgcn_s_barrier()
; #define SCHED __builtin_amdgcn_sched_barrier(0)
; template <int EPI, int lda, int ldb, int N, int K>
; __device__ __forceinline__ void gemm_phase(const u16* __restrict__ A, const u16* __restrict__ Bt, const GemmEpi ep, int wv) {
;     ...
;       BAR; WAIT_L(0); MMA(1, 0, At, B0); BAR; SCHED;
;       STAGE(SB(1, 1), Bt, ldb, bcol + HALF, t + 3);
;       WAIT_V(6); BAR; MMA(1, 1, At, B1); BAR;
;     }
;     { LDB(B0, 0, 0); LDA(At, 0, 0); STAGE(SA(1, 1), Ab, lda, brow + HALF, nt - 1);
;       BAR; WAIT_L(0); MMA(0, 0, At, B0); BAR;
;       LDB(B1, 0, 1); BAR; WAIT_L(0); MMA(0, 1, At, B1); BAR;
	s_waitcnt lgkmcnt(0)
	v_mfma_f32_16x16x32_bf16 v[60:63], v[172:175], v[188:191], v[60:63]
	v_mfma_f32_16x16x32_bf16 v[56:59], v[180:183], v[188:191], v[56:59]
	v_mfma_f32_16x16x32_bf16 v[52:55], v[172:175], v[196:199], v[52:55]
	v_mfma_f32_16x16x32_bf16 v[48:51], v[180:183], v[196:199], v[48:51]
	v_mfma_f32_16x16x32_bf16 v[44:47], v[172:175], v[204:207], v[44:47]
	v_mfma_f32_16x16x32_bf16 v[40:43], v[180:183], v[204:207], v[40:43]
	v_mfma_f32_16x16x32_bf16 v[36:39], v[172:175], v[212:215], v[36:39]
	v_mfma_f32_16x16x32_bf16 v[32:35], v[180:183], v[212:215], v[32:35]
	v_mfma_f32_16x16x32_bf16 v[60:63], v[176:179], v[192:195], v[60:63]
	v_mfma_f32_16x16x32_bf16 v[56:59], v[184:187], v[192:195], v[56:59]
	v_mfma_f32_16x16x32_bf16 v[52:55], v[176:179], v[200:203], v[52:55]
	v_mfma_f32_16x16x32_bf16 v[48:51], v[184:187], v[200:203], v[48:51]
	v_mfma_f32_16x16x32_bf16 v[44:47], v[176:179], v[208:211], v[44:47]
	v_mfma_f32_16x16x32_bf16 v[40:43], v[184:187], v[208:211], v[40:43]
	v_mfma_f32_16x16x32_bf16 v[36:39], v[176:179], v[216:219], v[36:39]
	v_mfma_f32_16x16x32_bf16 v[32:35], v[184:187], v[216:219], v[32:35]
	s_barrier
	v_readfirstlane_b32 s53, v159
	v_add_u32_e32 v171, 0x2000, v159
	v_lshl_add_u64 v[172:173], v[240:241], 0, s[44:45]
	s_mov_b32 m0, s53
	v_readfirstlane_b32 s53, v171
	global_load_lds_dwordx4 v[172:173], off
	v_lshl_add_u64 v[172:173], v[242:243], 0, s[44:45]
	s_mov_b32 m0, s53
	s_nop 0
	global_load_lds_dwordx4 v[172:173], off
	s_waitcnt vmcnt(6)
	s_barrier
	v_mfma_f32_16x16x32_bf16 v[28:31], v[220:223], v[188:191], v[28:31]
	v_mfma_f32_16x16x32_bf16 v[24:27], v[228:231], v[188:191], v[24:27]
	v_mfma_f32_16x16x32_bf16 v[20:23], v[220:223], v[196:199], v[20:23]
	v_mfma_f32_16x16x32_bf16 v[16:19], v[228:231], v[196:199], v[16:19]
	v_mfma_f32_16x16x32_bf16 v[12:15], v[220:223], v[204:207], v[12:15]
	v_mfma_f32_16x16x32_bf16 v[8:11], v[228:231], v[204:207], v[8:11]
	v_mfma_f32_16x16x32_bf16 v[4:7], v[220:223], v[212:215], v[4:7]
	v_mfma_f32_16x16x32_bf16 v[0:3], v[228:231], v[212:215], v[0:3]
	v_mfma_f32_16x16x32_bf16 v[28:31], v[224:227], v[192:195], v[28:31]
	v_mfma_f32_16x16x32_bf16 v[24:27], v[232:235], v[192:195], v[24:27]
	v_mfma_f32_16x16x32_bf16 v[20:23], v[224:227], v[200:203], v[20:23]
	v_mfma_f32_16x16x32_bf16 v[16:19], v[232:235], v[200:203], v[16:19]
	v_mfma_f32_16x16x32_bf16 v[12:15], v[224:227], v[208:211], v[12:15]
	v_mfma_f32_16x16x32_bf16 v[8:11], v[232:235], v[208:211], v[8:11]
	v_mfma_f32_16x16x32_bf16 v[4:7], v[224:227], v[216:219], v[4:7]
	v_mfma_f32_16x16x32_bf16 v[0:3], v[232:235], v[216:219], v[0:3]
	s_add_i32 s52, s52, 2
	s_add_u32 s50, s50, 0x100
	s_addc_u32 s51, s51, 0
	s_cmp_gt_u32 s52, 27
	s_barrier
	s_cbranch_scc0 .LBB0_770
	s_add_i32 s50, s48, 0x80
	s_mul_hi_i32 s51, s50, 0x1080
	s_mulk_i32 s50, 0x1080
	s_add_u32 s50, s61, s50
	s_addc_u32 s51, s62, s51
	v_lshl_add_u64 v[158:159], s[50:51], 0, v[128:129]
	v_readfirstlane_b32 s52, v169
	v_lshl_add_u64 v[158:159], v[158:159], 0, s[46:47]
	s_mov_b32 m0, s52
	ds_read_b128 v[134:137], v161
	ds_read_b128 v[138:141], v161 offset:1024
	ds_read_b128 v[172:175], v161 offset:2048
	ds_read_b128 v[176:179], v161 offset:3072
	ds_read_b128 v[180:183], v152
	ds_read_b128 v[184:187], v152 offset:1024
	ds_read_b128 v[188:191], v151
	ds_read_b128 v[192:195], v151 offset:1024
	ds_read_b128 v[196:199], v150
	ds_read_b128 v[200:203], v150 offset:1024
	ds_read_b128 v[204:207], v149
	ds_read_b128 v[208:211], v149 offset:1024
	global_load_lds_dwordx4 v[158:159], off
	v_lshl_add_u64 v[158:159], s[50:51], 0, v[132:133]
	v_readfirstlane_b32 s50, v170
	v_lshl_add_u64 v[158:159], v[158:159], 0, s[46:47]
	s_mov_b32 m0, s50
	s_nop 0
	global_load_lds_dwordx4 v[158:159], off
	s_barrier
	s_waitcnt lgkmcnt(0)
	v_mfma_f32_16x16x32_bf16 v[124:127], v[134:137], v[180:183], v[124:127]
	v_mfma_f32_16x16x32_bf16 v[120:123], v[172:175], v[180:183], v[120:123]
	v_mfma_f32_16x16x32_bf16 v[116:119], v[134:137], v[188:191], v[116:119]
	v_mfma_f32_16x16x32_bf16 v[112:115], v[172:175], v[188:191], v[112:115]
	v_mfma_f32_16x16x32_bf16 v[108:111], v[134:137], v[196:199], v[108:111]
	v_mfma_f32_16x16x32_bf16 v[104:107], v[172:175], v[196:199], v[104:107]
	v_mfma_f32_16x16x32_bf16 v[100:103], v[134:137], v[204:207], v[100:103]
	v_mfma_f32_16x16x32_bf16 v[96:99], v[172:175], v[204:207], v[96:99]
	v_mfma_f32_16x16x32_bf16 v[124:127], v[138:141], v[184:187], v[124:127]
	v_mfma_f32_16x16x32_bf16 v[120:123], v[176:179], v[184:187], v[120:123]
	v_mfma_f32_16x16x32_bf16 v[116:119], v[138:141], v[192:195], v[116:119]
	v_mfma_f32_16x16x32_bf16 v[112:115], v[176:179], v[192:195], v[112:115]
	v_mfma_f32_16x16x32_bf16 v[108:111], v[138:141], v[200:203], v[108:111]
	v_mfma_f32_16x16x32_bf16 v[104:107], v[176:179], v[200:203], v[104:107]
	v_mfma_f32_16x16x32_bf16 v[100:103], v[138:141], v[208:211], v[100:103]
	v_mfma_f32_16x16x32_bf16 v[96:99], v[176:179], v[208:211], v[96:99]
	s_barrier
	ds_read_b128 v[212:215], v160
	ds_read_b128 v[216:219], v160 offset:1024
	ds_read_b128 v[220:223], v160 offset:2048
	ds_read_b128 v[158:161], v160 offset:3072
	s_barrier
; #define LDA(dst, b, h) for (int m = 0; m < 4; ++m) for (int k = 0; k < 2; ++k) \
;     dst[m][k] = *reinterpret_cast<const bf16x8*>((char*)SA(b, h) + lds_byte(wr * 64 + m * 16 + fr, k * 32 + fq * 8))
; #define LDB(dst, b, h) for (int n = 0; n < 2; ++n) for (int k = 0; k < 2; ++k) \
;     dst[n][k] = *reinterpret_cast<const bf16x8*>((char*)SB(b, h) + lds_byte(wc * 32 + n * 16 + fr, k * 32 + fq * 8))
; #define MMA(ai, bj, At_, Bt_) do { __builtin_amdgcn_s_setprio(1); \
;     for (int k = 0; k < 2; ++k) for (int m = 0; m < 4; ++m) for (int n = 0; n < 2; ++n) \
;       acc[ai][bj][m][n] = __builtin_amdgcn_mfma_f32_16x16x32_bf16(At_[m][k], Bt_[n][k], acc[ai][bj][m][n], 0, 0, 0); \
;     __builtin_amdgcn_s_setprio(0); } while (0)
; #define WAIT_V(n) asm volatile("s_waitcnt vmcnt(" #n ")" ::: "memory")
; #define WAIT_L(n) asm volatile("s_waitcnt lgkmcnt(" #n ")" ::: "memory")
; #define BAR __builtin_amdgcn_s_barrier()
; template <int EPI, int lda, int ldb, int N, int K>
; __device__ __forceinline__ void gemm_phase(const u16* __restrict__ A, const u16* __restrict__ Bt, const GemmEpi ep, int wv) {
;     ...
;       LDB(B1, 0, 1); BAR; WAIT_L(0); MMA(0, 1, At, B1); BAR;
;       LDA(At, 0, 1); WAIT_V(4); BAR; WAIT_L(0); MMA(1, 0, At, B0); MMA(1, 1, At, B1); BAR; }
;     { LDB(B0, 1, 0); LDA(At, 1, 0); WAIT_V(2); BAR; WAIT_L(0); MMA(0, 0, At, B0); BAR;
	s_waitcnt lgkmcnt(0)
	v_mfma_f32_16x16x32_bf16 v[92:95], v[212:215], v[180:183], v[92:95]
	v_mfma_f32_16x16x32_bf16 v[88:91], v[220:223], v[180:183], v[88:91]
	v_mfma_f32_16x16x32_bf16 v[76:79], v[212:215], v[196:199], v[76:79]
	v_mfma_f32_16x16x32_bf16 v[72:75], v[220:223], v[196:199], v[72:75]
	v_mfma_f32_16x16x32_bf16 v[84:87], v[212:215], v[188:191], v[84:87]
	v_mfma_f32_16x16x32_bf16 v[80:83], v[220:223], v[188:191], v[80:83]
	v_mfma_f32_16x16x32_bf16 v[68:71], v[212:215], v[204:207], v[68:71]
	v_mfma_f32_16x16x32_bf16 v[64:67], v[220:223], v[204:207], v[64:67]
	v_mfma_f32_16x16x32_bf16 v[92:95], v[216:219], v[184:187], v[92:95]
	v_mfma_f32_16x16x32_bf16 v[88:91], v[158:161], v[184:187], v[88:91]
	v_mfma_f32_16x16x32_bf16 v[76:79], v[216:219], v[200:203], v[76:79]
	v_mfma_f32_16x16x32_bf16 v[72:75], v[158:161], v[200:203], v[72:75]
	v_mfma_f32_16x16x32_bf16 v[180:183], v[216:219], v[192:195], v[84:87]
	v_mfma_f32_16x16x32_bf16 v[184:187], v[158:161], v[192:195], v[80:83]
	v_mfma_f32_16x16x32_bf16 v[188:191], v[216:219], v[208:211], v[68:71]
	v_mfma_f32_16x16x32_bf16 v[192:195], v[158:161], v[208:211], v[64:67]
	s_barrier
	s_nop 0
	ds_read_b128 v[64:67], v152 offset:16384
	ds_read_b128 v[68:71], v152 offset:17408
	ds_read_b128 v[80:83], v151 offset:16384
	ds_read_b128 v[84:87], v151 offset:17408
	ds_read_b128 v[196:199], v150 offset:16384
	ds_read_b128 v[200:203], v150 offset:17408
	ds_read_b128 v[204:207], v149 offset:16384
	ds_read_b128 v[208:211], v149 offset:17408
	s_waitcnt vmcnt(4)
	s_barrier
	s_waitcnt lgkmcnt(0)
	v_mfma_f32_16x16x32_bf16 v[60:63], v[134:137], v[64:67], v[60:63]
	v_mfma_f32_16x16x32_bf16 v[56:59], v[172:175], v[64:67], v[56:59]
	v_mfma_f32_16x16x32_bf16 v[52:55], v[134:137], v[80:83], v[52:55]
	v_mfma_f32_16x16x32_bf16 v[48:51], v[172:175], v[80:83], v[48:51]
	v_mfma_f32_16x16x32_bf16 v[44:47], v[134:137], v[196:199], v[44:47]
	v_mfma_f32_16x16x32_bf16 v[40:43], v[172:175], v[196:199], v[40:43]
	v_mfma_f32_16x16x32_bf16 v[36:39], v[134:137], v[204:207], v[36:39]
	v_mfma_f32_16x16x32_bf16 v[32:35], v[172:175], v[204:207], v[32:35]
	v_mfma_f32_16x16x32_bf16 v[60:63], v[138:141], v[68:71], v[60:63]
	v_mfma_f32_16x16x32_bf16 v[56:59], v[176:179], v[68:71], v[56:59]
	v_mfma_f32_16x16x32_bf16 v[52:55], v[138:141], v[84:87], v[52:55]
	v_mfma_f32_16x16x32_bf16 v[48:51], v[176:179], v[84:87], v[48:51]
	v_mfma_f32_16x16x32_bf16 v[44:47], v[138:141], v[200:203], v[44:47]
	v_mfma_f32_16x16x32_bf16 v[40:43], v[176:179], v[200:203], v[40:43]
	v_mfma_f32_16x16x32_bf16 v[36:39], v[138:141], v[208:211], v[36:39]
	v_mfma_f32_16x16x32_bf16 v[32:35], v[176:179], v[208:211], v[32:35]
	v_mfma_f32_16x16x32_bf16 v[28:31], v[212:215], v[64:67], v[28:31]
	v_mfma_f32_16x16x32_bf16 v[24:27], v[220:223], v[64:67], v[24:27]
	v_mfma_f32_16x16x32_bf16 v[12:15], v[212:215], v[196:199], v[12:15]
	v_mfma_f32_16x16x32_bf16 v[8:11], v[220:223], v[196:199], v[8:11]
	v_mfma_f32_16x16x32_bf16 v[20:23], v[212:215], v[80:83], v[20:23]
	v_mfma_f32_16x16x32_bf16 v[16:19], v[220:223], v[80:83], v[16:19]
	v_mfma_f32_16x16x32_bf16 v[4:7], v[212:215], v[204:207], v[4:7]
	v_mfma_f32_16x16x32_bf16 v[0:3], v[220:223], v[204:207], v[0:3]
	v_mfma_f32_16x16x32_bf16 v[28:31], v[216:219], v[68:71], v[28:31]
	v_mfma_f32_16x16x32_bf16 v[24:27], v[158:161], v[68:71], v[24:27]
	v_mfma_f32_16x16x32_bf16 v[12:15], v[216:219], v[200:203], v[12:15]
	v_mfma_f32_16x16x32_bf16 v[8:11], v[158:161], v[200:203], v[8:11]
	v_mfma_f32_16x16x32_bf16 v[134:137], v[216:219], v[84:87], v[20:23]
	v_mfma_f32_16x16x32_bf16 v[138:141], v[158:161], v[84:87], v[16:19]
	v_mfma_f32_16x16x32_bf16 v[170:173], v[216:219], v[208:211], v[4:7]
	v_mfma_f32_16x16x32_bf16 v[158:161], v[158:161], v[208:211], v[0:3]
	s_barrier
	s_nop 0
	ds_read_b128 v[0:3], v156
	ds_read_b128 v[4:7], v156 offset:1024
	ds_read_b128 v[16:19], v156 offset:2048
	ds_read_b128 v[174:177], v156 offset:3072
	ds_read_b128 v[20:23], v152 offset:32768
	ds_read_b128 v[196:199], v152 offset:33792
	ds_read_b128 v[200:203], v151 offset:32768
	ds_read_b128 v[204:207], v151 offset:33792
	ds_read_b128 v[208:211], v150 offset:32768
	ds_read_b128 v[212:215], v150 offset:33792
	ds_read_b128 v[216:219], v149 offset:32768
	ds_read_b128 v[220:223], v149 offset:33792
	s_waitcnt vmcnt(2)
	s_barrier
; #define LDA(dst, b, h) for (int m = 0; m < 4; ++m) for (int k = 0; k < 2; ++k) \
;     dst[m][k] = *reinterpret_cast<const bf16x8*>((char*)SA(b, h) + lds_byte(wr * 64 + m * 16 + fr, k * 32 + fq * 8))
; #define LDB(dst, b, h) for (int n = 0; n < 2; ++n) for (int k = 0; k < 2; ++k) \
;     dst[n][k] = *reinterpret_cast<const bf16x8*>((char*)SB(b, h) + lds_byte(wc * 32 + n * 16 + fr, k * 32 + fq * 8))
; #define MMA(ai, bj, At_, Bt_) do { __builtin_amdgcn_s_setprio(1); \
;     for (int k = 0; k < 2; ++k) for (int m = 0; m < 4; ++m) for (int n = 0; n < 2; ++n) \
;       acc[ai][bj][m][n] = __builtin_amdgcn_mfma_f32_16x16x32_bf16(At_[m][k], Bt_[n][k], acc[ai][bj][m][n], 0, 0, 0); \
;     __builtin_amdgcn_s_setprio(0); } while (0)
; #define WAIT_V(n) asm volatile("s_waitcnt vmcnt(" #n ")" ::: "memory")
; #define WAIT_L(n) asm volatile("s_waitcnt lgkmcnt(" #n ")" ::: "memory")
; #define BAR __builtin_amdgcn_s_barrier()
; template <int EPI, int lda, int ldb, int N, int K>
; __device__ __forceinline__ void gemm_phase(const u16* __restrict__ A, const u16* __restrict__ Bt, const GemmEpi ep, int wv) {
;     ...
;     { LDB(B0, 1, 0); LDA(At, 1, 0); WAIT_V(2); BAR; WAIT_L(0); MMA(0, 0, At, B0); BAR;
;       LDB(B1, 1, 1); WAIT_V(0); BAR; WAIT_L(0); MMA(0, 1, At, B1); BAR;
;       LDA(At, 1, 1); BAR; WAIT_L(0); MMA(1, 0, At, B0); MMA(1, 1, At, B1); BAR; }
;     if (wr == 0) BAR;
	s_waitcnt lgkmcnt(0)
	v_mfma_f32_16x16x32_bf16 v[64:67], v[0:3], v[20:23], v[124:127]
	v_mfma_f32_16x16x32_bf16 v[68:71], v[16:19], v[20:23], v[120:123]
	v_mfma_f32_16x16x32_bf16 v[80:83], v[0:3], v[200:203], v[116:119]
	v_mfma_f32_16x16x32_bf16 v[84:87], v[16:19], v[200:203], v[112:115]
	v_mfma_f32_16x16x32_bf16 v[108:111], v[0:3], v[208:211], v[108:111]
	v_mfma_f32_16x16x32_bf16 v[104:107], v[16:19], v[208:211], v[104:107]
	v_mfma_f32_16x16x32_bf16 v[120:123], v[0:3], v[216:219], v[100:103]
	v_mfma_f32_16x16x32_bf16 v[124:127], v[16:19], v[216:219], v[96:99]
	v_mfma_f32_16x16x32_bf16 v[116:119], v[4:7], v[196:199], v[64:67]
	v_mfma_f32_16x16x32_bf16 v[112:115], v[174:177], v[196:199], v[68:71]
	v_mfma_f32_16x16x32_bf16 v[100:103], v[4:7], v[204:207], v[80:83]
	v_mfma_f32_16x16x32_bf16 v[96:99], v[174:177], v[204:207], v[84:87]
	v_mfma_f32_16x16x32_bf16 v[84:87], v[4:7], v[212:215], v[108:111]
	v_mfma_f32_16x16x32_bf16 v[80:83], v[174:177], v[212:215], v[104:107]
	v_mfma_f32_16x16x32_bf16 v[68:71], v[4:7], v[220:223], v[120:123]
	v_mfma_f32_16x16x32_bf16 v[64:67], v[174:177], v[220:223], v[124:127]
	s_barrier
	ds_read_b128 v[224:227], v154
	ds_read_b128 v[228:231], v154 offset:1024
	ds_read_b128 v[232:235], v154 offset:2048
	ds_read_b128 v[154:157], v154 offset:3072
	s_waitcnt vmcnt(0)
	s_barrier
	s_waitcnt lgkmcnt(0)
	v_mfma_f32_16x16x32_bf16 v[92:95], v[224:227], v[20:23], v[92:95]
	v_mfma_f32_16x16x32_bf16 v[20:23], v[232:235], v[20:23], v[88:91]
	v_mfma_f32_16x16x32_bf16 v[88:91], v[224:227], v[200:203], v[180:183]
	v_mfma_f32_16x16x32_bf16 v[104:107], v[232:235], v[200:203], v[184:187]
	v_mfma_f32_16x16x32_bf16 v[76:79], v[224:227], v[208:211], v[76:79]
	v_mfma_f32_16x16x32_bf16 v[72:75], v[232:235], v[208:211], v[72:75]
	v_mfma_f32_16x16x32_bf16 v[178:181], v[224:227], v[216:219], v[188:191]
	v_mfma_f32_16x16x32_bf16 v[182:185], v[232:235], v[216:219], v[192:195]
	v_mfma_f32_16x16x32_bf16 v[124:127], v[228:231], v[196:199], v[92:95]
	v_mfma_f32_16x16x32_bf16 v[120:123], v[154:157], v[196:199], v[20:23]
	v_mfma_f32_16x16x32_bf16 v[108:111], v[228:231], v[204:207], v[88:91]
	v_mfma_f32_16x16x32_bf16 v[104:107], v[154:157], v[204:207], v[104:107]
	v_mfma_f32_16x16x32_bf16 v[92:95], v[228:231], v[212:215], v[76:79]
	v_mfma_f32_16x16x32_bf16 v[88:91], v[154:157], v[212:215], v[72:75]
	v_mfma_f32_16x16x32_bf16 v[76:79], v[228:231], v[220:223], v[178:181]
	v_mfma_f32_16x16x32_bf16 v[72:75], v[154:157], v[220:223], v[182:185]
	s_barrier
	ds_read_b128 v[178:181], v152 offset:49152
	ds_read_b128 v[182:185], v152 offset:50176
	ds_read_b128 v[186:189], v151 offset:49152
	ds_read_b128 v[190:193], v151 offset:50176
	ds_read_b128 v[194:197], v150 offset:49152
	ds_read_b128 v[150:153], v150 offset:50176
	ds_read_b128 v[198:201], v149 offset:49152
	ds_read_b128 v[202:205], v149 offset:50176
	s_barrier
	s_waitcnt lgkmcnt(0)
	v_mfma_f32_16x16x32_bf16 v[20:23], v[0:3], v[178:181], v[60:63]
	v_mfma_f32_16x16x32_bf16 v[56:59], v[16:19], v[178:181], v[56:59]
	v_mfma_f32_16x16x32_bf16 v[60:63], v[0:3], v[186:189], v[52:55]
	v_mfma_f32_16x16x32_bf16 v[206:209], v[16:19], v[186:189], v[48:51]
	v_mfma_f32_16x16x32_bf16 v[44:47], v[0:3], v[194:197], v[44:47]
	v_mfma_f32_16x16x32_bf16 v[40:43], v[16:19], v[194:197], v[40:43]
	v_mfma_f32_16x16x32_bf16 v[0:3], v[0:3], v[198:201], v[36:39]
	v_mfma_f32_16x16x32_bf16 v[210:213], v[16:19], v[198:201], v[32:35]
	v_mfma_f32_16x16x32_bf16 v[52:55], v[4:7], v[182:185], v[20:23]
	v_mfma_f32_16x16x32_bf16 v[48:51], v[174:177], v[182:185], v[56:59]
	v_mfma_f32_16x16x32_bf16 v[36:39], v[4:7], v[190:193], v[60:63]
	v_mfma_f32_16x16x32_bf16 v[32:35], v[174:177], v[190:193], v[206:209]
	v_mfma_f32_16x16x32_bf16 v[20:23], v[4:7], v[150:153], v[44:47]
	v_mfma_f32_16x16x32_bf16 v[16:19], v[174:177], v[150:153], v[40:43]
	v_mfma_f32_16x16x32_bf16 v[4:7], v[4:7], v[202:205], v[0:3]
	v_mfma_f32_16x16x32_bf16 v[0:3], v[174:177], v[202:205], v[210:213]
	v_mfma_f32_16x16x32_bf16 v[28:31], v[224:227], v[178:181], v[28:31]
	v_mfma_f32_16x16x32_bf16 v[24:27], v[232:235], v[178:181], v[24:27]
	v_mfma_f32_16x16x32_bf16 v[40:43], v[224:227], v[186:189], v[134:137]
	v_mfma_f32_16x16x32_bf16 v[134:137], v[232:235], v[186:189], v[138:141]
	v_mfma_f32_16x16x32_bf16 v[12:15], v[224:227], v[194:197], v[12:15]
	v_mfma_f32_16x16x32_bf16 v[8:11], v[232:235], v[194:197], v[8:11]
	v_mfma_f32_16x16x32_bf16 v[138:141], v[224:227], v[198:201], v[170:173]
	v_mfma_f32_16x16x32_bf16 v[158:161], v[232:235], v[198:201], v[158:161]
	v_mfma_f32_16x16x32_bf16 v[60:63], v[228:231], v[182:185], v[28:31]
	v_mfma_f32_16x16x32_bf16 v[56:59], v[154:157], v[182:185], v[24:27]
	v_mfma_f32_16x16x32_bf16 v[44:47], v[228:231], v[190:193], v[40:43]
	v_mfma_f32_16x16x32_bf16 v[40:43], v[154:157], v[190:193], v[134:137]
	v_mfma_f32_16x16x32_bf16 v[28:31], v[228:231], v[150:153], v[12:15]
	v_mfma_f32_16x16x32_bf16 v[24:27], v[154:157], v[150:153], v[8:11]
	v_mfma_f32_16x16x32_bf16 v[12:15], v[228:231], v[202:205], v[138:141]
	v_mfma_f32_16x16x32_bf16 v[8:11], v[154:157], v[202:205], v[158:161]
	v_cmp_gt_u32_e32 vcc, s66, v130
	s_barrier
	s_and_saveexec_b64 s[50:51], vcc
	s_cbranch_execz .LBB0_773
	s_barrier

; #define STAGE(P, BASE, LD, br, kt) do { const char* _g = (const char*)((BASE) + (size_t)(br) * (LD) + (size_t)(kt) * 64); \
;     for (int _i = 0; _i < 2; ++_i) { int _b = tidx * 16 + _i * 8192; int _r, _c; stage_rc(_b, _r, _c); \
;       __builtin_amdgcn_global_load_lds((const unsigned*)(_g + (unsigned)((_r * (LD) + _c) * 2)), (unsigned*)((char*)(P) + _b), 16, 0, 0); } } while (0)
; #define LDA(dst, b, h) for (int m = 0; m < 4; ++m) for (int k = 0; k < 2; ++k) \
;     dst[m][k] = *reinterpret_cast<const bf16x8*>((char*)SA(b, h) + lds_byte(wr * 64 + m * 16 + fr, k * 32 + fq * 8))
; #define LDB(dst, b, h) for (int n = 0; n < 2; ++n) for (int k = 0; k < 2; ++k) \
;     dst[n][k] = *reinterpret_cast<const bf16x8*>((char*)SB(b, h) + lds_byte(wc * 32 + n * 16 + fr, k * 32 + fq * 8))
; #define MMA(ai, bj, At_, Bt_) do { __builtin_amdgcn_s_setprio(1); \
;     for (int k = 0; k < 2; ++k) for (int m = 0; m < 4; ++m) for (int n = 0; n < 2; ++n) \
;       acc[ai][bj][m][n] = __builtin_amdgcn_mfma_f32_16x16x32_bf16(At_[m][k], Bt_[n][k], acc[ai][bj][m][n], 0, 0, 0); \
;     __builtin_amdgcn_s_setprio(0); } while (0)
; #define WAIT_L(n) asm volatile("s_waitcnt lgkmcnt(" #n ")" ::: "memory")
; #define BAR __builtin_amdgcn_s_barrier()
; #define SCHED __builtin_amdgcn_sched_barrier(0)
; template <int EPI, int lda, int ldb, int N, int K>
; __device__ __forceinline__ void gemm_phase(const u16* __restrict__ A, const u16* __restrict__ Bt, const GemmEpi ep, int wv) {
;     ...
;     for (int t = 0; t < nt - 2; t += 2) {
;       LDB(B0, 0, 0); SCHED; LDA(At, 0, 0); STAGE(SA(1, 1), Ab, lda, brow + HALF, t + 1);
;       WAIT_L(8); BAR; WAIT_L(0); MMA(0, 0, At, B0); BAR; SCHED;
;       LDB(B1, 0, 1); STAGE(SB(0, 0), Bt, ldb, bcol, t + 2);
;       BAR; WAIT_L(0); MMA(0, 1, At, B1); BAR;
;       LDA(At, 0, 1); STAGE(SA(0, 0), Ab, lda, brow, t + 2);
;       BAR; WAIT_L(0); MMA(1, 0, At, B0); BAR; SCHED;
.LBB0_838:
	ds_read_b128 v[168:171], v164
	ds_read_b128 v[174:177], v164 offset:1024
	ds_read_b128 v[178:181], v164 offset:2048
	ds_read_b128 v[182:185], v164 offset:3072
	v_add_u32_e32 v172, 0xc000, v147
	v_lshl_add_u64 v[238:239], v[136:137], 0, s[50:51]
	v_readfirstlane_b32 s73, v172
	v_add_u32_e32 v173, 0xe000, v147
	v_lshl_add_u64 v[166:167], v[238:239], 0, s[22:23]
	s_mov_b32 m0, s73
	v_lshl_add_u64 v[240:241], v[134:135], 0, s[50:51]
	v_readfirstlane_b32 s73, v173
	ds_read_b128 v[186:189], v155
	ds_read_b128 v[190:193], v155 offset:1024
	ds_read_b128 v[194:197], v154
	ds_read_b128 v[198:201], v154 offset:1024
	ds_read_b128 v[202:205], v153
	ds_read_b128 v[206:209], v153 offset:1024
	ds_read_b128 v[210:213], v152
	ds_read_b128 v[214:217], v152 offset:1024
	global_load_lds_dwordx4 v[166:167], off
	v_lshl_add_u64 v[166:167], v[240:241], 0, s[22:23]
	s_mov_b32 m0, s73
	s_nop 0
	global_load_lds_dwordx4 v[166:167], off
	s_waitcnt lgkmcnt(8)
	s_barrier
	s_waitcnt lgkmcnt(0)
	v_mfma_f32_16x16x32_bf16 v[124:127], v[168:171], v[186:189], v[124:127]
	v_mfma_f32_16x16x32_bf16 v[120:123], v[178:181], v[186:189], v[120:123]
	v_mfma_f32_16x16x32_bf16 v[116:119], v[168:171], v[194:197], v[116:119]
	v_mfma_f32_16x16x32_bf16 v[112:115], v[178:181], v[194:197], v[112:115]
	v_mfma_f32_16x16x32_bf16 v[108:111], v[168:171], v[202:205], v[108:111]
	v_mfma_f32_16x16x32_bf16 v[104:107], v[178:181], v[202:205], v[104:107]
	v_mfma_f32_16x16x32_bf16 v[100:103], v[168:171], v[210:213], v[100:103]
	v_mfma_f32_16x16x32_bf16 v[96:99], v[178:181], v[210:213], v[96:99]
	v_mfma_f32_16x16x32_bf16 v[124:127], v[174:177], v[190:193], v[124:127]
	v_mfma_f32_16x16x32_bf16 v[120:123], v[182:185], v[190:193], v[120:123]
	v_mfma_f32_16x16x32_bf16 v[116:119], v[174:177], v[198:201], v[116:119]
	v_mfma_f32_16x16x32_bf16 v[112:115], v[182:185], v[198:201], v[112:115]
	v_mfma_f32_16x16x32_bf16 v[108:111], v[174:177], v[206:209], v[108:111]
	v_mfma_f32_16x16x32_bf16 v[104:107], v[182:185], v[206:209], v[104:107]
	v_mfma_f32_16x16x32_bf16 v[100:103], v[174:177], v[214:217], v[100:103]
	v_mfma_f32_16x16x32_bf16 v[96:99], v[182:185], v[214:217], v[96:99]
	s_barrier
	v_add_u32_e32 v165, s63, v156
	v_lshl_add_u64 v[242:243], v[144:145], 0, s[50:51]
	v_readfirstlane_b32 s73, v165
	v_lshl_add_u64 v[166:167], v[242:243], 0, s[24:25]
	s_mov_b32 m0, s73
	ds_read_b128 v[218:221], v163
	ds_read_b128 v[222:225], v163 offset:1024
	ds_read_b128 v[226:229], v163 offset:2048
	ds_read_b128 v[230:233], v163 offset:3072
	global_load_lds_dwordx4 v[166:167], off
	v_add_u32_e32 v166, 0x2000, v165
	v_lshl_add_u64 v[244:245], v[142:143], 0, s[50:51]
	v_readfirstlane_b32 s73, v166
	v_lshl_add_u64 v[234:235], v[244:245], 0, s[24:25]
	s_mov_b32 m0, s73
	s_nop 0
	global_load_lds_dwordx4 v[234:235], off
	s_barrier
	s_waitcnt lgkmcnt(0)
	v_mfma_f32_16x16x32_bf16 v[92:95], v[218:221], v[186:189], v[92:95]
	v_mfma_f32_16x16x32_bf16 v[88:91], v[226:229], v[186:189], v[88:91]
	v_mfma_f32_16x16x32_bf16 v[84:87], v[218:221], v[194:197], v[84:87]
	v_mfma_f32_16x16x32_bf16 v[80:83], v[226:229], v[194:197], v[80:83]
	v_mfma_f32_16x16x32_bf16 v[76:79], v[218:221], v[202:205], v[76:79]
	v_mfma_f32_16x16x32_bf16 v[72:75], v[226:229], v[202:205], v[72:75]
	v_mfma_f32_16x16x32_bf16 v[68:71], v[218:221], v[210:213], v[68:71]
	v_mfma_f32_16x16x32_bf16 v[64:67], v[226:229], v[210:213], v[64:67]
	v_mfma_f32_16x16x32_bf16 v[92:95], v[222:225], v[190:193], v[92:95]
	v_mfma_f32_16x16x32_bf16 v[88:91], v[230:233], v[190:193], v[88:91]
	v_mfma_f32_16x16x32_bf16 v[84:87], v[222:225], v[198:201], v[84:87]
	v_mfma_f32_16x16x32_bf16 v[80:83], v[230:233], v[198:201], v[80:83]
	v_mfma_f32_16x16x32_bf16 v[76:79], v[222:225], v[206:209], v[76:79]
	v_mfma_f32_16x16x32_bf16 v[72:75], v[230:233], v[206:209], v[72:75]
	v_mfma_f32_16x16x32_bf16 v[68:71], v[222:225], v[214:217], v[68:71]
	v_mfma_f32_16x16x32_bf16 v[64:67], v[230:233], v[214:217], v[64:67]
	v_readfirstlane_b32 s73, v147
	v_add_u32_e32 v167, 0x2000, v147
	v_lshl_add_u64 v[234:235], v[238:239], 0, s[26:27]
	s_mov_b32 m0, s73
	v_readfirstlane_b32 s73, v167
	s_barrier
	ds_read_b128 v[186:189], v155 offset:16384
	ds_read_b128 v[190:193], v155 offset:17408
	ds_read_b128 v[194:197], v154 offset:16384
	ds_read_b128 v[198:201], v154 offset:17408
	ds_read_b128 v[202:205], v153 offset:16384
	ds_read_b128 v[206:209], v153 offset:17408
	ds_read_b128 v[210:213], v152 offset:16384
	ds_read_b128 v[214:217], v152 offset:17408
	global_load_lds_dwordx4 v[234:235], off
	v_lshl_add_u64 v[234:235], v[240:241], 0, s[26:27]
	s_mov_b32 m0, s73
	s_nop 0
	global_load_lds_dwordx4 v[234:235], off
	s_barrier
	s_waitcnt lgkmcnt(0)
	v_mfma_f32_16x16x32_bf16 v[60:63], v[168:171], v[186:189], v[60:63]
	v_mfma_f32_16x16x32_bf16 v[56:59], v[178:181], v[186:189], v[56:59]
	v_mfma_f32_16x16x32_bf16 v[52:55], v[168:171], v[194:197], v[52:55]
	v_mfma_f32_16x16x32_bf16 v[48:51], v[178:181], v[194:197], v[48:51]
	v_mfma_f32_16x16x32_bf16 v[44:47], v[168:171], v[202:205], v[44:47]
	v_mfma_f32_16x16x32_bf16 v[40:43], v[178:181], v[202:205], v[40:43]
	v_mfma_f32_16x16x32_bf16 v[36:39], v[168:171], v[210:213], v[36:39]
	v_mfma_f32_16x16x32_bf16 v[32:35], v[178:181], v[210:213], v[32:35]
	v_mfma_f32_16x16x32_bf16 v[60:63], v[174:177], v[190:193], v[60:63]
	v_mfma_f32_16x16x32_bf16 v[56:59], v[182:185], v[190:193], v[56:59]
	v_mfma_f32_16x16x32_bf16 v[52:55], v[174:177], v[198:201], v[52:55]
	v_mfma_f32_16x16x32_bf16 v[48:51], v[182:185], v[198:201], v[48:51]
	v_mfma_f32_16x16x32_bf16 v[44:47], v[174:177], v[206:209], v[44:47]
	v_mfma_f32_16x16x32_bf16 v[40:43], v[182:185], v[206:209], v[40:43]
	v_mfma_f32_16x16x32_bf16 v[36:39], v[174:177], v[214:217], v[36:39]
	v_mfma_f32_16x16x32_bf16 v[32:35], v[182:185], v[214:217], v[32:35]
	s_barrier
; #define STAGE(P, BASE, LD, br, kt) do { const char* _g = (const char*)((BASE) + (size_t)(br) * (LD) + (size_t)(kt) * 64); \
;     for (int _i = 0; _i < 2; ++_i) { int _b = tidx * 16 + _i * 8192; int _r, _c; stage_rc(_b, _r, _c); \
;       __builtin_amdgcn_global_load_lds((const unsigned*)(_g + (unsigned)((_r * (LD) + _c) * 2)), (unsigned*)((char*)(P) + _b), 16, 0, 0); } } while (0)
; #define LDA(dst, b, h) for (int m = 0; m < 4; ++m) for (int k = 0; k < 2; ++k) \
;     dst[m][k] = *reinterpret_cast<const bf16x8*>((char*)SA(b, h) + lds_byte(wr * 64 + m * 16 + fr, k * 32 + fq * 8))
; #define LDB(dst, b, h) for (int n = 0; n < 2; ++n) for (int k = 0; k < 2; ++k) \
;     dst[n][k] = *reinterpret_cast<const bf16x8*>((char*)SB(b, h) + lds_byte(wc * 32 + n * 16 + fr, k * 32 + fq * 8))
; #define MMA(ai, bj, At_, Bt_) do { __builtin_amdgcn_s_setprio(1); \
;     for (int k = 0; k < 2; ++k) for (int m = 0; m < 4; ++m) for (int n = 0; n < 2; ++n) \
;       acc[ai][bj][m][n] = __builtin_amdgcn_mfma_f32_16x16x32_bf16(At_[m][k], Bt_[n][k], acc[ai][bj][m][n], 0, 0, 0); \
;     __builtin_amdgcn_s_setprio(0); } while (0)
; #define WAIT_V(n) asm volatile("s_waitcnt vmcnt(" #n ")" ::: "memory")
; #define WAIT_L(n) asm volatile("s_waitcnt lgkmcnt(" #n ")" ::: "memory")
; #define BAR __builtin_amdgcn_s_barrier()
; #define SCHED __builtin_amdgcn_sched_barrier(0)
; template <int EPI, int lda, int ldb, int N, int K>
; __device__ __forceinline__ void gemm_phase(const u16* __restrict__ A, const u16* __restrict__ Bt, const GemmEpi ep, int wv) {
;     ...
;       STAGE(SB(0, 1), Bt, ldb, bcol + HALF, t + 2);
;       WAIT_V(6); BAR; MMA(1, 1, At, B1); BAR;
;       LDB(B0, 1, 0); SCHED; LDA(At, 1, 0); STAGE(SA(0, 1), Ab, lda, brow + HALF, t + 2);
;       WAIT_L(8); BAR; WAIT_L(0); MMA(0, 0, At, B0); BAR; SCHED;
;       LDB(B1, 1, 1); STAGE(SB(1, 0), Bt, ldb, bcol, t + 3);
;       BAR; WAIT_L(0); MMA(0, 1, At, B1); BAR;
;       LDA(At, 1, 1); STAGE(SA(1, 0), Ab, lda, brow, t + 3);
	v_add_u32_e32 v168, s64, v156
	v_lshl_add_u64 v[246:247], v[140:141], 0, s[50:51]
	v_readfirstlane_b32 s73, v168
	v_add_u32_e32 v169, 0x2000, v168
	v_lshl_add_u64 v[170:171], v[246:247], 0, s[40:41]
	s_mov_b32 m0, s73
	v_lshl_add_u64 v[248:249], v[138:139], 0, s[50:51]
	v_readfirstlane_b32 s73, v169
	global_load_lds_dwordx4 v[170:171], off
	v_lshl_add_u64 v[170:171], v[248:249], 0, s[40:41]
	s_mov_b32 m0, s73
	s_nop 0
	global_load_lds_dwordx4 v[170:171], off
	s_waitcnt vmcnt(6)
	s_barrier
	v_mfma_f32_16x16x32_bf16 v[28:31], v[218:221], v[186:189], v[28:31]
	v_mfma_f32_16x16x32_bf16 v[24:27], v[226:229], v[186:189], v[24:27]
	v_mfma_f32_16x16x32_bf16 v[20:23], v[218:221], v[194:197], v[20:23]
	v_mfma_f32_16x16x32_bf16 v[16:19], v[226:229], v[194:197], v[16:19]
	v_mfma_f32_16x16x32_bf16 v[12:15], v[218:221], v[202:205], v[12:15]
	v_mfma_f32_16x16x32_bf16 v[8:11], v[226:229], v[202:205], v[8:11]
	v_mfma_f32_16x16x32_bf16 v[4:7], v[218:221], v[210:213], v[4:7]
	v_mfma_f32_16x16x32_bf16 v[0:3], v[226:229], v[210:213], v[0:3]
	v_mfma_f32_16x16x32_bf16 v[28:31], v[222:225], v[190:193], v[28:31]
	v_mfma_f32_16x16x32_bf16 v[24:27], v[230:233], v[190:193], v[24:27]
	v_mfma_f32_16x16x32_bf16 v[20:23], v[222:225], v[198:201], v[20:23]
	v_mfma_f32_16x16x32_bf16 v[16:19], v[230:233], v[198:201], v[16:19]
	v_mfma_f32_16x16x32_bf16 v[12:15], v[222:225], v[206:209], v[12:15]
	v_mfma_f32_16x16x32_bf16 v[8:11], v[230:233], v[206:209], v[8:11]
	v_mfma_f32_16x16x32_bf16 v[4:7], v[222:225], v[214:217], v[4:7]
	v_mfma_f32_16x16x32_bf16 v[0:3], v[230:233], v[214:217], v[0:3]
	s_barrier
	ds_read_b128 v[174:177], v159
	ds_read_b128 v[178:181], v159 offset:1024
	ds_read_b128 v[182:185], v159 offset:2048
	ds_read_b128 v[186:189], v159 offset:3072
	v_add_u32_e32 v170, 0x4000, v147
	v_add_u32_e32 v171, 0x6000, v147
	v_readfirstlane_b32 s73, v170
	v_lshl_add_u64 v[222:223], v[238:239], 0, s[42:43]
	s_mov_b32 m0, s73
	v_readfirstlane_b32 s73, v171
	ds_read_b128 v[190:193], v155 offset:32768
	ds_read_b128 v[194:197], v155 offset:33792
	ds_read_b128 v[198:201], v154 offset:32768
	ds_read_b128 v[202:205], v154 offset:33792
	ds_read_b128 v[206:209], v153 offset:32768
	ds_read_b128 v[210:213], v153 offset:33792
	ds_read_b128 v[214:217], v152 offset:32768
	ds_read_b128 v[218:221], v152 offset:33792
	global_load_lds_dwordx4 v[222:223], off
	v_lshl_add_u64 v[222:223], v[240:241], 0, s[42:43]
	s_mov_b32 m0, s73
	s_nop 0
	global_load_lds_dwordx4 v[222:223], off
	s_waitcnt lgkmcnt(8)
	s_barrier
	s_waitcnt lgkmcnt(0)
	v_mfma_f32_16x16x32_bf16 v[124:127], v[174:177], v[190:193], v[124:127]
	v_mfma_f32_16x16x32_bf16 v[120:123], v[182:185], v[190:193], v[120:123]
	v_mfma_f32_16x16x32_bf16 v[116:119], v[174:177], v[198:201], v[116:119]
	v_mfma_f32_16x16x32_bf16 v[112:115], v[182:185], v[198:201], v[112:115]
	v_mfma_f32_16x16x32_bf16 v[108:111], v[174:177], v[206:209], v[108:111]
	v_mfma_f32_16x16x32_bf16 v[104:107], v[182:185], v[206:209], v[104:107]
	v_mfma_f32_16x16x32_bf16 v[100:103], v[174:177], v[214:217], v[100:103]
	v_mfma_f32_16x16x32_bf16 v[96:99], v[182:185], v[214:217], v[96:99]
	v_mfma_f32_16x16x32_bf16 v[124:127], v[178:181], v[194:197], v[124:127]
	v_mfma_f32_16x16x32_bf16 v[120:123], v[186:189], v[194:197], v[120:123]
	v_mfma_f32_16x16x32_bf16 v[116:119], v[178:181], v[202:205], v[116:119]
	v_mfma_f32_16x16x32_bf16 v[112:115], v[186:189], v[202:205], v[112:115]
	v_mfma_f32_16x16x32_bf16 v[108:111], v[178:181], v[210:213], v[108:111]
	v_mfma_f32_16x16x32_bf16 v[104:107], v[186:189], v[210:213], v[104:107]
	v_mfma_f32_16x16x32_bf16 v[100:103], v[178:181], v[218:221], v[100:103]
	v_mfma_f32_16x16x32_bf16 v[96:99], v[186:189], v[218:221], v[96:99]
	s_barrier
	v_readfirstlane_b32 s73, v158
	v_lshl_add_u64 v[242:243], v[242:243], 0, s[44:45]
	s_mov_b32 m0, s73
	ds_read_b128 v[222:225], v157
	ds_read_b128 v[226:229], v157 offset:1024
	ds_read_b128 v[230:233], v157 offset:2048
	ds_read_b128 v[234:237], v157 offset:3072
	global_load_lds_dwordx4 v[242:243], off
	v_lshl_add_u64 v[242:243], v[244:245], 0, s[44:45]
	v_add_u32_e32 v244, 0x2000, v158
	s_nop 0
	v_readfirstlane_b32 s73, v244
	s_mov_b32 m0, s73
	s_nop 0
	global_load_lds_dwordx4 v[242:243], off
	s_barrier
	s_waitcnt lgkmcnt(0)
	v_mfma_f32_16x16x32_bf16 v[92:95], v[222:225], v[190:193], v[92:95]
	v_mfma_f32_16x16x32_bf16 v[88:91], v[230:233], v[190:193], v[88:91]
	v_mfma_f32_16x16x32_bf16 v[84:87], v[222:225], v[198:201], v[84:87]
	v_mfma_f32_16x16x32_bf16 v[80:83], v[230:233], v[198:201], v[80:83]
	v_mfma_f32_16x16x32_bf16 v[76:79], v[222:225], v[206:209], v[76:79]
	v_mfma_f32_16x16x32_bf16 v[72:75], v[230:233], v[206:209], v[72:75]
	v_mfma_f32_16x16x32_bf16 v[68:71], v[222:225], v[214:217], v[68:71]
	v_mfma_f32_16x16x32_bf16 v[64:67], v[230:233], v[214:217], v[64:67]
	v_mfma_f32_16x16x32_bf16 v[92:95], v[226:229], v[194:197], v[92:95]
	v_mfma_f32_16x16x32_bf16 v[88:91], v[234:237], v[194:197], v[88:91]
	v_mfma_f32_16x16x32_bf16 v[84:87], v[226:229], v[202:205], v[84:87]
	v_mfma_f32_16x16x32_bf16 v[80:83], v[234:237], v[202:205], v[80:83]
	v_mfma_f32_16x16x32_bf16 v[76:79], v[226:229], v[210:213], v[76:79]
	v_mfma_f32_16x16x32_bf16 v[72:75], v[234:237], v[210:213], v[72:75]
	v_mfma_f32_16x16x32_bf16 v[68:71], v[226:229], v[218:221], v[68:71]
	v_mfma_f32_16x16x32_bf16 v[64:67], v[234:237], v[218:221], v[64:67]
	v_readfirstlane_b32 s73, v160
	v_lshl_add_u64 v[238:239], v[238:239], 0, s[46:47]
	s_mov_b32 m0, s73
	v_readfirstlane_b32 s73, v161
	s_barrier
; #define STAGE(P, BASE, LD, br, kt) do { const char* _g = (const char*)((BASE) + (size_t)(br) * (LD) + (size_t)(kt) * 64); \
;     for (int _i = 0; _i < 2; ++_i) { int _b = tidx * 16 + _i * 8192; int _r, _c; stage_rc(_b, _r, _c); \
;       __builtin_amdgcn_global_load_lds((const unsigned*)(_g + (unsigned)((_r * (LD) + _c) * 2)), (unsigned*)((char*)(P) + _b), 16, 0, 0); } } while (0)
; #define LDA(dst, b, h) for (int m = 0; m < 4; ++m) for (int k = 0; k < 2; ++k) \
;     dst[m][k] = *reinterpret_cast<const bf16x8*>((char*)SA(b, h) + lds_byte(wr * 64 + m * 16 + fr, k * 32 + fq * 8))
; #define LDB(dst, b, h) for (int n = 0; n < 2; ++n) for (int k = 0; k < 2; ++k) \
;     dst[n][k] = *reinterpret_cast<const bf16x8*>((char*)SB(b, h) + lds_byte(wc * 32 + n * 16 + fr, k * 32 + fq * 8))
; #define MMA(ai, bj, At_, Bt_) do { __builtin_amdgcn_s_setprio(1); \
;     for (int k = 0; k < 2; ++k) for (int m = 0; m < 4; ++m) for (int n = 0; n < 2; ++n) \
;       acc[ai][bj][m][n] = __builtin_amdgcn_mfma_f32_16x16x32_bf16(At_[m][k], Bt_[n][k], acc[ai][bj][m][n], 0, 0, 0); \
;     __builtin_amdgcn_s_setprio(0); } while (0)
; #define WAIT_V(n) asm volatile("s_waitcnt vmcnt(" #n ")" ::: "memory")
; #define WAIT_L(n) asm volatile("s_waitcnt lgkmcnt(" #n ")" ::: "memory")
; #define BAR __builtin_amdgcn_s_barrier()
; #define SCHED __builtin_amdgcn_sched_barrier(0)
; template <int EPI, int lda, int ldb, int N, int K>
; __device__ __forceinline__ void gemm_phase(const u16* __restrict__ A, const u16* __restrict__ Bt, const GemmEpi ep, int wv) {
;     ...
;       LDA(At, 1, 1); STAGE(SA(1, 0), Ab, lda, brow, t + 3);
;       BAR; WAIT_L(0); MMA(1, 0, At, B0); BAR; SCHED;
;       STAGE(SB(1, 1), Bt, ldb, bcol + HALF, t + 3);
;       WAIT_V(6); BAR; MMA(1, 1, At, B1); BAR;
;     }
;     { LDB(B0, 0, 0); LDA(At, 0, 0); STAGE(SA(1, 1), Ab, lda, brow + HALF, nt - 1);
;       BAR; WAIT_L(0); MMA(0, 0, At, B0); BAR;
;       LDB(B1, 0, 1); BAR; WAIT_L(0); MMA(0, 1, At, B1); BAR;
	ds_read_b128 v[190:193], v155 offset:49152
	ds_read_b128 v[194:197], v155 offset:50176
	ds_read_b128 v[198:201], v154 offset:49152
	ds_read_b128 v[202:205], v154 offset:50176
	ds_read_b128 v[206:209], v153 offset:49152
	ds_read_b128 v[210:213], v153 offset:50176
	ds_read_b128 v[214:217], v152 offset:49152
	ds_read_b128 v[218:221], v152 offset:50176
	global_load_lds_dwordx4 v[238:239], off
	v_lshl_add_u64 v[238:239], v[240:241], 0, s[46:47]
	s_mov_b32 m0, s73
	s_nop 0
	global_load_lds_dwordx4 v[238:239], off
	s_barrier
	s_waitcnt lgkmcnt(0)
	v_mfma_f32_16x16x32_bf16 v[60:63], v[174:177], v[190:193], v[60:63]
	v_mfma_f32_16x16x32_bf16 v[56:59], v[182:185], v[190:193], v[56:59]
	v_mfma_f32_16x16x32_bf16 v[52:55], v[174:177], v[198:201], v[52:55]
	v_mfma_f32_16x16x32_bf16 v[48:51], v[182:185], v[198:201], v[48:51]
	v_mfma_f32_16x16x32_bf16 v[44:47], v[174:177], v[206:209], v[44:47]
	v_mfma_f32_16x16x32_bf16 v[40:43], v[182:185], v[206:209], v[40:43]
	v_mfma_f32_16x16x32_bf16 v[36:39], v[174:177], v[214:217], v[36:39]
	v_mfma_f32_16x16x32_bf16 v[32:35], v[182:185], v[214:217], v[32:35]
	v_mfma_f32_16x16x32_bf16 v[60:63], v[178:181], v[194:197], v[60:63]
	v_mfma_f32_16x16x32_bf16 v[56:59], v[186:189], v[194:197], v[56:59]
	v_mfma_f32_16x16x32_bf16 v[52:55], v[178:181], v[202:205], v[52:55]
	v_mfma_f32_16x16x32_bf16 v[48:51], v[186:189], v[202:205], v[48:51]
	v_mfma_f32_16x16x32_bf16 v[44:47], v[178:181], v[210:213], v[44:47]
	v_mfma_f32_16x16x32_bf16 v[40:43], v[186:189], v[210:213], v[40:43]
	v_mfma_f32_16x16x32_bf16 v[36:39], v[178:181], v[218:221], v[36:39]
	v_mfma_f32_16x16x32_bf16 v[32:35], v[186:189], v[218:221], v[32:35]
	s_barrier
	v_readfirstlane_b32 s73, v162
	v_add_u32_e32 v176, 0x2000, v162
	v_lshl_add_u64 v[174:175], v[246:247], 0, s[48:49]
	s_mov_b32 m0, s73
	v_readfirstlane_b32 s73, v176
	global_load_lds_dwordx4 v[174:175], off
	v_lshl_add_u64 v[174:175], v[248:249], 0, s[48:49]
	s_mov_b32 m0, s73
	s_nop 0
	global_load_lds_dwordx4 v[174:175], off
	s_waitcnt vmcnt(6)
	s_barrier
	v_mfma_f32_16x16x32_bf16 v[28:31], v[222:225], v[190:193], v[28:31]
	v_mfma_f32_16x16x32_bf16 v[24:27], v[230:233], v[190:193], v[24:27]
	v_mfma_f32_16x16x32_bf16 v[20:23], v[222:225], v[198:201], v[20:23]
	v_mfma_f32_16x16x32_bf16 v[16:19], v[230:233], v[198:201], v[16:19]
	v_mfma_f32_16x16x32_bf16 v[12:15], v[222:225], v[206:209], v[12:15]
	v_mfma_f32_16x16x32_bf16 v[8:11], v[230:233], v[206:209], v[8:11]
	v_mfma_f32_16x16x32_bf16 v[4:7], v[222:225], v[214:217], v[4:7]
	v_mfma_f32_16x16x32_bf16 v[0:3], v[230:233], v[214:217], v[0:3]
	v_mfma_f32_16x16x32_bf16 v[28:31], v[226:229], v[194:197], v[28:31]
	v_mfma_f32_16x16x32_bf16 v[24:27], v[234:237], v[194:197], v[24:27]
	v_mfma_f32_16x16x32_bf16 v[20:23], v[226:229], v[202:205], v[20:23]
	v_mfma_f32_16x16x32_bf16 v[16:19], v[234:237], v[202:205], v[16:19]
	v_mfma_f32_16x16x32_bf16 v[12:15], v[226:229], v[210:213], v[12:15]
	v_mfma_f32_16x16x32_bf16 v[8:11], v[234:237], v[210:213], v[8:11]
	v_mfma_f32_16x16x32_bf16 v[4:7], v[226:229], v[218:221], v[4:7]
	v_mfma_f32_16x16x32_bf16 v[0:3], v[234:237], v[218:221], v[0:3]
	s_add_i32 s72, s72, 2
	s_add_u32 s50, s50, 0x100
	s_addc_u32 s51, s51, 0
	s_cmpk_gt_u32 s72, 0x51
	s_barrier
	s_cbranch_scc0 .LBB0_838
	s_add_i32 s50, s18, 0x80
	s_mul_hi_i32 s51, s50, 0x2b00
	s_mulk_i32 s50, 0x2b00
	s_add_u32 s50, s56, s50
	s_addc_u32 s51, s57, s51
	s_add_u32 s50, s50, 0x2a80
	s_addc_u32 s51, s51, 0
	v_readfirstlane_b32 s72, v172
	v_lshl_add_u64 v[160:161], s[50:51], 0, v[128:129]
	s_mov_b32 m0, s72
	ds_read_b128 v[134:137], v164
	ds_read_b128 v[138:141], v164 offset:1024
	ds_read_b128 v[142:145], v164 offset:2048
	ds_read_b128 v[174:177], v164 offset:3072
	ds_read_b128 v[178:181], v155
	ds_read_b128 v[182:185], v155 offset:1024
	ds_read_b128 v[186:189], v154
	ds_read_b128 v[190:193], v154 offset:1024
	ds_read_b128 v[194:197], v153
	ds_read_b128 v[198:201], v153 offset:1024
	ds_read_b128 v[202:205], v152
	ds_read_b128 v[206:209], v152 offset:1024
	global_load_lds_dwordx4 v[160:161], off
	v_lshl_add_u64 v[160:161], s[50:51], 0, v[132:133]
	v_readfirstlane_b32 s50, v173
	s_mov_b32 m0, s50
	s_nop 0
	global_load_lds_dwordx4 v[160:161], off
	s_barrier
	s_waitcnt lgkmcnt(0)
	v_mfma_f32_16x16x32_bf16 v[124:127], v[134:137], v[178:181], v[124:127]
	v_mfma_f32_16x16x32_bf16 v[120:123], v[142:145], v[178:181], v[120:123]
	v_mfma_f32_16x16x32_bf16 v[116:119], v[134:137], v[186:189], v[116:119]
	v_mfma_f32_16x16x32_bf16 v[112:115], v[142:145], v[186:189], v[112:115]
	v_mfma_f32_16x16x32_bf16 v[108:111], v[134:137], v[194:197], v[108:111]
	v_mfma_f32_16x16x32_bf16 v[104:107], v[142:145], v[194:197], v[104:107]
	v_mfma_f32_16x16x32_bf16 v[100:103], v[134:137], v[202:205], v[100:103]
	v_mfma_f32_16x16x32_bf16 v[96:99], v[142:145], v[202:205], v[96:99]
	v_mfma_f32_16x16x32_bf16 v[124:127], v[138:141], v[182:185], v[124:127]
	v_mfma_f32_16x16x32_bf16 v[120:123], v[174:177], v[182:185], v[120:123]
	v_mfma_f32_16x16x32_bf16 v[116:119], v[138:141], v[190:193], v[116:119]
	v_mfma_f32_16x16x32_bf16 v[112:115], v[174:177], v[190:193], v[112:115]
	v_mfma_f32_16x16x32_bf16 v[108:111], v[138:141], v[198:201], v[108:111]
	v_mfma_f32_16x16x32_bf16 v[104:107], v[174:177], v[198:201], v[104:107]
	v_mfma_f32_16x16x32_bf16 v[100:103], v[138:141], v[206:209], v[100:103]
	v_mfma_f32_16x16x32_bf16 v[96:99], v[174:177], v[206:209], v[96:99]
	s_barrier
	ds_read_b128 v[210:213], v163
	ds_read_b128 v[214:217], v163 offset:1024
	ds_read_b128 v[218:221], v163 offset:2048
	ds_read_b128 v[160:163], v163 offset:3072
	s_barrier
; #define LDA(dst, b, h) for (int m = 0; m < 4; ++m) for (int k = 0; k < 2; ++k) \
;     dst[m][k] = *reinterpret_cast<const bf16x8*>((char*)SA(b, h) + lds_byte(wr * 64 + m * 16 + fr, k * 32 + fq * 8))
; #define LDB(dst, b, h) for (int n = 0; n < 2; ++n) for (int k = 0; k < 2; ++k) \
;     dst[n][k] = *reinterpret_cast<const bf16x8*>((char*)SB(b, h) + lds_byte(wc * 32 + n * 16 + fr, k * 32 + fq * 8))
; #define MMA(ai, bj, At_, Bt_) do { __builtin_amdgcn_s_setprio(1); \
;     for (int k = 0; k < 2; ++k) for (int m = 0; m < 4; ++m) for (int n = 0; n < 2; ++n) \
;       acc[ai][bj][m][n] = __builtin_amdgcn_mfma_f32_16x16x32_bf16(At_[m][k], Bt_[n][k], acc[ai][bj][m][n], 0, 0, 0); \
;     __builtin_amdgcn_s_setprio(0); } while (0)
; #define WAIT_V(n) asm volatile("s_waitcnt vmcnt(" #n ")" ::: "memory")
; #define WAIT_L(n) asm volatile("s_waitcnt lgkmcnt(" #n ")" ::: "memory")
; #define BAR __builtin_amdgcn_s_barrier()
; template <int EPI, int lda, int ldb, int N, int K>
; __device__ __forceinline__ void gemm_phase(const u16* __restrict__ A, const u16* __restrict__ Bt, const GemmEpi ep, int wv) {
;     ...
;       LDB(B1, 0, 1); BAR; WAIT_L(0); MMA(0, 1, At, B1); BAR;
;       LDA(At, 0, 1); WAIT_V(4); BAR; WAIT_L(0); MMA(1, 0, At, B0); MMA(1, 1, At, B1); BAR; }
;     { LDB(B0, 1, 0); LDA(At, 1, 0); WAIT_V(2); BAR; WAIT_L(0); MMA(0, 0, At, B0); BAR;
	s_waitcnt lgkmcnt(0)
	v_mfma_f32_16x16x32_bf16 v[92:95], v[210:213], v[178:181], v[92:95]
	v_mfma_f32_16x16x32_bf16 v[88:91], v[218:221], v[178:181], v[88:91]
	v_mfma_f32_16x16x32_bf16 v[76:79], v[210:213], v[194:197], v[76:79]
	v_mfma_f32_16x16x32_bf16 v[72:75], v[218:221], v[194:197], v[72:75]
	v_mfma_f32_16x16x32_bf16 v[84:87], v[210:213], v[186:189], v[84:87]
	v_mfma_f32_16x16x32_bf16 v[80:83], v[218:221], v[186:189], v[80:83]
	v_mfma_f32_16x16x32_bf16 v[68:71], v[210:213], v[202:205], v[68:71]
	v_mfma_f32_16x16x32_bf16 v[64:67], v[218:221], v[202:205], v[64:67]
	v_mfma_f32_16x16x32_bf16 v[92:95], v[214:217], v[182:185], v[92:95]
	v_mfma_f32_16x16x32_bf16 v[88:91], v[160:163], v[182:185], v[88:91]
	v_mfma_f32_16x16x32_bf16 v[76:79], v[214:217], v[198:201], v[76:79]
	v_mfma_f32_16x16x32_bf16 v[72:75], v[160:163], v[198:201], v[72:75]
	v_mfma_f32_16x16x32_bf16 v[178:181], v[214:217], v[190:193], v[84:87]
	v_mfma_f32_16x16x32_bf16 v[182:185], v[160:163], v[190:193], v[80:83]
	v_mfma_f32_16x16x32_bf16 v[186:189], v[214:217], v[206:209], v[68:71]
	v_mfma_f32_16x16x32_bf16 v[190:193], v[160:163], v[206:209], v[64:67]
	s_barrier
	s_nop 0
	ds_read_b128 v[64:67], v155 offset:16384
	ds_read_b128 v[68:71], v155 offset:17408
	ds_read_b128 v[80:83], v154 offset:16384
	ds_read_b128 v[84:87], v154 offset:17408
	ds_read_b128 v[194:197], v153 offset:16384
	ds_read_b128 v[198:201], v153 offset:17408
	ds_read_b128 v[202:205], v152 offset:16384
	ds_read_b128 v[206:209], v152 offset:17408
	s_waitcnt vmcnt(4)
	s_barrier
	s_waitcnt lgkmcnt(0)
	v_mfma_f32_16x16x32_bf16 v[60:63], v[134:137], v[64:67], v[60:63]
	v_mfma_f32_16x16x32_bf16 v[56:59], v[142:145], v[64:67], v[56:59]
	v_mfma_f32_16x16x32_bf16 v[52:55], v[134:137], v[80:83], v[52:55]
	v_mfma_f32_16x16x32_bf16 v[48:51], v[142:145], v[80:83], v[48:51]
	v_mfma_f32_16x16x32_bf16 v[44:47], v[134:137], v[194:197], v[44:47]
	v_mfma_f32_16x16x32_bf16 v[40:43], v[142:145], v[194:197], v[40:43]
	v_mfma_f32_16x16x32_bf16 v[36:39], v[134:137], v[202:205], v[36:39]
	v_mfma_f32_16x16x32_bf16 v[32:35], v[142:145], v[202:205], v[32:35]
	v_mfma_f32_16x16x32_bf16 v[60:63], v[138:141], v[68:71], v[60:63]
	v_mfma_f32_16x16x32_bf16 v[56:59], v[174:177], v[68:71], v[56:59]
	v_mfma_f32_16x16x32_bf16 v[52:55], v[138:141], v[84:87], v[52:55]
	v_mfma_f32_16x16x32_bf16 v[48:51], v[174:177], v[84:87], v[48:51]
	v_mfma_f32_16x16x32_bf16 v[44:47], v[138:141], v[198:201], v[44:47]
	v_mfma_f32_16x16x32_bf16 v[40:43], v[174:177], v[198:201], v[40:43]
	v_mfma_f32_16x16x32_bf16 v[36:39], v[138:141], v[206:209], v[36:39]
	v_mfma_f32_16x16x32_bf16 v[32:35], v[174:177], v[206:209], v[32:35]
	v_mfma_f32_16x16x32_bf16 v[28:31], v[210:213], v[64:67], v[28:31]
	v_mfma_f32_16x16x32_bf16 v[16:19], v[218:221], v[80:83], v[16:19]
	v_mfma_f32_16x16x32_bf16 v[12:15], v[210:213], v[194:197], v[12:15]
	v_mfma_f32_16x16x32_bf16 v[0:3], v[218:221], v[202:205], v[0:3]
	v_mfma_f32_16x16x32_bf16 v[24:27], v[218:221], v[64:67], v[24:27]
	v_mfma_f32_16x16x32_bf16 v[20:23], v[210:213], v[80:83], v[20:23]
	v_mfma_f32_16x16x32_bf16 v[8:11], v[218:221], v[194:197], v[8:11]
	v_mfma_f32_16x16x32_bf16 v[4:7], v[210:213], v[202:205], v[4:7]
	v_mfma_f32_16x16x32_bf16 v[28:31], v[214:217], v[68:71], v[28:31]
	v_mfma_f32_16x16x32_bf16 v[16:19], v[160:163], v[84:87], v[16:19]
	v_mfma_f32_16x16x32_bf16 v[12:15], v[214:217], v[198:201], v[12:15]
	v_mfma_f32_16x16x32_bf16 v[0:3], v[160:163], v[206:209], v[0:3]
	v_mfma_f32_16x16x32_bf16 v[134:137], v[160:163], v[68:71], v[24:27]
	v_mfma_f32_16x16x32_bf16 v[138:141], v[214:217], v[84:87], v[20:23]
	v_mfma_f32_16x16x32_bf16 v[142:145], v[160:163], v[198:201], v[8:11]
	v_mfma_f32_16x16x32_bf16 v[172:175], v[214:217], v[206:209], v[4:7]
	s_barrier
	s_nop 0
	ds_read_b128 v[4:7], v159
	ds_read_b128 v[8:11], v159 offset:1024
	ds_read_b128 v[20:23], v159 offset:2048
	ds_read_b128 v[158:161], v159 offset:3072
	ds_read_b128 v[24:27], v155 offset:32768
	ds_read_b128 v[194:197], v155 offset:33792
	ds_read_b128 v[198:201], v154 offset:32768
	ds_read_b128 v[202:205], v154 offset:33792
	ds_read_b128 v[206:209], v153 offset:32768
	ds_read_b128 v[210:213], v153 offset:33792
	ds_read_b128 v[214:217], v152 offset:32768
	ds_read_b128 v[218:221], v152 offset:33792
	s_waitcnt vmcnt(2)
	s_barrier
; #define LDA(dst, b, h) for (int m = 0; m < 4; ++m) for (int k = 0; k < 2; ++k) \
;     dst[m][k] = *reinterpret_cast<const bf16x8*>((char*)SA(b, h) + lds_byte(wr * 64 + m * 16 + fr, k * 32 + fq * 8))
; #define LDB(dst, b, h) for (int n = 0; n < 2; ++n) for (int k = 0; k < 2; ++k) \
;     dst[n][k] = *reinterpret_cast<const bf16x8*>((char*)SB(b, h) + lds_byte(wc * 32 + n * 16 + fr, k * 32 + fq * 8))
; #define MMA(ai, bj, At_, Bt_) do { __builtin_amdgcn_s_setprio(1); \
;     for (int k = 0; k < 2; ++k) for (int m = 0; m < 4; ++m) for (int n = 0; n < 2; ++n) \
;       acc[ai][bj][m][n] = __builtin_amdgcn_mfma_f32_16x16x32_bf16(At_[m][k], Bt_[n][k], acc[ai][bj][m][n], 0, 0, 0); \
;     __builtin_amdgcn_s_setprio(0); } while (0)
; #define WAIT_V(n) asm volatile("s_waitcnt vmcnt(" #n ")" ::: "memory")
; #define WAIT_L(n) asm volatile("s_waitcnt lgkmcnt(" #n ")" ::: "memory")
; #define BAR __builtin_amdgcn_s_barrier()
; template <int EPI, int lda, int ldb, int N, int K>
; __device__ __forceinline__ void gemm_phase(const u16* __restrict__ A, const u16* __restrict__ Bt, const GemmEpi ep, int wv) {
;     ...
;     { LDB(B0, 1, 0); LDA(At, 1, 0); WAIT_V(2); BAR; WAIT_L(0); MMA(0, 0, At, B0); BAR;
;       LDB(B1, 1, 1); WAIT_V(0); BAR; WAIT_L(0); MMA(0, 1, At, B1); BAR;
;       LDA(At, 1, 1); BAR; WAIT_L(0); MMA(1, 0, At, B0); MMA(1, 1, At, B1); BAR; }
;     if (wr == 0) BAR;
	s_waitcnt lgkmcnt(0)
	v_mfma_f32_16x16x32_bf16 v[64:67], v[4:7], v[24:27], v[124:127]
	v_mfma_f32_16x16x32_bf16 v[68:71], v[20:23], v[24:27], v[120:123]
	v_mfma_f32_16x16x32_bf16 v[80:83], v[4:7], v[198:201], v[116:119]
	v_mfma_f32_16x16x32_bf16 v[84:87], v[20:23], v[198:201], v[112:115]
	v_mfma_f32_16x16x32_bf16 v[108:111], v[4:7], v[206:209], v[108:111]
	v_mfma_f32_16x16x32_bf16 v[104:107], v[20:23], v[206:209], v[104:107]
	v_mfma_f32_16x16x32_bf16 v[120:123], v[4:7], v[214:217], v[100:103]
	v_mfma_f32_16x16x32_bf16 v[124:127], v[20:23], v[214:217], v[96:99]
	v_mfma_f32_16x16x32_bf16 v[116:119], v[8:11], v[194:197], v[64:67]
	v_mfma_f32_16x16x32_bf16 v[112:115], v[158:161], v[194:197], v[68:71]
	v_mfma_f32_16x16x32_bf16 v[100:103], v[8:11], v[202:205], v[80:83]
	v_mfma_f32_16x16x32_bf16 v[96:99], v[158:161], v[202:205], v[84:87]
	v_mfma_f32_16x16x32_bf16 v[84:87], v[8:11], v[210:213], v[108:111]
	v_mfma_f32_16x16x32_bf16 v[80:83], v[158:161], v[210:213], v[104:107]
	v_mfma_f32_16x16x32_bf16 v[68:71], v[8:11], v[218:221], v[120:123]
	v_mfma_f32_16x16x32_bf16 v[64:67], v[158:161], v[218:221], v[124:127]
	s_barrier
	ds_read_b128 v[222:225], v157
	ds_read_b128 v[226:229], v157 offset:1024
	ds_read_b128 v[230:233], v157 offset:2048
	ds_read_b128 v[234:237], v157 offset:3072
	s_waitcnt vmcnt(0)
	s_barrier
	s_waitcnt lgkmcnt(0)
	v_mfma_f32_16x16x32_bf16 v[92:95], v[222:225], v[24:27], v[92:95]
	v_mfma_f32_16x16x32_bf16 v[24:27], v[230:233], v[24:27], v[88:91]
	v_mfma_f32_16x16x32_bf16 v[88:91], v[222:225], v[198:201], v[178:181]
	v_mfma_f32_16x16x32_bf16 v[104:107], v[230:233], v[198:201], v[182:185]
	v_mfma_f32_16x16x32_bf16 v[76:79], v[222:225], v[206:209], v[76:79]
	v_mfma_f32_16x16x32_bf16 v[72:75], v[230:233], v[206:209], v[72:75]
	v_mfma_f32_16x16x32_bf16 v[176:179], v[222:225], v[214:217], v[186:189]
	v_mfma_f32_16x16x32_bf16 v[180:183], v[230:233], v[214:217], v[190:193]
	v_mfma_f32_16x16x32_bf16 v[124:127], v[226:229], v[194:197], v[92:95]
	v_mfma_f32_16x16x32_bf16 v[120:123], v[234:237], v[194:197], v[24:27]
	v_mfma_f32_16x16x32_bf16 v[108:111], v[226:229], v[202:205], v[88:91]
	v_mfma_f32_16x16x32_bf16 v[104:107], v[234:237], v[202:205], v[104:107]
	v_mfma_f32_16x16x32_bf16 v[92:95], v[226:229], v[210:213], v[76:79]
	v_mfma_f32_16x16x32_bf16 v[88:91], v[234:237], v[210:213], v[72:75]
	v_mfma_f32_16x16x32_bf16 v[76:79], v[226:229], v[218:221], v[176:179]
	v_mfma_f32_16x16x32_bf16 v[72:75], v[234:237], v[218:221], v[180:183]
	s_barrier
	ds_read_b128 v[176:179], v155 offset:49152
	ds_read_b128 v[180:183], v155 offset:50176
	ds_read_b128 v[184:187], v154 offset:49152
	ds_read_b128 v[154:157], v154 offset:50176
	ds_read_b128 v[188:191], v153 offset:49152
	ds_read_b128 v[192:195], v153 offset:50176
	ds_read_b128 v[196:199], v152 offset:49152
	ds_read_b128 v[200:203], v152 offset:50176
	s_barrier
	s_waitcnt lgkmcnt(0)
	v_mfma_f32_16x16x32_bf16 v[24:27], v[4:7], v[176:179], v[60:63]
	v_mfma_f32_16x16x32_bf16 v[60:63], v[20:23], v[176:179], v[56:59]
	v_mfma_f32_16x16x32_bf16 v[204:207], v[4:7], v[184:187], v[52:55]
	v_mfma_f32_16x16x32_bf16 v[48:51], v[20:23], v[184:187], v[48:51]
	v_mfma_f32_16x16x32_bf16 v[44:47], v[4:7], v[188:191], v[44:47]
	v_mfma_f32_16x16x32_bf16 v[208:211], v[20:23], v[188:191], v[40:43]
	v_mfma_f32_16x16x32_bf16 v[4:7], v[4:7], v[196:199], v[36:39]
	v_mfma_f32_16x16x32_bf16 v[32:35], v[20:23], v[196:199], v[32:35]
	v_mfma_f32_16x16x32_bf16 v[56:59], v[8:11], v[180:183], v[24:27]
	v_mfma_f32_16x16x32_bf16 v[52:55], v[158:161], v[180:183], v[60:63]
	v_mfma_f32_16x16x32_bf16 v[40:43], v[8:11], v[154:157], v[204:207]
	v_mfma_f32_16x16x32_bf16 v[36:39], v[158:161], v[154:157], v[48:51]
	v_mfma_f32_16x16x32_bf16 v[24:27], v[8:11], v[192:195], v[44:47]
	v_mfma_f32_16x16x32_bf16 v[20:23], v[158:161], v[192:195], v[208:211]
	v_mfma_f32_16x16x32_bf16 v[8:11], v[8:11], v[200:203], v[4:7]
	v_mfma_f32_16x16x32_bf16 v[4:7], v[158:161], v[200:203], v[32:35]
	v_mfma_f32_16x16x32_bf16 v[28:31], v[222:225], v[176:179], v[28:31]
	v_mfma_f32_16x16x32_bf16 v[32:35], v[230:233], v[176:179], v[134:137]
	v_mfma_f32_16x16x32_bf16 v[44:47], v[222:225], v[184:187], v[138:141]
	v_mfma_f32_16x16x32_bf16 v[16:19], v[230:233], v[184:187], v[16:19]
	v_mfma_f32_16x16x32_bf16 v[12:15], v[222:225], v[188:191], v[12:15]
	v_mfma_f32_16x16x32_bf16 v[134:137], v[230:233], v[188:191], v[142:145]
	v_mfma_f32_16x16x32_bf16 v[138:141], v[222:225], v[196:199], v[172:175]
	v_mfma_f32_16x16x32_bf16 v[0:3], v[230:233], v[196:199], v[0:3]
	v_mfma_f32_16x16x32_bf16 v[60:63], v[226:229], v[180:183], v[28:31]
	v_mfma_f32_16x16x32_bf16 v[48:51], v[234:237], v[180:183], v[32:35]
	v_mfma_f32_16x16x32_bf16 v[44:47], v[226:229], v[154:157], v[44:47]
	v_mfma_f32_16x16x32_bf16 v[32:35], v[234:237], v[154:157], v[16:19]
	v_mfma_f32_16x16x32_bf16 v[28:31], v[226:229], v[192:195], v[12:15]
	v_mfma_f32_16x16x32_bf16 v[16:19], v[234:237], v[192:195], v[134:137]
	v_mfma_f32_16x16x32_bf16 v[12:15], v[226:229], v[200:203], v[138:141]
	v_mfma_f32_16x16x32_bf16 v[0:3], v[234:237], v[200:203], v[0:3]
	v_cmp_gt_u32_e32 vcc, s69, v130
	s_barrier
	s_and_saveexec_b64 s[50:51], vcc
	s_cbranch_execz .LBB0_841
	s_barrier

; #define STAGE(P, BASE, LD, br, kt) do { const char* _g = (const char*)((BASE) + (size_t)(br) * (LD) + (size_t)(kt) * 64); \
;     for (int _i = 0; _i < 2; ++_i) { int _b = tidx * 16 + _i * 8192; int _r, _c; stage_rc(_b, _r, _c); \
;       __builtin_amdgcn_global_load_lds((const unsigned*)(_g + (unsigned)((_r * (LD) + _c) * 2)), (unsigned*)((char*)(P) + _b), 16, 0, 0); } } while (0)
; #define LDA(dst, b, h) for (int m = 0; m < 4; ++m) for (int k = 0; k < 2; ++k) \
;     dst[m][k] = *reinterpret_cast<const bf16x8*>((char*)SA(b, h) + lds_byte(wr * 64 + m * 16 + fr, k * 32 + fq * 8))
; #define LDB(dst, b, h) for (int n = 0; n < 2; ++n) for (int k = 0; k < 2; ++k) \
;     dst[n][k] = *reinterpret_cast<const bf16x8*>((char*)SB(b, h) + lds_byte(wc * 32 + n * 16 + fr, k * 32 + fq * 8))
; #define MMA(ai, bj, At_, Bt_) do { __builtin_amdgcn_s_setprio(1); \
;     for (int k = 0; k < 2; ++k) for (int m = 0; m < 4; ++m) for (int n = 0; n < 2; ++n) \
;       acc[ai][bj][m][n] = __builtin_amdgcn_mfma_f32_16x16x32_bf16(At_[m][k], Bt_[n][k], acc[ai][bj][m][n], 0, 0, 0); \
;     __builtin_amdgcn_s_setprio(0); } while (0)
; #define WAIT_L(n) asm volatile("s_waitcnt lgkmcnt(" #n ")" ::: "memory")
; #define BAR __builtin_amdgcn_s_barrier()
; #define SCHED __builtin_amdgcn_sched_barrier(0)
; template <int EPI, int lda, int ldb, int N, int K>
; __device__ __forceinline__ void gemm_phase(const u16* __restrict__ A, const u16* __restrict__ Bt, const GemmEpi ep, int wv) {
;     ...
;     for (int t = 0; t < nt - 2; t += 2) {
;       LDB(B0, 0, 0); SCHED; LDA(At, 0, 0); STAGE(SA(1, 1), Ab, lda, brow + HALF, t + 1);
;       WAIT_L(8); BAR; WAIT_L(0); MMA(0, 0, At, B0); BAR; SCHED;
;       LDB(B1, 0, 1); STAGE(SB(0, 0), Bt, ldb, bcol, t + 2);
;       BAR; WAIT_L(0); MMA(0, 1, At, B1); BAR;
;       LDA(At, 0, 1); STAGE(SA(0, 0), Ab, lda, brow, t + 2);
;       BAR; WAIT_L(0); MMA(1, 0, At, B0); BAR; SCHED;
.LBB0_1147:
	ds_read_b128 v[172:175], v161
	ds_read_b128 v[176:179], v161 offset:1024
	ds_read_b128 v[180:183], v161 offset:2048
	ds_read_b128 v[184:187], v161 offset:3072
	v_add_u32_e32 v169, 0xc000, v148
	v_lshl_add_u64 v[236:237], v[138:139], 0, s[60:61]
	v_readfirstlane_b32 s63, v169
	v_add_u32_e32 v170, 0xe000, v148
	v_lshl_add_u64 v[162:163], v[236:237], 0, s[22:23]
	s_mov_b32 m0, s63
	v_lshl_add_u64 v[238:239], v[140:141], 0, s[60:61]
	v_readfirstlane_b32 s63, v170
	ds_read_b128 v[164:167], v152
	ds_read_b128 v[188:191], v152 offset:1024
	ds_read_b128 v[192:195], v151
	ds_read_b128 v[196:199], v151 offset:1024
	ds_read_b128 v[200:203], v150
	ds_read_b128 v[204:207], v150 offset:1024
	ds_read_b128 v[208:211], v149
	ds_read_b128 v[212:215], v149 offset:1024
	global_load_lds_dwordx4 v[162:163], off
	v_lshl_add_u64 v[162:163], v[238:239], 0, s[22:23]
	s_mov_b32 m0, s63
	s_nop 0
	global_load_lds_dwordx4 v[162:163], off
	s_waitcnt lgkmcnt(8)
	s_barrier
	s_waitcnt lgkmcnt(0)
	v_mfma_f32_16x16x32_bf16 v[124:127], v[164:167], v[172:175], v[124:127]
	v_mfma_f32_16x16x32_bf16 v[120:123], v[164:167], v[180:183], v[120:123]
	v_mfma_f32_16x16x32_bf16 v[116:119], v[192:195], v[172:175], v[116:119]
	v_mfma_f32_16x16x32_bf16 v[112:115], v[192:195], v[180:183], v[112:115]
	v_mfma_f32_16x16x32_bf16 v[108:111], v[200:203], v[172:175], v[108:111]
	v_mfma_f32_16x16x32_bf16 v[104:107], v[200:203], v[180:183], v[104:107]
	v_mfma_f32_16x16x32_bf16 v[100:103], v[208:211], v[172:175], v[100:103]
	v_mfma_f32_16x16x32_bf16 v[96:99], v[208:211], v[180:183], v[96:99]
	v_mfma_f32_16x16x32_bf16 v[124:127], v[188:191], v[176:179], v[124:127]
	v_mfma_f32_16x16x32_bf16 v[120:123], v[188:191], v[184:187], v[120:123]
	v_mfma_f32_16x16x32_bf16 v[116:119], v[196:199], v[176:179], v[116:119]
	v_mfma_f32_16x16x32_bf16 v[112:115], v[196:199], v[184:187], v[112:115]
	v_mfma_f32_16x16x32_bf16 v[108:111], v[204:207], v[176:179], v[108:111]
	v_mfma_f32_16x16x32_bf16 v[104:107], v[204:207], v[184:187], v[104:107]
	v_mfma_f32_16x16x32_bf16 v[100:103], v[212:215], v[176:179], v[100:103]
	v_mfma_f32_16x16x32_bf16 v[96:99], v[212:215], v[184:187], v[96:99]
	s_barrier
	v_add_u32_e32 v162, s75, v154
	v_lshl_add_u64 v[240:241], v[134:135], 0, s[60:61]
	v_readfirstlane_b32 s63, v162
	v_add_u32_e32 v163, 0x2000, v162
	v_lshl_add_u64 v[232:233], v[240:241], 0, s[24:25]
	s_mov_b32 m0, s63
	v_lshl_add_u64 v[242:243], v[136:137], 0, s[60:61]
	v_readfirstlane_b32 s63, v163
	ds_read_b128 v[216:219], v160
	ds_read_b128 v[220:223], v160 offset:1024
	ds_read_b128 v[224:227], v160 offset:2048
	ds_read_b128 v[228:231], v160 offset:3072
	global_load_lds_dwordx4 v[232:233], off
	v_lshl_add_u64 v[232:233], v[242:243], 0, s[24:25]
	s_mov_b32 m0, s63
	s_nop 0
	global_load_lds_dwordx4 v[232:233], off
	s_barrier
	s_waitcnt lgkmcnt(0)
	v_mfma_f32_16x16x32_bf16 v[92:95], v[164:167], v[216:219], v[92:95]
	v_mfma_f32_16x16x32_bf16 v[88:91], v[164:167], v[224:227], v[88:91]
	v_mfma_f32_16x16x32_bf16 v[84:87], v[192:195], v[216:219], v[84:87]
	v_mfma_f32_16x16x32_bf16 v[80:83], v[192:195], v[224:227], v[80:83]
	v_mfma_f32_16x16x32_bf16 v[76:79], v[200:203], v[216:219], v[76:79]
	v_mfma_f32_16x16x32_bf16 v[72:75], v[200:203], v[224:227], v[72:75]
	v_mfma_f32_16x16x32_bf16 v[68:71], v[208:211], v[216:219], v[68:71]
	v_mfma_f32_16x16x32_bf16 v[64:67], v[208:211], v[224:227], v[64:67]
	v_mfma_f32_16x16x32_bf16 v[92:95], v[188:191], v[220:223], v[92:95]
	v_mfma_f32_16x16x32_bf16 v[88:91], v[188:191], v[228:231], v[88:91]
	v_mfma_f32_16x16x32_bf16 v[84:87], v[196:199], v[220:223], v[84:87]
	v_mfma_f32_16x16x32_bf16 v[80:83], v[196:199], v[228:231], v[80:83]
	v_mfma_f32_16x16x32_bf16 v[76:79], v[204:207], v[220:223], v[76:79]
	v_mfma_f32_16x16x32_bf16 v[72:75], v[204:207], v[228:231], v[72:75]
	v_mfma_f32_16x16x32_bf16 v[68:71], v[212:215], v[220:223], v[68:71]
	v_mfma_f32_16x16x32_bf16 v[64:67], v[212:215], v[228:231], v[64:67]
	v_readfirstlane_b32 s63, v148
	v_lshl_add_u64 v[164:165], v[236:237], 0, s[26:27]
	s_mov_b32 m0, s63
	s_barrier
	ds_read_b128 v[188:191], v152 offset:16384
	ds_read_b128 v[192:195], v152 offset:17408
	ds_read_b128 v[196:199], v151 offset:16384
	ds_read_b128 v[200:203], v151 offset:17408
	ds_read_b128 v[204:207], v150 offset:16384
	ds_read_b128 v[208:211], v150 offset:17408
	ds_read_b128 v[212:215], v149 offset:16384
	ds_read_b128 v[232:235], v149 offset:17408
	global_load_lds_dwordx4 v[164:165], off
	v_add_u32_e32 v164, 0x2000, v148
	v_lshl_add_u64 v[166:167], v[238:239], 0, s[26:27]
	v_readfirstlane_b32 s63, v164
	s_mov_b32 m0, s63
	s_nop 0
	global_load_lds_dwordx4 v[166:167], off
	s_barrier
	s_waitcnt lgkmcnt(0)
	v_mfma_f32_16x16x32_bf16 v[60:63], v[188:191], v[172:175], v[60:63]
	v_mfma_f32_16x16x32_bf16 v[56:59], v[188:191], v[180:183], v[56:59]
	v_mfma_f32_16x16x32_bf16 v[52:55], v[196:199], v[172:175], v[52:55]
	v_mfma_f32_16x16x32_bf16 v[48:51], v[196:199], v[180:183], v[48:51]
	v_mfma_f32_16x16x32_bf16 v[44:47], v[204:207], v[172:175], v[44:47]
	v_mfma_f32_16x16x32_bf16 v[40:43], v[204:207], v[180:183], v[40:43]
	v_mfma_f32_16x16x32_bf16 v[36:39], v[212:215], v[172:175], v[36:39]
	v_mfma_f32_16x16x32_bf16 v[32:35], v[212:215], v[180:183], v[32:35]
	v_mfma_f32_16x16x32_bf16 v[60:63], v[192:195], v[176:179], v[60:63]
	v_mfma_f32_16x16x32_bf16 v[56:59], v[192:195], v[184:187], v[56:59]
	v_mfma_f32_16x16x32_bf16 v[52:55], v[200:203], v[176:179], v[52:55]
	v_mfma_f32_16x16x32_bf16 v[48:51], v[200:203], v[184:187], v[48:51]
	v_mfma_f32_16x16x32_bf16 v[44:47], v[208:211], v[176:179], v[44:47]
	v_mfma_f32_16x16x32_bf16 v[40:43], v[208:211], v[184:187], v[40:43]
	v_mfma_f32_16x16x32_bf16 v[36:39], v[232:235], v[176:179], v[36:39]
	v_mfma_f32_16x16x32_bf16 v[32:35], v[232:235], v[184:187], v[32:35]
	s_barrier
; #define STAGE(P, BASE, LD, br, kt) do { const char* _g = (const char*)((BASE) + (size_t)(br) * (LD) + (size_t)(kt) * 64); \
;     for (int _i = 0; _i < 2; ++_i) { int _b = tidx * 16 + _i * 8192; int _r, _c; stage_rc(_b, _r, _c); \
;       __builtin_amdgcn_global_load_lds((const unsigned*)(_g + (unsigned)((_r * (LD) + _c) * 2)), (unsigned*)((char*)(P) + _b), 16, 0, 0); } } while (0)
; #define LDA(dst, b, h) for (int m = 0; m < 4; ++m) for (int k = 0; k < 2; ++k) \
;     dst[m][k] = *reinterpret_cast<const bf16x8*>((char*)SA(b, h) + lds_byte(wr * 64 + m * 16 + fr, k * 32 + fq * 8))
; #define LDB(dst, b, h) for (int n = 0; n < 2; ++n) for (int k = 0; k < 2; ++k) \
;     dst[n][k] = *reinterpret_cast<const bf16x8*>((char*)SB(b, h) + lds_byte(wc * 32 + n * 16 + fr, k * 32 + fq * 8))
; #define MMA(ai, bj, At_, Bt_) do { __builtin_amdgcn_s_setprio(1); \
;     for (int k = 0; k < 2; ++k) for (int m = 0; m < 4; ++m) for (int n = 0; n < 2; ++n) \
;       acc[ai][bj][m][n] = __builtin_amdgcn_mfma_f32_16x16x32_bf16(At_[m][k], Bt_[n][k], acc[ai][bj][m][n], 0, 0, 0); \
;     __builtin_amdgcn_s_setprio(0); } while (0)
; #define WAIT_V(n) asm volatile("s_waitcnt vmcnt(" #n ")" ::: "memory")
; #define WAIT_L(n) asm volatile("s_waitcnt lgkmcnt(" #n ")" ::: "memory")
; #define BAR __builtin_amdgcn_s_barrier()
; #define SCHED __builtin_amdgcn_sched_barrier(0)
; template <int EPI, int lda, int ldb, int N, int K>
; __device__ __forceinline__ void gemm_phase(const u16* __restrict__ A, const u16* __restrict__ Bt, const GemmEpi ep, int wv) {
;     ...
;       STAGE(SB(0, 1), Bt, ldb, bcol + HALF, t + 2);
;       WAIT_V(6); BAR; MMA(1, 1, At, B1); BAR;
;       LDB(B0, 1, 0); SCHED; LDA(At, 1, 0); STAGE(SA(0, 1), Ab, lda, brow + HALF, t + 2);
;       WAIT_L(8); BAR; WAIT_L(0); MMA(0, 0, At, B0); BAR; SCHED;
;       LDB(B1, 1, 1); STAGE(SB(1, 0), Bt, ldb, bcol, t + 3);
;       BAR; WAIT_L(0); MMA(0, 1, At, B1); BAR;
;       LDA(At, 1, 1); STAGE(SA(1, 0), Ab, lda, brow, t + 3);
	v_add_u32_e32 v165, s76, v154
	v_lshl_add_u64 v[166:167], v[240:241], 0, s[40:41]
	v_readfirstlane_b32 s63, v165
	s_mov_b32 m0, s63
	v_lshl_add_u64 v[172:173], v[242:243], 0, s[40:41]
	global_load_lds_dwordx4 v[166:167], off
	v_add_u32_e32 v166, 0x2000, v165
	s_nop 0
	v_readfirstlane_b32 s63, v166
	s_mov_b32 m0, s63
	s_nop 0
	global_load_lds_dwordx4 v[172:173], off
	s_waitcnt vmcnt(6)
	s_barrier
	v_mfma_f32_16x16x32_bf16 v[28:31], v[188:191], v[216:219], v[28:31]
	v_mfma_f32_16x16x32_bf16 v[24:27], v[188:191], v[224:227], v[24:27]
	v_mfma_f32_16x16x32_bf16 v[20:23], v[196:199], v[216:219], v[20:23]
	v_mfma_f32_16x16x32_bf16 v[16:19], v[196:199], v[224:227], v[16:19]
	v_mfma_f32_16x16x32_bf16 v[12:15], v[204:207], v[216:219], v[12:15]
	v_mfma_f32_16x16x32_bf16 v[8:11], v[204:207], v[224:227], v[8:11]
	v_mfma_f32_16x16x32_bf16 v[4:7], v[212:215], v[216:219], v[4:7]
	v_mfma_f32_16x16x32_bf16 v[0:3], v[212:215], v[224:227], v[0:3]
	v_mfma_f32_16x16x32_bf16 v[28:31], v[192:195], v[220:223], v[28:31]
	v_mfma_f32_16x16x32_bf16 v[24:27], v[192:195], v[228:231], v[24:27]
	v_mfma_f32_16x16x32_bf16 v[20:23], v[200:203], v[220:223], v[20:23]
	v_mfma_f32_16x16x32_bf16 v[16:19], v[200:203], v[228:231], v[16:19]
	v_mfma_f32_16x16x32_bf16 v[12:15], v[208:211], v[220:223], v[12:15]
	v_mfma_f32_16x16x32_bf16 v[8:11], v[208:211], v[228:231], v[8:11]
	v_mfma_f32_16x16x32_bf16 v[4:7], v[232:235], v[220:223], v[4:7]
	v_mfma_f32_16x16x32_bf16 v[0:3], v[232:235], v[228:231], v[0:3]
	s_barrier
	ds_read_b128 v[172:175], v155
	ds_read_b128 v[176:179], v155 offset:1024
	ds_read_b128 v[180:183], v155 offset:2048
	ds_read_b128 v[184:187], v155 offset:3072
	v_add_u32_e32 v167, 0x4000, v148
	v_add_u32_e32 v168, 0x6000, v148
	v_readfirstlane_b32 s63, v167
	v_lshl_add_u64 v[220:221], v[236:237], 0, s[42:43]
	s_mov_b32 m0, s63
	v_readfirstlane_b32 s63, v168
	ds_read_b128 v[188:191], v152 offset:32768
	ds_read_b128 v[192:195], v152 offset:33792
	ds_read_b128 v[196:199], v151 offset:32768
	ds_read_b128 v[200:203], v151 offset:33792
	ds_read_b128 v[204:207], v150 offset:32768
	ds_read_b128 v[208:211], v150 offset:33792
	ds_read_b128 v[212:215], v149 offset:32768
	ds_read_b128 v[216:219], v149 offset:33792
	global_load_lds_dwordx4 v[220:221], off
	v_lshl_add_u64 v[220:221], v[238:239], 0, s[42:43]
	s_mov_b32 m0, s63
	s_nop 0
	global_load_lds_dwordx4 v[220:221], off
	s_waitcnt lgkmcnt(8)
	s_barrier
	s_waitcnt lgkmcnt(0)
	v_mfma_f32_16x16x32_bf16 v[124:127], v[188:191], v[172:175], v[124:127]
	v_mfma_f32_16x16x32_bf16 v[120:123], v[188:191], v[180:183], v[120:123]
	v_mfma_f32_16x16x32_bf16 v[116:119], v[196:199], v[172:175], v[116:119]
	v_mfma_f32_16x16x32_bf16 v[112:115], v[196:199], v[180:183], v[112:115]
	v_mfma_f32_16x16x32_bf16 v[108:111], v[204:207], v[172:175], v[108:111]
	v_mfma_f32_16x16x32_bf16 v[104:107], v[204:207], v[180:183], v[104:107]
	v_mfma_f32_16x16x32_bf16 v[100:103], v[212:215], v[172:175], v[100:103]
	v_mfma_f32_16x16x32_bf16 v[96:99], v[212:215], v[180:183], v[96:99]
	v_mfma_f32_16x16x32_bf16 v[124:127], v[192:195], v[176:179], v[124:127]
	v_mfma_f32_16x16x32_bf16 v[120:123], v[192:195], v[184:187], v[120:123]
	v_mfma_f32_16x16x32_bf16 v[116:119], v[200:203], v[176:179], v[116:119]
	v_mfma_f32_16x16x32_bf16 v[112:115], v[200:203], v[184:187], v[112:115]
	v_mfma_f32_16x16x32_bf16 v[108:111], v[208:211], v[176:179], v[108:111]
	v_mfma_f32_16x16x32_bf16 v[104:107], v[208:211], v[184:187], v[104:107]
	v_mfma_f32_16x16x32_bf16 v[100:103], v[216:219], v[176:179], v[100:103]
	v_mfma_f32_16x16x32_bf16 v[96:99], v[216:219], v[184:187], v[96:99]
	s_barrier
	v_readfirstlane_b32 s63, v156
	v_add_u32_e32 v171, 0x2000, v156
	v_lshl_add_u64 v[244:245], v[240:241], 0, s[44:45]
	s_mov_b32 m0, s63
	v_readfirstlane_b32 s63, v171
	ds_read_b128 v[220:223], v153
	ds_read_b128 v[224:227], v153 offset:1024
	ds_read_b128 v[228:231], v153 offset:2048
	ds_read_b128 v[232:235], v153 offset:3072
	global_load_lds_dwordx4 v[244:245], off
	v_lshl_add_u64 v[244:245], v[242:243], 0, s[44:45]
	s_mov_b32 m0, s63
	s_nop 0
	global_load_lds_dwordx4 v[244:245], off
	s_barrier
	s_waitcnt lgkmcnt(0)
	v_mfma_f32_16x16x32_bf16 v[92:95], v[188:191], v[220:223], v[92:95]
	v_mfma_f32_16x16x32_bf16 v[88:91], v[188:191], v[228:231], v[88:91]
	v_mfma_f32_16x16x32_bf16 v[84:87], v[196:199], v[220:223], v[84:87]
	v_mfma_f32_16x16x32_bf16 v[80:83], v[196:199], v[228:231], v[80:83]
	v_mfma_f32_16x16x32_bf16 v[76:79], v[204:207], v[220:223], v[76:79]
	v_mfma_f32_16x16x32_bf16 v[72:75], v[204:207], v[228:231], v[72:75]
	v_mfma_f32_16x16x32_bf16 v[68:71], v[212:215], v[220:223], v[68:71]
	v_mfma_f32_16x16x32_bf16 v[64:67], v[212:215], v[228:231], v[64:67]
	v_mfma_f32_16x16x32_bf16 v[92:95], v[192:195], v[224:227], v[92:95]
	v_mfma_f32_16x16x32_bf16 v[88:91], v[192:195], v[232:235], v[88:91]
	v_mfma_f32_16x16x32_bf16 v[84:87], v[200:203], v[224:227], v[84:87]
	v_mfma_f32_16x16x32_bf16 v[80:83], v[200:203], v[232:235], v[80:83]
	v_mfma_f32_16x16x32_bf16 v[76:79], v[208:211], v[224:227], v[76:79]
	v_mfma_f32_16x16x32_bf16 v[72:75], v[208:211], v[232:235], v[72:75]
	v_mfma_f32_16x16x32_bf16 v[68:71], v[216:219], v[224:227], v[68:71]
	v_mfma_f32_16x16x32_bf16 v[64:67], v[216:219], v[232:235], v[64:67]
	v_readfirstlane_b32 s63, v157
	v_lshl_add_u64 v[236:237], v[236:237], 0, s[46:47]
	s_mov_b32 m0, s63
	v_readfirstlane_b32 s63, v158
	s_barrier
	ds_read_b128 v[188:191], v152 offset:49152
	ds_read_b128 v[192:195], v152 offset:50176
	ds_read_b128 v[196:199], v151 offset:49152
	ds_read_b128 v[200:203], v151 offset:50176
	ds_read_b128 v[204:207], v150 offset:49152
	ds_read_b128 v[208:211], v150 offset:50176
	ds_read_b128 v[212:215], v149 offset:49152
	ds_read_b128 v[216:219], v149 offset:50176
	global_load_lds_dwordx4 v[236:237], off
	v_lshl_add_u64 v[236:237], v[238:239], 0, s[46:47]
	s_mov_b32 m0, s63
	s_nop 0
	global_load_lds_dwordx4 v[236:237], off
	s_barrier
; #define STAGE(P, BASE, LD, br, kt) do { const char* _g = (const char*)((BASE) + (size_t)(br) * (LD) + (size_t)(kt) * 64); \
;     for (int _i = 0; _i < 2; ++_i) { int _b = tidx * 16 + _i * 8192; int _r, _c; stage_rc(_b, _r, _c); \
;       __builtin_amdgcn_global_load_lds((const unsigned*)(_g + (unsigned)((_r * (LD) + _c) * 2)), (unsigned*)((char*)(P) + _b), 16, 0, 0); } } while (0)
; #define LDA(dst, b, h) for (int m = 0; m < 4; ++m) for (int k = 0; k < 2; ++k) \
;     dst[m][k] = *reinterpret_cast<const bf16x8*>((char*)SA(b, h) + lds_byte(wr * 64 + m * 16 + fr, k * 32 + fq * 8))
; #define LDB(dst, b, h) for (int n = 0; n < 2; ++n) for (int k = 0; k < 2; ++k) \
;     dst[n][k] = *reinterpret_cast<const bf16x8*>((char*)SB(b, h) + lds_byte(wc * 32 + n * 16 + fr, k * 32 + fq * 8))
; #define MMA(ai, bj, At_, Bt_) do { __builtin_amdgcn_s_setprio(1); \
;     for (int k = 0; k < 2; ++k) for (int m = 0; m < 4; ++m) for (int n = 0; n < 2; ++n) \
;       acc[ai][bj][m][n] = __builtin_amdgcn_mfma_f32_16x16x32_bf16(At_[m][k], Bt_[n][k], acc[ai][bj][m][n], 0, 0, 0); \
;     __builtin_amdgcn_s_setprio(0); } while (0)
; #define WAIT_V(n) asm volatile("s_waitcnt vmcnt(" #n ")" ::: "memory")
; #define WAIT_L(n) asm volatile("s_waitcnt lgkmcnt(" #n ")" ::: "memory")
; #define BAR __builtin_amdgcn_s_barrier()
; #define SCHED __builtin_amdgcn_sched_barrier(0)
; template <int EPI, int lda, int ldb, int N, int K>
; __device__ __forceinline__ void gemm_phase(const u16* __restrict__ A, const u16* __restrict__ Bt, const GemmEpi ep, int wv) {
;     ...
;       BAR; WAIT_L(0); MMA(1, 0, At, B0); BAR; SCHED;
;       STAGE(SB(1, 1), Bt, ldb, bcol + HALF, t + 3);
;       WAIT_V(6); BAR; MMA(1, 1, At, B1); BAR;
;     }
;     { LDB(B0, 0, 0); LDA(At, 0, 0); STAGE(SA(1, 1), Ab, lda, brow + HALF, nt - 1);
;       BAR; WAIT_L(0); MMA(0, 0, At, B0); BAR;
;       LDB(B1, 0, 1); BAR; WAIT_L(0); MMA(0, 1, At, B1); BAR;
	s_waitcnt lgkmcnt(0)
	v_mfma_f32_16x16x32_bf16 v[60:63], v[188:191], v[172:175], v[60:63]
	v_mfma_f32_16x16x32_bf16 v[56:59], v[188:191], v[180:183], v[56:59]
	v_mfma_f32_16x16x32_bf16 v[52:55], v[196:199], v[172:175], v[52:55]
	v_mfma_f32_16x16x32_bf16 v[48:51], v[196:199], v[180:183], v[48:51]
	v_mfma_f32_16x16x32_bf16 v[44:47], v[204:207], v[172:175], v[44:47]
	v_mfma_f32_16x16x32_bf16 v[40:43], v[204:207], v[180:183], v[40:43]
	v_mfma_f32_16x16x32_bf16 v[36:39], v[212:215], v[172:175], v[36:39]
	v_mfma_f32_16x16x32_bf16 v[32:35], v[212:215], v[180:183], v[32:35]
	v_mfma_f32_16x16x32_bf16 v[60:63], v[192:195], v[176:179], v[60:63]
	v_mfma_f32_16x16x32_bf16 v[56:59], v[192:195], v[184:187], v[56:59]
	v_mfma_f32_16x16x32_bf16 v[52:55], v[200:203], v[176:179], v[52:55]
	v_mfma_f32_16x16x32_bf16 v[48:51], v[200:203], v[184:187], v[48:51]
	v_mfma_f32_16x16x32_bf16 v[44:47], v[208:211], v[176:179], v[44:47]
	v_mfma_f32_16x16x32_bf16 v[40:43], v[208:211], v[184:187], v[40:43]
	v_mfma_f32_16x16x32_bf16 v[36:39], v[216:219], v[176:179], v[36:39]
	v_mfma_f32_16x16x32_bf16 v[32:35], v[216:219], v[184:187], v[32:35]
	s_barrier
	v_readfirstlane_b32 s63, v159
	v_add_u32_e32 v171, 0x2000, v159
	v_lshl_add_u64 v[172:173], v[240:241], 0, s[48:49]
	s_mov_b32 m0, s63
	v_readfirstlane_b32 s63, v171
	global_load_lds_dwordx4 v[172:173], off
	v_lshl_add_u64 v[172:173], v[242:243], 0, s[48:49]
	s_mov_b32 m0, s63
	s_nop 0
	global_load_lds_dwordx4 v[172:173], off
	s_waitcnt vmcnt(6)
	s_barrier
	v_mfma_f32_16x16x32_bf16 v[28:31], v[188:191], v[220:223], v[28:31]
	v_mfma_f32_16x16x32_bf16 v[24:27], v[188:191], v[228:231], v[24:27]
	v_mfma_f32_16x16x32_bf16 v[20:23], v[196:199], v[220:223], v[20:23]
	v_mfma_f32_16x16x32_bf16 v[16:19], v[196:199], v[228:231], v[16:19]
	v_mfma_f32_16x16x32_bf16 v[12:15], v[204:207], v[220:223], v[12:15]
	v_mfma_f32_16x16x32_bf16 v[8:11], v[204:207], v[228:231], v[8:11]
	v_mfma_f32_16x16x32_bf16 v[4:7], v[212:215], v[220:223], v[4:7]
	v_mfma_f32_16x16x32_bf16 v[0:3], v[212:215], v[228:231], v[0:3]
	v_mfma_f32_16x16x32_bf16 v[28:31], v[192:195], v[224:227], v[28:31]
	v_mfma_f32_16x16x32_bf16 v[24:27], v[192:195], v[232:235], v[24:27]
	v_mfma_f32_16x16x32_bf16 v[20:23], v[200:203], v[224:227], v[20:23]
	v_mfma_f32_16x16x32_bf16 v[16:19], v[200:203], v[232:235], v[16:19]
	v_mfma_f32_16x16x32_bf16 v[12:15], v[208:211], v[224:227], v[12:15]
	v_mfma_f32_16x16x32_bf16 v[8:11], v[208:211], v[232:235], v[8:11]
	v_mfma_f32_16x16x32_bf16 v[4:7], v[216:219], v[224:227], v[4:7]
	v_mfma_f32_16x16x32_bf16 v[0:3], v[216:219], v[232:235], v[0:3]
	s_add_i32 s62, s62, 2
	s_add_u32 s60, s60, 0x100
	s_addc_u32 s61, s61, 0
	s_cmp_gt_u32 s62, 27
	s_barrier
	s_cbranch_scc0 .LBB0_1147
	s_add_i32 s60, s58, 0x80
	s_mul_hi_i32 s61, s60, 0x1080
	s_mulk_i32 s60, 0x1080
	s_add_u32 s60, s69, s60
	s_addc_u32 s61, s70, s61
	v_lshl_add_u64 v[208:209], s[60:61], 0, v[128:129]
	v_readfirstlane_b32 s62, v169
	v_lshl_add_u64 v[208:209], v[208:209], 0, s[50:51]
	s_mov_b32 m0, s62
	ds_read_b128 v[134:137], v161
	ds_read_b128 v[138:141], v161 offset:1024
	ds_read_b128 v[156:159], v161 offset:2048
	ds_read_b128 v[172:175], v161 offset:3072
	ds_read_b128 v[176:179], v152
	ds_read_b128 v[180:183], v152 offset:1024
	ds_read_b128 v[184:187], v151
	ds_read_b128 v[188:191], v151 offset:1024
	ds_read_b128 v[192:195], v150
	ds_read_b128 v[196:199], v150 offset:1024
	ds_read_b128 v[200:203], v149
	ds_read_b128 v[204:207], v149 offset:1024
	global_load_lds_dwordx4 v[208:209], off
	v_lshl_add_u64 v[208:209], s[60:61], 0, v[132:133]
	v_readfirstlane_b32 s60, v170
	v_lshl_add_u64 v[208:209], v[208:209], 0, s[50:51]
	s_mov_b32 m0, s60
	s_nop 0
	global_load_lds_dwordx4 v[208:209], off
	s_barrier
	s_waitcnt lgkmcnt(0)
	v_mfma_f32_16x16x32_bf16 v[124:127], v[176:179], v[134:137], v[124:127]
	v_mfma_f32_16x16x32_bf16 v[120:123], v[176:179], v[156:159], v[120:123]
	v_mfma_f32_16x16x32_bf16 v[116:119], v[184:187], v[134:137], v[116:119]
	v_mfma_f32_16x16x32_bf16 v[112:115], v[184:187], v[156:159], v[112:115]
	v_mfma_f32_16x16x32_bf16 v[108:111], v[192:195], v[134:137], v[108:111]
	v_mfma_f32_16x16x32_bf16 v[104:107], v[192:195], v[156:159], v[104:107]
	v_mfma_f32_16x16x32_bf16 v[100:103], v[200:203], v[134:137], v[100:103]
	v_mfma_f32_16x16x32_bf16 v[96:99], v[200:203], v[156:159], v[96:99]
	v_mfma_f32_16x16x32_bf16 v[124:127], v[180:183], v[138:141], v[124:127]
	v_mfma_f32_16x16x32_bf16 v[120:123], v[180:183], v[172:175], v[120:123]
	v_mfma_f32_16x16x32_bf16 v[116:119], v[188:191], v[138:141], v[116:119]
	v_mfma_f32_16x16x32_bf16 v[112:115], v[188:191], v[172:175], v[112:115]
	v_mfma_f32_16x16x32_bf16 v[108:111], v[196:199], v[138:141], v[108:111]
	v_mfma_f32_16x16x32_bf16 v[104:107], v[196:199], v[172:175], v[104:107]
	v_mfma_f32_16x16x32_bf16 v[100:103], v[204:207], v[138:141], v[100:103]
	v_mfma_f32_16x16x32_bf16 v[96:99], v[204:207], v[172:175], v[96:99]
	s_barrier
	ds_read_b128 v[208:211], v160
	ds_read_b128 v[212:215], v160 offset:1024
	ds_read_b128 v[216:219], v160 offset:2048
	ds_read_b128 v[220:223], v160 offset:3072
	s_barrier
; #define LDA(dst, b, h) for (int m = 0; m < 4; ++m) for (int k = 0; k < 2; ++k) \
;     dst[m][k] = *reinterpret_cast<const bf16x8*>((char*)SA(b, h) + lds_byte(wr * 64 + m * 16 + fr, k * 32 + fq * 8))
; #define LDB(dst, b, h) for (int n = 0; n < 2; ++n) for (int k = 0; k < 2; ++k) \
;     dst[n][k] = *reinterpret_cast<const bf16x8*>((char*)SB(b, h) + lds_byte(wc * 32 + n * 16 + fr, k * 32 + fq * 8))
; #define MMA(ai, bj, At_, Bt_) do { __builtin_amdgcn_s_setprio(1); \
;     for (int k = 0; k < 2; ++k) for (int m = 0; m < 4; ++m) for (int n = 0; n < 2; ++n) \
;       acc[ai][bj][m][n] = __builtin_amdgcn_mfma_f32_16x16x32_bf16(At_[m][k], Bt_[n][k], acc[ai][bj][m][n], 0, 0, 0); \
;     __builtin_amdgcn_s_setprio(0); } while (0)
; #define WAIT_V(n) asm volatile("s_waitcnt vmcnt(" #n ")" ::: "memory")
; #define WAIT_L(n) asm volatile("s_waitcnt lgkmcnt(" #n ")" ::: "memory")
; #define BAR __builtin_amdgcn_s_barrier()
; template <int EPI, int lda, int ldb, int N, int K>
; __device__ __forceinline__ void gemm_phase(const u16* __restrict__ A, const u16* __restrict__ Bt, const GemmEpi ep, int wv) {
;     ...
;       LDB(B1, 0, 1); BAR; WAIT_L(0); MMA(0, 1, At, B1); BAR;
;       LDA(At, 0, 1); WAIT_V(4); BAR; WAIT_L(0); MMA(1, 0, At, B0); MMA(1, 1, At, B1); BAR; }
;     { LDB(B0, 1, 0); LDA(At, 1, 0); WAIT_V(2); BAR; WAIT_L(0); MMA(0, 0, At, B0); BAR;
	s_waitcnt lgkmcnt(0)
	v_mfma_f32_16x16x32_bf16 v[92:95], v[176:179], v[208:211], v[92:95]
	v_mfma_f32_16x16x32_bf16 v[88:91], v[176:179], v[216:219], v[88:91]
	v_mfma_f32_16x16x32_bf16 v[76:79], v[192:195], v[208:211], v[76:79]
	v_mfma_f32_16x16x32_bf16 v[72:75], v[192:195], v[216:219], v[72:75]
	v_mfma_f32_16x16x32_bf16 v[84:87], v[184:187], v[208:211], v[84:87]
	v_mfma_f32_16x16x32_bf16 v[80:83], v[184:187], v[216:219], v[80:83]
	v_mfma_f32_16x16x32_bf16 v[68:71], v[200:203], v[208:211], v[68:71]
	v_mfma_f32_16x16x32_bf16 v[64:67], v[200:203], v[216:219], v[64:67]
	v_mfma_f32_16x16x32_bf16 v[92:95], v[180:183], v[212:215], v[92:95]
	v_mfma_f32_16x16x32_bf16 v[88:91], v[180:183], v[220:223], v[88:91]
	v_mfma_f32_16x16x32_bf16 v[76:79], v[196:199], v[212:215], v[76:79]
	v_mfma_f32_16x16x32_bf16 v[72:75], v[196:199], v[220:223], v[72:75]
	v_mfma_f32_16x16x32_bf16 v[176:179], v[188:191], v[212:215], v[84:87]
	v_mfma_f32_16x16x32_bf16 v[180:183], v[188:191], v[220:223], v[80:83]
	v_mfma_f32_16x16x32_bf16 v[184:187], v[204:207], v[212:215], v[68:71]
	v_mfma_f32_16x16x32_bf16 v[188:191], v[204:207], v[220:223], v[64:67]
	s_barrier
	s_nop 0
	ds_read_b128 v[64:67], v152 offset:16384
	ds_read_b128 v[68:71], v152 offset:17408
	ds_read_b128 v[80:83], v151 offset:16384
	ds_read_b128 v[84:87], v151 offset:17408
	ds_read_b128 v[192:195], v150 offset:16384
	ds_read_b128 v[196:199], v150 offset:17408
	ds_read_b128 v[200:203], v149 offset:16384
	ds_read_b128 v[204:207], v149 offset:17408
	s_waitcnt vmcnt(4)
	s_barrier
	s_waitcnt lgkmcnt(0)
	v_mfma_f32_16x16x32_bf16 v[60:63], v[64:67], v[134:137], v[60:63]
	v_mfma_f32_16x16x32_bf16 v[56:59], v[64:67], v[156:159], v[56:59]
	v_mfma_f32_16x16x32_bf16 v[52:55], v[80:83], v[134:137], v[52:55]
	v_mfma_f32_16x16x32_bf16 v[48:51], v[80:83], v[156:159], v[48:51]
	v_mfma_f32_16x16x32_bf16 v[44:47], v[192:195], v[134:137], v[44:47]
	v_mfma_f32_16x16x32_bf16 v[40:43], v[192:195], v[156:159], v[40:43]
	v_mfma_f32_16x16x32_bf16 v[36:39], v[200:203], v[134:137], v[36:39]
	v_mfma_f32_16x16x32_bf16 v[32:35], v[200:203], v[156:159], v[32:35]
	v_mfma_f32_16x16x32_bf16 v[60:63], v[68:71], v[138:141], v[60:63]
	v_mfma_f32_16x16x32_bf16 v[56:59], v[68:71], v[172:175], v[56:59]
	v_mfma_f32_16x16x32_bf16 v[52:55], v[84:87], v[138:141], v[52:55]
	v_mfma_f32_16x16x32_bf16 v[48:51], v[84:87], v[172:175], v[48:51]
	v_mfma_f32_16x16x32_bf16 v[44:47], v[196:199], v[138:141], v[44:47]
	v_mfma_f32_16x16x32_bf16 v[40:43], v[196:199], v[172:175], v[40:43]
	v_mfma_f32_16x16x32_bf16 v[36:39], v[204:207], v[138:141], v[36:39]
	v_mfma_f32_16x16x32_bf16 v[32:35], v[204:207], v[172:175], v[32:35]
	v_mfma_f32_16x16x32_bf16 v[28:31], v[64:67], v[208:211], v[28:31]
	v_mfma_f32_16x16x32_bf16 v[24:27], v[64:67], v[216:219], v[24:27]
	v_mfma_f32_16x16x32_bf16 v[12:15], v[192:195], v[208:211], v[12:15]
	v_mfma_f32_16x16x32_bf16 v[8:11], v[192:195], v[216:219], v[8:11]
	v_mfma_f32_16x16x32_bf16 v[20:23], v[80:83], v[208:211], v[20:23]
	v_mfma_f32_16x16x32_bf16 v[16:19], v[80:83], v[216:219], v[16:19]
	v_mfma_f32_16x16x32_bf16 v[4:7], v[200:203], v[208:211], v[4:7]
	v_mfma_f32_16x16x32_bf16 v[0:3], v[200:203], v[216:219], v[0:3]
	v_mfma_f32_16x16x32_bf16 v[28:31], v[68:71], v[212:215], v[28:31]
	v_mfma_f32_16x16x32_bf16 v[24:27], v[68:71], v[220:223], v[24:27]
	v_mfma_f32_16x16x32_bf16 v[12:15], v[196:199], v[212:215], v[12:15]
	v_mfma_f32_16x16x32_bf16 v[8:11], v[196:199], v[220:223], v[8:11]
	v_mfma_f32_16x16x32_bf16 v[134:137], v[84:87], v[212:215], v[20:23]
	v_mfma_f32_16x16x32_bf16 v[138:141], v[84:87], v[220:223], v[16:19]
	v_mfma_f32_16x16x32_bf16 v[156:159], v[204:207], v[212:215], v[4:7]
	v_mfma_f32_16x16x32_bf16 v[170:173], v[204:207], v[220:223], v[0:3]
	s_barrier
	s_nop 0
	ds_read_b128 v[0:3], v155
	ds_read_b128 v[4:7], v155 offset:1024
	ds_read_b128 v[16:19], v155 offset:2048
	ds_read_b128 v[192:195], v155 offset:3072
	ds_read_b128 v[20:23], v152 offset:32768
	ds_read_b128 v[196:199], v152 offset:33792
	ds_read_b128 v[200:203], v151 offset:32768
	ds_read_b128 v[204:207], v151 offset:33792
	ds_read_b128 v[208:211], v150 offset:32768
	ds_read_b128 v[212:215], v150 offset:33792
	ds_read_b128 v[216:219], v149 offset:32768
	ds_read_b128 v[220:223], v149 offset:33792
	s_waitcnt vmcnt(2)
	s_barrier
; #define LDA(dst, b, h) for (int m = 0; m < 4; ++m) for (int k = 0; k < 2; ++k) \
;     dst[m][k] = *reinterpret_cast<const bf16x8*>((char*)SA(b, h) + lds_byte(wr * 64 + m * 16 + fr, k * 32 + fq * 8))
; #define LDB(dst, b, h) for (int n = 0; n < 2; ++n) for (int k = 0; k < 2; ++k) \
;     dst[n][k] = *reinterpret_cast<const bf16x8*>((char*)SB(b, h) + lds_byte(wc * 32 + n * 16 + fr, k * 32 + fq * 8))
; #define MMA(ai, bj, At_, Bt_) do { __builtin_amdgcn_s_setprio(1); \
;     for (int k = 0; k < 2; ++k) for (int m = 0; m < 4; ++m) for (int n = 0; n < 2; ++n) \
;       acc[ai][bj][m][n] = __builtin_amdgcn_mfma_f32_16x16x32_bf16(At_[m][k], Bt_[n][k], acc[ai][bj][m][n], 0, 0, 0); \
;     __builtin_amdgcn_s_setprio(0); } while (0)
; #define WAIT_V(n) asm volatile("s_waitcnt vmcnt(" #n ")" ::: "memory")
; #define WAIT_L(n) asm volatile("s_waitcnt lgkmcnt(" #n ")" ::: "memory")
; #define BAR __builtin_amdgcn_s_barrier()
; template <int EPI, int lda, int ldb, int N, int K>
; __device__ __forceinline__ void gemm_phase(const u16* __restrict__ A, const u16* __restrict__ Bt, const GemmEpi ep, int wv) {
;     ...
;     { LDB(B0, 1, 0); LDA(At, 1, 0); WAIT_V(2); BAR; WAIT_L(0); MMA(0, 0, At, B0); BAR;
;       LDB(B1, 1, 1); WAIT_V(0); BAR; WAIT_L(0); MMA(0, 1, At, B1); BAR;
;       LDA(At, 1, 1); BAR; WAIT_L(0); MMA(1, 0, At, B0); MMA(1, 1, At, B1); BAR; }
;     if (wr == 0) BAR;
	s_waitcnt lgkmcnt(0)
	v_mfma_f32_16x16x32_bf16 v[64:67], v[20:23], v[0:3], v[124:127]
	v_mfma_f32_16x16x32_bf16 v[68:71], v[20:23], v[16:19], v[120:123]
	v_mfma_f32_16x16x32_bf16 v[80:83], v[200:203], v[0:3], v[116:119]
	v_mfma_f32_16x16x32_bf16 v[84:87], v[200:203], v[16:19], v[112:115]
	v_mfma_f32_16x16x32_bf16 v[108:111], v[208:211], v[0:3], v[108:111]
	v_mfma_f32_16x16x32_bf16 v[104:107], v[208:211], v[16:19], v[104:107]
	v_mfma_f32_16x16x32_bf16 v[120:123], v[216:219], v[0:3], v[100:103]
	v_mfma_f32_16x16x32_bf16 v[124:127], v[216:219], v[16:19], v[96:99]
	v_mfma_f32_16x16x32_bf16 v[116:119], v[196:199], v[4:7], v[64:67]
	v_mfma_f32_16x16x32_bf16 v[112:115], v[196:199], v[192:195], v[68:71]
	v_mfma_f32_16x16x32_bf16 v[100:103], v[204:207], v[4:7], v[80:83]
	v_mfma_f32_16x16x32_bf16 v[96:99], v[204:207], v[192:195], v[84:87]
	v_mfma_f32_16x16x32_bf16 v[84:87], v[212:215], v[4:7], v[108:111]
	v_mfma_f32_16x16x32_bf16 v[80:83], v[212:215], v[192:195], v[104:107]
	v_mfma_f32_16x16x32_bf16 v[68:71], v[220:223], v[4:7], v[120:123]
	v_mfma_f32_16x16x32_bf16 v[64:67], v[220:223], v[192:195], v[124:127]
	s_barrier
	ds_read_b128 v[224:227], v153
	ds_read_b128 v[228:231], v153 offset:1024
	ds_read_b128 v[232:235], v153 offset:2048
	ds_read_b128 v[236:239], v153 offset:3072
	s_waitcnt vmcnt(0)
	s_barrier
	s_waitcnt lgkmcnt(0)
	v_mfma_f32_16x16x32_bf16 v[92:95], v[20:23], v[224:227], v[92:95]
	v_mfma_f32_16x16x32_bf16 v[20:23], v[20:23], v[232:235], v[88:91]
	v_mfma_f32_16x16x32_bf16 v[88:91], v[200:203], v[224:227], v[176:179]
	v_mfma_f32_16x16x32_bf16 v[104:107], v[200:203], v[232:235], v[180:183]
	v_mfma_f32_16x16x32_bf16 v[76:79], v[208:211], v[224:227], v[76:79]
	v_mfma_f32_16x16x32_bf16 v[72:75], v[208:211], v[232:235], v[72:75]
	v_mfma_f32_16x16x32_bf16 v[174:177], v[216:219], v[224:227], v[184:187]
	v_mfma_f32_16x16x32_bf16 v[178:181], v[216:219], v[232:235], v[188:191]
	v_mfma_f32_16x16x32_bf16 v[124:127], v[196:199], v[228:231], v[92:95]
	v_mfma_f32_16x16x32_bf16 v[120:123], v[196:199], v[236:239], v[20:23]
	v_mfma_f32_16x16x32_bf16 v[108:111], v[204:207], v[228:231], v[88:91]
	v_mfma_f32_16x16x32_bf16 v[104:107], v[204:207], v[236:239], v[104:107]
	v_mfma_f32_16x16x32_bf16 v[92:95], v[212:215], v[228:231], v[76:79]
	v_mfma_f32_16x16x32_bf16 v[88:91], v[212:215], v[236:239], v[72:75]
	v_mfma_f32_16x16x32_bf16 v[76:79], v[220:223], v[228:231], v[174:177]
	v_mfma_f32_16x16x32_bf16 v[72:75], v[220:223], v[236:239], v[178:181]
	s_barrier
	ds_read_b128 v[174:177], v152 offset:49152
	ds_read_b128 v[152:155], v152 offset:50176
	ds_read_b128 v[178:181], v151 offset:49152
	ds_read_b128 v[182:185], v151 offset:50176
	ds_read_b128 v[186:189], v150 offset:49152
	ds_read_b128 v[196:199], v150 offset:50176
	ds_read_b128 v[200:203], v149 offset:49152
	ds_read_b128 v[204:207], v149 offset:50176
	s_barrier
	s_waitcnt lgkmcnt(0)
	v_mfma_f32_16x16x32_bf16 v[20:23], v[174:177], v[0:3], v[60:63]
	v_mfma_f32_16x16x32_bf16 v[56:59], v[174:177], v[16:19], v[56:59]
	v_mfma_f32_16x16x32_bf16 v[60:63], v[178:181], v[0:3], v[52:55]
	v_mfma_f32_16x16x32_bf16 v[208:211], v[178:181], v[16:19], v[48:51]
	v_mfma_f32_16x16x32_bf16 v[44:47], v[186:189], v[0:3], v[44:47]
	v_mfma_f32_16x16x32_bf16 v[40:43], v[186:189], v[16:19], v[40:43]
	v_mfma_f32_16x16x32_bf16 v[0:3], v[200:203], v[0:3], v[36:39]
	v_mfma_f32_16x16x32_bf16 v[212:215], v[200:203], v[16:19], v[32:35]
	v_mfma_f32_16x16x32_bf16 v[52:55], v[152:155], v[4:7], v[20:23]
	v_mfma_f32_16x16x32_bf16 v[48:51], v[152:155], v[192:195], v[56:59]
	v_mfma_f32_16x16x32_bf16 v[36:39], v[182:185], v[4:7], v[60:63]
	v_mfma_f32_16x16x32_bf16 v[32:35], v[182:185], v[192:195], v[208:211]
	v_mfma_f32_16x16x32_bf16 v[20:23], v[196:199], v[4:7], v[44:47]
	v_mfma_f32_16x16x32_bf16 v[16:19], v[196:199], v[192:195], v[40:43]
	v_mfma_f32_16x16x32_bf16 v[4:7], v[204:207], v[4:7], v[0:3]
	v_mfma_f32_16x16x32_bf16 v[0:3], v[204:207], v[192:195], v[212:215]
	v_mfma_f32_16x16x32_bf16 v[28:31], v[174:177], v[224:227], v[28:31]
	v_mfma_f32_16x16x32_bf16 v[24:27], v[174:177], v[232:235], v[24:27]
	v_mfma_f32_16x16x32_bf16 v[40:43], v[178:181], v[224:227], v[134:137]
	v_mfma_f32_16x16x32_bf16 v[134:137], v[178:181], v[232:235], v[138:141]
	v_mfma_f32_16x16x32_bf16 v[12:15], v[186:189], v[224:227], v[12:15]
	v_mfma_f32_16x16x32_bf16 v[8:11], v[186:189], v[232:235], v[8:11]
	v_mfma_f32_16x16x32_bf16 v[138:141], v[200:203], v[224:227], v[156:159]
	v_mfma_f32_16x16x32_bf16 v[156:159], v[200:203], v[232:235], v[170:173]
	v_mfma_f32_16x16x32_bf16 v[60:63], v[152:155], v[228:231], v[28:31]
	v_mfma_f32_16x16x32_bf16 v[56:59], v[152:155], v[236:239], v[24:27]
	v_mfma_f32_16x16x32_bf16 v[44:47], v[182:185], v[228:231], v[40:43]
	v_mfma_f32_16x16x32_bf16 v[40:43], v[182:185], v[236:239], v[134:137]
	v_mfma_f32_16x16x32_bf16 v[28:31], v[196:199], v[228:231], v[12:15]
	v_mfma_f32_16x16x32_bf16 v[24:27], v[196:199], v[236:239], v[8:11]
	v_mfma_f32_16x16x32_bf16 v[12:15], v[204:207], v[228:231], v[138:141]
	v_mfma_f32_16x16x32_bf16 v[8:11], v[204:207], v[236:239], v[156:159]
	v_cmp_gt_u32_e32 vcc, s80, v130
	s_barrier
	s_and_saveexec_b64 s[60:61], vcc
	s_cbranch_execz .LBB0_1150
	s_barrier

; #define STAGE(P, BASE, LD, br, kt) do { const char* _g = (const char*)((BASE) + (size_t)(br) * (LD) + (size_t)(kt) * 64); \
;     for (int _i = 0; _i < 2; ++_i) { int _b = tidx * 16 + _i * 8192; int _r, _c; stage_rc(_b, _r, _c); \
;       __builtin_amdgcn_global_load_lds((const unsigned*)(_g + (unsigned)((_r * (LD) + _c) * 2)), (unsigned*)((char*)(P) + _b), 16, 0, 0); } } while (0)
; #define LDA(dst, b, h) for (int m = 0; m < 4; ++m) for (int k = 0; k < 2; ++k) \
;     dst[m][k] = *reinterpret_cast<const bf16x8*>((char*)SA(b, h) + lds_byte(wr * 64 + m * 16 + fr, k * 32 + fq * 8))
; #define LDB(dst, b, h) for (int n = 0; n < 2; ++n) for (int k = 0; k < 2; ++k) \
;     dst[n][k] = *reinterpret_cast<const bf16x8*>((char*)SB(b, h) + lds_byte(wc * 32 + n * 16 + fr, k * 32 + fq * 8))
; #define MMA(ai, bj, At_, Bt_) do { __builtin_amdgcn_s_setprio(1); \
;     for (int k = 0; k < 2; ++k) for (int m = 0; m < 4; ++m) for (int n = 0; n < 2; ++n) \
;       acc[ai][bj][m][n] = __builtin_amdgcn_mfma_f32_16x16x32_bf16(At_[m][k], Bt_[n][k], acc[ai][bj][m][n], 0, 0, 0); \
;     __builtin_amdgcn_s_setprio(0); } while (0)
; #define WAIT_V(n) asm volatile("s_waitcnt vmcnt(" #n ")" ::: "memory")
; template <int EPI, int lda, int ldb, int N, int K>
; __device__ __forceinline__ void gemm_phase(const u16* __restrict__ A, const u16* __restrict__ Bt, const GemmEpi ep, int wv) {
;     ...
;     if constexpr (!PF) { TILE_COORDS(tile, brow, bcol, pn); STAGE4(brow, bcol, pn); }
;     const int wid = tidx >> 6, lane = tidx & 63, wr = wid >> 2, wc = wid & 3, fr = lane & 15, fq = lane >> 4;
;     const u16* Ab = A + (EPI == EPI_RG ? (pn >> 1) * 256 : 0);
;     f32x4 acc[2][2][4][2] = {};
;     bf16x8 At[4][2], B0[2][2], B1[2][2];
;     constexpr int nt = K / 64;
;     if (wr == 1) BAR;
;     WAIT_V(4); BAR;
;     STAGE(SB(1, 0), Bt, ldb, bcol, 1); STAGE(SA(1, 0), Ab, lda, brow, 1); STAGE(SB(1, 1), Bt, ldb, bcol + HALF, 1);
;     WAIT_V(6); BAR;
;     for (int t = 0; t < nt - 2; t += 2) {
;       LDB(B0, 0, 0); SCHED; LDA(At, 0, 0); STAGE(SA(1, 1), Ab, lda, brow + HALF, t + 1);
;       WAIT_L(8); BAR; WAIT_L(0); MMA(0, 0, At, B0); BAR; SCHED;
;       LDB(B1, 0, 1); STAGE(SB(0, 0), Bt, ldb, bcol, t + 2);
;       BAR; WAIT_L(0); MMA(0, 1, At, B1); BAR;
;       LDA(At, 0, 1); STAGE(SA(0, 0), Ab, lda, brow, t + 2);
;       BAR; WAIT_L(0); MMA(1, 0, At, B0); BAR; SCHED;
.LBB0_1248:
	s_or_b64 exec, exec, s[54:55]
	v_mov_b32_e32 v1, v129
	v_add_u32_e32 v7, s60, v6
	v_lshl_add_u64 v[12:13], s[46:47], 0, v[128:129]
	v_lshl_add_u64 v[14:15], s[46:47], 0, v[0:1]
	v_lshl_add_u64 v[2:3], s[52:53], 0, v[128:129]
	v_lshl_add_u64 v[0:1], s[52:53], 0, v[0:1]
	v_readfirstlane_b32 s53, v7
	v_add_u32_e32 v7, 0x2000, v7
	v_mov_b32_e32 v5, v129
	v_mov_b32_e32 v17, v129
	v_lshl_add_u64 v[26:27], v[12:13], 0, s[40:41]
	s_mov_b32 m0, s53
	v_readfirstlane_b32 s52, v7
	v_add_u32_e32 v7, 0x8000, v23
	v_lshl_add_u64 v[8:9], s[50:51], 0, v[4:5]
	v_lshl_add_u64 v[10:11], s[50:51], 0, v[16:17]
	s_waitcnt vmcnt(4)
	s_barrier
	global_load_lds_dwordx4 v[26:27], off
	v_lshl_add_u64 v[26:27], v[14:15], 0, s[40:41]
	s_mov_b32 m0, s52
	v_readfirstlane_b32 s51, v7
	v_add_u32_e32 v7, 0xa000, v23
	global_load_lds_dwordx4 v[26:27], off
	v_lshl_add_u64 v[26:27], v[8:9], 0, s[40:41]
	s_mov_b32 m0, s51
	v_readfirstlane_b32 s50, v7
	v_add_u32_e32 v25, s61, v6
	global_load_lds_dwordx4 v[26:27], off
	v_lshl_add_u64 v[26:27], v[10:11], 0, s[40:41]
	s_mov_b32 m0, s50
	v_readfirstlane_b32 s13, v25
	v_add_u32_e32 v25, 0x2000, v25
	global_load_lds_dwordx4 v[26:27], off
	v_lshl_add_u64 v[26:27], v[2:3], 0, s[40:41]
	s_mov_b32 m0, s13
	v_readfirstlane_b32 s11, v25
	global_load_lds_dwordx4 v[26:27], off
	v_lshl_add_u64 v[6:7], v[0:1], 0, s[40:41]
	s_mov_b32 m0, s11
	v_and_b32_e32 v132, 15, v20
	global_load_lds_dwordx4 v[6:7], off
	v_bfe_u32 v128, v20, 4, 2
	v_lshlrev_b32_e32 v7, 2, v20
	v_bfe_u32 v131, v130, 6, 2
	v_lshlrev_b32_e32 v25, 4, v128
	v_lshlrev_b32_e32 v6, 6, v132
	v_and_b32_e32 v50, 32, v7
	v_lshlrev_b32_e32 v126, 12, v131
	v_bitop3_b32 v127, v25, v50, v6 bitop3:0x36
	v_add3_u32 v133, s58, v127, v126
	s_waitcnt vmcnt(6)
	s_barrier
	ds_read_b128 v[26:29], v133
	ds_read_b128 v[30:33], v133 offset:1024
	ds_read_b128 v[34:37], v133 offset:2048
	ds_read_b128 v[38:41], v133 offset:3072
	v_lshl_add_u64 v[6:7], s[48:49], 0, v[4:5]
	v_lshl_add_u64 v[4:5], s[48:49], 0, v[16:17]
	v_lshlrev_b32_e32 v17, 6, v20
	v_and_b32_e32 v17, 0x3c0, v17
	v_add_u32_e32 v20, 0xc000, v23
	v_lshlrev_b32_e32 v16, 13, v143
	v_bitop3_b32 v17, v17, v50, v25 bitop3:0x36
	v_readfirstlane_b32 s47, v20
	v_add_u32_e32 v20, 0xe000, v23
	v_add3_u32 v228, 0, v127, v16
	v_add3_u32 v229, 0, v17, v16
	v_lshl_add_u64 v[16:17], v[6:7], 0, s[40:41]
	s_mov_b32 m0, s47
	v_readfirstlane_b32 s46, v20
	ds_read_b128 v[42:45], v228
	ds_read_b128 v[46:49], v228 offset:1024
	ds_read_b128 v[50:53], v229 offset:2048
	ds_read_b128 v[54:57], v229 offset:3072
	ds_read_b128 v[58:61], v229 offset:4096
	ds_read_b128 v[62:65], v229 offset:5120
	ds_read_b128 v[66:69], v229 offset:6144
	ds_read_b128 v[70:73], v229 offset:7168
	global_load_lds_dwordx4 v[16:17], off
	v_lshl_add_u64 v[16:17], v[4:5], 0, s[40:41]
	s_mov_b32 m0, s46
	s_nop 0
	global_load_lds_dwordx4 v[16:17], off
	s_waitcnt lgkmcnt(8)
	s_barrier
	s_waitcnt lgkmcnt(0)
	v_mfma_f32_16x16x32_bf16 v[74:77], v[42:45], v[26:29], 0
	v_mfma_f32_16x16x32_bf16 v[78:81], v[42:45], v[34:37], 0
	v_mfma_f32_16x16x32_bf16 v[82:85], v[50:53], v[26:29], 0
	v_mfma_f32_16x16x32_bf16 v[86:89], v[50:53], v[34:37], 0
	v_mfma_f32_16x16x32_bf16 v[90:93], v[58:61], v[26:29], 0
	v_mfma_f32_16x16x32_bf16 v[94:97], v[58:61], v[34:37], 0
	v_mfma_f32_16x16x32_bf16 v[98:101], v[66:69], v[26:29], 0
	v_mfma_f32_16x16x32_bf16 v[102:105], v[66:69], v[34:37], 0
	v_mfma_f32_16x16x32_bf16 v[74:77], v[46:49], v[30:33], v[74:77]
	v_mfma_f32_16x16x32_bf16 v[78:81], v[46:49], v[38:41], v[78:81]
	v_mfma_f32_16x16x32_bf16 v[82:85], v[54:57], v[30:33], v[82:85]
	v_mfma_f32_16x16x32_bf16 v[86:89], v[54:57], v[38:41], v[86:89]
	v_mfma_f32_16x16x32_bf16 v[90:93], v[62:65], v[30:33], v[90:93]
	v_mfma_f32_16x16x32_bf16 v[94:97], v[62:65], v[38:41], v[94:97]
	v_mfma_f32_16x16x32_bf16 v[98:101], v[70:73], v[30:33], v[98:101]
	v_mfma_f32_16x16x32_bf16 v[102:105], v[70:73], v[38:41], v[102:105]
	s_barrier
	v_readfirstlane_b32 s48, v21
	v_add_u32_e32 v20, 0x2000, v21
	v_add3_u32 v224, s59, v127, v126
	v_lshl_add_u64 v[16:17], v[12:13], 0, s[42:43]
	s_mov_b32 m0, s48
	v_readfirstlane_b32 s48, v20
	ds_read_b128 v[106:109], v224
	ds_read_b128 v[110:113], v224 offset:1024
	ds_read_b128 v[114:117], v224 offset:2048
	ds_read_b128 v[118:121], v224 offset:3072
	global_load_lds_dwordx4 v[16:17], off
	v_lshl_add_u64 v[16:17], v[14:15], 0, s[42:43]
	s_mov_b32 m0, s48
	s_nop 0
	global_load_lds_dwordx4 v[16:17], off
	s_barrier
	s_waitcnt lgkmcnt(0)
	v_mfma_f32_16x16x32_bf16 v[122:125], v[42:45], v[106:109], 0
	v_mfma_f32_16x16x32_bf16 v[42:45], v[42:45], v[114:117], 0
	v_mfma_f32_16x16x32_bf16 v[134:137], v[50:53], v[106:109], 0
	v_mfma_f32_16x16x32_bf16 v[50:53], v[50:53], v[114:117], 0
	v_mfma_f32_16x16x32_bf16 v[144:147], v[58:61], v[106:109], 0
	v_mfma_f32_16x16x32_bf16 v[58:61], v[58:61], v[114:117], 0
	v_mfma_f32_16x16x32_bf16 v[148:151], v[66:69], v[106:109], 0
	v_mfma_f32_16x16x32_bf16 v[66:69], v[66:69], v[114:117], 0
	v_mfma_f32_16x16x32_bf16 v[122:125], v[46:49], v[110:113], v[122:125]
	v_mfma_f32_16x16x32_bf16 v[42:45], v[46:49], v[118:121], v[42:45]
	v_mfma_f32_16x16x32_bf16 v[46:49], v[54:57], v[110:113], v[134:137]
	v_mfma_f32_16x16x32_bf16 v[50:53], v[54:57], v[118:121], v[50:53]
	v_mfma_f32_16x16x32_bf16 v[54:57], v[62:65], v[110:113], v[144:147]
	v_mfma_f32_16x16x32_bf16 v[58:61], v[62:65], v[118:121], v[58:61]
	v_mfma_f32_16x16x32_bf16 v[62:65], v[70:73], v[110:113], v[148:151]
	v_mfma_f32_16x16x32_bf16 v[66:69], v[70:73], v[118:121], v[66:69]
	v_readfirstlane_b32 s48, v23
	v_lshl_add_u64 v[16:17], v[8:9], 0, s[42:43]
	s_mov_b32 m0, s48
	v_readfirstlane_b32 s48, v24
	s_barrier
; #define STAGE(P, BASE, LD, br, kt) do { const char* _g = (const char*)((BASE) + (size_t)(br) * (LD) + (size_t)(kt) * 64); \
;     for (int _i = 0; _i < 2; ++_i) { int _b = tidx * 16 + _i * 8192; int _r, _c; stage_rc(_b, _r, _c); \
;       __builtin_amdgcn_global_load_lds((const unsigned*)(_g + (unsigned)((_r * (LD) + _c) * 2)), (unsigned*)((char*)(P) + _b), 16, 0, 0); } } while (0)
; #define LDA(dst, b, h) for (int m = 0; m < 4; ++m) for (int k = 0; k < 2; ++k) \
;     dst[m][k] = *reinterpret_cast<const bf16x8*>((char*)SA(b, h) + lds_byte(wr * 64 + m * 16 + fr, k * 32 + fq * 8))
; #define LDB(dst, b, h) for (int n = 0; n < 2; ++n) for (int k = 0; k < 2; ++k) \
;     dst[n][k] = *reinterpret_cast<const bf16x8*>((char*)SB(b, h) + lds_byte(wc * 32 + n * 16 + fr, k * 32 + fq * 8))
; #define MMA(ai, bj, At_, Bt_) do { __builtin_amdgcn_s_setprio(1); \
;     for (int k = 0; k < 2; ++k) for (int m = 0; m < 4; ++m) for (int n = 0; n < 2; ++n) \
;       acc[ai][bj][m][n] = __builtin_amdgcn_mfma_f32_16x16x32_bf16(At_[m][k], Bt_[n][k], acc[ai][bj][m][n], 0, 0, 0); \
;     __builtin_amdgcn_s_setprio(0); } while (0)
; #define WAIT_V(n) asm volatile("s_waitcnt vmcnt(" #n ")" ::: "memory")
; #define WAIT_L(n) asm volatile("s_waitcnt lgkmcnt(" #n ")" ::: "memory")
; #define BAR __builtin_amdgcn_s_barrier()
; #define SCHED __builtin_amdgcn_sched_barrier(0)
; template <int EPI, int lda, int ldb, int N, int K>
; __device__ __forceinline__ void gemm_phase(const u16* __restrict__ A, const u16* __restrict__ Bt, const GemmEpi ep, int wv) {
;     ...
;       BAR; WAIT_L(0); MMA(1, 0, At, B0); BAR; SCHED;
;       STAGE(SB(0, 1), Bt, ldb, bcol + HALF, t + 2);
;       WAIT_V(6); BAR; MMA(1, 1, At, B1); BAR;
;       LDB(B0, 1, 0); SCHED; LDA(At, 1, 0); STAGE(SA(0, 1), Ab, lda, brow + HALF, t + 2);
;       WAIT_L(8); BAR; WAIT_L(0); MMA(0, 0, At, B0); BAR; SCHED;
;       LDB(B1, 1, 1); STAGE(SB(1, 0), Bt, ldb, bcol, t + 3);
;       BAR; WAIT_L(0); MMA(0, 1, At, B1); BAR;
;       LDA(At, 1, 1); STAGE(SA(1, 0), Ab, lda, brow, t + 3);
;       BAR; WAIT_L(0); MMA(1, 0, At, B0); BAR; SCHED;
	ds_read_b128 v[70:73], v228 offset:16384
	ds_read_b128 v[134:137], v228 offset:17408
	ds_read_b128 v[144:147], v229 offset:18432
	ds_read_b128 v[148:151], v229 offset:19456
	ds_read_b128 v[152:155], v229 offset:20480
	ds_read_b128 v[156:159], v229 offset:21504
	ds_read_b128 v[160:163], v229 offset:22528
	ds_read_b128 v[164:167], v229 offset:23552
	global_load_lds_dwordx4 v[16:17], off
	v_lshl_add_u64 v[16:17], v[10:11], 0, s[42:43]
	s_mov_b32 m0, s48
	s_nop 0
	global_load_lds_dwordx4 v[16:17], off
	s_barrier
	s_waitcnt lgkmcnt(0)
	v_mfma_f32_16x16x32_bf16 v[168:171], v[70:73], v[26:29], 0
	v_mfma_f32_16x16x32_bf16 v[172:175], v[70:73], v[34:37], 0
	v_mfma_f32_16x16x32_bf16 v[176:179], v[144:147], v[26:29], 0
	v_mfma_f32_16x16x32_bf16 v[180:183], v[144:147], v[34:37], 0
	v_mfma_f32_16x16x32_bf16 v[184:187], v[152:155], v[26:29], 0
	v_mfma_f32_16x16x32_bf16 v[188:191], v[152:155], v[34:37], 0
	v_mfma_f32_16x16x32_bf16 v[24:27], v[160:163], v[26:29], 0
	v_mfma_f32_16x16x32_bf16 v[34:37], v[160:163], v[34:37], 0
	v_mfma_f32_16x16x32_bf16 v[168:171], v[134:137], v[30:33], v[168:171]
	v_mfma_f32_16x16x32_bf16 v[176:179], v[148:151], v[30:33], v[176:179]
	v_mfma_f32_16x16x32_bf16 v[184:187], v[156:159], v[30:33], v[184:187]
	v_mfma_f32_16x16x32_bf16 v[24:27], v[164:167], v[30:33], v[24:27]
	v_mfma_f32_16x16x32_bf16 v[28:31], v[164:167], v[38:41], v[34:37]
	v_mfma_f32_16x16x32_bf16 v[172:175], v[134:137], v[38:41], v[172:175]
	v_mfma_f32_16x16x32_bf16 v[180:183], v[148:151], v[38:41], v[180:183]
	v_mfma_f32_16x16x32_bf16 v[188:191], v[156:159], v[38:41], v[188:191]
	s_barrier
	v_readfirstlane_b32 s48, v22
	v_add_u32_e32 v20, 0x2000, v22
	v_lshl_add_u64 v[16:17], v[2:3], 0, s[42:43]
	s_mov_b32 m0, s48
	v_readfirstlane_b32 s48, v20
	global_load_lds_dwordx4 v[16:17], off
	v_lshl_add_u64 v[16:17], v[0:1], 0, s[42:43]
	s_mov_b32 m0, s48
	s_nop 0
	global_load_lds_dwordx4 v[16:17], off
	s_waitcnt vmcnt(6)
	s_barrier
	v_mfma_f32_16x16x32_bf16 v[20:23], v[70:73], v[106:109], 0
	v_mfma_f32_16x16x32_bf16 v[32:35], v[70:73], v[114:117], 0
	v_mfma_f32_16x16x32_bf16 v[36:39], v[144:147], v[106:109], 0
	v_mfma_f32_16x16x32_bf16 v[70:73], v[144:147], v[114:117], 0
	v_mfma_f32_16x16x32_bf16 v[144:147], v[152:155], v[106:109], 0
	v_mfma_f32_16x16x32_bf16 v[152:155], v[152:155], v[114:117], 0
	v_mfma_f32_16x16x32_bf16 v[106:109], v[160:163], v[106:109], 0
	v_mfma_f32_16x16x32_bf16 v[114:117], v[160:163], v[114:117], 0
	v_mfma_f32_16x16x32_bf16 v[20:23], v[134:137], v[110:113], v[20:23]
	v_mfma_f32_16x16x32_bf16 v[32:35], v[134:137], v[118:121], v[32:35]
	v_mfma_f32_16x16x32_bf16 v[36:39], v[148:151], v[110:113], v[36:39]
	v_mfma_f32_16x16x32_bf16 v[70:73], v[148:151], v[118:121], v[70:73]
	v_mfma_f32_16x16x32_bf16 v[134:137], v[156:159], v[110:113], v[144:147]
	v_mfma_f32_16x16x32_bf16 v[106:109], v[164:167], v[110:113], v[106:109]
	v_mfma_f32_16x16x32_bf16 v[110:113], v[164:167], v[118:121], v[114:117]
	v_mfma_f32_16x16x32_bf16 v[144:147], v[156:159], v[118:121], v[152:155]
	v_add3_u32 v225, s60, v127, v126
	s_barrier
	ds_read_b128 v[114:117], v225
	ds_read_b128 v[118:121], v225 offset:1024
	ds_read_b128 v[148:151], v225 offset:2048
	ds_read_b128 v[152:155], v225 offset:3072
	v_readfirstlane_b32 s48, v18
	v_lshl_add_u64 v[16:17], v[6:7], 0, s[42:43]
	s_mov_b32 m0, s48
	v_readfirstlane_b32 s48, v19
	ds_read_b128 v[156:159], v228 offset:32768
	ds_read_b128 v[160:163], v228 offset:33792
	ds_read_b128 v[164:167], v229 offset:34816
	ds_read_b128 v[192:195], v229 offset:35840
	ds_read_b128 v[196:199], v229 offset:36864
	ds_read_b128 v[200:203], v229 offset:37888
	ds_read_b128 v[204:207], v229 offset:38912
	ds_read_b128 v[208:211], v229 offset:39936
	global_load_lds_dwordx4 v[16:17], off
	v_lshl_add_u64 v[16:17], v[4:5], 0, s[42:43]
	s_mov_b32 m0, s48
	s_nop 0
	global_load_lds_dwordx4 v[16:17], off
	s_waitcnt lgkmcnt(8)
	s_barrier
	s_waitcnt lgkmcnt(0)
	v_mfma_f32_16x16x32_bf16 v[16:19], v[156:159], v[114:117], v[74:77]
	v_mfma_f32_16x16x32_bf16 v[74:77], v[156:159], v[148:151], v[78:81]
	v_mfma_f32_16x16x32_bf16 v[78:81], v[164:167], v[114:117], v[82:85]
	v_mfma_f32_16x16x32_bf16 v[82:85], v[164:167], v[148:151], v[86:89]
	v_mfma_f32_16x16x32_bf16 v[86:89], v[196:199], v[114:117], v[90:93]
	v_mfma_f32_16x16x32_bf16 v[90:93], v[196:199], v[148:151], v[94:97]
	v_mfma_f32_16x16x32_bf16 v[94:97], v[204:207], v[114:117], v[98:101]
	v_mfma_f32_16x16x32_bf16 v[98:101], v[204:207], v[148:151], v[102:105]
	v_mfma_f32_16x16x32_bf16 v[16:19], v[160:163], v[118:121], v[16:19]
	v_mfma_f32_16x16x32_bf16 v[74:77], v[160:163], v[152:155], v[74:77]
	v_mfma_f32_16x16x32_bf16 v[78:81], v[192:195], v[118:121], v[78:81]
	v_mfma_f32_16x16x32_bf16 v[82:85], v[192:195], v[152:155], v[82:85]
	v_mfma_f32_16x16x32_bf16 v[86:89], v[200:203], v[118:121], v[86:89]
	v_mfma_f32_16x16x32_bf16 v[90:93], v[200:203], v[152:155], v[90:93]
	v_mfma_f32_16x16x32_bf16 v[94:97], v[208:211], v[118:121], v[94:97]
	v_mfma_f32_16x16x32_bf16 v[98:101], v[208:211], v[152:155], v[98:101]
	s_barrier
	s_mov_b32 m0, s53
	v_add3_u32 v226, s61, v127, v126
	v_lshl_add_u64 v[12:13], v[12:13], 0, s[44:45]
	ds_read_b128 v[102:105], v226
	ds_read_b128 v[212:215], v226 offset:1024
	ds_read_b128 v[216:219], v226 offset:2048
	ds_read_b128 v[220:223], v226 offset:3072
	global_load_lds_dwordx4 v[12:13], off
	v_lshl_add_u64 v[12:13], v[14:15], 0, s[44:45]
	s_mov_b32 m0, s52
	s_nop 0
	global_load_lds_dwordx4 v[12:13], off
	s_barrier
; #define STAGE(P, BASE, LD, br, kt) do { const char* _g = (const char*)((BASE) + (size_t)(br) * (LD) + (size_t)(kt) * 64); \
;     for (int _i = 0; _i < 2; ++_i) { int _b = tidx * 16 + _i * 8192; int _r, _c; stage_rc(_b, _r, _c); \
;       __builtin_amdgcn_global_load_lds((const unsigned*)(_g + (unsigned)((_r * (LD) + _c) * 2)), (unsigned*)((char*)(P) + _b), 16, 0, 0); } } while (0)
; #define LDA(dst, b, h) for (int m = 0; m < 4; ++m) for (int k = 0; k < 2; ++k) \
;     dst[m][k] = *reinterpret_cast<const bf16x8*>((char*)SA(b, h) + lds_byte(wr * 64 + m * 16 + fr, k * 32 + fq * 8))
; #define LDB(dst, b, h) for (int n = 0; n < 2; ++n) for (int k = 0; k < 2; ++k) \
;     dst[n][k] = *reinterpret_cast<const bf16x8*>((char*)SB(b, h) + lds_byte(wc * 32 + n * 16 + fr, k * 32 + fq * 8))
; #define MMA(ai, bj, At_, Bt_) do { __builtin_amdgcn_s_setprio(1); \
;     for (int k = 0; k < 2; ++k) for (int m = 0; m < 4; ++m) for (int n = 0; n < 2; ++n) \
;       acc[ai][bj][m][n] = __builtin_amdgcn_mfma_f32_16x16x32_bf16(At_[m][k], Bt_[n][k], acc[ai][bj][m][n], 0, 0, 0); \
;     __builtin_amdgcn_s_setprio(0); } while (0)
; #define WAIT_V(n) asm volatile("s_waitcnt vmcnt(" #n ")" ::: "memory")
; #define WAIT_L(n) asm volatile("s_waitcnt lgkmcnt(" #n ")" ::: "memory")
; #define BAR __builtin_amdgcn_s_barrier()
; #define SCHED __builtin_amdgcn_sched_barrier(0)
; template <int EPI, int lda, int ldb, int N, int K>
; __device__ __forceinline__ void gemm_phase(const u16* __restrict__ A, const u16* __restrict__ Bt, const GemmEpi ep, int wv) {
;     ...
;       LDB(B1, 1, 1); STAGE(SB(1, 0), Bt, ldb, bcol, t + 3);
;       BAR; WAIT_L(0); MMA(0, 1, At, B1); BAR;
;       LDA(At, 1, 1); STAGE(SA(1, 0), Ab, lda, brow, t + 3);
;       BAR; WAIT_L(0); MMA(1, 0, At, B0); BAR; SCHED;
;       STAGE(SB(1, 1), Bt, ldb, bcol + HALF, t + 3);
;       WAIT_V(6); BAR; MMA(1, 1, At, B1); BAR;
;     }
;     { LDB(B0, 0, 0); LDA(At, 0, 0); STAGE(SA(1, 1), Ab, lda, brow + HALF, nt - 1);
;       BAR; WAIT_L(0); MMA(0, 0, At, B0); BAR;
	s_waitcnt lgkmcnt(0)
	v_mfma_f32_16x16x32_bf16 v[12:15], v[156:159], v[102:105], v[122:125]
	v_mfma_f32_16x16x32_bf16 v[40:43], v[156:159], v[216:219], v[42:45]
	v_mfma_f32_16x16x32_bf16 v[44:47], v[164:167], v[102:105], v[46:49]
	v_mfma_f32_16x16x32_bf16 v[48:51], v[164:167], v[216:219], v[50:53]
	v_mfma_f32_16x16x32_bf16 v[52:55], v[196:199], v[102:105], v[54:57]
	v_mfma_f32_16x16x32_bf16 v[56:59], v[196:199], v[216:219], v[58:61]
	v_mfma_f32_16x16x32_bf16 v[60:63], v[204:207], v[102:105], v[62:65]
	v_mfma_f32_16x16x32_bf16 v[64:67], v[204:207], v[216:219], v[66:69]
	v_mfma_f32_16x16x32_bf16 v[12:15], v[160:163], v[212:215], v[12:15]
	v_mfma_f32_16x16x32_bf16 v[40:43], v[160:163], v[220:223], v[40:43]
	v_mfma_f32_16x16x32_bf16 v[44:47], v[192:195], v[212:215], v[44:47]
	v_mfma_f32_16x16x32_bf16 v[48:51], v[192:195], v[220:223], v[48:51]
	v_mfma_f32_16x16x32_bf16 v[52:55], v[200:203], v[212:215], v[52:55]
	v_mfma_f32_16x16x32_bf16 v[56:59], v[200:203], v[220:223], v[56:59]
	v_mfma_f32_16x16x32_bf16 v[60:63], v[208:211], v[212:215], v[60:63]
	v_mfma_f32_16x16x32_bf16 v[64:67], v[208:211], v[220:223], v[64:67]
	s_mov_b32 m0, s51
	v_lshl_add_u64 v[8:9], v[8:9], 0, s[44:45]
	s_barrier
	ds_read_b128 v[122:125], v228 offset:49152
	ds_read_b128 v[156:159], v228 offset:50176
	ds_read_b128 v[160:163], v229 offset:51200
	ds_read_b128 v[164:167], v229 offset:52224
	ds_read_b128 v[192:195], v229 offset:53248
	ds_read_b128 v[196:199], v229 offset:54272
	ds_read_b128 v[200:203], v229 offset:55296
	ds_read_b128 v[204:207], v229 offset:56320
	global_load_lds_dwordx4 v[8:9], off
	v_lshl_add_u64 v[8:9], v[10:11], 0, s[44:45]
	s_mov_b32 m0, s50
	s_nop 0
	global_load_lds_dwordx4 v[8:9], off
	s_barrier
	s_waitcnt lgkmcnt(0)
	v_mfma_f32_16x16x32_bf16 v[8:11], v[122:125], v[114:117], v[168:171]
	v_mfma_f32_16x16x32_bf16 v[168:171], v[122:125], v[148:151], v[172:175]
	v_mfma_f32_16x16x32_bf16 v[24:27], v[200:203], v[114:117], v[24:27]
	v_mfma_f32_16x16x32_bf16 v[28:31], v[200:203], v[148:151], v[28:31]
	v_mfma_f32_16x16x32_bf16 v[172:175], v[160:163], v[114:117], v[176:179]
	v_mfma_f32_16x16x32_bf16 v[176:179], v[160:163], v[148:151], v[180:183]
	v_mfma_f32_16x16x32_bf16 v[180:183], v[192:195], v[114:117], v[184:187]
	v_mfma_f32_16x16x32_bf16 v[184:187], v[192:195], v[148:151], v[188:191]
	v_mfma_f32_16x16x32_bf16 v[8:11], v[156:159], v[118:121], v[8:11]
	v_mfma_f32_16x16x32_bf16 v[114:117], v[156:159], v[152:155], v[168:171]
	v_mfma_f32_16x16x32_bf16 v[24:27], v[204:207], v[118:121], v[24:27]
	v_mfma_f32_16x16x32_bf16 v[28:31], v[204:207], v[152:155], v[28:31]
	v_mfma_f32_16x16x32_bf16 v[148:151], v[164:167], v[118:121], v[172:175]
	v_mfma_f32_16x16x32_bf16 v[168:171], v[164:167], v[152:155], v[176:179]
	v_mfma_f32_16x16x32_bf16 v[172:175], v[196:199], v[118:121], v[180:183]
	v_mfma_f32_16x16x32_bf16 v[176:179], v[196:199], v[152:155], v[184:187]
	s_barrier
	s_mov_b32 m0, s13
	v_lshl_add_u64 v[2:3], v[2:3], 0, s[44:45]
	global_load_lds_dwordx4 v[2:3], off
	v_lshl_add_u64 v[0:1], v[0:1], 0, s[44:45]
	s_mov_b32 m0, s11
	s_nop 0
	global_load_lds_dwordx4 v[0:1], off
	s_waitcnt vmcnt(6)
	s_barrier
	v_mfma_f32_16x16x32_bf16 v[0:3], v[122:125], v[102:105], v[20:23]
	v_mfma_f32_16x16x32_bf16 v[20:23], v[122:125], v[216:219], v[32:35]
	v_mfma_f32_16x16x32_bf16 v[32:35], v[160:163], v[102:105], v[36:39]
	v_mfma_f32_16x16x32_bf16 v[36:39], v[160:163], v[216:219], v[70:73]
	v_mfma_f32_16x16x32_bf16 v[68:71], v[192:195], v[102:105], v[134:137]
	v_mfma_f32_16x16x32_bf16 v[118:121], v[192:195], v[216:219], v[144:147]
	v_mfma_f32_16x16x32_bf16 v[102:105], v[200:203], v[102:105], v[106:109]
	v_mfma_f32_16x16x32_bf16 v[106:109], v[200:203], v[216:219], v[110:113]
	v_mfma_f32_16x16x32_bf16 v[0:3], v[156:159], v[212:215], v[0:3]
	v_mfma_f32_16x16x32_bf16 v[20:23], v[156:159], v[220:223], v[20:23]
	v_mfma_f32_16x16x32_bf16 v[32:35], v[164:167], v[212:215], v[32:35]
	v_mfma_f32_16x16x32_bf16 v[36:39], v[164:167], v[220:223], v[36:39]
	v_mfma_f32_16x16x32_bf16 v[68:71], v[196:199], v[212:215], v[68:71]
	v_mfma_f32_16x16x32_bf16 v[110:113], v[196:199], v[220:223], v[118:121]
	v_mfma_f32_16x16x32_bf16 v[102:105], v[204:207], v[212:215], v[102:105]
	v_mfma_f32_16x16x32_bf16 v[106:109], v[204:207], v[220:223], v[106:109]
	s_mov_b32 m0, s47
	v_lshl_add_u64 v[6:7], v[6:7], 0, s[44:45]
	s_barrier
	ds_read_b128 v[118:121], v133
	ds_read_b128 v[122:125], v133 offset:1024
	ds_read_b128 v[134:137], v133 offset:2048
	ds_read_b128 v[144:147], v133 offset:3072
	ds_read_b128 v[152:155], v228
	ds_read_b128 v[156:159], v228 offset:1024
	ds_read_b128 v[160:163], v229 offset:2048
	ds_read_b128 v[164:167], v229 offset:3072
	ds_read_b128 v[180:183], v229 offset:4096
	ds_read_b128 v[184:187], v229 offset:5120
	ds_read_b128 v[188:191], v229 offset:6144
	ds_read_b128 v[192:195], v229 offset:7168
	global_load_lds_dwordx4 v[6:7], off
	v_lshl_add_u64 v[4:5], v[4:5], 0, s[44:45]
	s_mov_b32 m0, s46
	s_nop 0
	global_load_lds_dwordx4 v[4:5], off
	s_barrier
	s_waitcnt lgkmcnt(0)
	v_mfma_f32_16x16x32_bf16 v[4:7], v[152:155], v[118:121], v[16:19]
	v_mfma_f32_16x16x32_bf16 v[16:19], v[152:155], v[134:137], v[74:77]
	v_mfma_f32_16x16x32_bf16 v[72:75], v[160:163], v[118:121], v[78:81]
	v_mfma_f32_16x16x32_bf16 v[76:79], v[160:163], v[134:137], v[82:85]
	v_mfma_f32_16x16x32_bf16 v[80:83], v[180:183], v[118:121], v[86:89]
	v_mfma_f32_16x16x32_bf16 v[84:87], v[180:183], v[134:137], v[90:93]
	v_mfma_f32_16x16x32_bf16 v[88:91], v[188:191], v[118:121], v[94:97]
	v_mfma_f32_16x16x32_bf16 v[92:95], v[188:191], v[134:137], v[98:101]
	v_mfma_f32_16x16x32_bf16 v[4:7], v[156:159], v[122:125], v[4:7]
	v_mfma_f32_16x16x32_bf16 v[16:19], v[156:159], v[144:147], v[16:19]
	v_mfma_f32_16x16x32_bf16 v[72:75], v[164:167], v[122:125], v[72:75]
	v_mfma_f32_16x16x32_bf16 v[76:79], v[164:167], v[144:147], v[76:79]
	v_mfma_f32_16x16x32_bf16 v[80:83], v[184:187], v[122:125], v[80:83]
	v_mfma_f32_16x16x32_bf16 v[84:87], v[184:187], v[144:147], v[84:87]
	v_mfma_f32_16x16x32_bf16 v[88:91], v[192:195], v[122:125], v[88:91]
	v_mfma_f32_16x16x32_bf16 v[92:95], v[192:195], v[144:147], v[92:95]
	s_barrier
; #define LDA(dst, b, h) for (int m = 0; m < 4; ++m) for (int k = 0; k < 2; ++k) \
;     dst[m][k] = *reinterpret_cast<const bf16x8*>((char*)SA(b, h) + lds_byte(wr * 64 + m * 16 + fr, k * 32 + fq * 8))
; #define LDB(dst, b, h) for (int n = 0; n < 2; ++n) for (int k = 0; k < 2; ++k) \
;     dst[n][k] = *reinterpret_cast<const bf16x8*>((char*)SB(b, h) + lds_byte(wc * 32 + n * 16 + fr, k * 32 + fq * 8))
; #define MMA(ai, bj, At_, Bt_) do { __builtin_amdgcn_s_setprio(1); \
;     for (int k = 0; k < 2; ++k) for (int m = 0; m < 4; ++m) for (int n = 0; n < 2; ++n) \
;       acc[ai][bj][m][n] = __builtin_amdgcn_mfma_f32_16x16x32_bf16(At_[m][k], Bt_[n][k], acc[ai][bj][m][n], 0, 0, 0); \
;     __builtin_amdgcn_s_setprio(0); } while (0)
; #define WAIT_V(n) asm volatile("s_waitcnt vmcnt(" #n ")" ::: "memory")
; #define WAIT_L(n) asm volatile("s_waitcnt lgkmcnt(" #n ")" ::: "memory")
; #define BAR __builtin_amdgcn_s_barrier()
; template <int EPI, int lda, int ldb, int N, int K>
; __device__ __forceinline__ void gemm_phase(const u16* __restrict__ A, const u16* __restrict__ Bt, const GemmEpi ep, int wv) {
;     ...
;       LDB(B1, 0, 1); BAR; WAIT_L(0); MMA(0, 1, At, B1); BAR;
;       LDA(At, 0, 1); WAIT_V(4); BAR; WAIT_L(0); MMA(1, 0, At, B0); MMA(1, 1, At, B1); BAR; }
;     { LDB(B0, 1, 0); LDA(At, 1, 0); WAIT_V(2); BAR; WAIT_L(0); MMA(0, 0, At, B0); BAR;
	ds_read_b128 v[96:99], v224
	ds_read_b128 v[196:199], v224 offset:1024
	ds_read_b128 v[200:203], v224 offset:2048
	ds_read_b128 v[204:207], v224 offset:3072
	s_barrier
	s_waitcnt lgkmcnt(0)
	v_mfma_f32_16x16x32_bf16 v[12:15], v[152:155], v[96:99], v[12:15]
	v_mfma_f32_16x16x32_bf16 v[40:43], v[152:155], v[200:203], v[40:43]
	v_mfma_f32_16x16x32_bf16 v[52:55], v[180:183], v[96:99], v[52:55]
	v_mfma_f32_16x16x32_bf16 v[56:59], v[180:183], v[200:203], v[56:59]
	v_mfma_f32_16x16x32_bf16 v[64:67], v[188:191], v[200:203], v[64:67]
	v_mfma_f32_16x16x32_bf16 v[44:47], v[160:163], v[96:99], v[44:47]
	v_mfma_f32_16x16x32_bf16 v[48:51], v[160:163], v[200:203], v[48:51]
	v_mfma_f32_16x16x32_bf16 v[60:63], v[188:191], v[96:99], v[60:63]
	v_mfma_f32_16x16x32_bf16 v[12:15], v[156:159], v[196:199], v[12:15]
	v_mfma_f32_16x16x32_bf16 v[40:43], v[156:159], v[204:207], v[40:43]
	v_mfma_f32_16x16x32_bf16 v[52:55], v[184:187], v[196:199], v[52:55]
	v_mfma_f32_16x16x32_bf16 v[56:59], v[184:187], v[204:207], v[56:59]
	v_mfma_f32_16x16x32_bf16 v[64:67], v[192:195], v[204:207], v[64:67]
	v_mfma_f32_16x16x32_bf16 v[152:155], v[164:167], v[196:199], v[44:47]
	v_mfma_f32_16x16x32_bf16 v[156:159], v[164:167], v[204:207], v[48:51]
	v_mfma_f32_16x16x32_bf16 v[160:163], v[192:195], v[196:199], v[60:63]
	s_barrier
	ds_read_b128 v[44:47], v228 offset:16384
	ds_read_b128 v[48:51], v228 offset:17408
	ds_read_b128 v[60:63], v229 offset:18432
	ds_read_b128 v[164:167], v229 offset:19456
	ds_read_b128 v[180:183], v229 offset:20480
	ds_read_b128 v[184:187], v229 offset:21504
	ds_read_b128 v[188:191], v229 offset:22528
	ds_read_b128 v[192:195], v229 offset:23552
	s_waitcnt vmcnt(4)
	s_barrier
	s_waitcnt lgkmcnt(0)
	v_mfma_f32_16x16x32_bf16 v[8:11], v[44:47], v[118:121], v[8:11]
	v_mfma_f32_16x16x32_bf16 v[24:27], v[188:191], v[118:121], v[24:27]
	v_mfma_f32_16x16x32_bf16 v[28:31], v[188:191], v[134:137], v[28:31]
	v_mfma_f32_16x16x32_bf16 v[114:117], v[44:47], v[134:137], v[114:117]
	v_mfma_f32_16x16x32_bf16 v[148:151], v[60:63], v[118:121], v[148:151]
	v_mfma_f32_16x16x32_bf16 v[168:171], v[60:63], v[134:137], v[168:171]
	v_mfma_f32_16x16x32_bf16 v[172:175], v[180:183], v[118:121], v[172:175]
	v_mfma_f32_16x16x32_bf16 v[176:179], v[180:183], v[134:137], v[176:179]
	v_mfma_f32_16x16x32_bf16 v[8:11], v[48:51], v[122:125], v[8:11]
	v_mfma_f32_16x16x32_bf16 v[24:27], v[192:195], v[122:125], v[24:27]
	v_mfma_f32_16x16x32_bf16 v[28:31], v[192:195], v[144:147], v[28:31]
	v_mfma_f32_16x16x32_bf16 v[134:137], v[48:51], v[144:147], v[114:117]
	v_mfma_f32_16x16x32_bf16 v[148:151], v[164:167], v[122:125], v[148:151]
	v_mfma_f32_16x16x32_bf16 v[168:171], v[164:167], v[144:147], v[168:171]
	v_mfma_f32_16x16x32_bf16 v[172:175], v[184:187], v[122:125], v[172:175]
	v_mfma_f32_16x16x32_bf16 v[176:179], v[184:187], v[144:147], v[176:179]
	v_mfma_f32_16x16x32_bf16 v[0:3], v[44:47], v[96:99], v[0:3]
	v_mfma_f32_16x16x32_bf16 v[20:23], v[44:47], v[200:203], v[20:23]
	v_mfma_f32_16x16x32_bf16 v[44:47], v[180:183], v[96:99], v[68:71]
	v_mfma_f32_16x16x32_bf16 v[68:71], v[188:191], v[96:99], v[102:105]
	v_mfma_f32_16x16x32_bf16 v[32:35], v[60:63], v[96:99], v[32:35]
	v_mfma_f32_16x16x32_bf16 v[36:39], v[60:63], v[200:203], v[36:39]
	v_mfma_f32_16x16x32_bf16 v[60:63], v[180:183], v[200:203], v[110:113]
	v_mfma_f32_16x16x32_bf16 v[96:99], v[188:191], v[200:203], v[106:109]
	v_mfma_f32_16x16x32_bf16 v[20:23], v[48:51], v[204:207], v[20:23]
	v_mfma_f32_16x16x32_bf16 v[68:71], v[192:195], v[196:199], v[68:71]
	v_mfma_f32_16x16x32_bf16 v[144:147], v[48:51], v[196:199], v[0:3]
	v_mfma_f32_16x16x32_bf16 v[180:183], v[164:167], v[196:199], v[32:35]
	v_mfma_f32_16x16x32_bf16 v[164:167], v[164:167], v[204:207], v[36:39]
	v_mfma_f32_16x16x32_bf16 v[188:191], v[184:187], v[196:199], v[44:47]
	v_mfma_f32_16x16x32_bf16 v[184:187], v[184:187], v[204:207], v[60:63]
	v_mfma_f32_16x16x32_bf16 v[192:195], v[192:195], v[204:207], v[96:99]
	s_barrier
	ds_read_b128 v[0:3], v225
	ds_read_b128 v[196:199], v225 offset:1024
	ds_read_b128 v[200:203], v225 offset:2048
	ds_read_b128 v[204:207], v225 offset:3072
	ds_read_b128 v[36:39], v228 offset:32768
	ds_read_b128 v[100:103], v228 offset:33792
	ds_read_b128 v[108:111], v229 offset:34816
	ds_read_b128 v[208:211], v229 offset:35840
	ds_read_b128 v[116:119], v229 offset:36864
	ds_read_b128 v[212:215], v229 offset:37888
	ds_read_b128 v[124:127], v229 offset:38912
	ds_read_b128 v[216:219], v229 offset:39936
	s_waitcnt vmcnt(2)
	s_barrier
; #define LDA(dst, b, h) for (int m = 0; m < 4; ++m) for (int k = 0; k < 2; ++k) \
;     dst[m][k] = *reinterpret_cast<const bf16x8*>((char*)SA(b, h) + lds_byte(wr * 64 + m * 16 + fr, k * 32 + fq * 8))
; #define LDB(dst, b, h) for (int n = 0; n < 2; ++n) for (int k = 0; k < 2; ++k) \
;     dst[n][k] = *reinterpret_cast<const bf16x8*>((char*)SB(b, h) + lds_byte(wc * 32 + n * 16 + fr, k * 32 + fq * 8))
; #define MMA(ai, bj, At_, Bt_) do { __builtin_amdgcn_s_setprio(1); \
;     for (int k = 0; k < 2; ++k) for (int m = 0; m < 4; ++m) for (int n = 0; n < 2; ++n) \
;       acc[ai][bj][m][n] = __builtin_amdgcn_mfma_f32_16x16x32_bf16(At_[m][k], Bt_[n][k], acc[ai][bj][m][n], 0, 0, 0); \
;     __builtin_amdgcn_s_setprio(0); } while (0)
; #define WAIT_V(n) asm volatile("s_waitcnt vmcnt(" #n ")" ::: "memory")
; #define WAIT_L(n) asm volatile("s_waitcnt lgkmcnt(" #n ")" ::: "memory")
; #define BAR __builtin_amdgcn_s_barrier()
; template <int EPI, int lda, int ldb, int N, int K>
; __device__ __forceinline__ void gemm_phase(const u16* __restrict__ A, const u16* __restrict__ Bt, const GemmEpi ep, int wv) {
;     ...
;     { LDB(B0, 1, 0); LDA(At, 1, 0); WAIT_V(2); BAR; WAIT_L(0); MMA(0, 0, At, B0); BAR;
;       LDB(B1, 1, 1); WAIT_V(0); BAR; WAIT_L(0); MMA(0, 1, At, B1); BAR;
;       LDA(At, 1, 1); BAR; WAIT_L(0); MMA(1, 0, At, B0); MMA(1, 1, At, B1); BAR; }
;     if (wr == 0) BAR;
	s_waitcnt lgkmcnt(0)
	v_mfma_f32_16x16x32_bf16 v[4:7], v[36:39], v[0:3], v[4:7]
	v_mfma_f32_16x16x32_bf16 v[16:19], v[36:39], v[200:203], v[16:19]
	v_mfma_f32_16x16x32_bf16 v[32:35], v[108:111], v[0:3], v[72:75]
	v_mfma_f32_16x16x32_bf16 v[44:47], v[108:111], v[200:203], v[76:79]
	v_mfma_f32_16x16x32_bf16 v[72:75], v[116:119], v[0:3], v[80:83]
	v_mfma_f32_16x16x32_bf16 v[76:79], v[116:119], v[200:203], v[84:87]
	v_mfma_f32_16x16x32_bf16 v[80:83], v[124:127], v[0:3], v[88:91]
	v_mfma_f32_16x16x32_bf16 v[84:87], v[124:127], v[200:203], v[92:95]
	v_mfma_f32_16x16x32_bf16 v[120:123], v[100:103], v[196:199], v[4:7]
	v_mfma_f32_16x16x32_bf16 v[60:63], v[100:103], v[204:207], v[16:19]
	v_mfma_f32_16x16x32_bf16 v[112:115], v[208:211], v[196:199], v[32:35]
	v_mfma_f32_16x16x32_bf16 v[48:51], v[208:211], v[204:207], v[44:47]
	v_mfma_f32_16x16x32_bf16 v[104:107], v[212:215], v[196:199], v[72:75]
	v_mfma_f32_16x16x32_bf16 v[44:47], v[212:215], v[204:207], v[76:79]
	v_mfma_f32_16x16x32_bf16 v[96:99], v[216:219], v[196:199], v[80:83]
	v_mfma_f32_16x16x32_bf16 v[32:35], v[216:219], v[204:207], v[84:87]
	s_barrier
	ds_read_b128 v[4:7], v226
	ds_read_b128 v[220:223], v226 offset:1024
	ds_read_b128 v[76:79], v226 offset:2048
	ds_read_b128 v[224:227], v226 offset:3072
	s_waitcnt vmcnt(0)
	s_barrier
	s_waitcnt lgkmcnt(0)
	v_mfma_f32_16x16x32_bf16 v[12:15], v[36:39], v[4:7], v[12:15]
	v_mfma_f32_16x16x32_bf16 v[16:19], v[36:39], v[76:79], v[40:43]
	v_mfma_f32_16x16x32_bf16 v[36:39], v[108:111], v[4:7], v[152:155]
	v_mfma_f32_16x16x32_bf16 v[40:43], v[108:111], v[76:79], v[156:159]
	v_mfma_f32_16x16x32_bf16 v[72:75], v[116:119], v[4:7], v[52:55]
	v_mfma_f32_16x16x32_bf16 v[80:83], v[116:119], v[76:79], v[56:59]
	v_mfma_f32_16x16x32_bf16 v[84:87], v[124:127], v[4:7], v[160:163]
	v_mfma_f32_16x16x32_bf16 v[64:67], v[124:127], v[76:79], v[64:67]
	v_mfma_f32_16x16x32_bf16 v[124:127], v[100:103], v[220:223], v[12:15]
	v_mfma_f32_16x16x32_bf16 v[56:59], v[100:103], v[224:227], v[16:19]
	v_mfma_f32_16x16x32_bf16 v[116:119], v[208:211], v[220:223], v[36:39]
	v_mfma_f32_16x16x32_bf16 v[52:55], v[208:211], v[224:227], v[40:43]
	v_mfma_f32_16x16x32_bf16 v[108:111], v[212:215], v[220:223], v[72:75]
	v_mfma_f32_16x16x32_bf16 v[40:43], v[212:215], v[224:227], v[80:83]
	v_mfma_f32_16x16x32_bf16 v[100:103], v[216:219], v[220:223], v[84:87]
	v_mfma_f32_16x16x32_bf16 v[36:39], v[216:219], v[224:227], v[64:67]
	s_barrier
	ds_read_b128 v[84:87], v228 offset:49152
	ds_read_b128 v[152:155], v228 offset:50176
	ds_read_b128 v[92:95], v229 offset:51200
	ds_read_b128 v[156:159], v229 offset:52224
	ds_read_b128 v[160:163], v229 offset:53248
	ds_read_b128 v[208:211], v229 offset:54272
	ds_read_b128 v[212:215], v229 offset:55296
	ds_read_b128 v[216:219], v229 offset:56320
	s_barrier
	s_waitcnt lgkmcnt(0)
	v_mfma_f32_16x16x32_bf16 v[8:11], v[84:87], v[0:3], v[8:11]
	v_mfma_f32_16x16x32_bf16 v[12:15], v[84:87], v[200:203], v[134:137]
	v_mfma_f32_16x16x32_bf16 v[16:19], v[92:95], v[0:3], v[148:151]
	v_mfma_f32_16x16x32_bf16 v[64:67], v[92:95], v[200:203], v[168:171]
	v_mfma_f32_16x16x32_bf16 v[72:75], v[160:163], v[0:3], v[172:175]
	v_mfma_f32_16x16x32_bf16 v[134:137], v[160:163], v[200:203], v[176:179]
	v_mfma_f32_16x16x32_bf16 v[0:3], v[212:215], v[0:3], v[24:27]
	v_mfma_f32_16x16x32_bf16 v[24:27], v[212:215], v[200:203], v[28:31]
	v_mfma_f32_16x16x32_bf16 v[88:91], v[152:155], v[196:199], v[8:11]
	v_mfma_f32_16x16x32_bf16 v[28:31], v[152:155], v[204:207], v[12:15]
	v_mfma_f32_16x16x32_bf16 v[80:83], v[156:159], v[196:199], v[16:19]
	v_mfma_f32_16x16x32_bf16 v[16:19], v[156:159], v[204:207], v[64:67]
	v_mfma_f32_16x16x32_bf16 v[72:75], v[208:211], v[196:199], v[72:75]
	v_mfma_f32_16x16x32_bf16 v[12:15], v[208:211], v[204:207], v[134:137]
	v_mfma_f32_16x16x32_bf16 v[64:67], v[216:219], v[196:199], v[0:3]
	v_mfma_f32_16x16x32_bf16 v[0:3], v[216:219], v[204:207], v[24:27]
	v_mfma_f32_16x16x32_bf16 v[8:11], v[84:87], v[4:7], v[144:147]
	v_mfma_f32_16x16x32_bf16 v[20:23], v[84:87], v[76:79], v[20:23]
	v_mfma_f32_16x16x32_bf16 v[84:87], v[92:95], v[4:7], v[180:183]
	v_mfma_f32_16x16x32_bf16 v[134:137], v[92:95], v[76:79], v[164:167]
	v_mfma_f32_16x16x32_bf16 v[144:147], v[160:163], v[4:7], v[188:191]
	v_mfma_f32_16x16x32_bf16 v[148:151], v[160:163], v[76:79], v[184:187]
	v_mfma_f32_16x16x32_bf16 v[4:7], v[212:215], v[4:7], v[68:71]
	v_mfma_f32_16x16x32_bf16 v[160:163], v[212:215], v[76:79], v[192:195]
	v_mfma_f32_16x16x32_bf16 v[92:95], v[152:155], v[220:223], v[8:11]
	v_mfma_f32_16x16x32_bf16 v[24:27], v[152:155], v[224:227], v[20:23]
	v_mfma_f32_16x16x32_bf16 v[84:87], v[156:159], v[220:223], v[84:87]
	v_mfma_f32_16x16x32_bf16 v[20:23], v[156:159], v[224:227], v[134:137]
	v_mfma_f32_16x16x32_bf16 v[76:79], v[208:211], v[220:223], v[144:147]
	v_mfma_f32_16x16x32_bf16 v[8:11], v[208:211], v[224:227], v[148:151]
	v_mfma_f32_16x16x32_bf16 v[68:71], v[216:219], v[220:223], v[4:7]
	v_mfma_f32_16x16x32_bf16 v[4:7], v[216:219], v[224:227], v[160:163]
	v_cmp_gt_u32_e32 vcc, s62, v130
	s_barrier
	s_and_saveexec_b64 s[46:47], vcc
	s_cbranch_execz .LBB0_1245
	s_barrier
	s_branch .LBB0_1245

; #define STAGE(P, BASE, LD, br, kt) do { const char* _g = (const char*)((BASE) + (size_t)(br) * (LD) + (size_t)(kt) * 64); \
;     for (int _i = 0; _i < 2; ++_i) { int _b = tidx * 16 + _i * 8192; int _r, _c; stage_rc(_b, _r, _c); \
;       __builtin_amdgcn_global_load_lds((const unsigned*)(_g + (unsigned)((_r * (LD) + _c) * 2)), (unsigned*)((char*)(P) + _b), 16, 0, 0); } } while (0)
; #define LDA(dst, b, h) for (int m = 0; m < 4; ++m) for (int k = 0; k < 2; ++k) \
;     dst[m][k] = *reinterpret_cast<const bf16x8*>((char*)SA(b, h) + lds_byte(wr * 64 + m * 16 + fr, k * 32 + fq * 8))
; #define LDB(dst, b, h) for (int n = 0; n < 2; ++n) for (int k = 0; k < 2; ++k) \
;     dst[n][k] = *reinterpret_cast<const bf16x8*>((char*)SB(b, h) + lds_byte(wc * 32 + n * 16 + fr, k * 32 + fq * 8))
; #define MMA(ai, bj, At_, Bt_) do { __builtin_amdgcn_s_setprio(1); \
;     for (int k = 0; k < 2; ++k) for (int m = 0; m < 4; ++m) for (int n = 0; n < 2; ++n) \
;       acc[ai][bj][m][n] = __builtin_amdgcn_mfma_f32_16x16x32_bf16(At_[m][k], Bt_[n][k], acc[ai][bj][m][n], 0, 0, 0); \
;     __builtin_amdgcn_s_setprio(0); } while (0)
; #define WAIT_V(n) asm volatile("s_waitcnt vmcnt(" #n ")" ::: "memory")
; #define WAIT_L(n) asm volatile("s_waitcnt lgkmcnt(" #n ")" ::: "memory")
; #define BAR __builtin_amdgcn_s_barrier()
; #define SCHED __builtin_amdgcn_sched_barrier(0)
; template <int EPI, int lda, int ldb, int N, int K>
; __device__ __forceinline__ void gemm_phase(const u16* __restrict__ A, const u16* __restrict__ Bt, const GemmEpi ep, int wv) {
;     ...
;     if (wr == 1) BAR;
;     WAIT_V(4); BAR;
;     STAGE(SB(1, 0), Bt, ldb, bcol, 1); STAGE(SA(1, 0), Ab, lda, brow, 1); STAGE(SB(1, 1), Bt, ldb, bcol + HALF, 1);
;     WAIT_V(6); BAR;
;     for (int t = 0; t < nt - 2; t += 2) {
;       LDB(B0, 0, 0); SCHED; LDA(At, 0, 0); STAGE(SA(1, 1), Ab, lda, brow + HALF, t + 1);
;       WAIT_L(8); BAR; WAIT_L(0); MMA(0, 0, At, B0); BAR; SCHED;
;       LDB(B1, 0, 1); STAGE(SB(0, 0), Bt, ldb, bcol, t + 2);
;       BAR; WAIT_L(0); MMA(0, 1, At, B1); BAR;
;       LDA(At, 0, 1); STAGE(SA(0, 0), Ab, lda, brow, t + 2);
.LBB0_1349:
	s_or_b64 exec, exec, s[54:55]
	v_mov_b32_e32 v1, v129
	v_add_u32_e32 v7, s58, v6
	v_lshl_add_u64 v[12:13], s[46:47], 0, v[128:129]
	v_lshl_add_u64 v[14:15], s[46:47], 0, v[0:1]
	v_lshl_add_u64 v[2:3], s[52:53], 0, v[128:129]
	v_lshl_add_u64 v[0:1], s[52:53], 0, v[0:1]
	v_readfirstlane_b32 s53, v7
	v_add_u32_e32 v7, 0x2000, v7
	v_mov_b32_e32 v5, v129
	v_mov_b32_e32 v17, v129
	v_lshl_add_u64 v[26:27], v[12:13], 0, s[36:37]
	s_mov_b32 m0, s53
	v_readfirstlane_b32 s52, v7
	v_add_u32_e32 v7, 0x8000, v23
	v_lshl_add_u64 v[8:9], s[50:51], 0, v[4:5]
	v_lshl_add_u64 v[10:11], s[50:51], 0, v[16:17]
	s_waitcnt vmcnt(4)
	s_barrier
	global_load_lds_dwordx4 v[26:27], off
	v_lshl_add_u64 v[26:27], v[14:15], 0, s[36:37]
	s_mov_b32 m0, s52
	v_readfirstlane_b32 s51, v7
	v_add_u32_e32 v7, 0xa000, v23
	global_load_lds_dwordx4 v[26:27], off
	v_lshl_add_u64 v[26:27], v[8:9], 0, s[36:37]
	s_mov_b32 m0, s51
	v_readfirstlane_b32 s50, v7
	v_add_u32_e32 v25, s59, v6
	global_load_lds_dwordx4 v[26:27], off
	v_lshl_add_u64 v[26:27], v[10:11], 0, s[36:37]
	s_mov_b32 m0, s50
	v_readfirstlane_b32 s11, v25
	v_add_u32_e32 v25, 0x2000, v25
	global_load_lds_dwordx4 v[26:27], off
	v_lshl_add_u64 v[26:27], v[2:3], 0, s[36:37]
	s_mov_b32 m0, s11
	v_readfirstlane_b32 s5, v25
	global_load_lds_dwordx4 v[26:27], off
	v_lshl_add_u64 v[6:7], v[0:1], 0, s[36:37]
	s_mov_b32 m0, s5
	v_and_b32_e32 v132, 15, v20
	global_load_lds_dwordx4 v[6:7], off
	v_bfe_u32 v128, v20, 4, 2
	v_lshlrev_b32_e32 v7, 2, v20
	v_bfe_u32 v131, v130, 6, 2
	v_lshlrev_b32_e32 v25, 4, v128
	v_lshlrev_b32_e32 v6, 6, v132
	v_and_b32_e32 v50, 32, v7
	v_lshlrev_b32_e32 v126, 12, v131
	v_bitop3_b32 v127, v25, v50, v6 bitop3:0x36
	v_add3_u32 v133, s56, v127, v126
	s_waitcnt vmcnt(6)
	s_barrier
	ds_read_b128 v[26:29], v133
	ds_read_b128 v[30:33], v133 offset:1024
	ds_read_b128 v[34:37], v133 offset:2048
	ds_read_b128 v[38:41], v133 offset:3072
	v_lshl_add_u64 v[6:7], s[48:49], 0, v[4:5]
	v_lshl_add_u64 v[4:5], s[48:49], 0, v[16:17]
	v_lshlrev_b32_e32 v17, 6, v20
	v_and_b32_e32 v17, 0x3c0, v17
	v_add_u32_e32 v20, 0xc000, v23
	v_lshlrev_b32_e32 v16, 13, v139
	v_bitop3_b32 v17, v17, v50, v25 bitop3:0x36
	v_readfirstlane_b32 s47, v20
	v_add_u32_e32 v20, 0xe000, v23
	v_add3_u32 v228, 0, v127, v16
	v_add3_u32 v229, 0, v17, v16
	v_lshl_add_u64 v[16:17], v[6:7], 0, s[36:37]
	s_mov_b32 m0, s47
	v_readfirstlane_b32 s46, v20
	ds_read_b128 v[42:45], v228
	ds_read_b128 v[46:49], v228 offset:1024
	ds_read_b128 v[50:53], v229 offset:2048
	ds_read_b128 v[54:57], v229 offset:3072
	ds_read_b128 v[58:61], v229 offset:4096
	ds_read_b128 v[62:65], v229 offset:5120
	ds_read_b128 v[66:69], v229 offset:6144
	ds_read_b128 v[70:73], v229 offset:7168
	global_load_lds_dwordx4 v[16:17], off
	v_lshl_add_u64 v[16:17], v[4:5], 0, s[36:37]
	s_mov_b32 m0, s46
	s_nop 0
	global_load_lds_dwordx4 v[16:17], off
	s_waitcnt lgkmcnt(8)
	s_barrier
	s_waitcnt lgkmcnt(0)
	v_mfma_f32_16x16x32_bf16 v[74:77], v[42:45], v[26:29], 0
	v_mfma_f32_16x16x32_bf16 v[78:81], v[42:45], v[34:37], 0
	v_mfma_f32_16x16x32_bf16 v[82:85], v[50:53], v[26:29], 0
	v_mfma_f32_16x16x32_bf16 v[86:89], v[50:53], v[34:37], 0
	v_mfma_f32_16x16x32_bf16 v[90:93], v[58:61], v[26:29], 0
	v_mfma_f32_16x16x32_bf16 v[94:97], v[58:61], v[34:37], 0
	v_mfma_f32_16x16x32_bf16 v[98:101], v[66:69], v[26:29], 0
	v_mfma_f32_16x16x32_bf16 v[102:105], v[66:69], v[34:37], 0
	v_mfma_f32_16x16x32_bf16 v[74:77], v[46:49], v[30:33], v[74:77]
	v_mfma_f32_16x16x32_bf16 v[78:81], v[46:49], v[38:41], v[78:81]
	v_mfma_f32_16x16x32_bf16 v[82:85], v[54:57], v[30:33], v[82:85]
	v_mfma_f32_16x16x32_bf16 v[86:89], v[54:57], v[38:41], v[86:89]
	v_mfma_f32_16x16x32_bf16 v[90:93], v[62:65], v[30:33], v[90:93]
	v_mfma_f32_16x16x32_bf16 v[94:97], v[62:65], v[38:41], v[94:97]
	v_mfma_f32_16x16x32_bf16 v[98:101], v[70:73], v[30:33], v[98:101]
	v_mfma_f32_16x16x32_bf16 v[102:105], v[70:73], v[38:41], v[102:105]
	s_barrier
	v_readfirstlane_b32 s48, v21
	v_add_u32_e32 v20, 0x2000, v21
	v_add3_u32 v224, s57, v127, v126
	v_lshl_add_u64 v[16:17], v[12:13], 0, s[38:39]
	s_mov_b32 m0, s48
	v_readfirstlane_b32 s48, v20
	ds_read_b128 v[106:109], v224
	ds_read_b128 v[110:113], v224 offset:1024
	ds_read_b128 v[114:117], v224 offset:2048
	ds_read_b128 v[118:121], v224 offset:3072
	global_load_lds_dwordx4 v[16:17], off
	v_lshl_add_u64 v[16:17], v[14:15], 0, s[38:39]
	s_mov_b32 m0, s48
	s_nop 0
	global_load_lds_dwordx4 v[16:17], off
	s_barrier
	s_waitcnt lgkmcnt(0)
	v_mfma_f32_16x16x32_bf16 v[122:125], v[42:45], v[106:109], 0
	v_mfma_f32_16x16x32_bf16 v[42:45], v[42:45], v[114:117], 0
	v_mfma_f32_16x16x32_bf16 v[140:143], v[50:53], v[106:109], 0
	v_mfma_f32_16x16x32_bf16 v[50:53], v[50:53], v[114:117], 0
	v_mfma_f32_16x16x32_bf16 v[144:147], v[58:61], v[106:109], 0
	v_mfma_f32_16x16x32_bf16 v[58:61], v[58:61], v[114:117], 0
	v_mfma_f32_16x16x32_bf16 v[148:151], v[66:69], v[106:109], 0
	v_mfma_f32_16x16x32_bf16 v[66:69], v[66:69], v[114:117], 0
	v_mfma_f32_16x16x32_bf16 v[122:125], v[46:49], v[110:113], v[122:125]
	v_mfma_f32_16x16x32_bf16 v[42:45], v[46:49], v[118:121], v[42:45]
	v_mfma_f32_16x16x32_bf16 v[46:49], v[54:57], v[110:113], v[140:143]
	v_mfma_f32_16x16x32_bf16 v[50:53], v[54:57], v[118:121], v[50:53]
	v_mfma_f32_16x16x32_bf16 v[54:57], v[62:65], v[110:113], v[144:147]
	v_mfma_f32_16x16x32_bf16 v[58:61], v[62:65], v[118:121], v[58:61]
	v_mfma_f32_16x16x32_bf16 v[62:65], v[70:73], v[110:113], v[148:151]
	v_mfma_f32_16x16x32_bf16 v[66:69], v[70:73], v[118:121], v[66:69]
	v_readfirstlane_b32 s48, v23
	v_lshl_add_u64 v[16:17], v[8:9], 0, s[38:39]
	s_mov_b32 m0, s48
	v_readfirstlane_b32 s48, v24
	s_barrier
; #define STAGE(P, BASE, LD, br, kt) do { const char* _g = (const char*)((BASE) + (size_t)(br) * (LD) + (size_t)(kt) * 64); \
;     for (int _i = 0; _i < 2; ++_i) { int _b = tidx * 16 + _i * 8192; int _r, _c; stage_rc(_b, _r, _c); \
;       __builtin_amdgcn_global_load_lds((const unsigned*)(_g + (unsigned)((_r * (LD) + _c) * 2)), (unsigned*)((char*)(P) + _b), 16, 0, 0); } } while (0)
; #define LDA(dst, b, h) for (int m = 0; m < 4; ++m) for (int k = 0; k < 2; ++k) \
;     dst[m][k] = *reinterpret_cast<const bf16x8*>((char*)SA(b, h) + lds_byte(wr * 64 + m * 16 + fr, k * 32 + fq * 8))
; #define LDB(dst, b, h) for (int n = 0; n < 2; ++n) for (int k = 0; k < 2; ++k) \
;     dst[n][k] = *reinterpret_cast<const bf16x8*>((char*)SB(b, h) + lds_byte(wc * 32 + n * 16 + fr, k * 32 + fq * 8))
; #define MMA(ai, bj, At_, Bt_) do { __builtin_amdgcn_s_setprio(1); \
;     for (int k = 0; k < 2; ++k) for (int m = 0; m < 4; ++m) for (int n = 0; n < 2; ++n) \
;       acc[ai][bj][m][n] = __builtin_amdgcn_mfma_f32_16x16x32_bf16(At_[m][k], Bt_[n][k], acc[ai][bj][m][n], 0, 0, 0); \
;     __builtin_amdgcn_s_setprio(0); } while (0)
; #define WAIT_V(n) asm volatile("s_waitcnt vmcnt(" #n ")" ::: "memory")
; #define WAIT_L(n) asm volatile("s_waitcnt lgkmcnt(" #n ")" ::: "memory")
; #define BAR __builtin_amdgcn_s_barrier()
; #define SCHED __builtin_amdgcn_sched_barrier(0)
; template <int EPI, int lda, int ldb, int N, int K>
; __device__ __forceinline__ void gemm_phase(const u16* __restrict__ A, const u16* __restrict__ Bt, const GemmEpi ep, int wv) {
;     ...
;       LDA(At, 0, 1); STAGE(SA(0, 0), Ab, lda, brow, t + 2);
;       BAR; WAIT_L(0); MMA(1, 0, At, B0); BAR; SCHED;
;       STAGE(SB(0, 1), Bt, ldb, bcol + HALF, t + 2);
;       WAIT_V(6); BAR; MMA(1, 1, At, B1); BAR;
;       LDB(B0, 1, 0); SCHED; LDA(At, 1, 0); STAGE(SA(0, 1), Ab, lda, brow + HALF, t + 2);
;       WAIT_L(8); BAR; WAIT_L(0); MMA(0, 0, At, B0); BAR; SCHED;
	ds_read_b128 v[70:73], v228 offset:16384
	ds_read_b128 v[140:143], v228 offset:17408
	ds_read_b128 v[144:147], v229 offset:18432
	ds_read_b128 v[148:151], v229 offset:19456
	ds_read_b128 v[152:155], v229 offset:20480
	ds_read_b128 v[156:159], v229 offset:21504
	ds_read_b128 v[160:163], v229 offset:22528
	ds_read_b128 v[164:167], v229 offset:23552
	global_load_lds_dwordx4 v[16:17], off
	v_lshl_add_u64 v[16:17], v[10:11], 0, s[38:39]
	s_mov_b32 m0, s48
	s_nop 0
	global_load_lds_dwordx4 v[16:17], off
	s_barrier
	s_waitcnt lgkmcnt(0)
	v_mfma_f32_16x16x32_bf16 v[168:171], v[70:73], v[26:29], 0
	v_mfma_f32_16x16x32_bf16 v[172:175], v[70:73], v[34:37], 0
	v_mfma_f32_16x16x32_bf16 v[176:179], v[144:147], v[26:29], 0
	v_mfma_f32_16x16x32_bf16 v[180:183], v[144:147], v[34:37], 0
	v_mfma_f32_16x16x32_bf16 v[184:187], v[152:155], v[26:29], 0
	v_mfma_f32_16x16x32_bf16 v[188:191], v[152:155], v[34:37], 0
	v_mfma_f32_16x16x32_bf16 v[24:27], v[160:163], v[26:29], 0
	v_mfma_f32_16x16x32_bf16 v[34:37], v[160:163], v[34:37], 0
	v_mfma_f32_16x16x32_bf16 v[168:171], v[140:143], v[30:33], v[168:171]
	v_mfma_f32_16x16x32_bf16 v[176:179], v[148:151], v[30:33], v[176:179]
	v_mfma_f32_16x16x32_bf16 v[184:187], v[156:159], v[30:33], v[184:187]
	v_mfma_f32_16x16x32_bf16 v[24:27], v[164:167], v[30:33], v[24:27]
	v_mfma_f32_16x16x32_bf16 v[28:31], v[164:167], v[38:41], v[34:37]
	v_mfma_f32_16x16x32_bf16 v[172:175], v[140:143], v[38:41], v[172:175]
	v_mfma_f32_16x16x32_bf16 v[180:183], v[148:151], v[38:41], v[180:183]
	v_mfma_f32_16x16x32_bf16 v[188:191], v[156:159], v[38:41], v[188:191]
	s_barrier
	v_readfirstlane_b32 s48, v22
	v_add_u32_e32 v20, 0x2000, v22
	v_lshl_add_u64 v[16:17], v[2:3], 0, s[38:39]
	s_mov_b32 m0, s48
	v_readfirstlane_b32 s48, v20
	global_load_lds_dwordx4 v[16:17], off
	v_lshl_add_u64 v[16:17], v[0:1], 0, s[38:39]
	s_mov_b32 m0, s48
	s_nop 0
	global_load_lds_dwordx4 v[16:17], off
	s_waitcnt vmcnt(6)
	s_barrier
	v_mfma_f32_16x16x32_bf16 v[20:23], v[70:73], v[106:109], 0
	v_mfma_f32_16x16x32_bf16 v[32:35], v[70:73], v[114:117], 0
	v_mfma_f32_16x16x32_bf16 v[36:39], v[144:147], v[106:109], 0
	v_mfma_f32_16x16x32_bf16 v[70:73], v[144:147], v[114:117], 0
	v_mfma_f32_16x16x32_bf16 v[144:147], v[152:155], v[106:109], 0
	v_mfma_f32_16x16x32_bf16 v[152:155], v[152:155], v[114:117], 0
	v_mfma_f32_16x16x32_bf16 v[106:109], v[160:163], v[106:109], 0
	v_mfma_f32_16x16x32_bf16 v[114:117], v[160:163], v[114:117], 0
	v_mfma_f32_16x16x32_bf16 v[20:23], v[140:143], v[110:113], v[20:23]
	v_mfma_f32_16x16x32_bf16 v[32:35], v[140:143], v[118:121], v[32:35]
	v_mfma_f32_16x16x32_bf16 v[36:39], v[148:151], v[110:113], v[36:39]
	v_mfma_f32_16x16x32_bf16 v[70:73], v[148:151], v[118:121], v[70:73]
	v_mfma_f32_16x16x32_bf16 v[140:143], v[156:159], v[110:113], v[144:147]
	v_mfma_f32_16x16x32_bf16 v[106:109], v[164:167], v[110:113], v[106:109]
	v_mfma_f32_16x16x32_bf16 v[110:113], v[164:167], v[118:121], v[114:117]
	v_mfma_f32_16x16x32_bf16 v[144:147], v[156:159], v[118:121], v[152:155]
	v_add3_u32 v225, s58, v127, v126
	s_barrier
	ds_read_b128 v[114:117], v225
	ds_read_b128 v[118:121], v225 offset:1024
	ds_read_b128 v[148:151], v225 offset:2048
	ds_read_b128 v[152:155], v225 offset:3072
	v_readfirstlane_b32 s48, v18
	v_lshl_add_u64 v[16:17], v[6:7], 0, s[38:39]
	s_mov_b32 m0, s48
	v_readfirstlane_b32 s48, v19
	ds_read_b128 v[156:159], v228 offset:32768
	ds_read_b128 v[160:163], v228 offset:33792
	ds_read_b128 v[164:167], v229 offset:34816
	ds_read_b128 v[192:195], v229 offset:35840
	ds_read_b128 v[196:199], v229 offset:36864
	ds_read_b128 v[200:203], v229 offset:37888
	ds_read_b128 v[204:207], v229 offset:38912
	ds_read_b128 v[208:211], v229 offset:39936
	global_load_lds_dwordx4 v[16:17], off
	v_lshl_add_u64 v[16:17], v[4:5], 0, s[38:39]
	s_mov_b32 m0, s48
	s_nop 0
	global_load_lds_dwordx4 v[16:17], off
	s_waitcnt lgkmcnt(8)
	s_barrier
	s_waitcnt lgkmcnt(0)
	v_mfma_f32_16x16x32_bf16 v[16:19], v[156:159], v[114:117], v[74:77]
	v_mfma_f32_16x16x32_bf16 v[74:77], v[156:159], v[148:151], v[78:81]
	v_mfma_f32_16x16x32_bf16 v[78:81], v[164:167], v[114:117], v[82:85]
	v_mfma_f32_16x16x32_bf16 v[82:85], v[164:167], v[148:151], v[86:89]
	v_mfma_f32_16x16x32_bf16 v[86:89], v[196:199], v[114:117], v[90:93]
	v_mfma_f32_16x16x32_bf16 v[90:93], v[196:199], v[148:151], v[94:97]
	v_mfma_f32_16x16x32_bf16 v[94:97], v[204:207], v[114:117], v[98:101]
	v_mfma_f32_16x16x32_bf16 v[98:101], v[204:207], v[148:151], v[102:105]
	v_mfma_f32_16x16x32_bf16 v[16:19], v[160:163], v[118:121], v[16:19]
	v_mfma_f32_16x16x32_bf16 v[74:77], v[160:163], v[152:155], v[74:77]
	v_mfma_f32_16x16x32_bf16 v[78:81], v[192:195], v[118:121], v[78:81]
	v_mfma_f32_16x16x32_bf16 v[82:85], v[192:195], v[152:155], v[82:85]
	v_mfma_f32_16x16x32_bf16 v[86:89], v[200:203], v[118:121], v[86:89]
	v_mfma_f32_16x16x32_bf16 v[90:93], v[200:203], v[152:155], v[90:93]
	v_mfma_f32_16x16x32_bf16 v[94:97], v[208:211], v[118:121], v[94:97]
	v_mfma_f32_16x16x32_bf16 v[98:101], v[208:211], v[152:155], v[98:101]
	s_barrier
	s_mov_b32 m0, s53
	v_add3_u32 v226, s59, v127, v126
	v_lshl_add_u64 v[12:13], v[12:13], 0, s[40:41]
	ds_read_b128 v[102:105], v226
	ds_read_b128 v[212:215], v226 offset:1024
	ds_read_b128 v[216:219], v226 offset:2048
	ds_read_b128 v[220:223], v226 offset:3072
	global_load_lds_dwordx4 v[12:13], off
	v_lshl_add_u64 v[12:13], v[14:15], 0, s[40:41]
	s_mov_b32 m0, s52
	s_nop 0
	global_load_lds_dwordx4 v[12:13], off
	s_barrier
; #define STAGE(P, BASE, LD, br, kt) do { const char* _g = (const char*)((BASE) + (size_t)(br) * (LD) + (size_t)(kt) * 64); \
;     for (int _i = 0; _i < 2; ++_i) { int _b = tidx * 16 + _i * 8192; int _r, _c; stage_rc(_b, _r, _c); \
;       __builtin_amdgcn_global_load_lds((const unsigned*)(_g + (unsigned)((_r * (LD) + _c) * 2)), (unsigned*)((char*)(P) + _b), 16, 0, 0); } } while (0)
; #define LDA(dst, b, h) for (int m = 0; m < 4; ++m) for (int k = 0; k < 2; ++k) \
;     dst[m][k] = *reinterpret_cast<const bf16x8*>((char*)SA(b, h) + lds_byte(wr * 64 + m * 16 + fr, k * 32 + fq * 8))
; #define LDB(dst, b, h) for (int n = 0; n < 2; ++n) for (int k = 0; k < 2; ++k) \
;     dst[n][k] = *reinterpret_cast<const bf16x8*>((char*)SB(b, h) + lds_byte(wc * 32 + n * 16 + fr, k * 32 + fq * 8))
; #define MMA(ai, bj, At_, Bt_) do { __builtin_amdgcn_s_setprio(1); \
;     for (int k = 0; k < 2; ++k) for (int m = 0; m < 4; ++m) for (int n = 0; n < 2; ++n) \
;       acc[ai][bj][m][n] = __builtin_amdgcn_mfma_f32_16x16x32_bf16(At_[m][k], Bt_[n][k], acc[ai][bj][m][n], 0, 0, 0); \
;     __builtin_amdgcn_s_setprio(0); } while (0)
; #define WAIT_V(n) asm volatile("s_waitcnt vmcnt(" #n ")" ::: "memory")
; #define WAIT_L(n) asm volatile("s_waitcnt lgkmcnt(" #n ")" ::: "memory")
; #define BAR __builtin_amdgcn_s_barrier()
; #define SCHED __builtin_amdgcn_sched_barrier(0)
; template <int EPI, int lda, int ldb, int N, int K>
; __device__ __forceinline__ void gemm_phase(const u16* __restrict__ A, const u16* __restrict__ Bt, const GemmEpi ep, int wv) {
;     ...
;       LDB(B1, 1, 1); STAGE(SB(1, 0), Bt, ldb, bcol, t + 3);
;       BAR; WAIT_L(0); MMA(0, 1, At, B1); BAR;
;       LDA(At, 1, 1); STAGE(SA(1, 0), Ab, lda, brow, t + 3);
;       BAR; WAIT_L(0); MMA(1, 0, At, B0); BAR; SCHED;
;       STAGE(SB(1, 1), Bt, ldb, bcol + HALF, t + 3);
;       WAIT_V(6); BAR; MMA(1, 1, At, B1); BAR;
	s_waitcnt lgkmcnt(0)
	v_mfma_f32_16x16x32_bf16 v[12:15], v[156:159], v[102:105], v[122:125]
	v_mfma_f32_16x16x32_bf16 v[40:43], v[156:159], v[216:219], v[42:45]
	v_mfma_f32_16x16x32_bf16 v[44:47], v[164:167], v[102:105], v[46:49]
	v_mfma_f32_16x16x32_bf16 v[48:51], v[164:167], v[216:219], v[50:53]
	v_mfma_f32_16x16x32_bf16 v[52:55], v[196:199], v[102:105], v[54:57]
	v_mfma_f32_16x16x32_bf16 v[56:59], v[196:199], v[216:219], v[58:61]
	v_mfma_f32_16x16x32_bf16 v[60:63], v[204:207], v[102:105], v[62:65]
	v_mfma_f32_16x16x32_bf16 v[64:67], v[204:207], v[216:219], v[66:69]
	v_mfma_f32_16x16x32_bf16 v[12:15], v[160:163], v[212:215], v[12:15]
	v_mfma_f32_16x16x32_bf16 v[40:43], v[160:163], v[220:223], v[40:43]
	v_mfma_f32_16x16x32_bf16 v[44:47], v[192:195], v[212:215], v[44:47]
	v_mfma_f32_16x16x32_bf16 v[48:51], v[192:195], v[220:223], v[48:51]
	v_mfma_f32_16x16x32_bf16 v[52:55], v[200:203], v[212:215], v[52:55]
	v_mfma_f32_16x16x32_bf16 v[56:59], v[200:203], v[220:223], v[56:59]
	v_mfma_f32_16x16x32_bf16 v[60:63], v[208:211], v[212:215], v[60:63]
	v_mfma_f32_16x16x32_bf16 v[64:67], v[208:211], v[220:223], v[64:67]
	s_mov_b32 m0, s51
	v_lshl_add_u64 v[8:9], v[8:9], 0, s[40:41]
	s_barrier
	ds_read_b128 v[122:125], v228 offset:49152
	ds_read_b128 v[156:159], v228 offset:50176
	ds_read_b128 v[160:163], v229 offset:51200
	ds_read_b128 v[164:167], v229 offset:52224
	ds_read_b128 v[192:195], v229 offset:53248
	ds_read_b128 v[196:199], v229 offset:54272
	ds_read_b128 v[200:203], v229 offset:55296
	ds_read_b128 v[204:207], v229 offset:56320
	global_load_lds_dwordx4 v[8:9], off
	v_lshl_add_u64 v[8:9], v[10:11], 0, s[40:41]
	s_mov_b32 m0, s50
	s_nop 0
	global_load_lds_dwordx4 v[8:9], off
	s_barrier
	s_waitcnt lgkmcnt(0)
	v_mfma_f32_16x16x32_bf16 v[8:11], v[122:125], v[114:117], v[168:171]
	v_mfma_f32_16x16x32_bf16 v[168:171], v[122:125], v[148:151], v[172:175]
	v_mfma_f32_16x16x32_bf16 v[24:27], v[200:203], v[114:117], v[24:27]
	v_mfma_f32_16x16x32_bf16 v[28:31], v[200:203], v[148:151], v[28:31]
	v_mfma_f32_16x16x32_bf16 v[172:175], v[160:163], v[114:117], v[176:179]
	v_mfma_f32_16x16x32_bf16 v[176:179], v[160:163], v[148:151], v[180:183]
	v_mfma_f32_16x16x32_bf16 v[180:183], v[192:195], v[114:117], v[184:187]
	v_mfma_f32_16x16x32_bf16 v[184:187], v[192:195], v[148:151], v[188:191]
	v_mfma_f32_16x16x32_bf16 v[8:11], v[156:159], v[118:121], v[8:11]
	v_mfma_f32_16x16x32_bf16 v[114:117], v[156:159], v[152:155], v[168:171]
	v_mfma_f32_16x16x32_bf16 v[24:27], v[204:207], v[118:121], v[24:27]
	v_mfma_f32_16x16x32_bf16 v[28:31], v[204:207], v[152:155], v[28:31]
	v_mfma_f32_16x16x32_bf16 v[148:151], v[164:167], v[118:121], v[172:175]
	v_mfma_f32_16x16x32_bf16 v[168:171], v[164:167], v[152:155], v[176:179]
	v_mfma_f32_16x16x32_bf16 v[172:175], v[196:199], v[118:121], v[180:183]
	v_mfma_f32_16x16x32_bf16 v[176:179], v[196:199], v[152:155], v[184:187]
	s_barrier
	s_mov_b32 m0, s11
	v_lshl_add_u64 v[2:3], v[2:3], 0, s[40:41]
	global_load_lds_dwordx4 v[2:3], off
	v_lshl_add_u64 v[0:1], v[0:1], 0, s[40:41]
	s_mov_b32 m0, s5
	s_nop 0
	global_load_lds_dwordx4 v[0:1], off
	s_waitcnt vmcnt(6)
	s_barrier
	v_mfma_f32_16x16x32_bf16 v[0:3], v[122:125], v[102:105], v[20:23]
	v_mfma_f32_16x16x32_bf16 v[20:23], v[122:125], v[216:219], v[32:35]
	v_mfma_f32_16x16x32_bf16 v[32:35], v[160:163], v[102:105], v[36:39]
	v_mfma_f32_16x16x32_bf16 v[36:39], v[160:163], v[216:219], v[70:73]
	v_mfma_f32_16x16x32_bf16 v[68:71], v[192:195], v[102:105], v[140:143]
	v_mfma_f32_16x16x32_bf16 v[118:121], v[192:195], v[216:219], v[144:147]
	v_mfma_f32_16x16x32_bf16 v[102:105], v[200:203], v[102:105], v[106:109]
	v_mfma_f32_16x16x32_bf16 v[106:109], v[200:203], v[216:219], v[110:113]
	v_mfma_f32_16x16x32_bf16 v[0:3], v[156:159], v[212:215], v[0:3]
	v_mfma_f32_16x16x32_bf16 v[20:23], v[156:159], v[220:223], v[20:23]
	v_mfma_f32_16x16x32_bf16 v[32:35], v[164:167], v[212:215], v[32:35]
	v_mfma_f32_16x16x32_bf16 v[36:39], v[164:167], v[220:223], v[36:39]
	v_mfma_f32_16x16x32_bf16 v[68:71], v[196:199], v[212:215], v[68:71]
	v_mfma_f32_16x16x32_bf16 v[110:113], v[196:199], v[220:223], v[118:121]
	v_mfma_f32_16x16x32_bf16 v[102:105], v[204:207], v[212:215], v[102:105]
	v_mfma_f32_16x16x32_bf16 v[106:109], v[204:207], v[220:223], v[106:109]
	s_mov_b32 m0, s47
	v_lshl_add_u64 v[6:7], v[6:7], 0, s[40:41]
	s_barrier
	ds_read_b128 v[118:121], v133
	ds_read_b128 v[122:125], v133 offset:1024
	ds_read_b128 v[140:143], v133 offset:2048
	ds_read_b128 v[144:147], v133 offset:3072
	ds_read_b128 v[152:155], v228
	ds_read_b128 v[156:159], v228 offset:1024
	ds_read_b128 v[160:163], v229 offset:2048
	ds_read_b128 v[164:167], v229 offset:3072
	ds_read_b128 v[180:183], v229 offset:4096
	ds_read_b128 v[184:187], v229 offset:5120
	ds_read_b128 v[188:191], v229 offset:6144
	ds_read_b128 v[192:195], v229 offset:7168
	global_load_lds_dwordx4 v[6:7], off
	v_lshl_add_u64 v[4:5], v[4:5], 0, s[40:41]
	s_mov_b32 m0, s46
	s_nop 0
	global_load_lds_dwordx4 v[4:5], off
	s_barrier
	s_waitcnt lgkmcnt(0)
	v_mfma_f32_16x16x32_bf16 v[4:7], v[152:155], v[118:121], v[16:19]
	v_mfma_f32_16x16x32_bf16 v[16:19], v[152:155], v[140:143], v[74:77]
	v_mfma_f32_16x16x32_bf16 v[72:75], v[160:163], v[118:121], v[78:81]
	v_mfma_f32_16x16x32_bf16 v[76:79], v[160:163], v[140:143], v[82:85]
	v_mfma_f32_16x16x32_bf16 v[80:83], v[180:183], v[118:121], v[86:89]
	v_mfma_f32_16x16x32_bf16 v[84:87], v[180:183], v[140:143], v[90:93]
	v_mfma_f32_16x16x32_bf16 v[88:91], v[188:191], v[118:121], v[94:97]
	v_mfma_f32_16x16x32_bf16 v[92:95], v[188:191], v[140:143], v[98:101]
	v_mfma_f32_16x16x32_bf16 v[4:7], v[156:159], v[122:125], v[4:7]
	v_mfma_f32_16x16x32_bf16 v[16:19], v[156:159], v[144:147], v[16:19]
	v_mfma_f32_16x16x32_bf16 v[72:75], v[164:167], v[122:125], v[72:75]
	v_mfma_f32_16x16x32_bf16 v[76:79], v[164:167], v[144:147], v[76:79]
	v_mfma_f32_16x16x32_bf16 v[80:83], v[184:187], v[122:125], v[80:83]
	v_mfma_f32_16x16x32_bf16 v[84:87], v[184:187], v[144:147], v[84:87]
	v_mfma_f32_16x16x32_bf16 v[88:91], v[192:195], v[122:125], v[88:91]
	v_mfma_f32_16x16x32_bf16 v[92:95], v[192:195], v[144:147], v[92:95]
	s_barrier
; #define STAGE(P, BASE, LD, br, kt) do { const char* _g = (const char*)((BASE) + (size_t)(br) * (LD) + (size_t)(kt) * 64); \
;     for (int _i = 0; _i < 2; ++_i) { int _b = tidx * 16 + _i * 8192; int _r, _c; stage_rc(_b, _r, _c); \
;       __builtin_amdgcn_global_load_lds((const unsigned*)(_g + (unsigned)((_r * (LD) + _c) * 2)), (unsigned*)((char*)(P) + _b), 16, 0, 0); } } while (0)
; #define LDA(dst, b, h) for (int m = 0; m < 4; ++m) for (int k = 0; k < 2; ++k) \
;     dst[m][k] = *reinterpret_cast<const bf16x8*>((char*)SA(b, h) + lds_byte(wr * 64 + m * 16 + fr, k * 32 + fq * 8))
; #define LDB(dst, b, h) for (int n = 0; n < 2; ++n) for (int k = 0; k < 2; ++k) \
;     dst[n][k] = *reinterpret_cast<const bf16x8*>((char*)SB(b, h) + lds_byte(wc * 32 + n * 16 + fr, k * 32 + fq * 8))
; #define MMA(ai, bj, At_, Bt_) do { __builtin_amdgcn_s_setprio(1); \
;     for (int k = 0; k < 2; ++k) for (int m = 0; m < 4; ++m) for (int n = 0; n < 2; ++n) \
;       acc[ai][bj][m][n] = __builtin_amdgcn_mfma_f32_16x16x32_bf16(At_[m][k], Bt_[n][k], acc[ai][bj][m][n], 0, 0, 0); \
;     __builtin_amdgcn_s_setprio(0); } while (0)
; #define WAIT_V(n) asm volatile("s_waitcnt vmcnt(" #n ")" ::: "memory")
; #define WAIT_L(n) asm volatile("s_waitcnt lgkmcnt(" #n ")" ::: "memory")
; #define BAR __builtin_amdgcn_s_barrier()
; template <int EPI, int lda, int ldb, int N, int K>
; __device__ __forceinline__ void gemm_phase(const u16* __restrict__ A, const u16* __restrict__ Bt, const GemmEpi ep, int wv) {
;     ...
;     { LDB(B0, 0, 0); LDA(At, 0, 0); STAGE(SA(1, 1), Ab, lda, brow + HALF, nt - 1);
;       BAR; WAIT_L(0); MMA(0, 0, At, B0); BAR;
;       LDB(B1, 0, 1); BAR; WAIT_L(0); MMA(0, 1, At, B1); BAR;
;       LDA(At, 0, 1); WAIT_V(4); BAR; WAIT_L(0); MMA(1, 0, At, B0); MMA(1, 1, At, B1); BAR; }
;     { LDB(B0, 1, 0); LDA(At, 1, 0); WAIT_V(2); BAR; WAIT_L(0); MMA(0, 0, At, B0); BAR;
	ds_read_b128 v[96:99], v224
	ds_read_b128 v[196:199], v224 offset:1024
	ds_read_b128 v[200:203], v224 offset:2048
	ds_read_b128 v[204:207], v224 offset:3072
	s_barrier
	s_waitcnt lgkmcnt(0)
	v_mfma_f32_16x16x32_bf16 v[12:15], v[152:155], v[96:99], v[12:15]
	v_mfma_f32_16x16x32_bf16 v[40:43], v[152:155], v[200:203], v[40:43]
	v_mfma_f32_16x16x32_bf16 v[52:55], v[180:183], v[96:99], v[52:55]
	v_mfma_f32_16x16x32_bf16 v[56:59], v[180:183], v[200:203], v[56:59]
	v_mfma_f32_16x16x32_bf16 v[64:67], v[188:191], v[200:203], v[64:67]
	v_mfma_f32_16x16x32_bf16 v[44:47], v[160:163], v[96:99], v[44:47]
	v_mfma_f32_16x16x32_bf16 v[48:51], v[160:163], v[200:203], v[48:51]
	v_mfma_f32_16x16x32_bf16 v[60:63], v[188:191], v[96:99], v[60:63]
	v_mfma_f32_16x16x32_bf16 v[12:15], v[156:159], v[196:199], v[12:15]
	v_mfma_f32_16x16x32_bf16 v[40:43], v[156:159], v[204:207], v[40:43]
	v_mfma_f32_16x16x32_bf16 v[52:55], v[184:187], v[196:199], v[52:55]
	v_mfma_f32_16x16x32_bf16 v[56:59], v[184:187], v[204:207], v[56:59]
	v_mfma_f32_16x16x32_bf16 v[64:67], v[192:195], v[204:207], v[64:67]
	v_mfma_f32_16x16x32_bf16 v[152:155], v[164:167], v[196:199], v[44:47]
	v_mfma_f32_16x16x32_bf16 v[156:159], v[164:167], v[204:207], v[48:51]
	v_mfma_f32_16x16x32_bf16 v[160:163], v[192:195], v[196:199], v[60:63]
	s_barrier
	ds_read_b128 v[44:47], v228 offset:16384
	ds_read_b128 v[48:51], v228 offset:17408
	ds_read_b128 v[60:63], v229 offset:18432
	ds_read_b128 v[164:167], v229 offset:19456
	ds_read_b128 v[180:183], v229 offset:20480
	ds_read_b128 v[184:187], v229 offset:21504
	ds_read_b128 v[188:191], v229 offset:22528
	ds_read_b128 v[192:195], v229 offset:23552
	s_waitcnt vmcnt(4)
	s_barrier
	s_waitcnt lgkmcnt(0)
	v_mfma_f32_16x16x32_bf16 v[8:11], v[44:47], v[118:121], v[8:11]
	v_mfma_f32_16x16x32_bf16 v[24:27], v[188:191], v[118:121], v[24:27]
	v_mfma_f32_16x16x32_bf16 v[28:31], v[188:191], v[140:143], v[28:31]
	v_mfma_f32_16x16x32_bf16 v[114:117], v[44:47], v[140:143], v[114:117]
	v_mfma_f32_16x16x32_bf16 v[148:151], v[60:63], v[118:121], v[148:151]
	v_mfma_f32_16x16x32_bf16 v[168:171], v[60:63], v[140:143], v[168:171]
	v_mfma_f32_16x16x32_bf16 v[172:175], v[180:183], v[118:121], v[172:175]
	v_mfma_f32_16x16x32_bf16 v[176:179], v[180:183], v[140:143], v[176:179]
	v_mfma_f32_16x16x32_bf16 v[8:11], v[48:51], v[122:125], v[8:11]
	v_mfma_f32_16x16x32_bf16 v[24:27], v[192:195], v[122:125], v[24:27]
	v_mfma_f32_16x16x32_bf16 v[28:31], v[192:195], v[144:147], v[28:31]
	v_mfma_f32_16x16x32_bf16 v[140:143], v[48:51], v[144:147], v[114:117]
	v_mfma_f32_16x16x32_bf16 v[148:151], v[164:167], v[122:125], v[148:151]
	v_mfma_f32_16x16x32_bf16 v[168:171], v[164:167], v[144:147], v[168:171]
	v_mfma_f32_16x16x32_bf16 v[172:175], v[184:187], v[122:125], v[172:175]
	v_mfma_f32_16x16x32_bf16 v[176:179], v[184:187], v[144:147], v[176:179]
	v_mfma_f32_16x16x32_bf16 v[0:3], v[44:47], v[96:99], v[0:3]
	v_mfma_f32_16x16x32_bf16 v[20:23], v[44:47], v[200:203], v[20:23]
	v_mfma_f32_16x16x32_bf16 v[44:47], v[180:183], v[96:99], v[68:71]
	v_mfma_f32_16x16x32_bf16 v[68:71], v[188:191], v[96:99], v[102:105]
	v_mfma_f32_16x16x32_bf16 v[32:35], v[60:63], v[96:99], v[32:35]
	v_mfma_f32_16x16x32_bf16 v[36:39], v[60:63], v[200:203], v[36:39]
	v_mfma_f32_16x16x32_bf16 v[60:63], v[180:183], v[200:203], v[110:113]
	v_mfma_f32_16x16x32_bf16 v[96:99], v[188:191], v[200:203], v[106:109]
	v_mfma_f32_16x16x32_bf16 v[20:23], v[48:51], v[204:207], v[20:23]
	v_mfma_f32_16x16x32_bf16 v[68:71], v[192:195], v[196:199], v[68:71]
	v_mfma_f32_16x16x32_bf16 v[144:147], v[48:51], v[196:199], v[0:3]
	v_mfma_f32_16x16x32_bf16 v[180:183], v[164:167], v[196:199], v[32:35]
	v_mfma_f32_16x16x32_bf16 v[164:167], v[164:167], v[204:207], v[36:39]
	v_mfma_f32_16x16x32_bf16 v[188:191], v[184:187], v[196:199], v[44:47]
	v_mfma_f32_16x16x32_bf16 v[184:187], v[184:187], v[204:207], v[60:63]
	v_mfma_f32_16x16x32_bf16 v[192:195], v[192:195], v[204:207], v[96:99]
	s_barrier
	ds_read_b128 v[0:3], v225
	ds_read_b128 v[196:199], v225 offset:1024
	ds_read_b128 v[200:203], v225 offset:2048
	ds_read_b128 v[204:207], v225 offset:3072
	ds_read_b128 v[36:39], v228 offset:32768
	ds_read_b128 v[100:103], v228 offset:33792
	ds_read_b128 v[108:111], v229 offset:34816
	ds_read_b128 v[208:211], v229 offset:35840
	ds_read_b128 v[116:119], v229 offset:36864
	ds_read_b128 v[212:215], v229 offset:37888
	ds_read_b128 v[124:127], v229 offset:38912
	ds_read_b128 v[216:219], v229 offset:39936
	s_waitcnt vmcnt(2)
	s_barrier
; #define LDA(dst, b, h) for (int m = 0; m < 4; ++m) for (int k = 0; k < 2; ++k) \
;     dst[m][k] = *reinterpret_cast<const bf16x8*>((char*)SA(b, h) + lds_byte(wr * 64 + m * 16 + fr, k * 32 + fq * 8))
; #define LDB(dst, b, h) for (int n = 0; n < 2; ++n) for (int k = 0; k < 2; ++k) \
;     dst[n][k] = *reinterpret_cast<const bf16x8*>((char*)SB(b, h) + lds_byte(wc * 32 + n * 16 + fr, k * 32 + fq * 8))
; #define MMA(ai, bj, At_, Bt_) do { __builtin_amdgcn_s_setprio(1); \
;     for (int k = 0; k < 2; ++k) for (int m = 0; m < 4; ++m) for (int n = 0; n < 2; ++n) \
;       acc[ai][bj][m][n] = __builtin_amdgcn_mfma_f32_16x16x32_bf16(At_[m][k], Bt_[n][k], acc[ai][bj][m][n], 0, 0, 0); \
;     __builtin_amdgcn_s_setprio(0); } while (0)
; #define WAIT_V(n) asm volatile("s_waitcnt vmcnt(" #n ")" ::: "memory")
; #define WAIT_L(n) asm volatile("s_waitcnt lgkmcnt(" #n ")" ::: "memory")
; #define BAR __builtin_amdgcn_s_barrier()
; template <int EPI, int lda, int ldb, int N, int K>
; __device__ __forceinline__ void gemm_phase(const u16* __restrict__ A, const u16* __restrict__ Bt, const GemmEpi ep, int wv) {
;     ...
;     { LDB(B0, 1, 0); LDA(At, 1, 0); WAIT_V(2); BAR; WAIT_L(0); MMA(0, 0, At, B0); BAR;
;       LDB(B1, 1, 1); WAIT_V(0); BAR; WAIT_L(0); MMA(0, 1, At, B1); BAR;
;       LDA(At, 1, 1); BAR; WAIT_L(0); MMA(1, 0, At, B0); MMA(1, 1, At, B1); BAR; }
;     if (wr == 0) BAR;
	s_waitcnt lgkmcnt(0)
	v_mfma_f32_16x16x32_bf16 v[4:7], v[36:39], v[0:3], v[4:7]
	v_mfma_f32_16x16x32_bf16 v[16:19], v[36:39], v[200:203], v[16:19]
	v_mfma_f32_16x16x32_bf16 v[32:35], v[108:111], v[0:3], v[72:75]
	v_mfma_f32_16x16x32_bf16 v[44:47], v[108:111], v[200:203], v[76:79]
	v_mfma_f32_16x16x32_bf16 v[72:75], v[116:119], v[0:3], v[80:83]
	v_mfma_f32_16x16x32_bf16 v[76:79], v[116:119], v[200:203], v[84:87]
	v_mfma_f32_16x16x32_bf16 v[80:83], v[124:127], v[0:3], v[88:91]
	v_mfma_f32_16x16x32_bf16 v[84:87], v[124:127], v[200:203], v[92:95]
	v_mfma_f32_16x16x32_bf16 v[120:123], v[100:103], v[196:199], v[4:7]
	v_mfma_f32_16x16x32_bf16 v[60:63], v[100:103], v[204:207], v[16:19]
	v_mfma_f32_16x16x32_bf16 v[112:115], v[208:211], v[196:199], v[32:35]
	v_mfma_f32_16x16x32_bf16 v[48:51], v[208:211], v[204:207], v[44:47]
	v_mfma_f32_16x16x32_bf16 v[104:107], v[212:215], v[196:199], v[72:75]
	v_mfma_f32_16x16x32_bf16 v[44:47], v[212:215], v[204:207], v[76:79]
	v_mfma_f32_16x16x32_bf16 v[96:99], v[216:219], v[196:199], v[80:83]
	v_mfma_f32_16x16x32_bf16 v[32:35], v[216:219], v[204:207], v[84:87]
	s_barrier
	ds_read_b128 v[4:7], v226
	ds_read_b128 v[220:223], v226 offset:1024
	ds_read_b128 v[76:79], v226 offset:2048
	ds_read_b128 v[224:227], v226 offset:3072
	s_waitcnt vmcnt(0)
	s_barrier
	s_waitcnt lgkmcnt(0)
	v_mfma_f32_16x16x32_bf16 v[12:15], v[36:39], v[4:7], v[12:15]
	v_mfma_f32_16x16x32_bf16 v[16:19], v[36:39], v[76:79], v[40:43]
	v_mfma_f32_16x16x32_bf16 v[36:39], v[108:111], v[4:7], v[152:155]
	v_mfma_f32_16x16x32_bf16 v[40:43], v[108:111], v[76:79], v[156:159]
	v_mfma_f32_16x16x32_bf16 v[72:75], v[116:119], v[4:7], v[52:55]
	v_mfma_f32_16x16x32_bf16 v[80:83], v[116:119], v[76:79], v[56:59]
	v_mfma_f32_16x16x32_bf16 v[84:87], v[124:127], v[4:7], v[160:163]
	v_mfma_f32_16x16x32_bf16 v[64:67], v[124:127], v[76:79], v[64:67]
	v_mfma_f32_16x16x32_bf16 v[124:127], v[100:103], v[220:223], v[12:15]
	v_mfma_f32_16x16x32_bf16 v[56:59], v[100:103], v[224:227], v[16:19]
	v_mfma_f32_16x16x32_bf16 v[116:119], v[208:211], v[220:223], v[36:39]
	v_mfma_f32_16x16x32_bf16 v[52:55], v[208:211], v[224:227], v[40:43]
	v_mfma_f32_16x16x32_bf16 v[108:111], v[212:215], v[220:223], v[72:75]
	v_mfma_f32_16x16x32_bf16 v[40:43], v[212:215], v[224:227], v[80:83]
	v_mfma_f32_16x16x32_bf16 v[100:103], v[216:219], v[220:223], v[84:87]
	v_mfma_f32_16x16x32_bf16 v[36:39], v[216:219], v[224:227], v[64:67]
	s_barrier
	ds_read_b128 v[84:87], v228 offset:49152
	ds_read_b128 v[152:155], v228 offset:50176
	ds_read_b128 v[92:95], v229 offset:51200
	ds_read_b128 v[156:159], v229 offset:52224
	ds_read_b128 v[160:163], v229 offset:53248
	ds_read_b128 v[208:211], v229 offset:54272
	ds_read_b128 v[212:215], v229 offset:55296
	ds_read_b128 v[216:219], v229 offset:56320
	s_barrier
	s_waitcnt lgkmcnt(0)
	v_mfma_f32_16x16x32_bf16 v[8:11], v[84:87], v[0:3], v[8:11]
	v_mfma_f32_16x16x32_bf16 v[12:15], v[84:87], v[200:203], v[140:143]
	v_mfma_f32_16x16x32_bf16 v[16:19], v[92:95], v[0:3], v[148:151]
	v_mfma_f32_16x16x32_bf16 v[64:67], v[92:95], v[200:203], v[168:171]
	v_mfma_f32_16x16x32_bf16 v[72:75], v[160:163], v[0:3], v[172:175]
	v_mfma_f32_16x16x32_bf16 v[140:143], v[160:163], v[200:203], v[176:179]
	v_mfma_f32_16x16x32_bf16 v[0:3], v[212:215], v[0:3], v[24:27]
	v_mfma_f32_16x16x32_bf16 v[24:27], v[212:215], v[200:203], v[28:31]
	v_mfma_f32_16x16x32_bf16 v[88:91], v[152:155], v[196:199], v[8:11]
	v_mfma_f32_16x16x32_bf16 v[28:31], v[152:155], v[204:207], v[12:15]
	v_mfma_f32_16x16x32_bf16 v[80:83], v[156:159], v[196:199], v[16:19]
	v_mfma_f32_16x16x32_bf16 v[16:19], v[156:159], v[204:207], v[64:67]
	v_mfma_f32_16x16x32_bf16 v[72:75], v[208:211], v[196:199], v[72:75]
	v_mfma_f32_16x16x32_bf16 v[12:15], v[208:211], v[204:207], v[140:143]
	v_mfma_f32_16x16x32_bf16 v[64:67], v[216:219], v[196:199], v[0:3]
	v_mfma_f32_16x16x32_bf16 v[0:3], v[216:219], v[204:207], v[24:27]
	v_mfma_f32_16x16x32_bf16 v[8:11], v[84:87], v[4:7], v[144:147]
	v_mfma_f32_16x16x32_bf16 v[20:23], v[84:87], v[76:79], v[20:23]
	v_mfma_f32_16x16x32_bf16 v[84:87], v[92:95], v[4:7], v[180:183]
	v_mfma_f32_16x16x32_bf16 v[140:143], v[92:95], v[76:79], v[164:167]
	v_mfma_f32_16x16x32_bf16 v[144:147], v[160:163], v[4:7], v[188:191]
	v_mfma_f32_16x16x32_bf16 v[148:151], v[160:163], v[76:79], v[184:187]
	v_mfma_f32_16x16x32_bf16 v[4:7], v[212:215], v[4:7], v[68:71]
	v_mfma_f32_16x16x32_bf16 v[160:163], v[212:215], v[76:79], v[192:195]
	v_mfma_f32_16x16x32_bf16 v[92:95], v[152:155], v[220:223], v[8:11]
	v_mfma_f32_16x16x32_bf16 v[24:27], v[152:155], v[224:227], v[20:23]
	v_mfma_f32_16x16x32_bf16 v[84:87], v[156:159], v[220:223], v[84:87]
	v_mfma_f32_16x16x32_bf16 v[20:23], v[156:159], v[224:227], v[140:143]
	v_mfma_f32_16x16x32_bf16 v[76:79], v[208:211], v[220:223], v[144:147]
	v_mfma_f32_16x16x32_bf16 v[8:11], v[208:211], v[224:227], v[148:151]
	v_mfma_f32_16x16x32_bf16 v[68:71], v[216:219], v[220:223], v[4:7]
	v_mfma_f32_16x16x32_bf16 v[4:7], v[216:219], v[224:227], v[160:163]
	v_cmp_gt_u32_e32 vcc, s60, v130
	s_barrier
	s_and_saveexec_b64 s[46:47], vcc
	s_cbranch_execz .LBB0_1346
	s_barrier
	s_branch .LBB0_1346

; #define STAGE(P, BASE, LD, br, kt) do { const char* _g = (const char*)((BASE) + (size_t)(br) * (LD) + (size_t)(kt) * 64); \
;     for (int _i = 0; _i < 2; ++_i) { int _b = tidx * 16 + _i * 8192; int _r, _c; stage_rc(_b, _r, _c); \
;       __builtin_amdgcn_global_load_lds((const unsigned*)(_g + (unsigned)((_r * (LD) + _c) * 2)), (unsigned*)((char*)(P) + _b), 16, 0, 0); } } while (0)
; #define LDA(dst, b, h) for (int m = 0; m < 4; ++m) for (int k = 0; k < 2; ++k) \
;     dst[m][k] = *reinterpret_cast<const bf16x8*>((char*)SA(b, h) + lds_byte(wr * 64 + m * 16 + fr, k * 32 + fq * 8))
; #define LDB(dst, b, h) for (int n = 0; n < 2; ++n) for (int k = 0; k < 2; ++k) \
;     dst[n][k] = *reinterpret_cast<const bf16x8*>((char*)SB(b, h) + lds_byte(wc * 32 + n * 16 + fr, k * 32 + fq * 8))
; #define MMA(ai, bj, At_, Bt_) do { __builtin_amdgcn_s_setprio(1); \
;     for (int k = 0; k < 2; ++k) for (int m = 0; m < 4; ++m) for (int n = 0; n < 2; ++n) \
;       acc[ai][bj][m][n] = __builtin_amdgcn_mfma_f32_16x16x32_bf16(At_[m][k], Bt_[n][k], acc[ai][bj][m][n], 0, 0, 0); \
;     __builtin_amdgcn_s_setprio(0); } while (0)
; #define WAIT_V(n) asm volatile("s_waitcnt vmcnt(" #n ")" ::: "memory")
; #define WAIT_L(n) asm volatile("s_waitcnt lgkmcnt(" #n ")" ::: "memory")
; #define BAR __builtin_amdgcn_s_barrier()
; #define SCHED __builtin_amdgcn_sched_barrier(0)
; template <int EPI, int lda, int ldb, int N, int K>
; __device__ __forceinline__ void gemm_phase(const u16* __restrict__ A, const u16* __restrict__ Bt, const GemmEpi ep, int wv) {
;     ...
;       LDB(B0, 0, 0); SCHED; LDA(At, 0, 0); STAGE(SA(1, 1), Ab, lda, brow + HALF, t + 1);
;       WAIT_L(8); BAR; WAIT_L(0); MMA(0, 0, At, B0); BAR; SCHED;
;       LDB(B1, 0, 1); STAGE(SB(0, 0), Bt, ldb, bcol, t + 2);
;       BAR; WAIT_L(0); MMA(0, 1, At, B1); BAR;
;       LDA(At, 0, 1); STAGE(SA(0, 0), Ab, lda, brow, t + 2);
;       BAR; WAIT_L(0); MMA(1, 0, At, B0); BAR; SCHED;
;       STAGE(SB(0, 1), Bt, ldb, bcol + HALF, t + 2);
;       WAIT_V(6); BAR; MMA(1, 1, At, B1); BAR;
;       LDB(B0, 1, 0); SCHED; LDA(At, 1, 0); STAGE(SA(0, 1), Ab, lda, brow + HALF, t + 2);
;       WAIT_L(8); BAR; WAIT_L(0); MMA(0, 0, At, B0); BAR; SCHED;
.LBB0_1448:
	ds_read_b128 v[164:167], v160
	ds_read_b128 v[170:173], v160 offset:1024
	ds_read_b128 v[174:177], v160 offset:2048
	ds_read_b128 v[178:181], v160 offset:3072
	v_add_u32_e32 v168, 0xc000, v143
	v_lshl_add_u64 v[234:235], v[138:139], 0, s[44:45]
	v_readfirstlane_b32 s47, v168
	v_add_u32_e32 v169, 0xe000, v143
	v_lshl_add_u64 v[162:163], v[234:235], 0, s[20:21]
	s_mov_b32 m0, s47
	v_lshl_add_u64 v[236:237], v[140:141], 0, s[44:45]
	v_readfirstlane_b32 s47, v169
	ds_read_b128 v[182:185], v151
	ds_read_b128 v[186:189], v151 offset:1024
	ds_read_b128 v[190:193], v150
	ds_read_b128 v[194:197], v150 offset:1024
	ds_read_b128 v[198:201], v149
	ds_read_b128 v[202:205], v149 offset:1024
	ds_read_b128 v[206:209], v148
	ds_read_b128 v[210:213], v148 offset:1024
	global_load_lds_dwordx4 v[162:163], off
	v_lshl_add_u64 v[162:163], v[236:237], 0, s[20:21]
	s_mov_b32 m0, s47
	s_nop 0
	global_load_lds_dwordx4 v[162:163], off
	s_waitcnt lgkmcnt(8)
	s_barrier
	s_waitcnt lgkmcnt(0)
	v_mfma_f32_16x16x32_bf16 v[124:127], v[164:167], v[182:185], v[124:127]
	v_mfma_f32_16x16x32_bf16 v[120:123], v[174:177], v[182:185], v[120:123]
	v_mfma_f32_16x16x32_bf16 v[116:119], v[164:167], v[190:193], v[116:119]
	v_mfma_f32_16x16x32_bf16 v[112:115], v[174:177], v[190:193], v[112:115]
	v_mfma_f32_16x16x32_bf16 v[108:111], v[164:167], v[198:201], v[108:111]
	v_mfma_f32_16x16x32_bf16 v[104:107], v[174:177], v[198:201], v[104:107]
	v_mfma_f32_16x16x32_bf16 v[100:103], v[164:167], v[206:209], v[100:103]
	v_mfma_f32_16x16x32_bf16 v[96:99], v[174:177], v[206:209], v[96:99]
	v_mfma_f32_16x16x32_bf16 v[124:127], v[170:173], v[186:189], v[124:127]
	v_mfma_f32_16x16x32_bf16 v[120:123], v[178:181], v[186:189], v[120:123]
	v_mfma_f32_16x16x32_bf16 v[116:119], v[170:173], v[194:197], v[116:119]
	v_mfma_f32_16x16x32_bf16 v[112:115], v[178:181], v[194:197], v[112:115]
	v_mfma_f32_16x16x32_bf16 v[108:111], v[170:173], v[202:205], v[108:111]
	v_mfma_f32_16x16x32_bf16 v[104:107], v[178:181], v[202:205], v[104:107]
	v_mfma_f32_16x16x32_bf16 v[100:103], v[170:173], v[210:213], v[100:103]
	v_mfma_f32_16x16x32_bf16 v[96:99], v[178:181], v[210:213], v[96:99]
	s_barrier
	v_add_u32_e32 v161, s55, v153
	v_lshl_add_u64 v[238:239], v[134:135], 0, s[44:45]
	v_readfirstlane_b32 s47, v161
	v_lshl_add_u64 v[162:163], v[238:239], 0, s[22:23]
	s_mov_b32 m0, s47
	ds_read_b128 v[214:217], v159
	ds_read_b128 v[218:221], v159 offset:1024
	ds_read_b128 v[222:225], v159 offset:2048
	ds_read_b128 v[226:229], v159 offset:3072
	global_load_lds_dwordx4 v[162:163], off
	v_add_u32_e32 v162, 0x2000, v161
	v_lshl_add_u64 v[240:241], v[136:137], 0, s[44:45]
	v_readfirstlane_b32 s47, v162
	v_lshl_add_u64 v[230:231], v[240:241], 0, s[22:23]
	s_mov_b32 m0, s47
	s_nop 0
	global_load_lds_dwordx4 v[230:231], off
	s_barrier
	s_waitcnt lgkmcnt(0)
	v_mfma_f32_16x16x32_bf16 v[92:95], v[214:217], v[182:185], v[92:95]
	v_mfma_f32_16x16x32_bf16 v[88:91], v[222:225], v[182:185], v[88:91]
	v_mfma_f32_16x16x32_bf16 v[84:87], v[214:217], v[190:193], v[84:87]
	v_mfma_f32_16x16x32_bf16 v[80:83], v[222:225], v[190:193], v[80:83]
	v_mfma_f32_16x16x32_bf16 v[76:79], v[214:217], v[198:201], v[76:79]
	v_mfma_f32_16x16x32_bf16 v[72:75], v[222:225], v[198:201], v[72:75]
	v_mfma_f32_16x16x32_bf16 v[68:71], v[214:217], v[206:209], v[68:71]
	v_mfma_f32_16x16x32_bf16 v[64:67], v[222:225], v[206:209], v[64:67]
	v_mfma_f32_16x16x32_bf16 v[92:95], v[218:221], v[186:189], v[92:95]
	v_mfma_f32_16x16x32_bf16 v[88:91], v[226:229], v[186:189], v[88:91]
	v_mfma_f32_16x16x32_bf16 v[84:87], v[218:221], v[194:197], v[84:87]
	v_mfma_f32_16x16x32_bf16 v[80:83], v[226:229], v[194:197], v[80:83]
	v_mfma_f32_16x16x32_bf16 v[76:79], v[218:221], v[202:205], v[76:79]
	v_mfma_f32_16x16x32_bf16 v[72:75], v[226:229], v[202:205], v[72:75]
	v_mfma_f32_16x16x32_bf16 v[68:71], v[218:221], v[210:213], v[68:71]
	v_mfma_f32_16x16x32_bf16 v[64:67], v[226:229], v[210:213], v[64:67]
	v_readfirstlane_b32 s47, v143
	v_add_u32_e32 v163, 0x2000, v143
	v_lshl_add_u64 v[230:231], v[234:235], 0, s[24:25]
	s_mov_b32 m0, s47
	v_readfirstlane_b32 s47, v163
	s_barrier
	ds_read_b128 v[182:185], v151 offset:16384
	ds_read_b128 v[186:189], v151 offset:17408
	ds_read_b128 v[190:193], v150 offset:16384
	ds_read_b128 v[194:197], v150 offset:17408
	ds_read_b128 v[198:201], v149 offset:16384
	ds_read_b128 v[202:205], v149 offset:17408
	ds_read_b128 v[206:209], v148 offset:16384
	ds_read_b128 v[210:213], v148 offset:17408
	global_load_lds_dwordx4 v[230:231], off
	v_lshl_add_u64 v[230:231], v[236:237], 0, s[24:25]
	s_mov_b32 m0, s47
	s_nop 0
	global_load_lds_dwordx4 v[230:231], off
	s_barrier
	s_waitcnt lgkmcnt(0)
	v_mfma_f32_16x16x32_bf16 v[60:63], v[164:167], v[182:185], v[60:63]
	v_mfma_f32_16x16x32_bf16 v[56:59], v[174:177], v[182:185], v[56:59]
	v_mfma_f32_16x16x32_bf16 v[52:55], v[164:167], v[190:193], v[52:55]
	v_mfma_f32_16x16x32_bf16 v[48:51], v[174:177], v[190:193], v[48:51]
	v_mfma_f32_16x16x32_bf16 v[44:47], v[164:167], v[198:201], v[44:47]
	v_mfma_f32_16x16x32_bf16 v[40:43], v[174:177], v[198:201], v[40:43]
	v_mfma_f32_16x16x32_bf16 v[36:39], v[164:167], v[206:209], v[36:39]
	v_mfma_f32_16x16x32_bf16 v[32:35], v[174:177], v[206:209], v[32:35]
	v_mfma_f32_16x16x32_bf16 v[60:63], v[170:173], v[186:189], v[60:63]
	v_mfma_f32_16x16x32_bf16 v[56:59], v[178:181], v[186:189], v[56:59]
	v_mfma_f32_16x16x32_bf16 v[52:55], v[170:173], v[194:197], v[52:55]
	v_mfma_f32_16x16x32_bf16 v[48:51], v[178:181], v[194:197], v[48:51]
	v_mfma_f32_16x16x32_bf16 v[44:47], v[170:173], v[202:205], v[44:47]
	v_mfma_f32_16x16x32_bf16 v[40:43], v[178:181], v[202:205], v[40:43]
	v_mfma_f32_16x16x32_bf16 v[36:39], v[170:173], v[210:213], v[36:39]
	v_mfma_f32_16x16x32_bf16 v[32:35], v[178:181], v[210:213], v[32:35]
	s_barrier
; #define STAGE(P, BASE, LD, br, kt) do { const char* _g = (const char*)((BASE) + (size_t)(br) * (LD) + (size_t)(kt) * 64); \
;     for (int _i = 0; _i < 2; ++_i) { int _b = tidx * 16 + _i * 8192; int _r, _c; stage_rc(_b, _r, _c); \
;       __builtin_amdgcn_global_load_lds((const unsigned*)(_g + (unsigned)((_r * (LD) + _c) * 2)), (unsigned*)((char*)(P) + _b), 16, 0, 0); } } while (0)
; #define LDA(dst, b, h) for (int m = 0; m < 4; ++m) for (int k = 0; k < 2; ++k) \
;     dst[m][k] = *reinterpret_cast<const bf16x8*>((char*)SA(b, h) + lds_byte(wr * 64 + m * 16 + fr, k * 32 + fq * 8))
; #define LDB(dst, b, h) for (int n = 0; n < 2; ++n) for (int k = 0; k < 2; ++k) \
;     dst[n][k] = *reinterpret_cast<const bf16x8*>((char*)SB(b, h) + lds_byte(wc * 32 + n * 16 + fr, k * 32 + fq * 8))
; #define MMA(ai, bj, At_, Bt_) do { __builtin_amdgcn_s_setprio(1); \
;     for (int k = 0; k < 2; ++k) for (int m = 0; m < 4; ++m) for (int n = 0; n < 2; ++n) \
;       acc[ai][bj][m][n] = __builtin_amdgcn_mfma_f32_16x16x32_bf16(At_[m][k], Bt_[n][k], acc[ai][bj][m][n], 0, 0, 0); \
;     __builtin_amdgcn_s_setprio(0); } while (0)
; #define WAIT_V(n) asm volatile("s_waitcnt vmcnt(" #n ")" ::: "memory")
; #define WAIT_L(n) asm volatile("s_waitcnt lgkmcnt(" #n ")" ::: "memory")
; #define BAR __builtin_amdgcn_s_barrier()
; #define SCHED __builtin_amdgcn_sched_barrier(0)
; template <int EPI, int lda, int ldb, int N, int K>
; __device__ __forceinline__ void gemm_phase(const u16* __restrict__ A, const u16* __restrict__ Bt, const GemmEpi ep, int wv) {
;     ...
;       WAIT_V(6); BAR; MMA(1, 1, At, B1); BAR;
;       LDB(B0, 1, 0); SCHED; LDA(At, 1, 0); STAGE(SA(0, 1), Ab, lda, brow + HALF, t + 2);
;       WAIT_L(8); BAR; WAIT_L(0); MMA(0, 0, At, B0); BAR; SCHED;
;       LDB(B1, 1, 1); STAGE(SB(1, 0), Bt, ldb, bcol, t + 3);
;       BAR; WAIT_L(0); MMA(0, 1, At, B1); BAR;
;       LDA(At, 1, 1); STAGE(SA(1, 0), Ab, lda, brow, t + 3);
;       BAR; WAIT_L(0); MMA(1, 0, At, B0); BAR; SCHED;
	v_add_u32_e32 v164, s56, v153
	v_add_u32_e32 v165, 0x2000, v164
	v_readfirstlane_b32 s47, v164
	v_lshl_add_u64 v[166:167], v[238:239], 0, s[26:27]
	s_mov_b32 m0, s47
	v_readfirstlane_b32 s47, v165
	global_load_lds_dwordx4 v[166:167], off
	v_lshl_add_u64 v[166:167], v[240:241], 0, s[26:27]
	s_mov_b32 m0, s47
	s_nop 0
	global_load_lds_dwordx4 v[166:167], off
	s_waitcnt vmcnt(6)
	s_barrier
	v_mfma_f32_16x16x32_bf16 v[28:31], v[214:217], v[182:185], v[28:31]
	v_mfma_f32_16x16x32_bf16 v[24:27], v[222:225], v[182:185], v[24:27]
	v_mfma_f32_16x16x32_bf16 v[20:23], v[214:217], v[190:193], v[20:23]
	v_mfma_f32_16x16x32_bf16 v[16:19], v[222:225], v[190:193], v[16:19]
	v_mfma_f32_16x16x32_bf16 v[12:15], v[214:217], v[198:201], v[12:15]
	v_mfma_f32_16x16x32_bf16 v[8:11], v[222:225], v[198:201], v[8:11]
	v_mfma_f32_16x16x32_bf16 v[4:7], v[214:217], v[206:209], v[4:7]
	v_mfma_f32_16x16x32_bf16 v[0:3], v[222:225], v[206:209], v[0:3]
	v_mfma_f32_16x16x32_bf16 v[28:31], v[218:221], v[186:189], v[28:31]
	v_mfma_f32_16x16x32_bf16 v[24:27], v[226:229], v[186:189], v[24:27]
	v_mfma_f32_16x16x32_bf16 v[20:23], v[218:221], v[194:197], v[20:23]
	v_mfma_f32_16x16x32_bf16 v[16:19], v[226:229], v[194:197], v[16:19]
	v_mfma_f32_16x16x32_bf16 v[12:15], v[218:221], v[202:205], v[12:15]
	v_mfma_f32_16x16x32_bf16 v[8:11], v[226:229], v[202:205], v[8:11]
	v_mfma_f32_16x16x32_bf16 v[4:7], v[218:221], v[210:213], v[4:7]
	v_mfma_f32_16x16x32_bf16 v[0:3], v[226:229], v[210:213], v[0:3]
	s_barrier
	ds_read_b128 v[170:173], v154
	ds_read_b128 v[174:177], v154 offset:1024
	ds_read_b128 v[178:181], v154 offset:2048
	ds_read_b128 v[182:185], v154 offset:3072
	v_add_u32_e32 v166, 0x4000, v143
	v_add_u32_e32 v167, 0x6000, v143
	v_readfirstlane_b32 s47, v166
	v_lshl_add_u64 v[218:219], v[234:235], 0, s[34:35]
	s_mov_b32 m0, s47
	v_readfirstlane_b32 s47, v167
	ds_read_b128 v[186:189], v151 offset:32768
	ds_read_b128 v[190:193], v151 offset:33792
	ds_read_b128 v[194:197], v150 offset:32768
	ds_read_b128 v[198:201], v150 offset:33792
	ds_read_b128 v[202:205], v149 offset:32768
	ds_read_b128 v[206:209], v149 offset:33792
	ds_read_b128 v[210:213], v148 offset:32768
	ds_read_b128 v[214:217], v148 offset:33792
	global_load_lds_dwordx4 v[218:219], off
	v_lshl_add_u64 v[218:219], v[236:237], 0, s[34:35]
	s_mov_b32 m0, s47
	s_nop 0
	global_load_lds_dwordx4 v[218:219], off
	s_waitcnt lgkmcnt(8)
	s_barrier
	s_waitcnt lgkmcnt(0)
	v_mfma_f32_16x16x32_bf16 v[124:127], v[170:173], v[186:189], v[124:127]
	v_mfma_f32_16x16x32_bf16 v[120:123], v[178:181], v[186:189], v[120:123]
	v_mfma_f32_16x16x32_bf16 v[116:119], v[170:173], v[194:197], v[116:119]
	v_mfma_f32_16x16x32_bf16 v[112:115], v[178:181], v[194:197], v[112:115]
	v_mfma_f32_16x16x32_bf16 v[108:111], v[170:173], v[202:205], v[108:111]
	v_mfma_f32_16x16x32_bf16 v[104:107], v[178:181], v[202:205], v[104:107]
	v_mfma_f32_16x16x32_bf16 v[100:103], v[170:173], v[210:213], v[100:103]
	v_mfma_f32_16x16x32_bf16 v[96:99], v[178:181], v[210:213], v[96:99]
	v_mfma_f32_16x16x32_bf16 v[124:127], v[174:177], v[190:193], v[124:127]
	v_mfma_f32_16x16x32_bf16 v[120:123], v[182:185], v[190:193], v[120:123]
	v_mfma_f32_16x16x32_bf16 v[116:119], v[174:177], v[198:201], v[116:119]
	v_mfma_f32_16x16x32_bf16 v[112:115], v[182:185], v[198:201], v[112:115]
	v_mfma_f32_16x16x32_bf16 v[108:111], v[174:177], v[206:209], v[108:111]
	v_mfma_f32_16x16x32_bf16 v[104:107], v[182:185], v[206:209], v[104:107]
	v_mfma_f32_16x16x32_bf16 v[100:103], v[174:177], v[214:217], v[100:103]
	v_mfma_f32_16x16x32_bf16 v[96:99], v[182:185], v[214:217], v[96:99]
	s_barrier
	v_readfirstlane_b32 s47, v155
	v_add_u32_e32 v244, 0x2000, v155
	v_lshl_add_u64 v[242:243], v[238:239], 0, s[36:37]
	s_mov_b32 m0, s47
	v_readfirstlane_b32 s47, v244
	ds_read_b128 v[218:221], v152
	ds_read_b128 v[222:225], v152 offset:1024
	ds_read_b128 v[226:229], v152 offset:2048
	ds_read_b128 v[230:233], v152 offset:3072
	global_load_lds_dwordx4 v[242:243], off
	v_lshl_add_u64 v[242:243], v[240:241], 0, s[36:37]
	s_mov_b32 m0, s47
	s_nop 0
	global_load_lds_dwordx4 v[242:243], off
	s_barrier
	s_waitcnt lgkmcnt(0)
	v_mfma_f32_16x16x32_bf16 v[92:95], v[218:221], v[186:189], v[92:95]
	v_mfma_f32_16x16x32_bf16 v[88:91], v[226:229], v[186:189], v[88:91]
	v_mfma_f32_16x16x32_bf16 v[84:87], v[218:221], v[194:197], v[84:87]
	v_mfma_f32_16x16x32_bf16 v[80:83], v[226:229], v[194:197], v[80:83]
	v_mfma_f32_16x16x32_bf16 v[76:79], v[218:221], v[202:205], v[76:79]
	v_mfma_f32_16x16x32_bf16 v[72:75], v[226:229], v[202:205], v[72:75]
	v_mfma_f32_16x16x32_bf16 v[68:71], v[218:221], v[210:213], v[68:71]
	v_mfma_f32_16x16x32_bf16 v[64:67], v[226:229], v[210:213], v[64:67]
	v_mfma_f32_16x16x32_bf16 v[92:95], v[222:225], v[190:193], v[92:95]
	v_mfma_f32_16x16x32_bf16 v[88:91], v[230:233], v[190:193], v[88:91]
	v_mfma_f32_16x16x32_bf16 v[84:87], v[222:225], v[198:201], v[84:87]
	v_mfma_f32_16x16x32_bf16 v[80:83], v[230:233], v[198:201], v[80:83]
	v_mfma_f32_16x16x32_bf16 v[76:79], v[222:225], v[206:209], v[76:79]
	v_mfma_f32_16x16x32_bf16 v[72:75], v[230:233], v[206:209], v[72:75]
	v_mfma_f32_16x16x32_bf16 v[68:71], v[222:225], v[214:217], v[68:71]
	v_mfma_f32_16x16x32_bf16 v[64:67], v[230:233], v[214:217], v[64:67]
	v_readfirstlane_b32 s47, v156
	v_lshl_add_u64 v[234:235], v[234:235], 0, s[38:39]
	s_mov_b32 m0, s47
	v_readfirstlane_b32 s47, v157
	s_barrier
	ds_read_b128 v[186:189], v151 offset:49152
	ds_read_b128 v[190:193], v151 offset:50176
	ds_read_b128 v[194:197], v150 offset:49152
	ds_read_b128 v[198:201], v150 offset:50176
	ds_read_b128 v[202:205], v149 offset:49152
	ds_read_b128 v[206:209], v149 offset:50176
	ds_read_b128 v[210:213], v148 offset:49152
	ds_read_b128 v[214:217], v148 offset:50176
	global_load_lds_dwordx4 v[234:235], off
	v_lshl_add_u64 v[234:235], v[236:237], 0, s[38:39]
	s_mov_b32 m0, s47
	s_nop 0
	global_load_lds_dwordx4 v[234:235], off
	s_barrier
; #define STAGE(P, BASE, LD, br, kt) do { const char* _g = (const char*)((BASE) + (size_t)(br) * (LD) + (size_t)(kt) * 64); \
;     for (int _i = 0; _i < 2; ++_i) { int _b = tidx * 16 + _i * 8192; int _r, _c; stage_rc(_b, _r, _c); \
;       __builtin_amdgcn_global_load_lds((const unsigned*)(_g + (unsigned)((_r * (LD) + _c) * 2)), (unsigned*)((char*)(P) + _b), 16, 0, 0); } } while (0)
; #define LDA(dst, b, h) for (int m = 0; m < 4; ++m) for (int k = 0; k < 2; ++k) \
;     dst[m][k] = *reinterpret_cast<const bf16x8*>((char*)SA(b, h) + lds_byte(wr * 64 + m * 16 + fr, k * 32 + fq * 8))
; #define LDB(dst, b, h) for (int n = 0; n < 2; ++n) for (int k = 0; k < 2; ++k) \
;     dst[n][k] = *reinterpret_cast<const bf16x8*>((char*)SB(b, h) + lds_byte(wc * 32 + n * 16 + fr, k * 32 + fq * 8))
; #define MMA(ai, bj, At_, Bt_) do { __builtin_amdgcn_s_setprio(1); \
;     for (int k = 0; k < 2; ++k) for (int m = 0; m < 4; ++m) for (int n = 0; n < 2; ++n) \
;       acc[ai][bj][m][n] = __builtin_amdgcn_mfma_f32_16x16x32_bf16(At_[m][k], Bt_[n][k], acc[ai][bj][m][n], 0, 0, 0); \
;     __builtin_amdgcn_s_setprio(0); } while (0)
; #define WAIT_V(n) asm volatile("s_waitcnt vmcnt(" #n ")" ::: "memory")
; #define WAIT_L(n) asm volatile("s_waitcnt lgkmcnt(" #n ")" ::: "memory")
; #define BAR __builtin_amdgcn_s_barrier()
; #define SCHED __builtin_amdgcn_sched_barrier(0)
; template <int EPI, int lda, int ldb, int N, int K>
; __device__ __forceinline__ void gemm_phase(const u16* __restrict__ A, const u16* __restrict__ Bt, const GemmEpi ep, int wv) {
;     ...
;       BAR; WAIT_L(0); MMA(1, 0, At, B0); BAR; SCHED;
;       STAGE(SB(1, 1), Bt, ldb, bcol + HALF, t + 3);
;       WAIT_V(6); BAR; MMA(1, 1, At, B1); BAR;
;     }
;     { LDB(B0, 0, 0); LDA(At, 0, 0); STAGE(SA(1, 1), Ab, lda, brow + HALF, nt - 1);
;       BAR; WAIT_L(0); MMA(0, 0, At, B0); BAR;
	s_waitcnt lgkmcnt(0)
	v_mfma_f32_16x16x32_bf16 v[60:63], v[170:173], v[186:189], v[60:63]
	v_mfma_f32_16x16x32_bf16 v[56:59], v[178:181], v[186:189], v[56:59]
	v_mfma_f32_16x16x32_bf16 v[52:55], v[170:173], v[194:197], v[52:55]
	v_mfma_f32_16x16x32_bf16 v[48:51], v[178:181], v[194:197], v[48:51]
	v_mfma_f32_16x16x32_bf16 v[44:47], v[170:173], v[202:205], v[44:47]
	v_mfma_f32_16x16x32_bf16 v[40:43], v[178:181], v[202:205], v[40:43]
	v_mfma_f32_16x16x32_bf16 v[36:39], v[170:173], v[210:213], v[36:39]
	v_mfma_f32_16x16x32_bf16 v[32:35], v[178:181], v[210:213], v[32:35]
	v_mfma_f32_16x16x32_bf16 v[60:63], v[174:177], v[190:193], v[60:63]
	v_mfma_f32_16x16x32_bf16 v[56:59], v[182:185], v[190:193], v[56:59]
	v_mfma_f32_16x16x32_bf16 v[52:55], v[174:177], v[198:201], v[52:55]
	v_mfma_f32_16x16x32_bf16 v[48:51], v[182:185], v[198:201], v[48:51]
	v_mfma_f32_16x16x32_bf16 v[44:47], v[174:177], v[206:209], v[44:47]
	v_mfma_f32_16x16x32_bf16 v[40:43], v[182:185], v[206:209], v[40:43]
	v_mfma_f32_16x16x32_bf16 v[36:39], v[174:177], v[214:217], v[36:39]
	v_mfma_f32_16x16x32_bf16 v[32:35], v[182:185], v[214:217], v[32:35]
	s_barrier
	v_readfirstlane_b32 s47, v158
	v_add_u32_e32 v172, 0x2000, v158
	v_lshl_add_u64 v[170:171], v[238:239], 0, s[40:41]
	s_mov_b32 m0, s47
	v_readfirstlane_b32 s47, v172
	global_load_lds_dwordx4 v[170:171], off
	v_lshl_add_u64 v[170:171], v[240:241], 0, s[40:41]
	s_mov_b32 m0, s47
	s_nop 0
	global_load_lds_dwordx4 v[170:171], off
	s_waitcnt vmcnt(6)
	s_barrier
	v_mfma_f32_16x16x32_bf16 v[28:31], v[218:221], v[186:189], v[28:31]
	v_mfma_f32_16x16x32_bf16 v[24:27], v[226:229], v[186:189], v[24:27]
	v_mfma_f32_16x16x32_bf16 v[20:23], v[218:221], v[194:197], v[20:23]
	v_mfma_f32_16x16x32_bf16 v[16:19], v[226:229], v[194:197], v[16:19]
	v_mfma_f32_16x16x32_bf16 v[12:15], v[218:221], v[202:205], v[12:15]
	v_mfma_f32_16x16x32_bf16 v[8:11], v[226:229], v[202:205], v[8:11]
	v_mfma_f32_16x16x32_bf16 v[4:7], v[218:221], v[210:213], v[4:7]
	v_mfma_f32_16x16x32_bf16 v[0:3], v[226:229], v[210:213], v[0:3]
	v_mfma_f32_16x16x32_bf16 v[28:31], v[222:225], v[190:193], v[28:31]
	v_mfma_f32_16x16x32_bf16 v[24:27], v[230:233], v[190:193], v[24:27]
	v_mfma_f32_16x16x32_bf16 v[20:23], v[222:225], v[198:201], v[20:23]
	v_mfma_f32_16x16x32_bf16 v[16:19], v[230:233], v[198:201], v[16:19]
	v_mfma_f32_16x16x32_bf16 v[12:15], v[222:225], v[206:209], v[12:15]
	v_mfma_f32_16x16x32_bf16 v[8:11], v[230:233], v[206:209], v[8:11]
	v_mfma_f32_16x16x32_bf16 v[4:7], v[222:225], v[214:217], v[4:7]
	v_mfma_f32_16x16x32_bf16 v[0:3], v[230:233], v[214:217], v[0:3]
	s_add_i32 s46, s46, 2
	s_add_u32 s44, s44, 0x100
	s_addc_u32 s45, s45, 0
	s_cmp_gt_u32 s46, 27
	s_barrier
	s_cbranch_scc0 .LBB0_1448
	s_lshl_b64 s[44:45], s[16:17], 12
	s_add_u32 s44, s14, s44
	s_addc_u32 s45, s15, s45
	s_add_u32 s44, s44, 0x80000
	s_addc_u32 s45, s45, 0
	v_lshl_add_u64 v[156:157], s[44:45], 0, v[128:129]
	v_readfirstlane_b32 s46, v168
	v_lshl_add_u64 v[156:157], v[156:157], 0, s[42:43]
	s_mov_b32 m0, s46
	ds_read_b128 v[134:137], v160
	ds_read_b128 v[138:141], v160 offset:1024
	ds_read_b128 v[170:173], v160 offset:2048
	ds_read_b128 v[174:177], v160 offset:3072
	ds_read_b128 v[178:181], v151
	ds_read_b128 v[182:185], v151 offset:1024
	ds_read_b128 v[186:189], v150
	ds_read_b128 v[190:193], v150 offset:1024
	ds_read_b128 v[194:197], v149
	ds_read_b128 v[198:201], v149 offset:1024
	ds_read_b128 v[202:205], v148
	ds_read_b128 v[206:209], v148 offset:1024
	global_load_lds_dwordx4 v[156:157], off
	v_lshl_add_u64 v[156:157], s[44:45], 0, v[132:133]
	v_readfirstlane_b32 s44, v169
	v_lshl_add_u64 v[156:157], v[156:157], 0, s[42:43]
	s_mov_b32 m0, s44
	s_nop 0
	global_load_lds_dwordx4 v[156:157], off
	s_barrier
	s_waitcnt lgkmcnt(0)
	v_mfma_f32_16x16x32_bf16 v[124:127], v[134:137], v[178:181], v[124:127]
	v_mfma_f32_16x16x32_bf16 v[120:123], v[170:173], v[178:181], v[120:123]
	v_mfma_f32_16x16x32_bf16 v[116:119], v[134:137], v[186:189], v[116:119]
	v_mfma_f32_16x16x32_bf16 v[112:115], v[170:173], v[186:189], v[112:115]
	v_mfma_f32_16x16x32_bf16 v[108:111], v[134:137], v[194:197], v[108:111]
	v_mfma_f32_16x16x32_bf16 v[104:107], v[170:173], v[194:197], v[104:107]
	v_mfma_f32_16x16x32_bf16 v[100:103], v[134:137], v[202:205], v[100:103]
	v_mfma_f32_16x16x32_bf16 v[96:99], v[170:173], v[202:205], v[96:99]
	v_mfma_f32_16x16x32_bf16 v[124:127], v[138:141], v[182:185], v[124:127]
	v_mfma_f32_16x16x32_bf16 v[120:123], v[174:177], v[182:185], v[120:123]
	v_mfma_f32_16x16x32_bf16 v[116:119], v[138:141], v[190:193], v[116:119]
	v_mfma_f32_16x16x32_bf16 v[112:115], v[174:177], v[190:193], v[112:115]
	v_mfma_f32_16x16x32_bf16 v[108:111], v[138:141], v[198:201], v[108:111]
	v_mfma_f32_16x16x32_bf16 v[104:107], v[174:177], v[198:201], v[104:107]
	v_mfma_f32_16x16x32_bf16 v[100:103], v[138:141], v[206:209], v[100:103]
	v_mfma_f32_16x16x32_bf16 v[96:99], v[174:177], v[206:209], v[96:99]
	s_barrier
	ds_read_b128 v[210:213], v159
	ds_read_b128 v[214:217], v159 offset:1024
	ds_read_b128 v[218:221], v159 offset:2048
	ds_read_b128 v[156:159], v159 offset:3072
	s_barrier
; #define LDA(dst, b, h) for (int m = 0; m < 4; ++m) for (int k = 0; k < 2; ++k) \
;     dst[m][k] = *reinterpret_cast<const bf16x8*>((char*)SA(b, h) + lds_byte(wr * 64 + m * 16 + fr, k * 32 + fq * 8))
; #define LDB(dst, b, h) for (int n = 0; n < 2; ++n) for (int k = 0; k < 2; ++k) \
;     dst[n][k] = *reinterpret_cast<const bf16x8*>((char*)SB(b, h) + lds_byte(wc * 32 + n * 16 + fr, k * 32 + fq * 8))
; #define MMA(ai, bj, At_, Bt_) do { __builtin_amdgcn_s_setprio(1); \
;     for (int k = 0; k < 2; ++k) for (int m = 0; m < 4; ++m) for (int n = 0; n < 2; ++n) \
;       acc[ai][bj][m][n] = __builtin_amdgcn_mfma_f32_16x16x32_bf16(At_[m][k], Bt_[n][k], acc[ai][bj][m][n], 0, 0, 0); \
;     __builtin_amdgcn_s_setprio(0); } while (0)
; #define WAIT_V(n) asm volatile("s_waitcnt vmcnt(" #n ")" ::: "memory")
; #define WAIT_L(n) asm volatile("s_waitcnt lgkmcnt(" #n ")" ::: "memory")
; #define BAR __builtin_amdgcn_s_barrier()
; template <int EPI, int lda, int ldb, int N, int K>
; __device__ __forceinline__ void gemm_phase(const u16* __restrict__ A, const u16* __restrict__ Bt, const GemmEpi ep, int wv) {
;     ...
;       LDB(B1, 0, 1); BAR; WAIT_L(0); MMA(0, 1, At, B1); BAR;
;       LDA(At, 0, 1); WAIT_V(4); BAR; WAIT_L(0); MMA(1, 0, At, B0); MMA(1, 1, At, B1); BAR; }
;     { LDB(B0, 1, 0); LDA(At, 1, 0); WAIT_V(2); BAR; WAIT_L(0); MMA(0, 0, At, B0); BAR;
	s_waitcnt lgkmcnt(0)
	v_mfma_f32_16x16x32_bf16 v[92:95], v[210:213], v[178:181], v[92:95]
	v_mfma_f32_16x16x32_bf16 v[88:91], v[218:221], v[178:181], v[88:91]
	v_mfma_f32_16x16x32_bf16 v[76:79], v[210:213], v[194:197], v[76:79]
	v_mfma_f32_16x16x32_bf16 v[72:75], v[218:221], v[194:197], v[72:75]
	v_mfma_f32_16x16x32_bf16 v[84:87], v[210:213], v[186:189], v[84:87]
	v_mfma_f32_16x16x32_bf16 v[80:83], v[218:221], v[186:189], v[80:83]
	v_mfma_f32_16x16x32_bf16 v[68:71], v[210:213], v[202:205], v[68:71]
	v_mfma_f32_16x16x32_bf16 v[64:67], v[218:221], v[202:205], v[64:67]
	v_mfma_f32_16x16x32_bf16 v[92:95], v[214:217], v[182:185], v[92:95]
	v_mfma_f32_16x16x32_bf16 v[88:91], v[156:159], v[182:185], v[88:91]
	v_mfma_f32_16x16x32_bf16 v[76:79], v[214:217], v[198:201], v[76:79]
	v_mfma_f32_16x16x32_bf16 v[72:75], v[156:159], v[198:201], v[72:75]
	v_mfma_f32_16x16x32_bf16 v[178:181], v[214:217], v[190:193], v[84:87]
	v_mfma_f32_16x16x32_bf16 v[182:185], v[156:159], v[190:193], v[80:83]
	v_mfma_f32_16x16x32_bf16 v[186:189], v[214:217], v[206:209], v[68:71]
	v_mfma_f32_16x16x32_bf16 v[190:193], v[156:159], v[206:209], v[64:67]
	s_barrier
	s_nop 0
	ds_read_b128 v[64:67], v151 offset:16384
	ds_read_b128 v[68:71], v151 offset:17408
	ds_read_b128 v[80:83], v150 offset:16384
	ds_read_b128 v[84:87], v150 offset:17408
	ds_read_b128 v[194:197], v149 offset:16384
	ds_read_b128 v[198:201], v149 offset:17408
	ds_read_b128 v[202:205], v148 offset:16384
	ds_read_b128 v[206:209], v148 offset:17408
	s_waitcnt vmcnt(4)
	s_barrier
	s_waitcnt lgkmcnt(0)
	v_mfma_f32_16x16x32_bf16 v[60:63], v[134:137], v[64:67], v[60:63]
	v_mfma_f32_16x16x32_bf16 v[56:59], v[170:173], v[64:67], v[56:59]
	v_mfma_f32_16x16x32_bf16 v[52:55], v[134:137], v[80:83], v[52:55]
	v_mfma_f32_16x16x32_bf16 v[48:51], v[170:173], v[80:83], v[48:51]
	v_mfma_f32_16x16x32_bf16 v[44:47], v[134:137], v[194:197], v[44:47]
	v_mfma_f32_16x16x32_bf16 v[40:43], v[170:173], v[194:197], v[40:43]
	v_mfma_f32_16x16x32_bf16 v[36:39], v[134:137], v[202:205], v[36:39]
	v_mfma_f32_16x16x32_bf16 v[32:35], v[170:173], v[202:205], v[32:35]
	v_mfma_f32_16x16x32_bf16 v[60:63], v[138:141], v[68:71], v[60:63]
	v_mfma_f32_16x16x32_bf16 v[56:59], v[174:177], v[68:71], v[56:59]
	v_mfma_f32_16x16x32_bf16 v[52:55], v[138:141], v[84:87], v[52:55]
	v_mfma_f32_16x16x32_bf16 v[48:51], v[174:177], v[84:87], v[48:51]
	v_mfma_f32_16x16x32_bf16 v[44:47], v[138:141], v[198:201], v[44:47]
	v_mfma_f32_16x16x32_bf16 v[40:43], v[174:177], v[198:201], v[40:43]
	v_mfma_f32_16x16x32_bf16 v[36:39], v[138:141], v[206:209], v[36:39]
	v_mfma_f32_16x16x32_bf16 v[32:35], v[174:177], v[206:209], v[32:35]
	v_mfma_f32_16x16x32_bf16 v[28:31], v[210:213], v[64:67], v[28:31]
	v_mfma_f32_16x16x32_bf16 v[20:23], v[210:213], v[80:83], v[20:23]
	v_mfma_f32_16x16x32_bf16 v[12:15], v[210:213], v[194:197], v[12:15]
	v_mfma_f32_16x16x32_bf16 v[4:7], v[210:213], v[202:205], v[4:7]
	v_mfma_f32_16x16x32_bf16 v[24:27], v[218:221], v[64:67], v[24:27]
	v_mfma_f32_16x16x32_bf16 v[16:19], v[218:221], v[80:83], v[16:19]
	v_mfma_f32_16x16x32_bf16 v[8:11], v[218:221], v[194:197], v[8:11]
	v_mfma_f32_16x16x32_bf16 v[0:3], v[218:221], v[202:205], v[0:3]
	v_mfma_f32_16x16x32_bf16 v[28:31], v[214:217], v[68:71], v[28:31]
	v_mfma_f32_16x16x32_bf16 v[20:23], v[214:217], v[84:87], v[20:23]
	v_mfma_f32_16x16x32_bf16 v[12:15], v[214:217], v[198:201], v[12:15]
	v_mfma_f32_16x16x32_bf16 v[4:7], v[214:217], v[206:209], v[4:7]
	v_mfma_f32_16x16x32_bf16 v[134:137], v[156:159], v[68:71], v[24:27]
	v_mfma_f32_16x16x32_bf16 v[138:141], v[156:159], v[84:87], v[16:19]
	v_mfma_f32_16x16x32_bf16 v[168:171], v[156:159], v[198:201], v[8:11]
	v_mfma_f32_16x16x32_bf16 v[156:159], v[156:159], v[206:209], v[0:3]
	s_barrier
	s_nop 0
	ds_read_b128 v[0:3], v154
	ds_read_b128 v[8:11], v154 offset:1024
	ds_read_b128 v[16:19], v154 offset:2048
	ds_read_b128 v[172:175], v154 offset:3072
	ds_read_b128 v[24:27], v151 offset:32768
	ds_read_b128 v[194:197], v151 offset:33792
	ds_read_b128 v[198:201], v150 offset:32768
	ds_read_b128 v[202:205], v150 offset:33792
	ds_read_b128 v[206:209], v149 offset:32768
	ds_read_b128 v[210:213], v149 offset:33792
	ds_read_b128 v[214:217], v148 offset:32768
	ds_read_b128 v[218:221], v148 offset:33792
	s_waitcnt vmcnt(2)
	s_barrier
; #define LDA(dst, b, h) for (int m = 0; m < 4; ++m) for (int k = 0; k < 2; ++k) \
;     dst[m][k] = *reinterpret_cast<const bf16x8*>((char*)SA(b, h) + lds_byte(wr * 64 + m * 16 + fr, k * 32 + fq * 8))
; #define LDB(dst, b, h) for (int n = 0; n < 2; ++n) for (int k = 0; k < 2; ++k) \
;     dst[n][k] = *reinterpret_cast<const bf16x8*>((char*)SB(b, h) + lds_byte(wc * 32 + n * 16 + fr, k * 32 + fq * 8))
; #define MMA(ai, bj, At_, Bt_) do { __builtin_amdgcn_s_setprio(1); \
;     for (int k = 0; k < 2; ++k) for (int m = 0; m < 4; ++m) for (int n = 0; n < 2; ++n) \
;       acc[ai][bj][m][n] = __builtin_amdgcn_mfma_f32_16x16x32_bf16(At_[m][k], Bt_[n][k], acc[ai][bj][m][n], 0, 0, 0); \
;     __builtin_amdgcn_s_setprio(0); } while (0)
; #define WAIT_V(n) asm volatile("s_waitcnt vmcnt(" #n ")" ::: "memory")
; #define WAIT_L(n) asm volatile("s_waitcnt lgkmcnt(" #n ")" ::: "memory")
; #define BAR __builtin_amdgcn_s_barrier()
; template <int EPI, int lda, int ldb, int N, int K>
; __device__ __forceinline__ void gemm_phase(const u16* __restrict__ A, const u16* __restrict__ Bt, const GemmEpi ep, int wv) {
;     ...
;     { LDB(B0, 1, 0); LDA(At, 1, 0); WAIT_V(2); BAR; WAIT_L(0); MMA(0, 0, At, B0); BAR;
;       LDB(B1, 1, 1); WAIT_V(0); BAR; WAIT_L(0); MMA(0, 1, At, B1); BAR;
;       LDA(At, 1, 1); BAR; WAIT_L(0); MMA(1, 0, At, B0); MMA(1, 1, At, B1); BAR; }
;     if (wr == 0) BAR;
	s_waitcnt lgkmcnt(0)
	v_mfma_f32_16x16x32_bf16 v[64:67], v[0:3], v[24:27], v[124:127]
	v_mfma_f32_16x16x32_bf16 v[68:71], v[16:19], v[24:27], v[120:123]
	v_mfma_f32_16x16x32_bf16 v[80:83], v[0:3], v[198:201], v[116:119]
	v_mfma_f32_16x16x32_bf16 v[84:87], v[16:19], v[198:201], v[112:115]
	v_mfma_f32_16x16x32_bf16 v[108:111], v[0:3], v[206:209], v[108:111]
	v_mfma_f32_16x16x32_bf16 v[104:107], v[16:19], v[206:209], v[104:107]
	v_mfma_f32_16x16x32_bf16 v[120:123], v[0:3], v[214:217], v[100:103]
	v_mfma_f32_16x16x32_bf16 v[124:127], v[16:19], v[214:217], v[96:99]
	v_mfma_f32_16x16x32_bf16 v[116:119], v[8:11], v[194:197], v[64:67]
	v_mfma_f32_16x16x32_bf16 v[112:115], v[172:175], v[194:197], v[68:71]
	v_mfma_f32_16x16x32_bf16 v[100:103], v[8:11], v[202:205], v[80:83]
	v_mfma_f32_16x16x32_bf16 v[96:99], v[172:175], v[202:205], v[84:87]
	v_mfma_f32_16x16x32_bf16 v[84:87], v[8:11], v[210:213], v[108:111]
	v_mfma_f32_16x16x32_bf16 v[80:83], v[172:175], v[210:213], v[104:107]
	v_mfma_f32_16x16x32_bf16 v[68:71], v[8:11], v[218:221], v[120:123]
	v_mfma_f32_16x16x32_bf16 v[64:67], v[172:175], v[218:221], v[124:127]
	s_barrier
	ds_read_b128 v[222:225], v152
	ds_read_b128 v[226:229], v152 offset:1024
	ds_read_b128 v[230:233], v152 offset:2048
	ds_read_b128 v[152:155], v152 offset:3072
	s_waitcnt vmcnt(0)
	s_barrier
	s_waitcnt lgkmcnt(0)
	v_mfma_f32_16x16x32_bf16 v[92:95], v[222:225], v[24:27], v[92:95]
	v_mfma_f32_16x16x32_bf16 v[24:27], v[230:233], v[24:27], v[88:91]
	v_mfma_f32_16x16x32_bf16 v[88:91], v[222:225], v[198:201], v[178:181]
	v_mfma_f32_16x16x32_bf16 v[104:107], v[230:233], v[198:201], v[182:185]
	v_mfma_f32_16x16x32_bf16 v[76:79], v[222:225], v[206:209], v[76:79]
	v_mfma_f32_16x16x32_bf16 v[72:75], v[230:233], v[206:209], v[72:75]
	v_mfma_f32_16x16x32_bf16 v[176:179], v[222:225], v[214:217], v[186:189]
	v_mfma_f32_16x16x32_bf16 v[180:183], v[230:233], v[214:217], v[190:193]
	v_mfma_f32_16x16x32_bf16 v[124:127], v[226:229], v[194:197], v[92:95]
	v_mfma_f32_16x16x32_bf16 v[120:123], v[152:155], v[194:197], v[24:27]
	v_mfma_f32_16x16x32_bf16 v[108:111], v[226:229], v[202:205], v[88:91]
	v_mfma_f32_16x16x32_bf16 v[104:107], v[152:155], v[202:205], v[104:107]
	v_mfma_f32_16x16x32_bf16 v[92:95], v[226:229], v[210:213], v[76:79]
	v_mfma_f32_16x16x32_bf16 v[88:91], v[152:155], v[210:213], v[72:75]
	v_mfma_f32_16x16x32_bf16 v[76:79], v[226:229], v[218:221], v[176:179]
	v_mfma_f32_16x16x32_bf16 v[72:75], v[152:155], v[218:221], v[180:183]
	s_barrier
	ds_read_b128 v[176:179], v151 offset:49152
	ds_read_b128 v[180:183], v151 offset:50176
	ds_read_b128 v[184:187], v150 offset:49152
	ds_read_b128 v[188:191], v150 offset:50176
	ds_read_b128 v[192:195], v149 offset:49152
	ds_read_b128 v[196:199], v149 offset:50176
	ds_read_b128 v[200:203], v148 offset:49152
	ds_read_b128 v[148:151], v148 offset:50176
	s_barrier
	s_waitcnt lgkmcnt(0)
	v_mfma_f32_16x16x32_bf16 v[24:27], v[0:3], v[176:179], v[60:63]
	v_mfma_f32_16x16x32_bf16 v[60:63], v[16:19], v[176:179], v[56:59]
	v_mfma_f32_16x16x32_bf16 v[52:55], v[0:3], v[184:187], v[52:55]
	v_mfma_f32_16x16x32_bf16 v[204:207], v[16:19], v[184:187], v[48:51]
	v_mfma_f32_16x16x32_bf16 v[44:47], v[0:3], v[192:195], v[44:47]
	v_mfma_f32_16x16x32_bf16 v[208:211], v[16:19], v[192:195], v[40:43]
	v_mfma_f32_16x16x32_bf16 v[0:3], v[0:3], v[200:203], v[36:39]
	v_mfma_f32_16x16x32_bf16 v[36:39], v[16:19], v[200:203], v[32:35]
	v_mfma_f32_16x16x32_bf16 v[56:59], v[8:11], v[180:183], v[24:27]
	v_mfma_f32_16x16x32_bf16 v[48:51], v[172:175], v[180:183], v[60:63]
	v_mfma_f32_16x16x32_bf16 v[40:43], v[8:11], v[188:191], v[52:55]
	v_mfma_f32_16x16x32_bf16 v[32:35], v[172:175], v[188:191], v[204:207]
	v_mfma_f32_16x16x32_bf16 v[24:27], v[8:11], v[196:199], v[44:47]
	v_mfma_f32_16x16x32_bf16 v[16:19], v[172:175], v[196:199], v[208:211]
	v_mfma_f32_16x16x32_bf16 v[8:11], v[8:11], v[148:151], v[0:3]
	v_mfma_f32_16x16x32_bf16 v[0:3], v[172:175], v[148:151], v[36:39]
	v_mfma_f32_16x16x32_bf16 v[28:31], v[222:225], v[176:179], v[28:31]
	v_mfma_f32_16x16x32_bf16 v[36:39], v[230:233], v[176:179], v[134:137]
	v_mfma_f32_16x16x32_bf16 v[20:23], v[222:225], v[184:187], v[20:23]
	v_mfma_f32_16x16x32_bf16 v[134:137], v[230:233], v[184:187], v[138:141]
	v_mfma_f32_16x16x32_bf16 v[12:15], v[222:225], v[192:195], v[12:15]
	v_mfma_f32_16x16x32_bf16 v[138:141], v[230:233], v[192:195], v[168:171]
	v_mfma_f32_16x16x32_bf16 v[4:7], v[222:225], v[200:203], v[4:7]
	v_mfma_f32_16x16x32_bf16 v[156:159], v[230:233], v[200:203], v[156:159]
	v_mfma_f32_16x16x32_bf16 v[60:63], v[226:229], v[180:183], v[28:31]
	v_mfma_f32_16x16x32_bf16 v[52:55], v[152:155], v[180:183], v[36:39]
	v_mfma_f32_16x16x32_bf16 v[44:47], v[226:229], v[188:191], v[20:23]
	v_mfma_f32_16x16x32_bf16 v[36:39], v[152:155], v[188:191], v[134:137]
	v_mfma_f32_16x16x32_bf16 v[28:31], v[226:229], v[196:199], v[12:15]
	v_mfma_f32_16x16x32_bf16 v[20:23], v[152:155], v[196:199], v[138:141]
	v_mfma_f32_16x16x32_bf16 v[12:15], v[226:229], v[148:151], v[4:7]
	v_mfma_f32_16x16x32_bf16 v[4:7], v[152:155], v[148:151], v[156:159]
	v_cmp_gt_u32_e32 vcc, s60, v130
	s_barrier
	s_and_saveexec_b64 s[44:45], vcc
	s_cbranch_execz .LBB0_1451
	s_barrier

; #define STAGE(P, BASE, LD, br, kt) do { const char* _g = (const char*)((BASE) + (size_t)(br) * (LD) + (size_t)(kt) * 64); \
;     for (int _i = 0; _i < 2; ++_i) { int _b = tidx * 16 + _i * 8192; int _r, _c; stage_rc(_b, _r, _c); \
;       __builtin_amdgcn_global_load_lds((const unsigned*)(_g + (unsigned)((_r * (LD) + _c) * 2)), (unsigned*)((char*)(P) + _b), 16, 0, 0); } } while (0)
; #define LDA(dst, b, h) for (int m = 0; m < 4; ++m) for (int k = 0; k < 2; ++k) \
;     dst[m][k] = *reinterpret_cast<const bf16x8*>((char*)SA(b, h) + lds_byte(wr * 64 + m * 16 + fr, k * 32 + fq * 8))
; #define LDB(dst, b, h) for (int n = 0; n < 2; ++n) for (int k = 0; k < 2; ++k) \
;     dst[n][k] = *reinterpret_cast<const bf16x8*>((char*)SB(b, h) + lds_byte(wc * 32 + n * 16 + fr, k * 32 + fq * 8))
; #define MMA(ai, bj, At_, Bt_) do { __builtin_amdgcn_s_setprio(1); \
;     for (int k = 0; k < 2; ++k) for (int m = 0; m < 4; ++m) for (int n = 0; n < 2; ++n) \
;       acc[ai][bj][m][n] = __builtin_amdgcn_mfma_f32_16x16x32_bf16(At_[m][k], Bt_[n][k], acc[ai][bj][m][n], 0, 0, 0); \
;     __builtin_amdgcn_s_setprio(0); } while (0)
; #define WAIT_V(n) asm volatile("s_waitcnt vmcnt(" #n ")" ::: "memory")
; #define WAIT_L(n) asm volatile("s_waitcnt lgkmcnt(" #n ")" ::: "memory")
; #define BAR __builtin_amdgcn_s_barrier()
; #define SCHED __builtin_amdgcn_sched_barrier(0)
; template <int EPI, int lda, int ldb, int N, int K>
; __device__ __forceinline__ void gemm_phase(const u16* __restrict__ A, const u16* __restrict__ Bt, const GemmEpi ep, int wv) {
;     ...
;       LDB(B0, 0, 0); SCHED; LDA(At, 0, 0); STAGE(SA(1, 1), Ab, lda, brow + HALF, t + 1);
;       WAIT_L(8); BAR; WAIT_L(0); MMA(0, 0, At, B0); BAR; SCHED;
;       LDB(B1, 0, 1); STAGE(SB(0, 0), Bt, ldb, bcol, t + 2);
;       BAR; WAIT_L(0); MMA(0, 1, At, B1); BAR;
;       LDA(At, 0, 1); STAGE(SA(0, 0), Ab, lda, brow, t + 2);
;       BAR; WAIT_L(0); MMA(1, 0, At, B0); BAR; SCHED;
;       STAGE(SB(0, 1), Bt, ldb, bcol + HALF, t + 2);
;       WAIT_V(6); BAR; MMA(1, 1, At, B1); BAR;
;       LDB(B0, 1, 0); SCHED; LDA(At, 1, 0); STAGE(SA(0, 1), Ab, lda, brow + HALF, t + 2);
;       WAIT_L(8); BAR; WAIT_L(0); MMA(0, 0, At, B0); BAR; SCHED;
.LBB0_1564:
	ds_read_b128 v[172:175], v161
	ds_read_b128 v[176:179], v161 offset:1024
	ds_read_b128 v[180:183], v161 offset:2048
	ds_read_b128 v[184:187], v161 offset:3072
	v_add_u32_e32 v169, 0xc000, v148
	v_lshl_add_u64 v[236:237], v[136:137], 0, s[40:41]
	v_readfirstlane_b32 s43, v169
	v_add_u32_e32 v170, 0xe000, v148
	v_lshl_add_u64 v[162:163], v[236:237], 0, s[14:15]
	s_mov_b32 m0, s43
	v_lshl_add_u64 v[238:239], v[134:135], 0, s[40:41]
	v_readfirstlane_b32 s43, v170
	ds_read_b128 v[164:167], v152
	ds_read_b128 v[188:191], v152 offset:1024
	ds_read_b128 v[192:195], v151
	ds_read_b128 v[196:199], v151 offset:1024
	ds_read_b128 v[200:203], v150
	ds_read_b128 v[204:207], v150 offset:1024
	ds_read_b128 v[208:211], v149
	ds_read_b128 v[212:215], v149 offset:1024
	global_load_lds_dwordx4 v[162:163], off
	v_lshl_add_u64 v[162:163], v[238:239], 0, s[14:15]
	s_mov_b32 m0, s43
	s_nop 0
	global_load_lds_dwordx4 v[162:163], off
	s_waitcnt lgkmcnt(8)
	s_barrier
	s_waitcnt lgkmcnt(0)
	v_mfma_f32_16x16x32_bf16 v[124:127], v[172:175], v[164:167], v[124:127]
	v_mfma_f32_16x16x32_bf16 v[120:123], v[180:183], v[164:167], v[120:123]
	v_mfma_f32_16x16x32_bf16 v[116:119], v[172:175], v[192:195], v[116:119]
	v_mfma_f32_16x16x32_bf16 v[112:115], v[180:183], v[192:195], v[112:115]
	v_mfma_f32_16x16x32_bf16 v[108:111], v[172:175], v[200:203], v[108:111]
	v_mfma_f32_16x16x32_bf16 v[104:107], v[180:183], v[200:203], v[104:107]
	v_mfma_f32_16x16x32_bf16 v[100:103], v[172:175], v[208:211], v[100:103]
	v_mfma_f32_16x16x32_bf16 v[96:99], v[180:183], v[208:211], v[96:99]
	v_mfma_f32_16x16x32_bf16 v[124:127], v[176:179], v[188:191], v[124:127]
	v_mfma_f32_16x16x32_bf16 v[120:123], v[184:187], v[188:191], v[120:123]
	v_mfma_f32_16x16x32_bf16 v[116:119], v[176:179], v[196:199], v[116:119]
	v_mfma_f32_16x16x32_bf16 v[112:115], v[184:187], v[196:199], v[112:115]
	v_mfma_f32_16x16x32_bf16 v[108:111], v[176:179], v[204:207], v[108:111]
	v_mfma_f32_16x16x32_bf16 v[104:107], v[184:187], v[204:207], v[104:107]
	v_mfma_f32_16x16x32_bf16 v[100:103], v[176:179], v[212:215], v[100:103]
	v_mfma_f32_16x16x32_bf16 v[96:99], v[184:187], v[212:215], v[96:99]
	s_barrier
	v_add_u32_e32 v162, s52, v153
	v_lshl_add_u64 v[240:241], v[140:141], 0, s[40:41]
	v_readfirstlane_b32 s43, v162
	v_add_u32_e32 v163, 0x2000, v162
	v_lshl_add_u64 v[232:233], v[240:241], 0, s[16:17]
	s_mov_b32 m0, s43
	v_lshl_add_u64 v[242:243], v[138:139], 0, s[40:41]
	v_readfirstlane_b32 s43, v163
	ds_read_b128 v[216:219], v160
	ds_read_b128 v[220:223], v160 offset:1024
	ds_read_b128 v[224:227], v160 offset:2048
	ds_read_b128 v[228:231], v160 offset:3072
	global_load_lds_dwordx4 v[232:233], off
	v_lshl_add_u64 v[232:233], v[242:243], 0, s[16:17]
	s_mov_b32 m0, s43
	s_nop 0
	global_load_lds_dwordx4 v[232:233], off
	s_barrier
	s_waitcnt lgkmcnt(0)
	v_mfma_f32_16x16x32_bf16 v[92:95], v[216:219], v[164:167], v[92:95]
	v_mfma_f32_16x16x32_bf16 v[88:91], v[224:227], v[164:167], v[88:91]
	v_mfma_f32_16x16x32_bf16 v[84:87], v[216:219], v[192:195], v[84:87]
	v_mfma_f32_16x16x32_bf16 v[80:83], v[224:227], v[192:195], v[80:83]
	v_mfma_f32_16x16x32_bf16 v[76:79], v[216:219], v[200:203], v[76:79]
	v_mfma_f32_16x16x32_bf16 v[72:75], v[224:227], v[200:203], v[72:75]
	v_mfma_f32_16x16x32_bf16 v[68:71], v[216:219], v[208:211], v[68:71]
	v_mfma_f32_16x16x32_bf16 v[64:67], v[224:227], v[208:211], v[64:67]
	v_mfma_f32_16x16x32_bf16 v[92:95], v[220:223], v[188:191], v[92:95]
	v_mfma_f32_16x16x32_bf16 v[88:91], v[228:231], v[188:191], v[88:91]
	v_mfma_f32_16x16x32_bf16 v[84:87], v[220:223], v[196:199], v[84:87]
	v_mfma_f32_16x16x32_bf16 v[80:83], v[228:231], v[196:199], v[80:83]
	v_mfma_f32_16x16x32_bf16 v[76:79], v[220:223], v[204:207], v[76:79]
	v_mfma_f32_16x16x32_bf16 v[72:75], v[228:231], v[204:207], v[72:75]
	v_mfma_f32_16x16x32_bf16 v[68:71], v[220:223], v[212:215], v[68:71]
	v_mfma_f32_16x16x32_bf16 v[64:67], v[228:231], v[212:215], v[64:67]
	v_readfirstlane_b32 s43, v148
	v_lshl_add_u64 v[164:165], v[236:237], 0, s[18:19]
	s_mov_b32 m0, s43
	s_barrier
	ds_read_b128 v[188:191], v152 offset:16384
	ds_read_b128 v[192:195], v152 offset:17408
	ds_read_b128 v[196:199], v151 offset:16384
	ds_read_b128 v[200:203], v151 offset:17408
	ds_read_b128 v[204:207], v150 offset:16384
	ds_read_b128 v[208:211], v150 offset:17408
	ds_read_b128 v[212:215], v149 offset:16384
	ds_read_b128 v[232:235], v149 offset:17408
	global_load_lds_dwordx4 v[164:165], off
	v_add_u32_e32 v164, 0x2000, v148
	v_lshl_add_u64 v[166:167], v[238:239], 0, s[18:19]
	v_readfirstlane_b32 s43, v164
	s_mov_b32 m0, s43
	s_nop 0
	global_load_lds_dwordx4 v[166:167], off
	s_barrier
	s_waitcnt lgkmcnt(0)
	v_mfma_f32_16x16x32_bf16 v[60:63], v[172:175], v[188:191], v[60:63]
	v_mfma_f32_16x16x32_bf16 v[56:59], v[180:183], v[188:191], v[56:59]
	v_mfma_f32_16x16x32_bf16 v[52:55], v[172:175], v[196:199], v[52:55]
	v_mfma_f32_16x16x32_bf16 v[48:51], v[180:183], v[196:199], v[48:51]
	v_mfma_f32_16x16x32_bf16 v[44:47], v[172:175], v[204:207], v[44:47]
	v_mfma_f32_16x16x32_bf16 v[40:43], v[180:183], v[204:207], v[40:43]
	v_mfma_f32_16x16x32_bf16 v[36:39], v[172:175], v[212:215], v[36:39]
	v_mfma_f32_16x16x32_bf16 v[32:35], v[180:183], v[212:215], v[32:35]
	v_mfma_f32_16x16x32_bf16 v[60:63], v[176:179], v[192:195], v[60:63]
	v_mfma_f32_16x16x32_bf16 v[56:59], v[184:187], v[192:195], v[56:59]
	v_mfma_f32_16x16x32_bf16 v[52:55], v[176:179], v[200:203], v[52:55]
	v_mfma_f32_16x16x32_bf16 v[48:51], v[184:187], v[200:203], v[48:51]
	v_mfma_f32_16x16x32_bf16 v[44:47], v[176:179], v[208:211], v[44:47]
	v_mfma_f32_16x16x32_bf16 v[40:43], v[184:187], v[208:211], v[40:43]
	v_mfma_f32_16x16x32_bf16 v[36:39], v[176:179], v[232:235], v[36:39]
	v_mfma_f32_16x16x32_bf16 v[32:35], v[184:187], v[232:235], v[32:35]
	s_barrier
; #define STAGE(P, BASE, LD, br, kt) do { const char* _g = (const char*)((BASE) + (size_t)(br) * (LD) + (size_t)(kt) * 64); \
;     for (int _i = 0; _i < 2; ++_i) { int _b = tidx * 16 + _i * 8192; int _r, _c; stage_rc(_b, _r, _c); \
;       __builtin_amdgcn_global_load_lds((const unsigned*)(_g + (unsigned)((_r * (LD) + _c) * 2)), (unsigned*)((char*)(P) + _b), 16, 0, 0); } } while (0)
; #define LDA(dst, b, h) for (int m = 0; m < 4; ++m) for (int k = 0; k < 2; ++k) \
;     dst[m][k] = *reinterpret_cast<const bf16x8*>((char*)SA(b, h) + lds_byte(wr * 64 + m * 16 + fr, k * 32 + fq * 8))
; #define LDB(dst, b, h) for (int n = 0; n < 2; ++n) for (int k = 0; k < 2; ++k) \
;     dst[n][k] = *reinterpret_cast<const bf16x8*>((char*)SB(b, h) + lds_byte(wc * 32 + n * 16 + fr, k * 32 + fq * 8))
; #define MMA(ai, bj, At_, Bt_) do { __builtin_amdgcn_s_setprio(1); \
;     for (int k = 0; k < 2; ++k) for (int m = 0; m < 4; ++m) for (int n = 0; n < 2; ++n) \
;       acc[ai][bj][m][n] = __builtin_amdgcn_mfma_f32_16x16x32_bf16(At_[m][k], Bt_[n][k], acc[ai][bj][m][n], 0, 0, 0); \
;     __builtin_amdgcn_s_setprio(0); } while (0)
; #define WAIT_V(n) asm volatile("s_waitcnt vmcnt(" #n ")" ::: "memory")
; #define WAIT_L(n) asm volatile("s_waitcnt lgkmcnt(" #n ")" ::: "memory")
; #define BAR __builtin_amdgcn_s_barrier()
; #define SCHED __builtin_amdgcn_sched_barrier(0)
; template <int EPI, int lda, int ldb, int N, int K>
; __device__ __forceinline__ void gemm_phase(const u16* __restrict__ A, const u16* __restrict__ Bt, const GemmEpi ep, int wv) {
;     ...
;       WAIT_V(6); BAR; MMA(1, 1, At, B1); BAR;
;       LDB(B0, 1, 0); SCHED; LDA(At, 1, 0); STAGE(SA(0, 1), Ab, lda, brow + HALF, t + 2);
;       WAIT_L(8); BAR; WAIT_L(0); MMA(0, 0, At, B0); BAR; SCHED;
;       LDB(B1, 1, 1); STAGE(SB(1, 0), Bt, ldb, bcol, t + 3);
;       BAR; WAIT_L(0); MMA(0, 1, At, B1); BAR;
;       LDA(At, 1, 1); STAGE(SA(1, 0), Ab, lda, brow, t + 3);
;       BAR; WAIT_L(0); MMA(1, 0, At, B0); BAR; SCHED;
	v_add_u32_e32 v165, s53, v153
	v_lshl_add_u64 v[166:167], v[240:241], 0, s[20:21]
	v_readfirstlane_b32 s43, v165
	s_mov_b32 m0, s43
	v_lshl_add_u64 v[172:173], v[242:243], 0, s[20:21]
	global_load_lds_dwordx4 v[166:167], off
	v_add_u32_e32 v166, 0x2000, v165
	s_nop 0
	v_readfirstlane_b32 s43, v166
	s_mov_b32 m0, s43
	s_nop 0
	global_load_lds_dwordx4 v[172:173], off
	s_waitcnt vmcnt(6)
	s_barrier
	v_mfma_f32_16x16x32_bf16 v[28:31], v[216:219], v[188:191], v[28:31]
	v_mfma_f32_16x16x32_bf16 v[24:27], v[224:227], v[188:191], v[24:27]
	v_mfma_f32_16x16x32_bf16 v[20:23], v[216:219], v[196:199], v[20:23]
	v_mfma_f32_16x16x32_bf16 v[16:19], v[224:227], v[196:199], v[16:19]
	v_mfma_f32_16x16x32_bf16 v[12:15], v[216:219], v[204:207], v[12:15]
	v_mfma_f32_16x16x32_bf16 v[8:11], v[224:227], v[204:207], v[8:11]
	v_mfma_f32_16x16x32_bf16 v[4:7], v[216:219], v[212:215], v[4:7]
	v_mfma_f32_16x16x32_bf16 v[0:3], v[224:227], v[212:215], v[0:3]
	v_mfma_f32_16x16x32_bf16 v[28:31], v[220:223], v[192:195], v[28:31]
	v_mfma_f32_16x16x32_bf16 v[24:27], v[228:231], v[192:195], v[24:27]
	v_mfma_f32_16x16x32_bf16 v[20:23], v[220:223], v[200:203], v[20:23]
	v_mfma_f32_16x16x32_bf16 v[16:19], v[228:231], v[200:203], v[16:19]
	v_mfma_f32_16x16x32_bf16 v[12:15], v[220:223], v[208:211], v[12:15]
	v_mfma_f32_16x16x32_bf16 v[8:11], v[228:231], v[208:211], v[8:11]
	v_mfma_f32_16x16x32_bf16 v[4:7], v[220:223], v[232:235], v[4:7]
	v_mfma_f32_16x16x32_bf16 v[0:3], v[228:231], v[232:235], v[0:3]
	s_barrier
	ds_read_b128 v[172:175], v156
	ds_read_b128 v[176:179], v156 offset:1024
	ds_read_b128 v[180:183], v156 offset:2048
	ds_read_b128 v[184:187], v156 offset:3072
	v_add_u32_e32 v167, 0x4000, v148
	v_add_u32_e32 v168, 0x6000, v148
	v_readfirstlane_b32 s43, v167
	v_lshl_add_u64 v[220:221], v[236:237], 0, s[22:23]
	s_mov_b32 m0, s43
	v_readfirstlane_b32 s43, v168
	ds_read_b128 v[188:191], v152 offset:32768
	ds_read_b128 v[192:195], v152 offset:33792
	ds_read_b128 v[196:199], v151 offset:32768
	ds_read_b128 v[200:203], v151 offset:33792
	ds_read_b128 v[204:207], v150 offset:32768
	ds_read_b128 v[208:211], v150 offset:33792
	ds_read_b128 v[212:215], v149 offset:32768
	ds_read_b128 v[216:219], v149 offset:33792
	global_load_lds_dwordx4 v[220:221], off
	v_lshl_add_u64 v[220:221], v[238:239], 0, s[22:23]
	s_mov_b32 m0, s43
	s_nop 0
	global_load_lds_dwordx4 v[220:221], off
	s_waitcnt lgkmcnt(8)
	s_barrier
	s_waitcnt lgkmcnt(0)
	v_mfma_f32_16x16x32_bf16 v[124:127], v[172:175], v[188:191], v[124:127]
	v_mfma_f32_16x16x32_bf16 v[120:123], v[180:183], v[188:191], v[120:123]
	v_mfma_f32_16x16x32_bf16 v[116:119], v[172:175], v[196:199], v[116:119]
	v_mfma_f32_16x16x32_bf16 v[112:115], v[180:183], v[196:199], v[112:115]
	v_mfma_f32_16x16x32_bf16 v[108:111], v[172:175], v[204:207], v[108:111]
	v_mfma_f32_16x16x32_bf16 v[104:107], v[180:183], v[204:207], v[104:107]
	v_mfma_f32_16x16x32_bf16 v[100:103], v[172:175], v[212:215], v[100:103]
	v_mfma_f32_16x16x32_bf16 v[96:99], v[180:183], v[212:215], v[96:99]
	v_mfma_f32_16x16x32_bf16 v[124:127], v[176:179], v[192:195], v[124:127]
	v_mfma_f32_16x16x32_bf16 v[120:123], v[184:187], v[192:195], v[120:123]
	v_mfma_f32_16x16x32_bf16 v[116:119], v[176:179], v[200:203], v[116:119]
	v_mfma_f32_16x16x32_bf16 v[112:115], v[184:187], v[200:203], v[112:115]
	v_mfma_f32_16x16x32_bf16 v[108:111], v[176:179], v[208:211], v[108:111]
	v_mfma_f32_16x16x32_bf16 v[104:107], v[184:187], v[208:211], v[104:107]
	v_mfma_f32_16x16x32_bf16 v[100:103], v[176:179], v[216:219], v[100:103]
	v_mfma_f32_16x16x32_bf16 v[96:99], v[184:187], v[216:219], v[96:99]
	s_barrier
	v_readfirstlane_b32 s43, v155
	v_add_u32_e32 v171, 0x2000, v155
	v_lshl_add_u64 v[244:245], v[240:241], 0, s[24:25]
	s_mov_b32 m0, s43
	v_readfirstlane_b32 s43, v171
	ds_read_b128 v[220:223], v154
	ds_read_b128 v[224:227], v154 offset:1024
	ds_read_b128 v[228:231], v154 offset:2048
	ds_read_b128 v[232:235], v154 offset:3072
	global_load_lds_dwordx4 v[244:245], off
	v_lshl_add_u64 v[244:245], v[242:243], 0, s[24:25]
	s_mov_b32 m0, s43
	s_nop 0
	global_load_lds_dwordx4 v[244:245], off
	s_barrier
	s_waitcnt lgkmcnt(0)
	v_mfma_f32_16x16x32_bf16 v[92:95], v[220:223], v[188:191], v[92:95]
	v_mfma_f32_16x16x32_bf16 v[88:91], v[228:231], v[188:191], v[88:91]
	v_mfma_f32_16x16x32_bf16 v[84:87], v[220:223], v[196:199], v[84:87]
	v_mfma_f32_16x16x32_bf16 v[80:83], v[228:231], v[196:199], v[80:83]
	v_mfma_f32_16x16x32_bf16 v[76:79], v[220:223], v[204:207], v[76:79]
	v_mfma_f32_16x16x32_bf16 v[72:75], v[228:231], v[204:207], v[72:75]
	v_mfma_f32_16x16x32_bf16 v[68:71], v[220:223], v[212:215], v[68:71]
	v_mfma_f32_16x16x32_bf16 v[64:67], v[228:231], v[212:215], v[64:67]
	v_mfma_f32_16x16x32_bf16 v[92:95], v[224:227], v[192:195], v[92:95]
	v_mfma_f32_16x16x32_bf16 v[88:91], v[232:235], v[192:195], v[88:91]
	v_mfma_f32_16x16x32_bf16 v[84:87], v[224:227], v[200:203], v[84:87]
	v_mfma_f32_16x16x32_bf16 v[80:83], v[232:235], v[200:203], v[80:83]
	v_mfma_f32_16x16x32_bf16 v[76:79], v[224:227], v[208:211], v[76:79]
	v_mfma_f32_16x16x32_bf16 v[72:75], v[232:235], v[208:211], v[72:75]
	v_mfma_f32_16x16x32_bf16 v[68:71], v[224:227], v[216:219], v[68:71]
	v_mfma_f32_16x16x32_bf16 v[64:67], v[232:235], v[216:219], v[64:67]
	v_readfirstlane_b32 s43, v157
	v_lshl_add_u64 v[236:237], v[236:237], 0, s[26:27]
	s_mov_b32 m0, s43
	v_readfirstlane_b32 s43, v158
	s_barrier
	ds_read_b128 v[188:191], v152 offset:49152
	ds_read_b128 v[192:195], v152 offset:50176
	ds_read_b128 v[196:199], v151 offset:49152
	ds_read_b128 v[200:203], v151 offset:50176
	ds_read_b128 v[204:207], v150 offset:49152
	ds_read_b128 v[208:211], v150 offset:50176
	ds_read_b128 v[212:215], v149 offset:49152
	ds_read_b128 v[216:219], v149 offset:50176
	global_load_lds_dwordx4 v[236:237], off
	v_lshl_add_u64 v[236:237], v[238:239], 0, s[26:27]
	s_mov_b32 m0, s43
	s_nop 0
	global_load_lds_dwordx4 v[236:237], off
	s_barrier
; #define STAGE(P, BASE, LD, br, kt) do { const char* _g = (const char*)((BASE) + (size_t)(br) * (LD) + (size_t)(kt) * 64); \
;     for (int _i = 0; _i < 2; ++_i) { int _b = tidx * 16 + _i * 8192; int _r, _c; stage_rc(_b, _r, _c); \
;       __builtin_amdgcn_global_load_lds((const unsigned*)(_g + (unsigned)((_r * (LD) + _c) * 2)), (unsigned*)((char*)(P) + _b), 16, 0, 0); } } while (0)
; #define LDA(dst, b, h) for (int m = 0; m < 4; ++m) for (int k = 0; k < 2; ++k) \
;     dst[m][k] = *reinterpret_cast<const bf16x8*>((char*)SA(b, h) + lds_byte(wr * 64 + m * 16 + fr, k * 32 + fq * 8))
; #define LDB(dst, b, h) for (int n = 0; n < 2; ++n) for (int k = 0; k < 2; ++k) \
;     dst[n][k] = *reinterpret_cast<const bf16x8*>((char*)SB(b, h) + lds_byte(wc * 32 + n * 16 + fr, k * 32 + fq * 8))
; #define MMA(ai, bj, At_, Bt_) do { __builtin_amdgcn_s_setprio(1); \
;     for (int k = 0; k < 2; ++k) for (int m = 0; m < 4; ++m) for (int n = 0; n < 2; ++n) \
;       acc[ai][bj][m][n] = __builtin_amdgcn_mfma_f32_16x16x32_bf16(At_[m][k], Bt_[n][k], acc[ai][bj][m][n], 0, 0, 0); \
;     __builtin_amdgcn_s_setprio(0); } while (0)
; #define WAIT_V(n) asm volatile("s_waitcnt vmcnt(" #n ")" ::: "memory")
; #define WAIT_L(n) asm volatile("s_waitcnt lgkmcnt(" #n ")" ::: "memory")
; #define BAR __builtin_amdgcn_s_barrier()
; #define SCHED __builtin_amdgcn_sched_barrier(0)
; template <int EPI, int lda, int ldb, int N, int K>
; __device__ __forceinline__ void gemm_phase(const u16* __restrict__ A, const u16* __restrict__ Bt, const GemmEpi ep, int wv) {
;     ...
;       BAR; WAIT_L(0); MMA(1, 0, At, B0); BAR; SCHED;
;       STAGE(SB(1, 1), Bt, ldb, bcol + HALF, t + 3);
;       WAIT_V(6); BAR; MMA(1, 1, At, B1); BAR;
;     }
;     { LDB(B0, 0, 0); LDA(At, 0, 0); STAGE(SA(1, 1), Ab, lda, brow + HALF, nt - 1);
;       BAR; WAIT_L(0); MMA(0, 0, At, B0); BAR;
	s_waitcnt lgkmcnt(0)
	v_mfma_f32_16x16x32_bf16 v[60:63], v[172:175], v[188:191], v[60:63]
	v_mfma_f32_16x16x32_bf16 v[56:59], v[180:183], v[188:191], v[56:59]
	v_mfma_f32_16x16x32_bf16 v[52:55], v[172:175], v[196:199], v[52:55]
	v_mfma_f32_16x16x32_bf16 v[48:51], v[180:183], v[196:199], v[48:51]
	v_mfma_f32_16x16x32_bf16 v[44:47], v[172:175], v[204:207], v[44:47]
	v_mfma_f32_16x16x32_bf16 v[40:43], v[180:183], v[204:207], v[40:43]
	v_mfma_f32_16x16x32_bf16 v[36:39], v[172:175], v[212:215], v[36:39]
	v_mfma_f32_16x16x32_bf16 v[32:35], v[180:183], v[212:215], v[32:35]
	v_mfma_f32_16x16x32_bf16 v[60:63], v[176:179], v[192:195], v[60:63]
	v_mfma_f32_16x16x32_bf16 v[56:59], v[184:187], v[192:195], v[56:59]
	v_mfma_f32_16x16x32_bf16 v[52:55], v[176:179], v[200:203], v[52:55]
	v_mfma_f32_16x16x32_bf16 v[48:51], v[184:187], v[200:203], v[48:51]
	v_mfma_f32_16x16x32_bf16 v[44:47], v[176:179], v[208:211], v[44:47]
	v_mfma_f32_16x16x32_bf16 v[40:43], v[184:187], v[208:211], v[40:43]
	v_mfma_f32_16x16x32_bf16 v[36:39], v[176:179], v[216:219], v[36:39]
	v_mfma_f32_16x16x32_bf16 v[32:35], v[184:187], v[216:219], v[32:35]
	s_barrier
	v_readfirstlane_b32 s43, v159
	v_add_u32_e32 v171, 0x2000, v159
	v_lshl_add_u64 v[172:173], v[240:241], 0, s[34:35]
	s_mov_b32 m0, s43
	v_readfirstlane_b32 s43, v171
	global_load_lds_dwordx4 v[172:173], off
	v_lshl_add_u64 v[172:173], v[242:243], 0, s[34:35]
	s_mov_b32 m0, s43
	s_nop 0
	global_load_lds_dwordx4 v[172:173], off
	s_waitcnt vmcnt(6)
	s_barrier
	v_mfma_f32_16x16x32_bf16 v[28:31], v[220:223], v[188:191], v[28:31]
	v_mfma_f32_16x16x32_bf16 v[24:27], v[228:231], v[188:191], v[24:27]
	v_mfma_f32_16x16x32_bf16 v[20:23], v[220:223], v[196:199], v[20:23]
	v_mfma_f32_16x16x32_bf16 v[16:19], v[228:231], v[196:199], v[16:19]
	v_mfma_f32_16x16x32_bf16 v[12:15], v[220:223], v[204:207], v[12:15]
	v_mfma_f32_16x16x32_bf16 v[8:11], v[228:231], v[204:207], v[8:11]
	v_mfma_f32_16x16x32_bf16 v[4:7], v[220:223], v[212:215], v[4:7]
	v_mfma_f32_16x16x32_bf16 v[0:3], v[228:231], v[212:215], v[0:3]
	v_mfma_f32_16x16x32_bf16 v[28:31], v[224:227], v[192:195], v[28:31]
	v_mfma_f32_16x16x32_bf16 v[24:27], v[232:235], v[192:195], v[24:27]
	v_mfma_f32_16x16x32_bf16 v[20:23], v[224:227], v[200:203], v[20:23]
	v_mfma_f32_16x16x32_bf16 v[16:19], v[232:235], v[200:203], v[16:19]
	v_mfma_f32_16x16x32_bf16 v[12:15], v[224:227], v[208:211], v[12:15]
	v_mfma_f32_16x16x32_bf16 v[8:11], v[232:235], v[208:211], v[8:11]
	v_mfma_f32_16x16x32_bf16 v[4:7], v[224:227], v[216:219], v[4:7]
	v_mfma_f32_16x16x32_bf16 v[0:3], v[232:235], v[216:219], v[0:3]
	s_add_i32 s42, s42, 2
	s_add_u32 s40, s40, 0x100
	s_addc_u32 s41, s41, 0
	s_cmp_gt_u32 s42, 27
	s_barrier
	s_cbranch_scc0 .LBB0_1564
	s_add_i32 s40, s38, 0x80
	s_mul_hi_i32 s41, s40, 0x1080
	s_mulk_i32 s40, 0x1080
	s_add_u32 s40, s49, s40
	s_addc_u32 s41, s50, s41
	v_lshl_add_u64 v[158:159], s[40:41], 0, v[128:129]
	v_readfirstlane_b32 s42, v169
	v_lshl_add_u64 v[158:159], v[158:159], 0, s[36:37]
	s_mov_b32 m0, s42
	ds_read_b128 v[134:137], v161
	ds_read_b128 v[138:141], v161 offset:1024
	ds_read_b128 v[172:175], v161 offset:2048
	ds_read_b128 v[176:179], v161 offset:3072
	ds_read_b128 v[180:183], v152
	ds_read_b128 v[184:187], v152 offset:1024
	ds_read_b128 v[188:191], v151
	ds_read_b128 v[192:195], v151 offset:1024
	ds_read_b128 v[196:199], v150
	ds_read_b128 v[200:203], v150 offset:1024
	ds_read_b128 v[204:207], v149
	ds_read_b128 v[208:211], v149 offset:1024
	global_load_lds_dwordx4 v[158:159], off
	v_lshl_add_u64 v[158:159], s[40:41], 0, v[132:133]
	v_readfirstlane_b32 s40, v170
	v_lshl_add_u64 v[158:159], v[158:159], 0, s[36:37]
	s_mov_b32 m0, s40
	s_nop 0
	global_load_lds_dwordx4 v[158:159], off
	s_barrier
	s_waitcnt lgkmcnt(0)
	v_mfma_f32_16x16x32_bf16 v[124:127], v[134:137], v[180:183], v[124:127]
	v_mfma_f32_16x16x32_bf16 v[120:123], v[172:175], v[180:183], v[120:123]
	v_mfma_f32_16x16x32_bf16 v[116:119], v[134:137], v[188:191], v[116:119]
	v_mfma_f32_16x16x32_bf16 v[112:115], v[172:175], v[188:191], v[112:115]
	v_mfma_f32_16x16x32_bf16 v[108:111], v[134:137], v[196:199], v[108:111]
	v_mfma_f32_16x16x32_bf16 v[104:107], v[172:175], v[196:199], v[104:107]
	v_mfma_f32_16x16x32_bf16 v[100:103], v[134:137], v[204:207], v[100:103]
	v_mfma_f32_16x16x32_bf16 v[96:99], v[172:175], v[204:207], v[96:99]
	v_mfma_f32_16x16x32_bf16 v[124:127], v[138:141], v[184:187], v[124:127]
	v_mfma_f32_16x16x32_bf16 v[120:123], v[176:179], v[184:187], v[120:123]
	v_mfma_f32_16x16x32_bf16 v[116:119], v[138:141], v[192:195], v[116:119]
	v_mfma_f32_16x16x32_bf16 v[112:115], v[176:179], v[192:195], v[112:115]
	v_mfma_f32_16x16x32_bf16 v[108:111], v[138:141], v[200:203], v[108:111]
	v_mfma_f32_16x16x32_bf16 v[104:107], v[176:179], v[200:203], v[104:107]
	v_mfma_f32_16x16x32_bf16 v[100:103], v[138:141], v[208:211], v[100:103]
	v_mfma_f32_16x16x32_bf16 v[96:99], v[176:179], v[208:211], v[96:99]
	s_barrier
	ds_read_b128 v[212:215], v160
	ds_read_b128 v[216:219], v160 offset:1024
	ds_read_b128 v[220:223], v160 offset:2048
	ds_read_b128 v[158:161], v160 offset:3072
	s_barrier
; #define LDA(dst, b, h) for (int m = 0; m < 4; ++m) for (int k = 0; k < 2; ++k) \
;     dst[m][k] = *reinterpret_cast<const bf16x8*>((char*)SA(b, h) + lds_byte(wr * 64 + m * 16 + fr, k * 32 + fq * 8))
; #define LDB(dst, b, h) for (int n = 0; n < 2; ++n) for (int k = 0; k < 2; ++k) \
;     dst[n][k] = *reinterpret_cast<const bf16x8*>((char*)SB(b, h) + lds_byte(wc * 32 + n * 16 + fr, k * 32 + fq * 8))
; #define MMA(ai, bj, At_, Bt_) do { __builtin_amdgcn_s_setprio(1); \
;     for (int k = 0; k < 2; ++k) for (int m = 0; m < 4; ++m) for (int n = 0; n < 2; ++n) \
;       acc[ai][bj][m][n] = __builtin_amdgcn_mfma_f32_16x16x32_bf16(At_[m][k], Bt_[n][k], acc[ai][bj][m][n], 0, 0, 0); \
;     __builtin_amdgcn_s_setprio(0); } while (0)
; #define WAIT_V(n) asm volatile("s_waitcnt vmcnt(" #n ")" ::: "memory")
; #define WAIT_L(n) asm volatile("s_waitcnt lgkmcnt(" #n ")" ::: "memory")
; #define BAR __builtin_amdgcn_s_barrier()
; template <int EPI, int lda, int ldb, int N, int K>
; __device__ __forceinline__ void gemm_phase(const u16* __restrict__ A, const u16* __restrict__ Bt, const GemmEpi ep, int wv) {
;     ...
;       LDB(B1, 0, 1); BAR; WAIT_L(0); MMA(0, 1, At, B1); BAR;
;       LDA(At, 0, 1); WAIT_V(4); BAR; WAIT_L(0); MMA(1, 0, At, B0); MMA(1, 1, At, B1); BAR; }
;     { LDB(B0, 1, 0); LDA(At, 1, 0); WAIT_V(2); BAR; WAIT_L(0); MMA(0, 0, At, B0); BAR;
	s_waitcnt lgkmcnt(0)
	v_mfma_f32_16x16x32_bf16 v[92:95], v[212:215], v[180:183], v[92:95]
	v_mfma_f32_16x16x32_bf16 v[88:91], v[220:223], v[180:183], v[88:91]
	v_mfma_f32_16x16x32_bf16 v[76:79], v[212:215], v[196:199], v[76:79]
	v_mfma_f32_16x16x32_bf16 v[72:75], v[220:223], v[196:199], v[72:75]
	v_mfma_f32_16x16x32_bf16 v[84:87], v[212:215], v[188:191], v[84:87]
	v_mfma_f32_16x16x32_bf16 v[80:83], v[220:223], v[188:191], v[80:83]
	v_mfma_f32_16x16x32_bf16 v[68:71], v[212:215], v[204:207], v[68:71]
	v_mfma_f32_16x16x32_bf16 v[64:67], v[220:223], v[204:207], v[64:67]
	v_mfma_f32_16x16x32_bf16 v[92:95], v[216:219], v[184:187], v[92:95]
	v_mfma_f32_16x16x32_bf16 v[88:91], v[158:161], v[184:187], v[88:91]
	v_mfma_f32_16x16x32_bf16 v[76:79], v[216:219], v[200:203], v[76:79]
	v_mfma_f32_16x16x32_bf16 v[72:75], v[158:161], v[200:203], v[72:75]
	v_mfma_f32_16x16x32_bf16 v[180:183], v[216:219], v[192:195], v[84:87]
	v_mfma_f32_16x16x32_bf16 v[184:187], v[158:161], v[192:195], v[80:83]
	v_mfma_f32_16x16x32_bf16 v[188:191], v[216:219], v[208:211], v[68:71]
	v_mfma_f32_16x16x32_bf16 v[192:195], v[158:161], v[208:211], v[64:67]
	s_barrier
	s_nop 0
	ds_read_b128 v[64:67], v152 offset:16384
	ds_read_b128 v[68:71], v152 offset:17408
	ds_read_b128 v[80:83], v151 offset:16384
	ds_read_b128 v[84:87], v151 offset:17408
	ds_read_b128 v[196:199], v150 offset:16384
	ds_read_b128 v[200:203], v150 offset:17408
	ds_read_b128 v[204:207], v149 offset:16384
	ds_read_b128 v[208:211], v149 offset:17408
	s_waitcnt vmcnt(4)
	s_barrier
	s_waitcnt lgkmcnt(0)
	v_mfma_f32_16x16x32_bf16 v[60:63], v[134:137], v[64:67], v[60:63]
	v_mfma_f32_16x16x32_bf16 v[56:59], v[172:175], v[64:67], v[56:59]
	v_mfma_f32_16x16x32_bf16 v[52:55], v[134:137], v[80:83], v[52:55]
	v_mfma_f32_16x16x32_bf16 v[48:51], v[172:175], v[80:83], v[48:51]
	v_mfma_f32_16x16x32_bf16 v[44:47], v[134:137], v[196:199], v[44:47]
	v_mfma_f32_16x16x32_bf16 v[40:43], v[172:175], v[196:199], v[40:43]
	v_mfma_f32_16x16x32_bf16 v[36:39], v[134:137], v[204:207], v[36:39]
	v_mfma_f32_16x16x32_bf16 v[32:35], v[172:175], v[204:207], v[32:35]
	v_mfma_f32_16x16x32_bf16 v[60:63], v[138:141], v[68:71], v[60:63]
	v_mfma_f32_16x16x32_bf16 v[56:59], v[176:179], v[68:71], v[56:59]
	v_mfma_f32_16x16x32_bf16 v[52:55], v[138:141], v[84:87], v[52:55]
	v_mfma_f32_16x16x32_bf16 v[48:51], v[176:179], v[84:87], v[48:51]
	v_mfma_f32_16x16x32_bf16 v[44:47], v[138:141], v[200:203], v[44:47]
	v_mfma_f32_16x16x32_bf16 v[40:43], v[176:179], v[200:203], v[40:43]
	v_mfma_f32_16x16x32_bf16 v[36:39], v[138:141], v[208:211], v[36:39]
	v_mfma_f32_16x16x32_bf16 v[32:35], v[176:179], v[208:211], v[32:35]
	v_mfma_f32_16x16x32_bf16 v[28:31], v[212:215], v[64:67], v[28:31]
	v_mfma_f32_16x16x32_bf16 v[24:27], v[220:223], v[64:67], v[24:27]
	v_mfma_f32_16x16x32_bf16 v[12:15], v[212:215], v[196:199], v[12:15]
	v_mfma_f32_16x16x32_bf16 v[8:11], v[220:223], v[196:199], v[8:11]
	v_mfma_f32_16x16x32_bf16 v[20:23], v[212:215], v[80:83], v[20:23]
	v_mfma_f32_16x16x32_bf16 v[16:19], v[220:223], v[80:83], v[16:19]
	v_mfma_f32_16x16x32_bf16 v[4:7], v[212:215], v[204:207], v[4:7]
	v_mfma_f32_16x16x32_bf16 v[0:3], v[220:223], v[204:207], v[0:3]
	v_mfma_f32_16x16x32_bf16 v[28:31], v[216:219], v[68:71], v[28:31]
	v_mfma_f32_16x16x32_bf16 v[24:27], v[158:161], v[68:71], v[24:27]
	v_mfma_f32_16x16x32_bf16 v[12:15], v[216:219], v[200:203], v[12:15]
	v_mfma_f32_16x16x32_bf16 v[8:11], v[158:161], v[200:203], v[8:11]
	v_mfma_f32_16x16x32_bf16 v[134:137], v[216:219], v[84:87], v[20:23]
	v_mfma_f32_16x16x32_bf16 v[138:141], v[158:161], v[84:87], v[16:19]
	v_mfma_f32_16x16x32_bf16 v[170:173], v[216:219], v[208:211], v[4:7]
	v_mfma_f32_16x16x32_bf16 v[158:161], v[158:161], v[208:211], v[0:3]
	s_barrier
	s_nop 0
	ds_read_b128 v[0:3], v156
	ds_read_b128 v[4:7], v156 offset:1024
	ds_read_b128 v[16:19], v156 offset:2048
	ds_read_b128 v[174:177], v156 offset:3072
	ds_read_b128 v[20:23], v152 offset:32768
	ds_read_b128 v[196:199], v152 offset:33792
	ds_read_b128 v[200:203], v151 offset:32768
	ds_read_b128 v[204:207], v151 offset:33792
	ds_read_b128 v[208:211], v150 offset:32768
	ds_read_b128 v[212:215], v150 offset:33792
	ds_read_b128 v[216:219], v149 offset:32768
	ds_read_b128 v[220:223], v149 offset:33792
	s_waitcnt vmcnt(2)
	s_barrier
; #define LDA(dst, b, h) for (int m = 0; m < 4; ++m) for (int k = 0; k < 2; ++k) \
;     dst[m][k] = *reinterpret_cast<const bf16x8*>((char*)SA(b, h) + lds_byte(wr * 64 + m * 16 + fr, k * 32 + fq * 8))
; #define LDB(dst, b, h) for (int n = 0; n < 2; ++n) for (int k = 0; k < 2; ++k) \
;     dst[n][k] = *reinterpret_cast<const bf16x8*>((char*)SB(b, h) + lds_byte(wc * 32 + n * 16 + fr, k * 32 + fq * 8))
; #define MMA(ai, bj, At_, Bt_) do { __builtin_amdgcn_s_setprio(1); \
;     for (int k = 0; k < 2; ++k) for (int m = 0; m < 4; ++m) for (int n = 0; n < 2; ++n) \
;       acc[ai][bj][m][n] = __builtin_amdgcn_mfma_f32_16x16x32_bf16(At_[m][k], Bt_[n][k], acc[ai][bj][m][n], 0, 0, 0); \
;     __builtin_amdgcn_s_setprio(0); } while (0)
; #define WAIT_V(n) asm volatile("s_waitcnt vmcnt(" #n ")" ::: "memory")
; #define WAIT_L(n) asm volatile("s_waitcnt lgkmcnt(" #n ")" ::: "memory")
; #define BAR __builtin_amdgcn_s_barrier()
; template <int EPI, int lda, int ldb, int N, int K>
; __device__ __forceinline__ void gemm_phase(const u16* __restrict__ A, const u16* __restrict__ Bt, const GemmEpi ep, int wv) {
;     ...
;     { LDB(B0, 1, 0); LDA(At, 1, 0); WAIT_V(2); BAR; WAIT_L(0); MMA(0, 0, At, B0); BAR;
;       LDB(B1, 1, 1); WAIT_V(0); BAR; WAIT_L(0); MMA(0, 1, At, B1); BAR;
;       LDA(At, 1, 1); BAR; WAIT_L(0); MMA(1, 0, At, B0); MMA(1, 1, At, B1); BAR; }
;     if (wr == 0) BAR;
	s_waitcnt lgkmcnt(0)
	v_mfma_f32_16x16x32_bf16 v[64:67], v[0:3], v[20:23], v[124:127]
	v_mfma_f32_16x16x32_bf16 v[68:71], v[16:19], v[20:23], v[120:123]
	v_mfma_f32_16x16x32_bf16 v[80:83], v[0:3], v[200:203], v[116:119]
	v_mfma_f32_16x16x32_bf16 v[84:87], v[16:19], v[200:203], v[112:115]
	v_mfma_f32_16x16x32_bf16 v[108:111], v[0:3], v[208:211], v[108:111]
	v_mfma_f32_16x16x32_bf16 v[104:107], v[16:19], v[208:211], v[104:107]
	v_mfma_f32_16x16x32_bf16 v[120:123], v[0:3], v[216:219], v[100:103]
	v_mfma_f32_16x16x32_bf16 v[124:127], v[16:19], v[216:219], v[96:99]
	v_mfma_f32_16x16x32_bf16 v[116:119], v[4:7], v[196:199], v[64:67]
	v_mfma_f32_16x16x32_bf16 v[112:115], v[174:177], v[196:199], v[68:71]
	v_mfma_f32_16x16x32_bf16 v[100:103], v[4:7], v[204:207], v[80:83]
	v_mfma_f32_16x16x32_bf16 v[96:99], v[174:177], v[204:207], v[84:87]
	v_mfma_f32_16x16x32_bf16 v[84:87], v[4:7], v[212:215], v[108:111]
	v_mfma_f32_16x16x32_bf16 v[80:83], v[174:177], v[212:215], v[104:107]
	v_mfma_f32_16x16x32_bf16 v[68:71], v[4:7], v[220:223], v[120:123]
	v_mfma_f32_16x16x32_bf16 v[64:67], v[174:177], v[220:223], v[124:127]
	s_barrier
	ds_read_b128 v[224:227], v154
	ds_read_b128 v[228:231], v154 offset:1024
	ds_read_b128 v[232:235], v154 offset:2048
	ds_read_b128 v[154:157], v154 offset:3072
	s_waitcnt vmcnt(0)
	s_barrier
	s_waitcnt lgkmcnt(0)
	v_mfma_f32_16x16x32_bf16 v[92:95], v[224:227], v[20:23], v[92:95]
	v_mfma_f32_16x16x32_bf16 v[20:23], v[232:235], v[20:23], v[88:91]
	v_mfma_f32_16x16x32_bf16 v[88:91], v[224:227], v[200:203], v[180:183]
	v_mfma_f32_16x16x32_bf16 v[104:107], v[232:235], v[200:203], v[184:187]
	v_mfma_f32_16x16x32_bf16 v[76:79], v[224:227], v[208:211], v[76:79]
	v_mfma_f32_16x16x32_bf16 v[72:75], v[232:235], v[208:211], v[72:75]
	v_mfma_f32_16x16x32_bf16 v[178:181], v[224:227], v[216:219], v[188:191]
	v_mfma_f32_16x16x32_bf16 v[182:185], v[232:235], v[216:219], v[192:195]
	v_mfma_f32_16x16x32_bf16 v[124:127], v[228:231], v[196:199], v[92:95]
	v_mfma_f32_16x16x32_bf16 v[120:123], v[154:157], v[196:199], v[20:23]
	v_mfma_f32_16x16x32_bf16 v[108:111], v[228:231], v[204:207], v[88:91]
	v_mfma_f32_16x16x32_bf16 v[104:107], v[154:157], v[204:207], v[104:107]
	v_mfma_f32_16x16x32_bf16 v[92:95], v[228:231], v[212:215], v[76:79]
	v_mfma_f32_16x16x32_bf16 v[88:91], v[154:157], v[212:215], v[72:75]
	v_mfma_f32_16x16x32_bf16 v[76:79], v[228:231], v[220:223], v[178:181]
	v_mfma_f32_16x16x32_bf16 v[72:75], v[154:157], v[220:223], v[182:185]
	s_barrier
	ds_read_b128 v[178:181], v152 offset:49152
	ds_read_b128 v[182:185], v152 offset:50176
	ds_read_b128 v[186:189], v151 offset:49152
	ds_read_b128 v[190:193], v151 offset:50176
	ds_read_b128 v[194:197], v150 offset:49152
	ds_read_b128 v[150:153], v150 offset:50176
	ds_read_b128 v[198:201], v149 offset:49152
	ds_read_b128 v[202:205], v149 offset:50176
	s_barrier
	s_waitcnt lgkmcnt(0)
	v_mfma_f32_16x16x32_bf16 v[20:23], v[0:3], v[178:181], v[60:63]
	v_mfma_f32_16x16x32_bf16 v[56:59], v[16:19], v[178:181], v[56:59]
	v_mfma_f32_16x16x32_bf16 v[60:63], v[0:3], v[186:189], v[52:55]
	v_mfma_f32_16x16x32_bf16 v[206:209], v[16:19], v[186:189], v[48:51]
	v_mfma_f32_16x16x32_bf16 v[44:47], v[0:3], v[194:197], v[44:47]
	v_mfma_f32_16x16x32_bf16 v[40:43], v[16:19], v[194:197], v[40:43]
	v_mfma_f32_16x16x32_bf16 v[0:3], v[0:3], v[198:201], v[36:39]
	v_mfma_f32_16x16x32_bf16 v[210:213], v[16:19], v[198:201], v[32:35]
	v_mfma_f32_16x16x32_bf16 v[52:55], v[4:7], v[182:185], v[20:23]
	v_mfma_f32_16x16x32_bf16 v[48:51], v[174:177], v[182:185], v[56:59]
	v_mfma_f32_16x16x32_bf16 v[36:39], v[4:7], v[190:193], v[60:63]
	v_mfma_f32_16x16x32_bf16 v[32:35], v[174:177], v[190:193], v[206:209]
	v_mfma_f32_16x16x32_bf16 v[20:23], v[4:7], v[150:153], v[44:47]
	v_mfma_f32_16x16x32_bf16 v[16:19], v[174:177], v[150:153], v[40:43]
	v_mfma_f32_16x16x32_bf16 v[4:7], v[4:7], v[202:205], v[0:3]
	v_mfma_f32_16x16x32_bf16 v[0:3], v[174:177], v[202:205], v[210:213]
	v_mfma_f32_16x16x32_bf16 v[28:31], v[224:227], v[178:181], v[28:31]
	v_mfma_f32_16x16x32_bf16 v[24:27], v[232:235], v[178:181], v[24:27]
	v_mfma_f32_16x16x32_bf16 v[40:43], v[224:227], v[186:189], v[134:137]
	v_mfma_f32_16x16x32_bf16 v[134:137], v[232:235], v[186:189], v[138:141]
	v_mfma_f32_16x16x32_bf16 v[12:15], v[224:227], v[194:197], v[12:15]
	v_mfma_f32_16x16x32_bf16 v[8:11], v[232:235], v[194:197], v[8:11]
	v_mfma_f32_16x16x32_bf16 v[138:141], v[224:227], v[198:201], v[170:173]
	v_mfma_f32_16x16x32_bf16 v[158:161], v[232:235], v[198:201], v[158:161]
	v_mfma_f32_16x16x32_bf16 v[60:63], v[228:231], v[182:185], v[28:31]
	v_mfma_f32_16x16x32_bf16 v[56:59], v[154:157], v[182:185], v[24:27]
	v_mfma_f32_16x16x32_bf16 v[44:47], v[228:231], v[190:193], v[40:43]
	v_mfma_f32_16x16x32_bf16 v[40:43], v[154:157], v[190:193], v[134:137]
	v_mfma_f32_16x16x32_bf16 v[28:31], v[228:231], v[150:153], v[12:15]
	v_mfma_f32_16x16x32_bf16 v[24:27], v[154:157], v[150:153], v[8:11]
	v_mfma_f32_16x16x32_bf16 v[12:15], v[228:231], v[202:205], v[138:141]
	v_mfma_f32_16x16x32_bf16 v[8:11], v[154:157], v[202:205], v[158:161]
	v_cmp_gt_u32_e32 vcc, s54, v130
	s_barrier
	s_and_saveexec_b64 s[40:41], vcc
	s_cbranch_execz .LBB0_1567
	s_barrier

; #define STAGE(P, BASE, LD, br, kt) do { const char* _g = (const char*)((BASE) + (size_t)(br) * (LD) + (size_t)(kt) * 64); \
;     for (int _i = 0; _i < 2; ++_i) { int _b = tidx * 16 + _i * 8192; int _r, _c; stage_rc(_b, _r, _c); \
;       __builtin_amdgcn_global_load_lds((const unsigned*)(_g + (unsigned)((_r * (LD) + _c) * 2)), (unsigned*)((char*)(P) + _b), 16, 0, 0); } } while (0)
; #define LDA(dst, b, h) for (int m = 0; m < 4; ++m) for (int k = 0; k < 2; ++k) \
;     dst[m][k] = *reinterpret_cast<const bf16x8*>((char*)SA(b, h) + lds_byte(wr * 64 + m * 16 + fr, k * 32 + fq * 8))
; #define LDB(dst, b, h) for (int n = 0; n < 2; ++n) for (int k = 0; k < 2; ++k) \
;     dst[n][k] = *reinterpret_cast<const bf16x8*>((char*)SB(b, h) + lds_byte(wc * 32 + n * 16 + fr, k * 32 + fq * 8))
; #define MMA(ai, bj, At_, Bt_) do { __builtin_amdgcn_s_setprio(1); \
;     for (int k = 0; k < 2; ++k) for (int m = 0; m < 4; ++m) for (int n = 0; n < 2; ++n) \
;       acc[ai][bj][m][n] = __builtin_amdgcn_mfma_f32_16x16x32_bf16(At_[m][k], Bt_[n][k], acc[ai][bj][m][n], 0, 0, 0); \
;     __builtin_amdgcn_s_setprio(0); } while (0)
; #define WAIT_V(n) asm volatile("s_waitcnt vmcnt(" #n ")" ::: "memory")
; #define WAIT_L(n) asm volatile("s_waitcnt lgkmcnt(" #n ")" ::: "memory")
; #define BAR __builtin_amdgcn_s_barrier()
; #define SCHED __builtin_amdgcn_sched_barrier(0)
; template <int EPI, int lda, int ldb, int N, int K>
; __device__ __forceinline__ void gemm_phase(const u16* __restrict__ A, const u16* __restrict__ Bt, const GemmEpi ep, int wv) {
;     ...
;       LDB(B0, 0, 0); SCHED; LDA(At, 0, 0); STAGE(SA(1, 1), Ab, lda, brow + HALF, t + 1);
;       WAIT_L(8); BAR; WAIT_L(0); MMA(0, 0, At, B0); BAR; SCHED;
;       LDB(B1, 0, 1); STAGE(SB(0, 0), Bt, ldb, bcol, t + 2);
;       BAR; WAIT_L(0); MMA(0, 1, At, B1); BAR;
;       LDA(At, 0, 1); STAGE(SA(0, 0), Ab, lda, brow, t + 2);
;       BAR; WAIT_L(0); MMA(1, 0, At, B0); BAR; SCHED;
;       STAGE(SB(0, 1), Bt, ldb, bcol + HALF, t + 2);
;       WAIT_V(6); BAR; MMA(1, 1, At, B1); BAR;
;       LDB(B0, 1, 0); SCHED; LDA(At, 1, 0); STAGE(SA(0, 1), Ab, lda, brow + HALF, t + 2);
;       WAIT_L(8); BAR; WAIT_L(0); MMA(0, 0, At, B0); BAR; SCHED;
.LBB0_1624:
	ds_read_b128 v[174:177], v163
	ds_read_b128 v[178:181], v163 offset:1024
	ds_read_b128 v[182:185], v163 offset:2048
	ds_read_b128 v[186:189], v163 offset:3072
	v_add_u32_e32 v171, 0xc000, v149
	v_lshl_add_u64 v[238:239], v[134:135], 0, s[28:29]
	v_readfirstlane_b32 s50, v171
	v_add_u32_e32 v172, 0xe000, v149
	v_lshl_add_u64 v[164:165], v[238:239], 0, s[10:11]
	s_mov_b32 m0, s50
	v_lshl_add_u64 v[240:241], v[132:133], 0, s[28:29]
	v_readfirstlane_b32 s50, v172
	ds_read_b128 v[166:169], v154
	ds_read_b128 v[190:193], v154 offset:1024
	ds_read_b128 v[194:197], v153
	ds_read_b128 v[198:201], v153 offset:1024
	ds_read_b128 v[202:205], v151
	ds_read_b128 v[206:209], v151 offset:1024
	ds_read_b128 v[210:213], v150
	ds_read_b128 v[214:217], v150 offset:1024
	global_load_lds_dwordx4 v[164:165], off
	v_lshl_add_u64 v[164:165], v[240:241], 0, s[10:11]
	s_mov_b32 m0, s50
	s_nop 0
	global_load_lds_dwordx4 v[164:165], off
	s_waitcnt lgkmcnt(8)
	s_barrier
	s_waitcnt lgkmcnt(0)
	v_mfma_f32_16x16x32_bf16 v[124:127], v[166:169], v[174:177], v[124:127]
	v_mfma_f32_16x16x32_bf16 v[120:123], v[166:169], v[182:185], v[120:123]
	v_mfma_f32_16x16x32_bf16 v[116:119], v[194:197], v[174:177], v[116:119]
	v_mfma_f32_16x16x32_bf16 v[112:115], v[194:197], v[182:185], v[112:115]
	v_mfma_f32_16x16x32_bf16 v[108:111], v[202:205], v[174:177], v[108:111]
	v_mfma_f32_16x16x32_bf16 v[104:107], v[202:205], v[182:185], v[104:107]
	v_mfma_f32_16x16x32_bf16 v[100:103], v[210:213], v[174:177], v[100:103]
	v_mfma_f32_16x16x32_bf16 v[96:99], v[210:213], v[182:185], v[96:99]
	v_mfma_f32_16x16x32_bf16 v[124:127], v[190:193], v[178:181], v[124:127]
	v_mfma_f32_16x16x32_bf16 v[120:123], v[190:193], v[186:189], v[120:123]
	v_mfma_f32_16x16x32_bf16 v[116:119], v[198:201], v[178:181], v[116:119]
	v_mfma_f32_16x16x32_bf16 v[112:115], v[198:201], v[186:189], v[112:115]
	v_mfma_f32_16x16x32_bf16 v[108:111], v[206:209], v[178:181], v[108:111]
	v_mfma_f32_16x16x32_bf16 v[104:107], v[206:209], v[186:189], v[104:107]
	v_mfma_f32_16x16x32_bf16 v[100:103], v[214:217], v[178:181], v[100:103]
	v_mfma_f32_16x16x32_bf16 v[96:99], v[214:217], v[186:189], v[96:99]
	s_barrier
	v_add_u32_e32 v164, s40, v155
	v_lshl_add_u64 v[242:243], v[142:143], 0, s[28:29]
	v_readfirstlane_b32 s50, v164
	v_add_u32_e32 v165, 0x2000, v164
	v_lshl_add_u64 v[234:235], v[242:243], 0, s[12:13]
	s_mov_b32 m0, s50
	v_lshl_add_u64 v[244:245], v[140:141], 0, s[28:29]
	v_readfirstlane_b32 s50, v165
	ds_read_b128 v[218:221], v162
	ds_read_b128 v[222:225], v162 offset:1024
	ds_read_b128 v[226:229], v162 offset:2048
	ds_read_b128 v[230:233], v162 offset:3072
	global_load_lds_dwordx4 v[234:235], off
	v_lshl_add_u64 v[234:235], v[244:245], 0, s[12:13]
	s_mov_b32 m0, s50
	s_nop 0
	global_load_lds_dwordx4 v[234:235], off
	s_barrier
	s_waitcnt lgkmcnt(0)
	v_mfma_f32_16x16x32_bf16 v[92:95], v[166:169], v[218:221], v[92:95]
	v_mfma_f32_16x16x32_bf16 v[88:91], v[166:169], v[226:229], v[88:91]
	v_mfma_f32_16x16x32_bf16 v[84:87], v[194:197], v[218:221], v[84:87]
	v_mfma_f32_16x16x32_bf16 v[80:83], v[194:197], v[226:229], v[80:83]
	v_mfma_f32_16x16x32_bf16 v[76:79], v[202:205], v[218:221], v[76:79]
	v_mfma_f32_16x16x32_bf16 v[72:75], v[202:205], v[226:229], v[72:75]
	v_mfma_f32_16x16x32_bf16 v[68:71], v[210:213], v[218:221], v[68:71]
	v_mfma_f32_16x16x32_bf16 v[64:67], v[210:213], v[226:229], v[64:67]
	v_mfma_f32_16x16x32_bf16 v[92:95], v[190:193], v[222:225], v[92:95]
	v_mfma_f32_16x16x32_bf16 v[88:91], v[190:193], v[230:233], v[88:91]
	v_mfma_f32_16x16x32_bf16 v[84:87], v[198:201], v[222:225], v[84:87]
	v_mfma_f32_16x16x32_bf16 v[80:83], v[198:201], v[230:233], v[80:83]
	v_mfma_f32_16x16x32_bf16 v[76:79], v[206:209], v[222:225], v[76:79]
	v_mfma_f32_16x16x32_bf16 v[72:75], v[206:209], v[230:233], v[72:75]
	v_mfma_f32_16x16x32_bf16 v[68:71], v[214:217], v[222:225], v[68:71]
	v_mfma_f32_16x16x32_bf16 v[64:67], v[214:217], v[230:233], v[64:67]
	v_readfirstlane_b32 s50, v149
	v_lshl_add_u64 v[166:167], v[238:239], 0, s[14:15]
	s_mov_b32 m0, s50
	s_barrier
	ds_read_b128 v[190:193], v154 offset:16384
	ds_read_b128 v[194:197], v154 offset:17408
	ds_read_b128 v[198:201], v153 offset:16384
	ds_read_b128 v[202:205], v153 offset:17408
	ds_read_b128 v[206:209], v151 offset:16384
	ds_read_b128 v[210:213], v151 offset:17408
	ds_read_b128 v[214:217], v150 offset:16384
	ds_read_b128 v[234:237], v150 offset:17408
	global_load_lds_dwordx4 v[166:167], off
	v_add_u32_e32 v166, 0x2000, v149
	v_lshl_add_u64 v[168:169], v[240:241], 0, s[14:15]
	v_readfirstlane_b32 s50, v166
	s_mov_b32 m0, s50
	s_nop 0
	global_load_lds_dwordx4 v[168:169], off
	s_barrier
	s_waitcnt lgkmcnt(0)
	v_mfma_f32_16x16x32_bf16 v[60:63], v[190:193], v[174:177], v[60:63]
	v_mfma_f32_16x16x32_bf16 v[56:59], v[190:193], v[182:185], v[56:59]
	v_mfma_f32_16x16x32_bf16 v[52:55], v[198:201], v[174:177], v[52:55]
	v_mfma_f32_16x16x32_bf16 v[48:51], v[198:201], v[182:185], v[48:51]
	v_mfma_f32_16x16x32_bf16 v[44:47], v[206:209], v[174:177], v[44:47]
	v_mfma_f32_16x16x32_bf16 v[40:43], v[206:209], v[182:185], v[40:43]
	v_mfma_f32_16x16x32_bf16 v[36:39], v[214:217], v[174:177], v[36:39]
	v_mfma_f32_16x16x32_bf16 v[32:35], v[214:217], v[182:185], v[32:35]
	v_mfma_f32_16x16x32_bf16 v[60:63], v[194:197], v[178:181], v[60:63]
	v_mfma_f32_16x16x32_bf16 v[56:59], v[194:197], v[186:189], v[56:59]
	v_mfma_f32_16x16x32_bf16 v[52:55], v[202:205], v[178:181], v[52:55]
	v_mfma_f32_16x16x32_bf16 v[48:51], v[202:205], v[186:189], v[48:51]
	v_mfma_f32_16x16x32_bf16 v[44:47], v[210:213], v[178:181], v[44:47]
	v_mfma_f32_16x16x32_bf16 v[40:43], v[210:213], v[186:189], v[40:43]
	v_mfma_f32_16x16x32_bf16 v[36:39], v[234:237], v[178:181], v[36:39]
	v_mfma_f32_16x16x32_bf16 v[32:35], v[234:237], v[186:189], v[32:35]
	s_barrier
; #define STAGE(P, BASE, LD, br, kt) do { const char* _g = (const char*)((BASE) + (size_t)(br) * (LD) + (size_t)(kt) * 64); \
;     for (int _i = 0; _i < 2; ++_i) { int _b = tidx * 16 + _i * 8192; int _r, _c; stage_rc(_b, _r, _c); \
;       __builtin_amdgcn_global_load_lds((const unsigned*)(_g + (unsigned)((_r * (LD) + _c) * 2)), (unsigned*)((char*)(P) + _b), 16, 0, 0); } } while (0)
; #define LDA(dst, b, h) for (int m = 0; m < 4; ++m) for (int k = 0; k < 2; ++k) \
;     dst[m][k] = *reinterpret_cast<const bf16x8*>((char*)SA(b, h) + lds_byte(wr * 64 + m * 16 + fr, k * 32 + fq * 8))
; #define LDB(dst, b, h) for (int n = 0; n < 2; ++n) for (int k = 0; k < 2; ++k) \
;     dst[n][k] = *reinterpret_cast<const bf16x8*>((char*)SB(b, h) + lds_byte(wc * 32 + n * 16 + fr, k * 32 + fq * 8))
; #define MMA(ai, bj, At_, Bt_) do { __builtin_amdgcn_s_setprio(1); \
;     for (int k = 0; k < 2; ++k) for (int m = 0; m < 4; ++m) for (int n = 0; n < 2; ++n) \
;       acc[ai][bj][m][n] = __builtin_amdgcn_mfma_f32_16x16x32_bf16(At_[m][k], Bt_[n][k], acc[ai][bj][m][n], 0, 0, 0); \
;     __builtin_amdgcn_s_setprio(0); } while (0)
; #define WAIT_V(n) asm volatile("s_waitcnt vmcnt(" #n ")" ::: "memory")
; #define WAIT_L(n) asm volatile("s_waitcnt lgkmcnt(" #n ")" ::: "memory")
; #define BAR __builtin_amdgcn_s_barrier()
; #define SCHED __builtin_amdgcn_sched_barrier(0)
; template <int EPI, int lda, int ldb, int N, int K>
; __device__ __forceinline__ void gemm_phase(const u16* __restrict__ A, const u16* __restrict__ Bt, const GemmEpi ep, int wv) {
;     ...
;       WAIT_V(6); BAR; MMA(1, 1, At, B1); BAR;
;       LDB(B0, 1, 0); SCHED; LDA(At, 1, 0); STAGE(SA(0, 1), Ab, lda, brow + HALF, t + 2);
;       WAIT_L(8); BAR; WAIT_L(0); MMA(0, 0, At, B0); BAR; SCHED;
;       LDB(B1, 1, 1); STAGE(SB(1, 0), Bt, ldb, bcol, t + 3);
;       BAR; WAIT_L(0); MMA(0, 1, At, B1); BAR;
;       LDA(At, 1, 1); STAGE(SA(1, 0), Ab, lda, brow, t + 3);
;       BAR; WAIT_L(0); MMA(1, 0, At, B0); BAR; SCHED;
	v_add_u32_e32 v167, s41, v155
	v_lshl_add_u64 v[246:247], v[138:139], 0, s[28:29]
	v_readfirstlane_b32 s50, v167
	v_lshl_add_u64 v[168:169], v[246:247], 0, s[16:17]
	s_mov_b32 m0, s50
	v_lshl_add_u64 v[248:249], v[136:137], 0, s[28:29]
	global_load_lds_dwordx4 v[168:169], off
	v_add_u32_e32 v168, 0x2000, v167
	v_lshl_add_u64 v[174:175], v[248:249], 0, s[16:17]
	v_readfirstlane_b32 s50, v168
	s_mov_b32 m0, s50
	s_nop 0
	global_load_lds_dwordx4 v[174:175], off
	s_waitcnt vmcnt(6)
	s_barrier
	v_mfma_f32_16x16x32_bf16 v[28:31], v[190:193], v[218:221], v[28:31]
	v_mfma_f32_16x16x32_bf16 v[24:27], v[190:193], v[226:229], v[24:27]
	v_mfma_f32_16x16x32_bf16 v[20:23], v[198:201], v[218:221], v[20:23]
	v_mfma_f32_16x16x32_bf16 v[16:19], v[198:201], v[226:229], v[16:19]
	v_mfma_f32_16x16x32_bf16 v[12:15], v[206:209], v[218:221], v[12:15]
	v_mfma_f32_16x16x32_bf16 v[8:11], v[206:209], v[226:229], v[8:11]
	v_mfma_f32_16x16x32_bf16 v[4:7], v[214:217], v[218:221], v[4:7]
	v_mfma_f32_16x16x32_bf16 v[0:3], v[214:217], v[226:229], v[0:3]
	v_mfma_f32_16x16x32_bf16 v[28:31], v[194:197], v[222:225], v[28:31]
	v_mfma_f32_16x16x32_bf16 v[24:27], v[194:197], v[230:233], v[24:27]
	v_mfma_f32_16x16x32_bf16 v[20:23], v[202:205], v[222:225], v[20:23]
	v_mfma_f32_16x16x32_bf16 v[16:19], v[202:205], v[230:233], v[16:19]
	v_mfma_f32_16x16x32_bf16 v[12:15], v[210:213], v[222:225], v[12:15]
	v_mfma_f32_16x16x32_bf16 v[8:11], v[210:213], v[230:233], v[8:11]
	v_mfma_f32_16x16x32_bf16 v[4:7], v[234:237], v[222:225], v[4:7]
	v_mfma_f32_16x16x32_bf16 v[0:3], v[234:237], v[230:233], v[0:3]
	s_barrier
	ds_read_b128 v[174:177], v158
	ds_read_b128 v[178:181], v158 offset:1024
	ds_read_b128 v[182:185], v158 offset:2048
	ds_read_b128 v[186:189], v158 offset:3072
	v_add_u32_e32 v169, 0x4000, v149
	v_add_u32_e32 v170, 0x6000, v149
	v_readfirstlane_b32 s50, v169
	v_lshl_add_u64 v[222:223], v[238:239], 0, s[18:19]
	s_mov_b32 m0, s50
	v_readfirstlane_b32 s50, v170
	ds_read_b128 v[190:193], v154 offset:32768
	ds_read_b128 v[194:197], v154 offset:33792
	ds_read_b128 v[198:201], v153 offset:32768
	ds_read_b128 v[202:205], v153 offset:33792
	ds_read_b128 v[206:209], v151 offset:32768
	ds_read_b128 v[210:213], v151 offset:33792
	ds_read_b128 v[214:217], v150 offset:32768
	ds_read_b128 v[218:221], v150 offset:33792
	global_load_lds_dwordx4 v[222:223], off
	v_lshl_add_u64 v[222:223], v[240:241], 0, s[18:19]
	s_mov_b32 m0, s50
	s_nop 0
	global_load_lds_dwordx4 v[222:223], off
	s_waitcnt lgkmcnt(8)
	s_barrier
	s_waitcnt lgkmcnt(0)
	v_mfma_f32_16x16x32_bf16 v[124:127], v[190:193], v[174:177], v[124:127]
	v_mfma_f32_16x16x32_bf16 v[120:123], v[190:193], v[182:185], v[120:123]
	v_mfma_f32_16x16x32_bf16 v[116:119], v[198:201], v[174:177], v[116:119]
	v_mfma_f32_16x16x32_bf16 v[112:115], v[198:201], v[182:185], v[112:115]
	v_mfma_f32_16x16x32_bf16 v[108:111], v[206:209], v[174:177], v[108:111]
	v_mfma_f32_16x16x32_bf16 v[104:107], v[206:209], v[182:185], v[104:107]
	v_mfma_f32_16x16x32_bf16 v[100:103], v[214:217], v[174:177], v[100:103]
	v_mfma_f32_16x16x32_bf16 v[96:99], v[214:217], v[182:185], v[96:99]
	v_mfma_f32_16x16x32_bf16 v[124:127], v[194:197], v[178:181], v[124:127]
	v_mfma_f32_16x16x32_bf16 v[120:123], v[194:197], v[186:189], v[120:123]
	v_mfma_f32_16x16x32_bf16 v[116:119], v[202:205], v[178:181], v[116:119]
	v_mfma_f32_16x16x32_bf16 v[112:115], v[202:205], v[186:189], v[112:115]
	v_mfma_f32_16x16x32_bf16 v[108:111], v[210:213], v[178:181], v[108:111]
	v_mfma_f32_16x16x32_bf16 v[104:107], v[210:213], v[186:189], v[104:107]
	v_mfma_f32_16x16x32_bf16 v[100:103], v[218:221], v[178:181], v[100:103]
	v_mfma_f32_16x16x32_bf16 v[96:99], v[218:221], v[186:189], v[96:99]
	s_barrier
	v_readfirstlane_b32 s50, v157
	v_add_u32_e32 v173, 0x2000, v157
	v_lshl_add_u64 v[242:243], v[242:243], 0, s[20:21]
	s_mov_b32 m0, s50
	v_readfirstlane_b32 s50, v173
	ds_read_b128 v[222:225], v156
	ds_read_b128 v[226:229], v156 offset:1024
	ds_read_b128 v[230:233], v156 offset:2048
	ds_read_b128 v[234:237], v156 offset:3072
	global_load_lds_dwordx4 v[242:243], off
	v_lshl_add_u64 v[242:243], v[244:245], 0, s[20:21]
	s_mov_b32 m0, s50
	s_nop 0
	global_load_lds_dwordx4 v[242:243], off
	s_barrier
	s_waitcnt lgkmcnt(0)
	v_mfma_f32_16x16x32_bf16 v[92:95], v[190:193], v[222:225], v[92:95]
	v_mfma_f32_16x16x32_bf16 v[88:91], v[190:193], v[230:233], v[88:91]
	v_mfma_f32_16x16x32_bf16 v[84:87], v[198:201], v[222:225], v[84:87]
	v_mfma_f32_16x16x32_bf16 v[80:83], v[198:201], v[230:233], v[80:83]
	v_mfma_f32_16x16x32_bf16 v[76:79], v[206:209], v[222:225], v[76:79]
	v_mfma_f32_16x16x32_bf16 v[72:75], v[206:209], v[230:233], v[72:75]
	v_mfma_f32_16x16x32_bf16 v[68:71], v[214:217], v[222:225], v[68:71]
	v_mfma_f32_16x16x32_bf16 v[64:67], v[214:217], v[230:233], v[64:67]
	v_mfma_f32_16x16x32_bf16 v[92:95], v[194:197], v[226:229], v[92:95]
	v_mfma_f32_16x16x32_bf16 v[88:91], v[194:197], v[234:237], v[88:91]
	v_mfma_f32_16x16x32_bf16 v[84:87], v[202:205], v[226:229], v[84:87]
	v_mfma_f32_16x16x32_bf16 v[80:83], v[202:205], v[234:237], v[80:83]
	v_mfma_f32_16x16x32_bf16 v[76:79], v[210:213], v[226:229], v[76:79]
	v_mfma_f32_16x16x32_bf16 v[72:75], v[210:213], v[234:237], v[72:75]
	v_mfma_f32_16x16x32_bf16 v[68:71], v[218:221], v[226:229], v[68:71]
	v_mfma_f32_16x16x32_bf16 v[64:67], v[218:221], v[234:237], v[64:67]
	v_readfirstlane_b32 s50, v159
	v_lshl_add_u64 v[238:239], v[238:239], 0, s[22:23]
	s_mov_b32 m0, s50
	v_readfirstlane_b32 s50, v160
	s_barrier
; #define STAGE(P, BASE, LD, br, kt) do { const char* _g = (const char*)((BASE) + (size_t)(br) * (LD) + (size_t)(kt) * 64); \
;     for (int _i = 0; _i < 2; ++_i) { int _b = tidx * 16 + _i * 8192; int _r, _c; stage_rc(_b, _r, _c); \
;       __builtin_amdgcn_global_load_lds((const unsigned*)(_g + (unsigned)((_r * (LD) + _c) * 2)), (unsigned*)((char*)(P) + _b), 16, 0, 0); } } while (0)
; #define LDA(dst, b, h) for (int m = 0; m < 4; ++m) for (int k = 0; k < 2; ++k) \
;     dst[m][k] = *reinterpret_cast<const bf16x8*>((char*)SA(b, h) + lds_byte(wr * 64 + m * 16 + fr, k * 32 + fq * 8))
; #define LDB(dst, b, h) for (int n = 0; n < 2; ++n) for (int k = 0; k < 2; ++k) \
;     dst[n][k] = *reinterpret_cast<const bf16x8*>((char*)SB(b, h) + lds_byte(wc * 32 + n * 16 + fr, k * 32 + fq * 8))
; #define MMA(ai, bj, At_, Bt_) do { __builtin_amdgcn_s_setprio(1); \
;     for (int k = 0; k < 2; ++k) for (int m = 0; m < 4; ++m) for (int n = 0; n < 2; ++n) \
;       acc[ai][bj][m][n] = __builtin_amdgcn_mfma_f32_16x16x32_bf16(At_[m][k], Bt_[n][k], acc[ai][bj][m][n], 0, 0, 0); \
;     __builtin_amdgcn_s_setprio(0); } while (0)
; #define WAIT_V(n) asm volatile("s_waitcnt vmcnt(" #n ")" ::: "memory")
; #define WAIT_L(n) asm volatile("s_waitcnt lgkmcnt(" #n ")" ::: "memory")
; #define BAR __builtin_amdgcn_s_barrier()
; #define SCHED __builtin_amdgcn_sched_barrier(0)
; template <int EPI, int lda, int ldb, int N, int K>
; __device__ __forceinline__ void gemm_phase(const u16* __restrict__ A, const u16* __restrict__ Bt, const GemmEpi ep, int wv) {
;     ...
;       LDA(At, 1, 1); STAGE(SA(1, 0), Ab, lda, brow, t + 3);
;       BAR; WAIT_L(0); MMA(1, 0, At, B0); BAR; SCHED;
;       STAGE(SB(1, 1), Bt, ldb, bcol + HALF, t + 3);
;       WAIT_V(6); BAR; MMA(1, 1, At, B1); BAR;
;     }
;     { LDB(B0, 0, 0); LDA(At, 0, 0); STAGE(SA(1, 1), Ab, lda, brow + HALF, nt - 1);
;       BAR; WAIT_L(0); MMA(0, 0, At, B0); BAR;
	ds_read_b128 v[190:193], v154 offset:49152
	ds_read_b128 v[194:197], v154 offset:50176
	ds_read_b128 v[198:201], v153 offset:49152
	ds_read_b128 v[202:205], v153 offset:50176
	ds_read_b128 v[206:209], v151 offset:49152
	ds_read_b128 v[210:213], v151 offset:50176
	ds_read_b128 v[214:217], v150 offset:49152
	ds_read_b128 v[218:221], v150 offset:50176
	global_load_lds_dwordx4 v[238:239], off
	v_lshl_add_u64 v[238:239], v[240:241], 0, s[22:23]
	s_mov_b32 m0, s50
	s_nop 0
	global_load_lds_dwordx4 v[238:239], off
	s_barrier
	s_waitcnt lgkmcnt(0)
	v_mfma_f32_16x16x32_bf16 v[60:63], v[190:193], v[174:177], v[60:63]
	v_mfma_f32_16x16x32_bf16 v[56:59], v[190:193], v[182:185], v[56:59]
	v_mfma_f32_16x16x32_bf16 v[52:55], v[198:201], v[174:177], v[52:55]
	v_mfma_f32_16x16x32_bf16 v[48:51], v[198:201], v[182:185], v[48:51]
	v_mfma_f32_16x16x32_bf16 v[44:47], v[206:209], v[174:177], v[44:47]
	v_mfma_f32_16x16x32_bf16 v[40:43], v[206:209], v[182:185], v[40:43]
	v_mfma_f32_16x16x32_bf16 v[36:39], v[214:217], v[174:177], v[36:39]
	v_mfma_f32_16x16x32_bf16 v[32:35], v[214:217], v[182:185], v[32:35]
	v_mfma_f32_16x16x32_bf16 v[60:63], v[194:197], v[178:181], v[60:63]
	v_mfma_f32_16x16x32_bf16 v[56:59], v[194:197], v[186:189], v[56:59]
	v_mfma_f32_16x16x32_bf16 v[52:55], v[202:205], v[178:181], v[52:55]
	v_mfma_f32_16x16x32_bf16 v[48:51], v[202:205], v[186:189], v[48:51]
	v_mfma_f32_16x16x32_bf16 v[44:47], v[210:213], v[178:181], v[44:47]
	v_mfma_f32_16x16x32_bf16 v[40:43], v[210:213], v[186:189], v[40:43]
	v_mfma_f32_16x16x32_bf16 v[36:39], v[218:221], v[178:181], v[36:39]
	v_mfma_f32_16x16x32_bf16 v[32:35], v[218:221], v[186:189], v[32:35]
	s_barrier
	v_readfirstlane_b32 s50, v161
	v_add_u32_e32 v173, 0x2000, v161
	v_lshl_add_u64 v[174:175], v[246:247], 0, s[24:25]
	s_mov_b32 m0, s50
	v_readfirstlane_b32 s50, v173
	global_load_lds_dwordx4 v[174:175], off
	v_lshl_add_u64 v[174:175], v[248:249], 0, s[24:25]
	s_mov_b32 m0, s50
	s_nop 0
	global_load_lds_dwordx4 v[174:175], off
	s_waitcnt vmcnt(6)
	s_barrier
	v_mfma_f32_16x16x32_bf16 v[28:31], v[190:193], v[222:225], v[28:31]
	v_mfma_f32_16x16x32_bf16 v[24:27], v[190:193], v[230:233], v[24:27]
	v_mfma_f32_16x16x32_bf16 v[20:23], v[198:201], v[222:225], v[20:23]
	v_mfma_f32_16x16x32_bf16 v[16:19], v[198:201], v[230:233], v[16:19]
	v_mfma_f32_16x16x32_bf16 v[12:15], v[206:209], v[222:225], v[12:15]
	v_mfma_f32_16x16x32_bf16 v[8:11], v[206:209], v[230:233], v[8:11]
	v_mfma_f32_16x16x32_bf16 v[4:7], v[214:217], v[222:225], v[4:7]
	v_mfma_f32_16x16x32_bf16 v[0:3], v[214:217], v[230:233], v[0:3]
	v_mfma_f32_16x16x32_bf16 v[28:31], v[194:197], v[226:229], v[28:31]
	v_mfma_f32_16x16x32_bf16 v[24:27], v[194:197], v[234:237], v[24:27]
	v_mfma_f32_16x16x32_bf16 v[20:23], v[202:205], v[226:229], v[20:23]
	v_mfma_f32_16x16x32_bf16 v[16:19], v[202:205], v[234:237], v[16:19]
	v_mfma_f32_16x16x32_bf16 v[12:15], v[210:213], v[226:229], v[12:15]
	v_mfma_f32_16x16x32_bf16 v[8:11], v[210:213], v[234:237], v[8:11]
	v_mfma_f32_16x16x32_bf16 v[4:7], v[218:221], v[226:229], v[4:7]
	v_mfma_f32_16x16x32_bf16 v[0:3], v[218:221], v[234:237], v[0:3]
	s_add_i32 s49, s49, 2
	s_add_u32 s28, s28, 0x100
	s_addc_u32 s29, s29, 0
	s_cmpk_gt_u32 s49, 0x51
	s_barrier
	s_cbranch_scc0 .LBB0_1624
	s_add_i32 s28, s48, 0x80
	s_mul_hi_i32 s29, s28, 0x2b00
	s_mulk_i32 s28, 0x2b00
	s_add_u32 s28, s34, s28
	s_addc_u32 s29, s35, s29
	s_add_u32 s28, s28, 0x2a80
	s_addc_u32 s29, s29, 0
	v_readfirstlane_b32 s49, v171
	v_lshl_add_u64 v[160:161], s[28:29], 0, v[128:129]
	s_mov_b32 m0, s49
	ds_read_b128 v[132:135], v163
	ds_read_b128 v[136:139], v163 offset:1024
	ds_read_b128 v[140:143], v163 offset:2048
	ds_read_b128 v[174:177], v163 offset:3072
	ds_read_b128 v[178:181], v154
	ds_read_b128 v[182:185], v154 offset:1024
	ds_read_b128 v[186:189], v153
	ds_read_b128 v[190:193], v153 offset:1024
	ds_read_b128 v[194:197], v151
	ds_read_b128 v[198:201], v151 offset:1024
	ds_read_b128 v[202:205], v150
	ds_read_b128 v[206:209], v150 offset:1024
	global_load_lds_dwordx4 v[160:161], off
	v_lshl_add_u64 v[160:161], s[28:29], 0, v[130:131]
	v_readfirstlane_b32 s28, v172
	s_mov_b32 m0, s28
	s_nop 0
	global_load_lds_dwordx4 v[160:161], off
	s_barrier
	s_waitcnt lgkmcnt(0)
	v_mfma_f32_16x16x32_bf16 v[124:127], v[178:181], v[132:135], v[124:127]
	v_mfma_f32_16x16x32_bf16 v[120:123], v[178:181], v[140:143], v[120:123]
	v_mfma_f32_16x16x32_bf16 v[116:119], v[186:189], v[132:135], v[116:119]
	v_mfma_f32_16x16x32_bf16 v[112:115], v[186:189], v[140:143], v[112:115]
	v_mfma_f32_16x16x32_bf16 v[108:111], v[194:197], v[132:135], v[108:111]
	v_mfma_f32_16x16x32_bf16 v[104:107], v[194:197], v[140:143], v[104:107]
	v_mfma_f32_16x16x32_bf16 v[100:103], v[202:205], v[132:135], v[100:103]
	v_mfma_f32_16x16x32_bf16 v[96:99], v[202:205], v[140:143], v[96:99]
	v_mfma_f32_16x16x32_bf16 v[124:127], v[182:185], v[136:139], v[124:127]
	v_mfma_f32_16x16x32_bf16 v[120:123], v[182:185], v[174:177], v[120:123]
	v_mfma_f32_16x16x32_bf16 v[116:119], v[190:193], v[136:139], v[116:119]
	v_mfma_f32_16x16x32_bf16 v[112:115], v[190:193], v[174:177], v[112:115]
	v_mfma_f32_16x16x32_bf16 v[108:111], v[198:201], v[136:139], v[108:111]
	v_mfma_f32_16x16x32_bf16 v[104:107], v[198:201], v[174:177], v[104:107]
	v_mfma_f32_16x16x32_bf16 v[100:103], v[206:209], v[136:139], v[100:103]
	v_mfma_f32_16x16x32_bf16 v[96:99], v[206:209], v[174:177], v[96:99]
	s_barrier
	ds_read_b128 v[210:213], v162
	ds_read_b128 v[214:217], v162 offset:1024
	ds_read_b128 v[218:221], v162 offset:2048
	ds_read_b128 v[160:163], v162 offset:3072
	s_barrier
; #define LDA(dst, b, h) for (int m = 0; m < 4; ++m) for (int k = 0; k < 2; ++k) \
;     dst[m][k] = *reinterpret_cast<const bf16x8*>((char*)SA(b, h) + lds_byte(wr * 64 + m * 16 + fr, k * 32 + fq * 8))
; #define LDB(dst, b, h) for (int n = 0; n < 2; ++n) for (int k = 0; k < 2; ++k) \
;     dst[n][k] = *reinterpret_cast<const bf16x8*>((char*)SB(b, h) + lds_byte(wc * 32 + n * 16 + fr, k * 32 + fq * 8))
; #define MMA(ai, bj, At_, Bt_) do { __builtin_amdgcn_s_setprio(1); \
;     for (int k = 0; k < 2; ++k) for (int m = 0; m < 4; ++m) for (int n = 0; n < 2; ++n) \
;       acc[ai][bj][m][n] = __builtin_amdgcn_mfma_f32_16x16x32_bf16(At_[m][k], Bt_[n][k], acc[ai][bj][m][n], 0, 0, 0); \
;     __builtin_amdgcn_s_setprio(0); } while (0)
; #define WAIT_V(n) asm volatile("s_waitcnt vmcnt(" #n ")" ::: "memory")
; #define WAIT_L(n) asm volatile("s_waitcnt lgkmcnt(" #n ")" ::: "memory")
; #define BAR __builtin_amdgcn_s_barrier()
; template <int EPI, int lda, int ldb, int N, int K>
; __device__ __forceinline__ void gemm_phase(const u16* __restrict__ A, const u16* __restrict__ Bt, const GemmEpi ep, int wv) {
;     ...
;       LDB(B1, 0, 1); BAR; WAIT_L(0); MMA(0, 1, At, B1); BAR;
;       LDA(At, 0, 1); WAIT_V(4); BAR; WAIT_L(0); MMA(1, 0, At, B0); MMA(1, 1, At, B1); BAR; }
;     { LDB(B0, 1, 0); LDA(At, 1, 0); WAIT_V(2); BAR; WAIT_L(0); MMA(0, 0, At, B0); BAR;
	s_waitcnt lgkmcnt(0)
	v_mfma_f32_16x16x32_bf16 v[92:95], v[178:181], v[210:213], v[92:95]
	v_mfma_f32_16x16x32_bf16 v[88:91], v[178:181], v[218:221], v[88:91]
	v_mfma_f32_16x16x32_bf16 v[72:75], v[194:197], v[218:221], v[72:75]
	v_mfma_f32_16x16x32_bf16 v[68:71], v[202:205], v[210:213], v[68:71]
	v_mfma_f32_16x16x32_bf16 v[84:87], v[186:189], v[210:213], v[84:87]
	v_mfma_f32_16x16x32_bf16 v[80:83], v[186:189], v[218:221], v[80:83]
	v_mfma_f32_16x16x32_bf16 v[76:79], v[194:197], v[210:213], v[76:79]
	v_mfma_f32_16x16x32_bf16 v[64:67], v[202:205], v[218:221], v[64:67]
	v_mfma_f32_16x16x32_bf16 v[92:95], v[182:185], v[214:217], v[92:95]
	v_mfma_f32_16x16x32_bf16 v[88:91], v[182:185], v[160:163], v[88:91]
	v_mfma_f32_16x16x32_bf16 v[72:75], v[198:201], v[160:163], v[72:75]
	v_mfma_f32_16x16x32_bf16 v[68:71], v[206:209], v[214:217], v[68:71]
	v_mfma_f32_16x16x32_bf16 v[178:181], v[190:193], v[214:217], v[84:87]
	v_mfma_f32_16x16x32_bf16 v[182:185], v[190:193], v[160:163], v[80:83]
	v_mfma_f32_16x16x32_bf16 v[186:189], v[198:201], v[214:217], v[76:79]
	v_mfma_f32_16x16x32_bf16 v[190:193], v[206:209], v[160:163], v[64:67]
	s_barrier
	s_nop 0
	ds_read_b128 v[64:67], v154 offset:16384
	ds_read_b128 v[76:79], v154 offset:17408
	ds_read_b128 v[80:83], v153 offset:16384
	ds_read_b128 v[84:87], v153 offset:17408
	ds_read_b128 v[194:197], v151 offset:16384
	ds_read_b128 v[198:201], v151 offset:17408
	ds_read_b128 v[202:205], v150 offset:16384
	ds_read_b128 v[206:209], v150 offset:17408
	s_waitcnt vmcnt(4)
	s_barrier
	s_waitcnt lgkmcnt(0)
	v_mfma_f32_16x16x32_bf16 v[60:63], v[64:67], v[132:135], v[60:63]
	v_mfma_f32_16x16x32_bf16 v[56:59], v[64:67], v[140:143], v[56:59]
	v_mfma_f32_16x16x32_bf16 v[52:55], v[80:83], v[132:135], v[52:55]
	v_mfma_f32_16x16x32_bf16 v[48:51], v[80:83], v[140:143], v[48:51]
	v_mfma_f32_16x16x32_bf16 v[44:47], v[194:197], v[132:135], v[44:47]
	v_mfma_f32_16x16x32_bf16 v[40:43], v[194:197], v[140:143], v[40:43]
	v_mfma_f32_16x16x32_bf16 v[36:39], v[202:205], v[132:135], v[36:39]
	v_mfma_f32_16x16x32_bf16 v[32:35], v[202:205], v[140:143], v[32:35]
	v_mfma_f32_16x16x32_bf16 v[60:63], v[76:79], v[136:139], v[60:63]
	v_mfma_f32_16x16x32_bf16 v[56:59], v[76:79], v[174:177], v[56:59]
	v_mfma_f32_16x16x32_bf16 v[52:55], v[84:87], v[136:139], v[52:55]
	v_mfma_f32_16x16x32_bf16 v[48:51], v[84:87], v[174:177], v[48:51]
	v_mfma_f32_16x16x32_bf16 v[44:47], v[198:201], v[136:139], v[44:47]
	v_mfma_f32_16x16x32_bf16 v[40:43], v[198:201], v[174:177], v[40:43]
	v_mfma_f32_16x16x32_bf16 v[36:39], v[206:209], v[136:139], v[36:39]
	v_mfma_f32_16x16x32_bf16 v[32:35], v[206:209], v[174:177], v[32:35]
	v_mfma_f32_16x16x32_bf16 v[28:31], v[64:67], v[210:213], v[28:31]
	v_mfma_f32_16x16x32_bf16 v[24:27], v[64:67], v[218:221], v[24:27]
	v_mfma_f32_16x16x32_bf16 v[12:15], v[194:197], v[210:213], v[12:15]
	v_mfma_f32_16x16x32_bf16 v[8:11], v[194:197], v[218:221], v[8:11]
	v_mfma_f32_16x16x32_bf16 v[20:23], v[80:83], v[210:213], v[20:23]
	v_mfma_f32_16x16x32_bf16 v[16:19], v[80:83], v[218:221], v[16:19]
	v_mfma_f32_16x16x32_bf16 v[4:7], v[202:205], v[210:213], v[4:7]
	v_mfma_f32_16x16x32_bf16 v[0:3], v[202:205], v[218:221], v[0:3]
	v_mfma_f32_16x16x32_bf16 v[28:31], v[76:79], v[214:217], v[28:31]
	v_mfma_f32_16x16x32_bf16 v[24:27], v[76:79], v[160:163], v[24:27]
	v_mfma_f32_16x16x32_bf16 v[12:15], v[198:201], v[214:217], v[12:15]
	v_mfma_f32_16x16x32_bf16 v[8:11], v[198:201], v[160:163], v[8:11]
	v_mfma_f32_16x16x32_bf16 v[132:135], v[84:87], v[214:217], v[20:23]
	v_mfma_f32_16x16x32_bf16 v[136:139], v[84:87], v[160:163], v[16:19]
	v_mfma_f32_16x16x32_bf16 v[140:143], v[206:209], v[214:217], v[4:7]
	v_mfma_f32_16x16x32_bf16 v[160:163], v[206:209], v[160:163], v[0:3]
	s_barrier
	s_nop 0
	ds_read_b128 v[0:3], v158
	ds_read_b128 v[4:7], v158 offset:1024
	ds_read_b128 v[16:19], v158 offset:2048
	ds_read_b128 v[172:175], v158 offset:3072
	ds_read_b128 v[20:23], v154 offset:32768
	ds_read_b128 v[194:197], v154 offset:33792
	ds_read_b128 v[198:201], v153 offset:32768
	ds_read_b128 v[202:205], v153 offset:33792
	ds_read_b128 v[206:209], v151 offset:32768
	ds_read_b128 v[210:213], v151 offset:33792
	ds_read_b128 v[214:217], v150 offset:32768
	ds_read_b128 v[218:221], v150 offset:33792
	s_waitcnt vmcnt(2)
	s_barrier
; #define LDA(dst, b, h) for (int m = 0; m < 4; ++m) for (int k = 0; k < 2; ++k) \
;     dst[m][k] = *reinterpret_cast<const bf16x8*>((char*)SA(b, h) + lds_byte(wr * 64 + m * 16 + fr, k * 32 + fq * 8))
; #define LDB(dst, b, h) for (int n = 0; n < 2; ++n) for (int k = 0; k < 2; ++k) \
;     dst[n][k] = *reinterpret_cast<const bf16x8*>((char*)SB(b, h) + lds_byte(wc * 32 + n * 16 + fr, k * 32 + fq * 8))
; #define MMA(ai, bj, At_, Bt_) do { __builtin_amdgcn_s_setprio(1); \
;     for (int k = 0; k < 2; ++k) for (int m = 0; m < 4; ++m) for (int n = 0; n < 2; ++n) \
;       acc[ai][bj][m][n] = __builtin_amdgcn_mfma_f32_16x16x32_bf16(At_[m][k], Bt_[n][k], acc[ai][bj][m][n], 0, 0, 0); \
;     __builtin_amdgcn_s_setprio(0); } while (0)
; #define WAIT_V(n) asm volatile("s_waitcnt vmcnt(" #n ")" ::: "memory")
; #define WAIT_L(n) asm volatile("s_waitcnt lgkmcnt(" #n ")" ::: "memory")
; #define BAR __builtin_amdgcn_s_barrier()
; template <int EPI, int lda, int ldb, int N, int K>
; __device__ __forceinline__ void gemm_phase(const u16* __restrict__ A, const u16* __restrict__ Bt, const GemmEpi ep, int wv) {
;     ...
;     { LDB(B0, 1, 0); LDA(At, 1, 0); WAIT_V(2); BAR; WAIT_L(0); MMA(0, 0, At, B0); BAR;
;       LDB(B1, 1, 1); WAIT_V(0); BAR; WAIT_L(0); MMA(0, 1, At, B1); BAR;
;       LDA(At, 1, 1); BAR; WAIT_L(0); MMA(1, 0, At, B0); MMA(1, 1, At, B1); BAR; }
;     if (wr == 0) BAR;
	s_waitcnt lgkmcnt(0)
	v_mfma_f32_16x16x32_bf16 v[64:67], v[20:23], v[0:3], v[124:127]
	v_mfma_f32_16x16x32_bf16 v[76:79], v[20:23], v[16:19], v[120:123]
	v_mfma_f32_16x16x32_bf16 v[80:83], v[198:201], v[0:3], v[116:119]
	v_mfma_f32_16x16x32_bf16 v[84:87], v[198:201], v[16:19], v[112:115]
	v_mfma_f32_16x16x32_bf16 v[108:111], v[206:209], v[0:3], v[108:111]
	v_mfma_f32_16x16x32_bf16 v[104:107], v[206:209], v[16:19], v[104:107]
	v_mfma_f32_16x16x32_bf16 v[120:123], v[214:217], v[0:3], v[100:103]
	v_mfma_f32_16x16x32_bf16 v[124:127], v[214:217], v[16:19], v[96:99]
	v_mfma_f32_16x16x32_bf16 v[116:119], v[194:197], v[4:7], v[64:67]
	v_mfma_f32_16x16x32_bf16 v[112:115], v[194:197], v[172:175], v[76:79]
	v_mfma_f32_16x16x32_bf16 v[100:103], v[202:205], v[4:7], v[80:83]
	v_mfma_f32_16x16x32_bf16 v[96:99], v[202:205], v[172:175], v[84:87]
	v_mfma_f32_16x16x32_bf16 v[84:87], v[210:213], v[4:7], v[108:111]
	v_mfma_f32_16x16x32_bf16 v[80:83], v[210:213], v[172:175], v[104:107]
	v_mfma_f32_16x16x32_bf16 v[76:79], v[218:221], v[4:7], v[120:123]
	v_mfma_f32_16x16x32_bf16 v[64:67], v[218:221], v[172:175], v[124:127]
	s_barrier
	ds_read_b128 v[222:225], v156
	ds_read_b128 v[226:229], v156 offset:1024
	ds_read_b128 v[230:233], v156 offset:2048
	ds_read_b128 v[156:159], v156 offset:3072
	s_waitcnt vmcnt(0)
	s_barrier
	s_waitcnt lgkmcnt(0)
	v_mfma_f32_16x16x32_bf16 v[92:95], v[20:23], v[222:225], v[92:95]
	v_mfma_f32_16x16x32_bf16 v[20:23], v[20:23], v[230:233], v[88:91]
	v_mfma_f32_16x16x32_bf16 v[88:91], v[198:201], v[222:225], v[178:181]
	v_mfma_f32_16x16x32_bf16 v[104:107], v[198:201], v[230:233], v[182:185]
	v_mfma_f32_16x16x32_bf16 v[176:179], v[206:209], v[222:225], v[186:189]
	v_mfma_f32_16x16x32_bf16 v[72:75], v[206:209], v[230:233], v[72:75]
	v_mfma_f32_16x16x32_bf16 v[68:71], v[214:217], v[222:225], v[68:71]
	v_mfma_f32_16x16x32_bf16 v[180:183], v[214:217], v[230:233], v[190:193]
	v_mfma_f32_16x16x32_bf16 v[124:127], v[194:197], v[226:229], v[92:95]
	v_mfma_f32_16x16x32_bf16 v[120:123], v[194:197], v[156:159], v[20:23]
	v_mfma_f32_16x16x32_bf16 v[108:111], v[202:205], v[226:229], v[88:91]
	v_mfma_f32_16x16x32_bf16 v[104:107], v[202:205], v[156:159], v[104:107]
	v_mfma_f32_16x16x32_bf16 v[92:95], v[210:213], v[226:229], v[176:179]
	v_mfma_f32_16x16x32_bf16 v[88:91], v[210:213], v[156:159], v[72:75]
	v_mfma_f32_16x16x32_bf16 v[72:75], v[218:221], v[226:229], v[68:71]
	v_mfma_f32_16x16x32_bf16 v[68:71], v[218:221], v[156:159], v[180:183]
	s_barrier
	ds_read_b128 v[176:179], v154 offset:49152
	ds_read_b128 v[180:183], v154 offset:50176
	ds_read_b128 v[184:187], v153 offset:49152
	ds_read_b128 v[188:191], v153 offset:50176
	ds_read_b128 v[192:195], v151 offset:49152
	ds_read_b128 v[196:199], v151 offset:50176
	ds_read_b128 v[200:203], v150 offset:49152
	ds_read_b128 v[204:207], v150 offset:50176
	s_barrier
	s_waitcnt lgkmcnt(0)
	v_mfma_f32_16x16x32_bf16 v[20:23], v[176:179], v[0:3], v[60:63]
	v_mfma_f32_16x16x32_bf16 v[56:59], v[176:179], v[16:19], v[56:59]
	v_mfma_f32_16x16x32_bf16 v[60:63], v[184:187], v[0:3], v[52:55]
	v_mfma_f32_16x16x32_bf16 v[208:211], v[184:187], v[16:19], v[48:51]
	v_mfma_f32_16x16x32_bf16 v[44:47], v[192:195], v[0:3], v[44:47]
	v_mfma_f32_16x16x32_bf16 v[40:43], v[192:195], v[16:19], v[40:43]
	v_mfma_f32_16x16x32_bf16 v[0:3], v[200:203], v[0:3], v[36:39]
	v_mfma_f32_16x16x32_bf16 v[212:215], v[200:203], v[16:19], v[32:35]
	v_mfma_f32_16x16x32_bf16 v[52:55], v[180:183], v[4:7], v[20:23]
	v_mfma_f32_16x16x32_bf16 v[48:51], v[180:183], v[172:175], v[56:59]
	v_mfma_f32_16x16x32_bf16 v[36:39], v[188:191], v[4:7], v[60:63]
	v_mfma_f32_16x16x32_bf16 v[32:35], v[188:191], v[172:175], v[208:211]
	v_mfma_f32_16x16x32_bf16 v[20:23], v[196:199], v[4:7], v[44:47]
	v_mfma_f32_16x16x32_bf16 v[16:19], v[196:199], v[172:175], v[40:43]
	v_mfma_f32_16x16x32_bf16 v[4:7], v[204:207], v[4:7], v[0:3]
	v_mfma_f32_16x16x32_bf16 v[0:3], v[204:207], v[172:175], v[212:215]
	v_mfma_f32_16x16x32_bf16 v[28:31], v[176:179], v[222:225], v[28:31]
	v_mfma_f32_16x16x32_bf16 v[24:27], v[176:179], v[230:233], v[24:27]
	v_mfma_f32_16x16x32_bf16 v[40:43], v[184:187], v[222:225], v[132:135]
	v_mfma_f32_16x16x32_bf16 v[132:135], v[184:187], v[230:233], v[136:139]
	v_mfma_f32_16x16x32_bf16 v[12:15], v[192:195], v[222:225], v[12:15]
	v_mfma_f32_16x16x32_bf16 v[8:11], v[192:195], v[230:233], v[8:11]
	v_mfma_f32_16x16x32_bf16 v[136:139], v[200:203], v[222:225], v[140:143]
	v_mfma_f32_16x16x32_bf16 v[140:143], v[200:203], v[230:233], v[160:163]
	v_mfma_f32_16x16x32_bf16 v[60:63], v[180:183], v[226:229], v[28:31]
	v_mfma_f32_16x16x32_bf16 v[56:59], v[180:183], v[156:159], v[24:27]
	v_mfma_f32_16x16x32_bf16 v[44:47], v[188:191], v[226:229], v[40:43]
	v_mfma_f32_16x16x32_bf16 v[40:43], v[188:191], v[156:159], v[132:135]
	v_mfma_f32_16x16x32_bf16 v[28:31], v[196:199], v[226:229], v[12:15]
	v_mfma_f32_16x16x32_bf16 v[24:27], v[196:199], v[156:159], v[8:11]
	v_mfma_f32_16x16x32_bf16 v[12:15], v[204:207], v[226:229], v[136:139]
	v_mfma_f32_16x16x32_bf16 v[8:11], v[204:207], v[156:159], v[140:143]
	v_cmp_gt_u32_e32 vcc, s46, v147
	s_barrier
	s_and_saveexec_b64 s[28:29], vcc
	s_cbranch_execz .LBB0_1627
	s_barrier
